# PEER list build without the 64-step ballot loop: LDS atomics give ranks inside (token, chunk), run tables computed lane-parallel
# speedup vs baseline: 1.0025x; 1.0025x over previous
; __device__ __forceinline__ unsigned f2key(float f) { const unsigned u = __float_as_uint(f); return (u & 0x80000000u) ? ~u : (u | 0x80000000u); }
; __device__ __forceinline__ void peer_tile(const Args& A, LAS unsigned char* lds, int tile) {
;     ...
;         const int tg = w & 3, hg = w >> 2, tl = 16 * tg + l15;
;         const size_t m = (size_t)tile * 64 + tl;
;         unsigned LA[4][2][16];
; #pragma unroll
;         for (int hh = 0; hh < 4; ++hh) {
;             const int h = 4 * hg + hh;
; #pragma unroll
;             for (int p = 0; p < 2; ++p) {
;                 const int hp = 2 * h + p;
;                 unsigned k0[16], k1[16];
;                 { const bf16_t* sp = QRY + m * 2048 + hp * 128 + 32 * g;
;                   const u32x4 s0 = *(const u32x4*)sp, s1 = *(const u32x4*)(sp + 8), s2 = *(const u32x4*)(sp + 16), s3 = *(const u32x4*)(sp + 24);
;                   const unsigned sw[16] = {s0.x, s0.y, s0.z, s0.w, s1.x, s1.y, s1.z, s1.w, s2.x, s2.y, s2.z, s2.w, s3.x, s3.y, s3.z, s3.w};
; #pragma unroll
;                   for (int i = 0; i < 16; ++i) {
;                       const float lo = (float)__builtin_bit_cast(_Float16, (unsigned short)(sw[i] & 0xffffu)), hi = (float)__builtin_bit_cast(_Float16, (unsigned short)(sw[i] >> 16));
;                       const unsigned klo = (f2key(lo) & ~127u) | (unsigned)(127 - (32 * g + 2 * i)), khi = (f2key(hi) & ~127u) | (unsigned)(127 - (32 * g + 2 * i + 1));
;                       if (i < 8) { k0[2 * i] = klo; k0[2 * i + 1] = khi; } else { k1[2 * (i - 8)] = klo; k1[2 * (i - 8) + 1] = khi; } } }
.LBB0_699:
	v_mov_b32_e32 v19, v214
	s_ashr_i32 s3, s2, 31
	v_ashrrev_i32_e32 v7, 6, v19
	v_and_b32_e32 v0, 15, v19
	v_lshlrev_b32_e32 v1, 4, v7
	v_and_or_b32 v13, v1, 48, v0
	s_lshl_b64 s[28:29], s[2:3], 6
	v_or_b32_e32 v0, s28, v13
	v_mov_b32_e32 v1, s29
	v_bfe_u32 v221, v19, 4, 2
	v_ashrrev_i32_e32 v11, 8, v19
	v_lshlrev_b64 v[0:1], 12, v[0:1]
	v_lshlrev_b32_e32 v2, 10, v11
	v_lshl_add_u64 v[0:1], s[54:55], 0, v[0:1]
	v_lshlrev_b32_e32 v112, 6, v221
	v_lshl_add_u64 v[0:1], v[0:1], 0, v[112:113]
	v_ashrrev_i32_e32 v3, 31, v2
	v_lshl_add_u64 v[4:5], v[2:3], 1, v[0:1]
	global_load_dwordx4 v[20:23], v[4:5], off
	global_load_dwordx4 v[24:27], v[4:5], off offset:16
	global_load_dwordx4 v[0:3], v[4:5], off offset:48
	global_load_dwordx4 v[28:31], v[4:5], off offset:32
	v_lshlrev_b32_e32 v15, 5, v221
	v_or_b32_e32 v8, 8, v15
	v_or_b32_e32 v14, 2, v15
	v_or_b32_e32 v12, 4, v15
	v_or_b32_e32 v10, 6, v15
	v_and_b32_e32 v9, 63, v19
	v_cmp_gt_u32_e64 s[0:1], 16, v9
	v_cmp_gt_u32_e64 s[4:5], 32, v9
	v_mul_lo_u32 v6, v19, s17
	s_mov_b32 s3, 8
	s_waitcnt vmcnt(3)
	v_cvt_f32_f16_sdwa v17, v20 dst_sel:DWORD dst_unused:UNUSED_PAD src0_sel:WORD_1
	v_cvt_f32_f16_e32 v16, v20
	v_cvt_f32_f16_sdwa v20, v21 dst_sel:DWORD dst_unused:UNUSED_PAD src0_sel:WORD_1
	v_cvt_f32_f16_e32 v18, v21
	v_cvt_f32_f16_e32 v21, v22
	v_cvt_f32_f16_sdwa v22, v22 dst_sel:DWORD dst_unused:UNUSED_PAD src0_sel:WORD_1
	v_not_b32_e32 v34, v17
	v_or_b32_e32 v35, 0x80000000, v17
	v_cmp_gt_i32_e32 vcc, 0, v17
	v_not_b32_e32 v36, v16
	v_or_b32_e32 v37, 0x80000000, v16
	v_cndmask_b32_e32 v17, v35, v34, vcc
	v_cmp_gt_i32_e32 vcc, 0, v16
	v_cvt_f32_f16_e32 v32, v23
	v_cvt_f32_f16_sdwa v23, v23 dst_sel:DWORD dst_unused:UNUSED_PAD src0_sel:WORD_1
	v_not_b32_e32 v38, v20
	v_or_b32_e32 v39, 0x80000000, v20
	v_cndmask_b32_e32 v16, v37, v36, vcc
	v_cmp_gt_i32_e32 vcc, 0, v20
	v_not_b32_e32 v40, v18
	v_or_b32_e32 v41, 0x80000000, v18
	v_cndmask_b32_e32 v20, v39, v38, vcc
	v_cmp_gt_i32_e32 vcc, 0, v18
	s_waitcnt vmcnt(2)
	v_cvt_f32_f16_e32 v33, v24
	v_cvt_f32_f16_sdwa v24, v24 dst_sel:DWORD dst_unused:UNUSED_PAD src0_sel:WORD_1
	v_not_b32_e32 v42, v22
	v_or_b32_e32 v43, 0x80000000, v22
	v_cndmask_b32_e32 v18, v41, v40, vcc
	v_cmp_gt_i32_e32 vcc, 0, v22
	v_not_b32_e32 v44, v21
	v_or_b32_e32 v45, 0x80000000, v21
	v_cndmask_b32_e32 v22, v43, v42, vcc
	v_cmp_gt_i32_e32 vcc, 0, v21
	v_not_b32_e32 v46, v23
	v_or_b32_e32 v47, 0x80000000, v23
	v_cndmask_b32_e32 v21, v45, v44, vcc
	v_cmp_gt_i32_e32 vcc, 0, v23
	v_not_b32_e32 v48, v32
	v_or_b32_e32 v49, 0x80000000, v32
	v_cndmask_b32_e32 v23, v47, v46, vcc
	v_cmp_gt_i32_e32 vcc, 0, v32
	v_and_b32_e32 v16, 0xffffff80, v16
	v_not_b32_e32 v50, v24
	v_or_b32_e32 v51, 0x80000000, v24
	v_cndmask_b32_e32 v32, v49, v48, vcc
	v_sub_u32_e32 v16, v16, v15
	v_cmp_gt_i32_e32 vcc, 0, v24
	v_add_u32_e32 v35, 0x7f, v16
	v_and_b32_e32 v17, 0xffffff80, v17
	v_cndmask_b32_e32 v16, v51, v50, vcc
	v_and_b32_e32 v16, 0xffffff80, v16
	v_sub_u32_e32 v17, v17, v15
	v_sub_u32_e32 v16, v16, v8
	v_add_u32_e32 v34, 0x7e, v17
	v_add_u32_e32 v41, 0x7e, v16
	v_not_b32_e32 v16, v33
	v_or_b32_e32 v17, 0x80000000, v33
	v_cmp_gt_i32_e32 vcc, 0, v33
	v_and_b32_e32 v20, 0xffffff80, v20
	v_and_b32_e32 v18, 0xffffff80, v18
	v_cndmask_b32_e32 v16, v17, v16, vcc
	v_cvt_f32_f16_sdwa v17, v25 dst_sel:DWORD dst_unused:UNUSED_PAD src0_sel:WORD_1
	v_and_b32_e32 v21, 0xffffff80, v21
	v_sub_u32_e32 v20, v20, v14
	v_sub_u32_e32 v18, v18, v14
	v_sub_u32_e32 v21, v21, v12
	v_add_u32_e32 v36, 0x7e, v20
	v_add_u32_e32 v37, 0x7f, v18
	v_add_u32_e32 v39, 0x7f, v21
	v_and_b32_e32 v16, 0xffffff80, v16
	v_cvt_f32_f16_e32 v18, v25
	v_not_b32_e32 v20, v17
	v_or_b32_e32 v21, 0x80000000, v17
	v_cmp_gt_i32_e32 vcc, 0, v17
	v_sub_u32_e32 v16, v16, v8
	v_add_u32_e32 v33, 0x7f, v16
	v_cndmask_b32_e32 v17, v21, v20, vcc
	v_or_b32_e32 v16, 10, v15
	v_and_b32_e32 v17, 0xffffff80, v17
	v_sub_u32_e32 v17, v17, v16
	v_add_u32_e32 v42, 0x7e, v17
	v_not_b32_e32 v17, v18
	v_or_b32_e32 v20, 0x80000000, v18
	v_cmp_gt_i32_e32 vcc, 0, v18
	v_cvt_f32_f16_sdwa v18, v26 dst_sel:DWORD dst_unused:UNUSED_PAD src0_sel:WORD_1
	v_and_b32_e32 v22, 0xffffff80, v22
	v_sub_u32_e32 v22, v22, v12
	v_cndmask_b32_e32 v17, v20, v17, vcc
	v_add_u32_e32 v38, 0x7e, v22
	v_and_b32_e32 v17, 0xffffff80, v17
	v_cvt_f32_f16_e32 v20, v26
	v_not_b32_e32 v21, v18
	v_or_b32_e32 v22, 0x80000000, v18
	v_cmp_gt_i32_e32 vcc, 0, v18
	v_sub_u32_e32 v17, v17, v16
	v_add_u32_e32 v43, 0x7f, v17
	v_cndmask_b32_e32 v18, v22, v21, vcc
	v_or_b32_e32 v17, 12, v15
	v_and_b32_e32 v18, 0xffffff80, v18
	v_sub_u32_e32 v18, v18, v17
	v_add_u32_e32 v44, 0x7e, v18
	v_not_b32_e32 v18, v20
	v_or_b32_e32 v21, 0x80000000, v20
	v_cmp_gt_i32_e32 vcc, 0, v20
	v_cvt_f32_f16_sdwa v20, v27 dst_sel:DWORD dst_unused:UNUSED_PAD src0_sel:WORD_1
	v_and_b32_e32 v23, 0xffffff80, v23
	v_sub_u32_e32 v23, v23, v10
	v_cndmask_b32_e32 v18, v21, v18, vcc
	v_add_u32_e32 v40, 0x7e, v23
	v_and_b32_e32 v18, 0xffffff80, v18
	v_cvt_f32_f16_e32 v21, v27
	v_not_b32_e32 v22, v20
	v_or_b32_e32 v23, 0x80000000, v20
	v_cmp_gt_i32_e32 vcc, 0, v20
	v_sub_u32_e32 v18, v18, v17
	v_add_u32_e32 v45, 0x7f, v18
	v_cndmask_b32_e32 v20, v23, v22, vcc
	v_or_b32_e32 v18, 14, v15
	v_and_b32_e32 v20, 0xffffff80, v20
	v_sub_u32_e32 v20, v20, v18
	v_add_u32_e32 v27, 0x7e, v20
	v_not_b32_e32 v20, v21
	v_or_b32_e32 v22, 0x80000000, v21
	v_cmp_gt_i32_e32 vcc, 0, v21
	s_waitcnt vmcnt(0)
; __device__ __forceinline__ unsigned f2key(float f) { const unsigned u = __float_as_uint(f); return (u & 0x80000000u) ? ~u : (u | 0x80000000u); }
; __device__ __forceinline__ void peer_tile(const Args& A, LAS unsigned char* lds, int tile) {
;     ...
;                 { const bf16_t* sp = QRY + m * 2048 + hp * 128 + 32 * g;
;                   const u32x4 s0 = *(const u32x4*)sp, s1 = *(const u32x4*)(sp + 8), s2 = *(const u32x4*)(sp + 16), s3 = *(const u32x4*)(sp + 24);
;                   const unsigned sw[16] = {s0.x, s0.y, s0.z, s0.w, s1.x, s1.y, s1.z, s1.w, s2.x, s2.y, s2.z, s2.w, s3.x, s3.y, s3.z, s3.w};
; #pragma unroll
;                   for (int i = 0; i < 16; ++i) {
;                       const float lo = (float)__builtin_bit_cast(_Float16, (unsigned short)(sw[i] & 0xffffu)), hi = (float)__builtin_bit_cast(_Float16, (unsigned short)(sw[i] >> 16));
;                       const unsigned klo = (f2key(lo) & ~127u) | (unsigned)(127 - (32 * g + 2 * i)), khi = (f2key(hi) & ~127u) | (unsigned)(127 - (32 * g + 2 * i + 1));
;                       if (i < 8) { k0[2 * i] = klo; k0[2 * i + 1] = khi; } else { k1[2 * (i - 8)] = klo; k1[2 * (i - 8) + 1] = khi; } } }
;                 sort16_desc(k0); sort16_desc(k1); merge16(k0, k1);
	v_cvt_f32_f16_sdwa v21, v28 dst_sel:DWORD dst_unused:UNUSED_PAD src0_sel:WORD_1
	v_and_b32_e32 v32, 0xffffff80, v32
	v_cndmask_b32_e32 v20, v22, v20, vcc
	v_and_b32_e32 v20, 0xffffff80, v20
	v_cvt_f32_f16_e32 v22, v28
	v_not_b32_e32 v23, v21
	v_or_b32_e32 v24, 0x80000000, v21
	v_cmp_gt_i32_e32 vcc, 0, v21
	v_sub_u32_e32 v20, v20, v18
	v_add_u32_e32 v46, 0x7f, v20
	v_cndmask_b32_e32 v21, v24, v23, vcc
	v_or_b32_e32 v20, 16, v15
	v_and_b32_e32 v21, 0xffffff80, v21
	v_sub_u32_e32 v21, v21, v20
	v_add_u32_e32 v47, 0x7e, v21
	v_not_b32_e32 v21, v22
	v_or_b32_e32 v23, 0x80000000, v22
	v_cmp_gt_i32_e32 vcc, 0, v22
	v_cvt_f32_f16_sdwa v22, v29 dst_sel:DWORD dst_unused:UNUSED_PAD src0_sel:WORD_1
	v_sub_u32_e32 v32, v32, v10
	v_cndmask_b32_e32 v21, v23, v21, vcc
	v_and_b32_e32 v21, 0xffffff80, v21
	v_cvt_f32_f16_e32 v23, v29
	v_not_b32_e32 v24, v22
	v_or_b32_e32 v25, 0x80000000, v22
	v_cmp_gt_i32_e32 vcc, 0, v22
	v_sub_u32_e32 v21, v21, v20
	v_add_u32_e32 v48, 0x7f, v21
	v_cndmask_b32_e32 v22, v25, v24, vcc
	v_or_b32_e32 v21, 18, v15
	v_and_b32_e32 v22, 0xffffff80, v22
	v_sub_u32_e32 v22, v22, v21
	v_add_u32_e32 v29, 0x7e, v22
	v_not_b32_e32 v22, v23
	v_or_b32_e32 v24, 0x80000000, v23
	v_cmp_gt_i32_e32 vcc, 0, v23
	v_cvt_f32_f16_sdwa v23, v30 dst_sel:DWORD dst_unused:UNUSED_PAD src0_sel:WORD_1
	v_add_u32_e32 v32, 0x7f, v32
	v_cndmask_b32_e32 v22, v24, v22, vcc
	v_and_b32_e32 v22, 0xffffff80, v22
	v_cvt_f32_f16_e32 v24, v30
	v_not_b32_e32 v25, v23
	v_or_b32_e32 v26, 0x80000000, v23
	v_cmp_gt_i32_e32 vcc, 0, v23
	v_sub_u32_e32 v22, v22, v21
	v_add_u32_e32 v49, 0x7f, v22
	v_cndmask_b32_e32 v23, v26, v25, vcc
	v_or_b32_e32 v22, 20, v15
	v_and_b32_e32 v23, 0xffffff80, v23
	v_sub_u32_e32 v23, v23, v22
	v_add_u32_e32 v30, 0x7e, v23
	v_not_b32_e32 v23, v24
	v_or_b32_e32 v25, 0x80000000, v24
	v_cmp_gt_i32_e32 vcc, 0, v24
	v_cvt_f32_f16_sdwa v24, v31 dst_sel:DWORD dst_unused:UNUSED_PAD src0_sel:WORD_1
	v_max_u32_e32 v64, v48, v47
	v_cndmask_b32_e32 v23, v25, v23, vcc
	v_and_b32_e32 v23, 0xffffff80, v23
	v_cvt_f32_f16_e32 v25, v31
	v_not_b32_e32 v26, v24
	v_or_b32_e32 v28, 0x80000000, v24
	v_cmp_gt_i32_e32 vcc, 0, v24
	v_sub_u32_e32 v23, v23, v22
	v_add_u32_e32 v50, 0x7f, v23
	v_cndmask_b32_e32 v24, v28, v26, vcc
	v_or_b32_e32 v23, 22, v15
	v_and_b32_e32 v24, 0xffffff80, v24
	v_sub_u32_e32 v24, v24, v23
	v_add_u32_e32 v31, 0x7e, v24
	v_not_b32_e32 v24, v25
	v_or_b32_e32 v26, 0x80000000, v25
	v_cmp_gt_i32_e32 vcc, 0, v25
	v_cvt_f32_f16_sdwa v25, v0 dst_sel:DWORD dst_unused:UNUSED_PAD src0_sel:WORD_1
	v_cvt_f32_f16_e32 v0, v0
	v_cndmask_b32_e32 v24, v26, v24, vcc
	v_and_b32_e32 v24, 0xffffff80, v24
	v_not_b32_e32 v26, v25
	v_or_b32_e32 v28, 0x80000000, v25
	v_cmp_gt_i32_e32 vcc, 0, v25
	v_sub_u32_e32 v24, v24, v23
	v_add_u32_e32 v51, 0x7f, v24
	v_cndmask_b32_e32 v25, v28, v26, vcc
	v_or_b32_e32 v24, 24, v15
	v_and_b32_e32 v25, 0xffffff80, v25
	v_sub_u32_e32 v25, v25, v24
	v_add_u32_e32 v52, 0x7e, v25
	v_not_b32_e32 v25, v0
	v_or_b32_e32 v26, 0x80000000, v0
	v_cmp_gt_i32_e32 vcc, 0, v0
	v_min_u32_e32 v47, v48, v47
	v_max_u32_e32 v48, v29, v49
	v_cndmask_b32_e32 v0, v26, v25, vcc
	v_cvt_f32_f16_sdwa v26, v1 dst_sel:DWORD dst_unused:UNUSED_PAD src0_sel:WORD_1
	v_cvt_f32_f16_e32 v1, v1
	v_or_b32_e32 v25, 26, v15
	v_and_b32_e32 v0, 0xffffff80, v0
	v_not_b32_e32 v28, v26
	v_or_b32_e32 v53, 0x80000000, v26
	v_cmp_gt_i32_e32 vcc, 0, v26
	v_sub_u32_e32 v0, v0, v24
	v_add_u32_e32 v0, 0x7f, v0
	v_cndmask_b32_e32 v26, v53, v28, vcc
	v_and_b32_e32 v26, 0xffffff80, v26
	v_sub_u32_e32 v26, v26, v25
	v_add_u32_e32 v53, 0x7e, v26
	v_not_b32_e32 v26, v1
	v_or_b32_e32 v28, 0x80000000, v1
	v_cmp_gt_i32_e32 vcc, 0, v1
	v_min_u32_e32 v29, v29, v49
	v_max_u32_e32 v49, v50, v30
	v_cndmask_b32_e32 v1, v28, v26, vcc
	v_cvt_f32_f16_sdwa v28, v2 dst_sel:DWORD dst_unused:UNUSED_PAD src0_sel:WORD_1
	v_cvt_f32_f16_e32 v2, v2
	v_or_b32_e32 v26, 28, v15
	v_and_b32_e32 v1, 0xffffff80, v1
	v_not_b32_e32 v54, v28
	v_or_b32_e32 v55, 0x80000000, v28
	v_cmp_gt_i32_e32 vcc, 0, v28
	v_sub_u32_e32 v1, v1, v25
	v_add_u32_e32 v1, 0x7f, v1
	v_cndmask_b32_e32 v28, v55, v54, vcc
	v_and_b32_e32 v28, 0xffffff80, v28
	v_sub_u32_e32 v28, v28, v26
	v_add_u32_e32 v54, 0x7e, v28
	v_not_b32_e32 v28, v2
	v_or_b32_e32 v55, 0x80000000, v2
	v_cmp_gt_i32_e32 vcc, 0, v2
	v_min_u32_e32 v30, v50, v30
	v_max_u32_e32 v50, v31, v51
	v_cndmask_b32_e32 v2, v55, v28, vcc
	v_cvt_f32_f16_e32 v55, v3
	v_cvt_f32_f16_sdwa v3, v3 dst_sel:DWORD dst_unused:UNUSED_PAD src0_sel:WORD_1
	v_and_b32_e32 v2, 0xffffff80, v2
	v_or_b32_e32 v28, 30, v15
	v_not_b32_e32 v56, v55
	v_or_b32_e32 v57, 0x80000000, v55
	v_cmp_gt_i32_e32 vcc, 0, v55
	v_sub_u32_e32 v2, v2, v26
	v_add_u32_e32 v2, 0x7f, v2
	v_cndmask_b32_e32 v55, v57, v56, vcc
	v_not_b32_e32 v56, v3
	v_or_b32_e32 v57, 0x80000000, v3
	v_cmp_gt_i32_e32 vcc, 0, v3
	v_and_b32_e32 v55, 0xffffff80, v55
	v_sub_u32_e32 v55, v55, v28
	v_cndmask_b32_e32 v3, v57, v56, vcc
	v_and_b32_e32 v3, 0xffffff80, v3
	v_sub_u32_e32 v3, v3, v28
	v_add_u32_e32 v55, 0x7f, v55
	v_add_u32_e32 v3, 0x7e, v3
	v_max_u32_e32 v56, v35, v34
	v_min_u32_e32 v34, v35, v34
	v_max_u32_e32 v35, v36, v37
	v_min_u32_e32 v36, v36, v37
	v_max_u32_e32 v37, v39, v38
	v_min_u32_e32 v38, v39, v38
	v_max_u32_e32 v39, v40, v32
	v_min_u32_e32 v32, v40, v32
	v_max_u32_e32 v40, v33, v41
	v_min_u32_e32 v33, v33, v41
	v_max_u32_e32 v41, v42, v43
	v_min_u32_e32 v42, v42, v43
	v_max_u32_e32 v43, v45, v44
	v_min_u32_e32 v44, v45, v44
	v_max_u32_e32 v45, v27, v46
	v_min_u32_e32 v27, v27, v46
	v_min_u32_e32 v31, v31, v51
	v_max_u32_e32 v51, v0, v52
	v_min_u32_e32 v0, v0, v52
	v_max_u32_e32 v52, v53, v1
	v_min_u32_e32 v1, v53, v1
	v_max_u32_e32 v53, v2, v54
; #define CE_DESC(a, b) do { const unsigned _mx = (a) > (b) ? (a) : (b), _mn = (a) > (b) ? (b) : (a); (a) = _mx; (b) = _mn; } while (0)
; __device__ __forceinline__ void sort16_desc(unsigned (&k)[16]) {
; #pragma unroll
;     for (int size = 2; size <= 16; size <<= 1)
; #pragma unroll
;         for (int stride = size >> 1; stride > 0; stride >>= 1)
; #pragma unroll
;             for (int i = 0; i < 16; ++i) { const int j = i ^ stride;
;                 if (j > i) { if ((i & size) == 0) CE_DESC(k[i], k[j]); else CE_DESC(k[j], k[i]); } }
; }
	v_min_u32_e32 v2, v2, v54
	v_max_u32_e32 v54, v3, v55
	v_min_u32_e32 v3, v3, v55
	v_max_u32_e32 v46, v56, v36
	v_min_u32_e32 v36, v56, v36
	v_max_u32_e32 v56, v34, v35
	v_min_u32_e32 v34, v34, v35
	v_max_u32_e32 v35, v32, v37
	v_min_u32_e32 v32, v32, v37
	v_max_u32_e32 v37, v39, v38
	v_min_u32_e32 v38, v39, v38
	v_max_u32_e32 v39, v40, v42
	v_min_u32_e32 v40, v40, v42
	v_max_u32_e32 v42, v33, v41
	v_min_u32_e32 v33, v33, v41
	v_max_u32_e32 v41, v27, v43
	v_min_u32_e32 v27, v27, v43
	v_max_u32_e32 v43, v45, v44
	v_min_u32_e32 v44, v45, v44
	v_max_u32_e32 v55, v64, v29
	v_min_u32_e32 v29, v64, v29
	v_max_u32_e32 v64, v47, v48
	v_min_u32_e32 v47, v47, v48
	v_max_u32_e32 v48, v31, v49
	v_min_u32_e32 v31, v31, v49
	v_max_u32_e32 v49, v50, v30
	v_min_u32_e32 v30, v50, v30
	v_max_u32_e32 v50, v51, v1
	v_min_u32_e32 v1, v51, v1
	v_max_u32_e32 v51, v0, v52
	v_min_u32_e32 v0, v0, v52
	v_max_u32_e32 v52, v3, v53
	v_min_u32_e32 v3, v3, v53
	v_max_u32_e32 v53, v54, v2
	v_min_u32_e32 v2, v54, v2
	v_max_u32_e32 v45, v46, v56
	v_min_u32_e32 v46, v46, v56
	v_max_u32_e32 v56, v36, v34
	v_min_u32_e32 v34, v36, v34
	v_max_u32_e32 v36, v38, v32
	v_min_u32_e32 v32, v38, v32
	v_max_u32_e32 v38, v37, v35
	v_min_u32_e32 v35, v37, v35
	v_max_u32_e32 v37, v39, v42
	v_min_u32_e32 v39, v39, v42
	v_max_u32_e32 v42, v40, v33
	v_min_u32_e32 v33, v40, v33
	v_max_u32_e32 v40, v44, v27
	v_min_u32_e32 v27, v44, v27
	v_max_u32_e32 v44, v43, v41
	v_min_u32_e32 v41, v43, v41
	v_max_u32_e32 v54, v55, v64
	v_min_u32_e32 v55, v55, v64
	v_max_u32_e32 v64, v29, v47
	v_min_u32_e32 v29, v29, v47
	v_max_u32_e32 v47, v30, v31
	v_min_u32_e32 v30, v30, v31
	v_max_u32_e32 v31, v49, v48
	v_min_u32_e32 v48, v49, v48
	v_max_u32_e32 v49, v50, v51
	v_min_u32_e32 v50, v50, v51
	v_max_u32_e32 v51, v1, v0
	v_min_u32_e32 v0, v1, v0
	v_max_u32_e32 v1, v2, v3
	v_min_u32_e32 v2, v2, v3
	v_max_u32_e32 v3, v53, v52
	v_min_u32_e32 v52, v53, v52
	v_max_u32_e32 v43, v45, v32
	v_min_u32_e32 v32, v45, v32
	v_max_u32_e32 v45, v46, v36
	v_min_u32_e32 v36, v46, v36
	v_max_u32_e32 v46, v56, v35
	v_min_u32_e32 v35, v56, v35
	v_max_u32_e32 v56, v34, v38
	v_min_u32_e32 v34, v34, v38
	v_max_u32_e32 v38, v27, v37
	v_min_u32_e32 v27, v27, v37
	v_max_u32_e32 v37, v40, v39
	v_min_u32_e32 v39, v40, v39
	v_max_u32_e32 v40, v41, v42
	v_min_u32_e32 v41, v41, v42
	v_max_u32_e32 v42, v44, v33
	v_min_u32_e32 v33, v44, v33
	v_max_u32_e32 v53, v54, v30
	v_min_u32_e32 v30, v54, v30
	v_max_u32_e32 v54, v55, v47
	v_min_u32_e32 v47, v55, v47
	v_max_u32_e32 v55, v64, v48
	v_min_u32_e32 v48, v64, v48
	v_max_u32_e32 v64, v29, v31
	v_min_u32_e32 v29, v29, v31
	v_max_u32_e32 v31, v2, v49
	v_min_u32_e32 v2, v2, v49
	v_max_u32_e32 v49, v1, v50
	v_min_u32_e32 v1, v1, v50
	v_max_u32_e32 v50, v52, v51
	v_min_u32_e32 v51, v52, v51
	v_max_u32_e32 v52, v3, v0
	v_min_u32_e32 v0, v3, v0
	v_max_u32_e32 v44, v43, v46
	v_min_u32_e32 v43, v43, v46
	v_max_u32_e32 v46, v45, v56
	v_min_u32_e32 v45, v45, v56
	v_max_u32_e32 v56, v32, v35
	v_min_u32_e32 v32, v32, v35
	v_max_u32_e32 v35, v36, v34
	v_min_u32_e32 v34, v36, v34
	v_max_u32_e32 v36, v41, v27
	v_min_u32_e32 v27, v41, v27
	v_max_u32_e32 v41, v33, v39
	v_min_u32_e32 v33, v33, v39
	v_max_u32_e32 v39, v40, v38
	v_min_u32_e32 v38, v40, v38
	v_max_u32_e32 v40, v42, v37
	v_min_u32_e32 v37, v42, v37
	v_max_u32_e32 v3, v53, v55
	v_min_u32_e32 v53, v53, v55
	v_max_u32_e32 v55, v54, v64
	v_min_u32_e32 v54, v54, v64
	v_max_u32_e32 v64, v30, v48
	v_min_u32_e32 v30, v30, v48
	v_max_u32_e32 v48, v47, v29
	v_min_u32_e32 v29, v47, v29
	v_max_u32_e32 v47, v51, v2
	v_min_u32_e32 v2, v51, v2
	v_max_u32_e32 v51, v0, v1
	v_min_u32_e32 v0, v0, v1
	v_max_u32_e32 v1, v50, v31
	v_min_u32_e32 v31, v50, v31
	v_max_u32_e32 v50, v52, v49
	v_min_u32_e32 v49, v52, v49
	v_max_u32_e32 v42, v44, v46
	v_min_u32_e32 v44, v44, v46
	v_max_u32_e32 v46, v43, v45
	v_min_u32_e32 v43, v43, v45
	v_max_u32_e32 v45, v56, v35
	v_min_u32_e32 v35, v56, v35
	v_max_u32_e32 v56, v32, v34
	v_min_u32_e32 v32, v32, v34
	v_max_u32_e32 v34, v33, v27
	v_min_u32_e32 v27, v33, v27
	v_max_u32_e32 v33, v41, v36
	v_min_u32_e32 v36, v41, v36
	v_max_u32_e32 v41, v37, v38
	v_min_u32_e32 v37, v37, v38
	v_max_u32_e32 v38, v40, v39
	v_min_u32_e32 v39, v40, v39
	v_max_u32_e32 v52, v3, v55
	v_min_u32_e32 v3, v3, v55
	v_max_u32_e32 v55, v53, v54
	v_min_u32_e32 v53, v53, v54
	v_max_u32_e32 v54, v64, v48
	v_min_u32_e32 v48, v64, v48
	v_max_u32_e32 v64, v30, v29
	v_min_u32_e32 v29, v30, v29
	v_max_u32_e32 v30, v0, v2
	v_min_u32_e32 v0, v0, v2
	v_max_u32_e32 v2, v51, v47
	v_min_u32_e32 v47, v51, v47
	v_max_u32_e32 v51, v49, v31
	v_min_u32_e32 v31, v49, v31
	v_max_u32_e32 v49, v50, v1
	v_min_u32_e32 v1, v50, v1
	v_max_u32_e32 v40, v42, v27
	v_min_u32_e32 v27, v42, v27
	v_max_u32_e32 v42, v44, v34
	v_min_u32_e32 v34, v44, v34
	v_max_u32_e32 v44, v46, v36
	v_min_u32_e32 v36, v46, v36
	v_max_u32_e32 v46, v43, v33
	v_min_u32_e32 v33, v43, v33
	v_max_u32_e32 v43, v45, v37
	v_min_u32_e32 v37, v45, v37
	v_max_u32_e32 v45, v35, v41
	v_min_u32_e32 v35, v35, v41
	v_max_u32_e32 v41, v56, v39
	v_min_u32_e32 v39, v56, v39
	v_max_u32_e32 v56, v32, v38
	v_min_u32_e32 v32, v32, v38
	v_max_u32_e32 v50, v52, v0
	v_min_u32_e32 v0, v52, v0
	v_max_u32_e32 v52, v3, v30
	v_min_u32_e32 v3, v3, v30
	v_max_u32_e32 v30, v55, v47
	v_min_u32_e32 v47, v55, v47
	v_max_u32_e32 v55, v53, v2
	v_min_u32_e32 v2, v53, v2
	v_max_u32_e32 v53, v54, v31
	v_min_u32_e32 v31, v54, v31
	v_max_u32_e32 v54, v48, v51
	v_min_u32_e32 v48, v48, v51
	v_max_u32_e32 v51, v64, v1
	v_min_u32_e32 v1, v64, v1
	v_max_u32_e32 v64, v29, v49
	v_min_u32_e32 v29, v29, v49
	v_max_u32_e32 v38, v40, v43
	v_min_u32_e32 v40, v40, v43
; #define CE_DESC(a, b) do { const unsigned _mx = (a) > (b) ? (a) : (b), _mn = (a) > (b) ? (b) : (a); (a) = _mx; (b) = _mn; } while (0)
; __device__ __forceinline__ void merge16(unsigned (&a)[16], const unsigned (&b)[16]) {
; #pragma unroll
;     for (int i = 0; i < 16; ++i) a[i] = a[i] > b[15 - i] ? a[i] : b[15 - i];
; #pragma unroll
;     for (int stride = 8; stride > 0; stride >>= 1)
; #pragma unroll
;         for (int i = 0; i < 16; ++i) { const int j = i ^ stride; if (j > i) CE_DESC(a[i], a[j]); }
; }
; __device__ __forceinline__ void peer_tile(const Args& A, LAS unsigned char* lds, int tile) {
;     ...
;                 sort16_desc(k0); sort16_desc(k1); merge16(k0, k1);
; #pragma unroll
;                 for (int msk = 16; msk <= 32; msk <<= 1) {
; #pragma unroll
;                     for (int i = 0; i < 16; ++i) k1[i] = (unsigned)__shfl_xor((int)k0[i], msk);
;                     merge16(k0, k1); }
	v_max_u32_e32 v43, v42, v45
	v_min_u32_e32 v42, v42, v45
	v_max_u32_e32 v45, v44, v41
	v_min_u32_e32 v41, v44, v41
	v_max_u32_e32 v44, v46, v56
	v_min_u32_e32 v46, v46, v56
	v_max_u32_e32 v56, v27, v37
	v_min_u32_e32 v27, v27, v37
	v_max_u32_e32 v37, v34, v35
	v_min_u32_e32 v34, v34, v35
	v_max_u32_e32 v35, v36, v39
	v_min_u32_e32 v36, v36, v39
	v_max_u32_e32 v39, v33, v32
	v_min_u32_e32 v32, v33, v32
	v_max_u32_e32 v49, v50, v53
	v_min_u32_e32 v50, v50, v53
	v_max_u32_e32 v53, v52, v54
	v_min_u32_e32 v52, v52, v54
	v_max_u32_e32 v54, v30, v51
	v_min_u32_e32 v30, v30, v51
	v_max_u32_e32 v51, v55, v64
	v_min_u32_e32 v55, v55, v64
	v_max_u32_e32 v64, v0, v31
	v_min_u32_e32 v0, v0, v31
	v_max_u32_e32 v31, v3, v48
	v_min_u32_e32 v3, v3, v48
	v_max_u32_e32 v48, v47, v1
	v_min_u32_e32 v1, v47, v1
	v_max_u32_e32 v47, v2, v29
	v_min_u32_e32 v2, v2, v29
	v_max_u32_e32 v33, v38, v45
	v_min_u32_e32 v38, v38, v45
	v_max_u32_e32 v45, v43, v44
	v_min_u32_e32 v43, v43, v44
	v_max_u32_e32 v44, v40, v41
	v_min_u32_e32 v40, v40, v41
	v_max_u32_e32 v41, v42, v46
	v_min_u32_e32 v42, v42, v46
	v_max_u32_e32 v46, v56, v35
	v_min_u32_e32 v35, v56, v35
	v_max_u32_e32 v56, v37, v39
	v_min_u32_e32 v37, v37, v39
	v_max_u32_e32 v39, v27, v36
	v_min_u32_e32 v27, v27, v36
	v_max_u32_e32 v36, v34, v32
	v_min_u32_e32 v32, v34, v32
	v_max_u32_e32 v29, v49, v54
	v_min_u32_e32 v49, v49, v54
	v_max_u32_e32 v54, v53, v51
	v_min_u32_e32 v51, v53, v51
	v_max_u32_e32 v53, v50, v30
	v_min_u32_e32 v30, v50, v30
	v_max_u32_e32 v50, v52, v55
	v_min_u32_e32 v52, v52, v55
	v_max_u32_e32 v55, v64, v48
	v_min_u32_e32 v48, v64, v48
	v_max_u32_e32 v64, v31, v47
	v_min_u32_e32 v31, v31, v47
	v_max_u32_e32 v47, v0, v1
	v_min_u32_e32 v0, v0, v1
	v_max_u32_e32 v1, v3, v2
	v_min_u32_e32 v2, v3, v2
	v_min_u32_e32 v34, v33, v45
	v_min_u32_e32 v57, v38, v43
	v_min_u32_e32 v58, v44, v41
	v_min_u32_e32 v59, v40, v42
	v_min_u32_e32 v60, v46, v56
	v_min_u32_e32 v61, v35, v37
	v_min_u32_e32 v62, v39, v36
	v_min_u32_e32 v63, v27, v32
	v_min_u32_e32 v3, v29, v54
	v_min_u32_e32 v65, v49, v51
	v_min_u32_e32 v66, v53, v50
	v_min_u32_e32 v67, v30, v52
	v_min_u32_e32 v68, v55, v64
	v_min_u32_e32 v69, v48, v31
	v_min_u32_e32 v70, v47, v1
	v_min_u32_e32 v71, v0, v2
	v_max3_u32 v33, v33, v45, v71
	v_max3_u32 v0, v34, v0, v2
	v_max3_u32 v2, v38, v43, v70
	v_max3_u32 v1, v57, v47, v1
	v_max3_u32 v34, v44, v41, v69
	v_max3_u32 v31, v58, v48, v31
	v_max3_u32 v38, v40, v42, v68
	v_max3_u32 v40, v59, v55, v64
	v_max3_u32 v41, v46, v56, v67
	v_max3_u32 v30, v60, v30, v52
	v_max3_u32 v35, v35, v37, v66
	v_max3_u32 v37, v61, v53, v50
	v_max3_u32 v36, v39, v36, v65
	v_max3_u32 v39, v62, v49, v51
	v_max3_u32 v3, v27, v32, v3
	v_max3_u32 v27, v63, v29, v54
	v_max_u32_e32 v29, v33, v41
	v_min_u32_e32 v32, v33, v41
	v_max_u32_e32 v33, v0, v30
	v_min_u32_e32 v0, v0, v30
	v_max_u32_e32 v30, v2, v35
	v_min_u32_e32 v2, v2, v35
	v_max_u32_e32 v35, v1, v37
	v_min_u32_e32 v1, v1, v37
	v_max_u32_e32 v37, v34, v36
	v_min_u32_e32 v34, v34, v36
	v_max_u32_e32 v36, v31, v39
	v_min_u32_e32 v31, v31, v39
	v_max_u32_e32 v39, v38, v3
	v_min_u32_e32 v3, v38, v3
	v_max_u32_e32 v38, v40, v27
	v_min_u32_e32 v27, v40, v27
	v_max_u32_e32 v40, v29, v37
	v_min_u32_e32 v29, v29, v37
	v_max_u32_e32 v37, v33, v36
	v_min_u32_e32 v33, v33, v36
	v_max_u32_e32 v36, v30, v39
	v_min_u32_e32 v30, v30, v39
	v_max_u32_e32 v39, v35, v38
	v_min_u32_e32 v35, v35, v38
	v_max_u32_e32 v38, v32, v34
	v_min_u32_e32 v32, v32, v34
	v_max_u32_e32 v34, v0, v31
	v_min_u32_e32 v0, v0, v31
	v_max_u32_e32 v31, v2, v3
	v_min_u32_e32 v2, v2, v3
	v_max_u32_e32 v3, v1, v27
	v_min_u32_e32 v1, v1, v27
	v_max_u32_e32 v27, v40, v36
	v_min_u32_e32 v36, v40, v36
	v_max_u32_e32 v40, v37, v39
	v_min_u32_e32 v37, v37, v39
	v_max_u32_e32 v39, v29, v30
	v_min_u32_e32 v29, v29, v30
	v_max_u32_e32 v30, v33, v35
	v_min_u32_e32 v33, v33, v35
	v_max_u32_e32 v35, v38, v31
	v_min_u32_e32 v31, v38, v31
	v_max_u32_e32 v38, v34, v3
	v_min_u32_e32 v3, v34, v3
	v_max_u32_e32 v34, v32, v2
	v_min_u32_e32 v2, v32, v2
	v_max_u32_e32 v32, v0, v1
	v_min_u32_e32 v0, v0, v1
	v_cmp_lt_i32_e32 vcc, v217, v216
	v_max_u32_e32 v41, v36, v37
	v_min_u32_e32 v36, v36, v37
	v_max_u32_e32 v37, v39, v30
	v_min_u32_e32 v30, v39, v30
	v_max_u32_e32 v39, v29, v33
	v_min_u32_e32 v29, v29, v33
	v_max_u32_e32 v33, v35, v38
	v_min_u32_e32 v35, v35, v38
	v_max_u32_e32 v38, v31, v3
	v_min_u32_e32 v3, v31, v3
	v_max_u32_e32 v31, v34, v32
	v_min_u32_e32 v32, v34, v32
	v_max_u32_e32 v34, v2, v0
	v_min_u32_e32 v0, v2, v0
	v_cndmask_b32_e32 v2, v215, v217, vcc
	v_max_u32_e32 v1, v27, v40
	v_min_u32_e32 v40, v27, v40
	v_lshlrev_b32_e32 v27, 2, v2
	ds_bpermute_b32 v2, v27, v1
	ds_bpermute_b32 v42, v27, v40
	ds_bpermute_b32 v43, v27, v41
	ds_bpermute_b32 v44, v27, v36
	ds_bpermute_b32 v45, v27, v37
	ds_bpermute_b32 v46, v27, v30
	ds_bpermute_b32 v47, v27, v39
	ds_bpermute_b32 v48, v27, v29
	ds_bpermute_b32 v49, v27, v33
	ds_bpermute_b32 v50, v27, v35
	ds_bpermute_b32 v51, v27, v38
	ds_bpermute_b32 v52, v27, v0
	ds_bpermute_b32 v53, v27, v34
	ds_bpermute_b32 v54, v27, v32
	ds_bpermute_b32 v55, v27, v31
	ds_bpermute_b32 v56, v27, v3
	s_waitcnt lgkmcnt(4)
	v_max_u32_e32 v1, v1, v52
	s_waitcnt lgkmcnt(3)
	v_max_u32_e32 v40, v40, v53
	s_waitcnt lgkmcnt(2)
	v_max_u32_e32 v41, v41, v54
	s_waitcnt lgkmcnt(1)
	v_max_u32_e32 v36, v36, v55
	s_waitcnt lgkmcnt(0)
; __device__ __forceinline__ void peer_tile(const Args& A, LAS unsigned char* lds, int tile) {
;     ...
;                 sort16_desc(k0); sort16_desc(k1); merge16(k0, k1);
; #pragma unroll
;                 for (int msk = 16; msk <= 32; msk <<= 1) {
; #pragma unroll
;                     for (int i = 0; i < 16; ++i) k1[i] = (unsigned)__shfl_xor((int)k0[i], msk);
;                     merge16(k0, k1); }
; #pragma unroll
;                 for (int i = 0; i < 16; ++i) LA[hh][p][i] = k0[i];
;             }
	v_max_u32_e32 v37, v37, v56
	v_max_u32_e32 v30, v30, v51
	v_max_u32_e32 v39, v39, v50
	v_max_u32_e32 v29, v29, v49
	v_max_u32_e32 v33, v33, v48
	v_max_u32_e32 v35, v35, v47
	v_max_u32_e32 v38, v38, v46
	v_max_u32_e32 v3, v3, v45
	v_max_u32_e32 v31, v31, v44
	v_max_u32_e32 v32, v32, v43
	v_max_u32_e32 v34, v34, v42
	v_max_u32_e32 v0, v0, v2
	v_max_u32_e32 v2, v1, v33
	v_min_u32_e32 v1, v1, v33
	v_max_u32_e32 v33, v40, v35
	v_min_u32_e32 v35, v40, v35
	v_max_u32_e32 v40, v41, v38
	v_min_u32_e32 v38, v41, v38
	v_max_u32_e32 v41, v36, v3
	v_min_u32_e32 v3, v36, v3
	v_max_u32_e32 v36, v37, v31
	v_min_u32_e32 v31, v37, v31
	v_max_u32_e32 v37, v30, v32
	v_min_u32_e32 v30, v30, v32
	v_max_u32_e32 v32, v39, v34
	v_min_u32_e32 v34, v39, v34
	v_max_u32_e32 v39, v29, v0
	v_min_u32_e32 v0, v29, v0
	v_max_u32_e32 v29, v2, v36
	v_min_u32_e32 v2, v2, v36
	v_max_u32_e32 v36, v33, v37
	v_min_u32_e32 v33, v33, v37
	v_max_u32_e32 v37, v40, v32
	v_min_u32_e32 v32, v40, v32
	v_max_u32_e32 v40, v41, v39
	v_min_u32_e32 v39, v41, v39
	v_max_u32_e32 v41, v1, v31
	v_min_u32_e32 v1, v1, v31
	v_max_u32_e32 v31, v35, v30
	v_min_u32_e32 v30, v35, v30
	v_max_u32_e32 v35, v38, v34
	v_min_u32_e32 v34, v38, v34
	v_max_u32_e32 v38, v3, v0
	v_min_u32_e32 v0, v3, v0
	v_max_u32_e32 v3, v29, v37
	v_min_u32_e32 v29, v29, v37
	v_max_u32_e32 v37, v36, v40
	v_min_u32_e32 v36, v36, v40
	v_max_u32_e32 v40, v2, v32
	v_min_u32_e32 v2, v2, v32
	v_max_u32_e32 v32, v33, v39
	v_min_u32_e32 v33, v33, v39
	v_max_u32_e32 v39, v41, v35
	v_min_u32_e32 v35, v41, v35
	v_max_u32_e32 v41, v31, v38
	v_min_u32_e32 v31, v31, v38
	v_max_u32_e32 v38, v1, v34
	v_min_u32_e32 v1, v1, v34
	v_max_u32_e32 v34, v30, v0
	v_min_u32_e32 v0, v30, v0
	v_cmp_lt_i32_e32 vcc, v218, v216
	v_max_u32_e32 v42, v40, v32
	v_min_u32_e32 v32, v40, v32
	v_max_u32_e32 v40, v2, v33
	v_min_u32_e32 v2, v2, v33
	v_max_u32_e32 v33, v39, v41
	v_min_u32_e32 v39, v39, v41
	v_max_u32_e32 v41, v35, v31
	v_min_u32_e32 v31, v35, v31
	v_max_u32_e32 v35, v38, v34
	v_min_u32_e32 v34, v38, v34
	v_max_u32_e32 v38, v1, v0
	v_min_u32_e32 v0, v1, v0
	v_cndmask_b32_e32 v1, v215, v218, vcc
	v_max_u32_e32 v30, v3, v37
	v_min_u32_e32 v3, v3, v37
	v_max_u32_e32 v37, v29, v36
	v_min_u32_e32 v36, v29, v36
	v_lshlrev_b32_e32 v29, 2, v1
	ds_bpermute_b32 v46, v29, v0
	ds_bpermute_b32 v1, v29, v30
	ds_bpermute_b32 v43, v29, v3
	ds_bpermute_b32 v44, v29, v37
	ds_bpermute_b32 v45, v29, v36
	s_waitcnt lgkmcnt(4)
	v_max_u32_e32 v30, v30, v46
	global_load_dwordx4 v[46:49], v[4:5], off offset:272
	global_load_dwordx4 v[50:53], v[4:5], off offset:256
	ds_bpermute_b32 v54, v29, v42
	ds_bpermute_b32 v55, v29, v32
	ds_bpermute_b32 v56, v29, v40
	ds_bpermute_b32 v57, v29, v2
	ds_bpermute_b32 v58, v29, v33
	ds_bpermute_b32 v59, v29, v39
	ds_bpermute_b32 v60, v29, v41
	ds_bpermute_b32 v61, v29, v31
	ds_bpermute_b32 v62, v29, v35
	ds_bpermute_b32 v63, v29, v38
	ds_bpermute_b32 v64, v29, v34
	s_waitcnt lgkmcnt(4)
	v_max_u32_e32 v32, v32, v60
	s_waitcnt lgkmcnt(3)
	v_max_u32_e32 v42, v42, v61
	s_waitcnt lgkmcnt(2)
	v_max_u32_e32 v36, v36, v62
	s_waitcnt lgkmcnt(1)
	v_max_u32_e32 v3, v3, v63
	s_waitcnt lgkmcnt(0)
	v_max_u32_e32 v37, v37, v64
	v_max_u32_e32 v40, v40, v59
	v_max_u32_e32 v2, v2, v58
	v_max_u32_e32 v33, v33, v57
	v_max_u32_e32 v39, v39, v56
	v_max_u32_e32 v41, v41, v55
	v_max_u32_e32 v31, v31, v54
	v_max_u32_e32 v35, v35, v45
	v_max_u32_e32 v34, v34, v44
	v_max_u32_e32 v38, v38, v43
	v_max_u32_e32 v0, v0, v1
	v_max_u32_e32 v1, v30, v33
	v_min_u32_e32 v30, v30, v33
	v_max_u32_e32 v33, v3, v39
	v_min_u32_e32 v3, v3, v39
	v_max_u32_e32 v39, v37, v41
	v_min_u32_e32 v37, v37, v41
	v_max_u32_e32 v41, v36, v31
	v_min_u32_e32 v31, v36, v31
	v_max_u32_e32 v36, v42, v35
	v_min_u32_e32 v35, v42, v35
	v_max_u32_e32 v42, v32, v34
	v_min_u32_e32 v32, v32, v34
	v_max_u32_e32 v34, v40, v38
	v_min_u32_e32 v38, v40, v38
	v_max_u32_e32 v40, v2, v0
	v_min_u32_e32 v0, v2, v0
	v_max_u32_e32 v2, v1, v36
	v_min_u32_e32 v1, v1, v36
	v_max_u32_e32 v36, v33, v42
	v_min_u32_e32 v33, v33, v42
	v_max_u32_e32 v42, v39, v34
	v_min_u32_e32 v34, v39, v34
	v_max_u32_e32 v39, v41, v40
	v_min_u32_e32 v40, v41, v40
	v_max_u32_e32 v41, v30, v35
	v_min_u32_e32 v30, v30, v35
	v_max_u32_e32 v35, v3, v32
	v_min_u32_e32 v3, v3, v32
	v_max_u32_e32 v32, v37, v38
	v_min_u32_e32 v37, v37, v38
	v_max_u32_e32 v38, v31, v0
	v_min_u32_e32 v0, v31, v0
	v_max_u32_e32 v31, v2, v42
	v_min_u32_e32 v2, v2, v42
	v_max_u32_e32 v42, v36, v39
	v_min_u32_e32 v36, v36, v39
	v_max_u32_e32 v39, v1, v34
	v_min_u32_e32 v1, v1, v34
	v_max_u32_e32 v34, v33, v40
	v_min_u32_e32 v33, v33, v40
	v_max_u32_e32 v54, v41, v32
	v_min_u32_e32 v32, v41, v32
	v_max_u32_e32 v55, v35, v38
	v_min_u32_e32 v56, v35, v38
	v_max_u32_e32 v57, v30, v37
	v_min_u32_e32 v30, v30, v37
	v_max_u32_e32 v58, v3, v0
	v_min_u32_e32 v0, v3, v0
	v_max_u32_e32 v45, v31, v42
	v_min_u32_e32 v44, v31, v42
	v_max_u32_e32 v43, v2, v36
	v_min_u32_e32 v42, v2, v36
	v_max_u32_e32 v41, v39, v34
	v_min_u32_e32 v40, v39, v34
	v_max_u32_e32 v39, v1, v33
	v_min_u32_e32 v38, v1, v33
	v_max_u32_e32 v37, v54, v55
	v_min_u32_e32 v36, v54, v55
	v_max_u32_e32 v35, v32, v56
	v_min_u32_e32 v34, v32, v56
	v_max_u32_e32 v33, v57, v58
	v_min_u32_e32 v32, v57, v58
	v_max_u32_e32 v31, v30, v0
	v_min_u32_e32 v30, v30, v0
	global_load_dwordx4 v[0:3], v[4:5], off offset:304
	global_load_dwordx4 v[54:57], v[4:5], off offset:288
	s_waitcnt vmcnt(2)
; __device__ __forceinline__ unsigned f2key(float f) { const unsigned u = __float_as_uint(f); return (u & 0x80000000u) ? ~u : (u | 0x80000000u); }
; __device__ __forceinline__ void peer_tile(const Args& A, LAS unsigned char* lds, int tile) {
;     ...
;                 const int hp = 2 * h + p;
;                 unsigned k0[16], k1[16];
;                 { const bf16_t* sp = QRY + m * 2048 + hp * 128 + 32 * g;
;                   const u32x4 s0 = *(const u32x4*)sp, s1 = *(const u32x4*)(sp + 8), s2 = *(const u32x4*)(sp + 16), s3 = *(const u32x4*)(sp + 24);
;                   const unsigned sw[16] = {s0.x, s0.y, s0.z, s0.w, s1.x, s1.y, s1.z, s1.w, s2.x, s2.y, s2.z, s2.w, s3.x, s3.y, s3.z, s3.w};
; #pragma unroll
;                   for (int i = 0; i < 16; ++i) {
;                       const float lo = (float)__builtin_bit_cast(_Float16, (unsigned short)(sw[i] & 0xffffu)), hi = (float)__builtin_bit_cast(_Float16, (unsigned short)(sw[i] >> 16));
;                       const unsigned klo = (f2key(lo) & ~127u) | (unsigned)(127 - (32 * g + 2 * i)), khi = (f2key(hi) & ~127u) | (unsigned)(127 - (32 * g + 2 * i + 1));
;                       if (i < 8) { k0[2 * i] = klo; k0[2 * i + 1] = khi; } else { k1[2 * (i - 8)] = klo; k1[2 * (i - 8) + 1] = khi; } } }
	v_cvt_f32_f16_sdwa v58, v50 dst_sel:DWORD dst_unused:UNUSED_PAD src0_sel:WORD_1
	v_cvt_f32_f16_e32 v50, v50
	v_not_b32_e32 v59, v58
	v_or_b32_e32 v60, 0x80000000, v58
	v_cmp_gt_i32_e32 vcc, 0, v58
	s_nop 1
	v_cndmask_b32_e32 v58, v60, v59, vcc
	v_not_b32_e32 v59, v50
	v_or_b32_e32 v60, 0x80000000, v50
	v_cmp_gt_i32_e32 vcc, 0, v50
	v_and_b32_e32 v58, 0xffffff80, v58
	v_sub_u32_e32 v58, v58, v15
	v_cndmask_b32_e32 v50, v60, v59, vcc
	v_cvt_f32_f16_sdwa v59, v51 dst_sel:DWORD dst_unused:UNUSED_PAD src0_sel:WORD_1
	v_cvt_f32_f16_e32 v51, v51
	v_and_b32_e32 v50, 0xffffff80, v50
	v_sub_u32_e32 v50, v50, v15
	v_not_b32_e32 v60, v59
	v_or_b32_e32 v61, 0x80000000, v59
	v_cmp_gt_i32_e32 vcc, 0, v59
	v_add_u32_e32 v58, 0x7e, v58
	v_add_u32_e32 v50, 0x7f, v50
	v_cndmask_b32_e32 v59, v61, v60, vcc
	v_not_b32_e32 v60, v51
	v_or_b32_e32 v61, 0x80000000, v51
	v_cmp_gt_i32_e32 vcc, 0, v51
	v_and_b32_e32 v59, 0xffffff80, v59
	v_sub_u32_e32 v59, v59, v14
	v_cndmask_b32_e32 v51, v61, v60, vcc
	v_cvt_f32_f16_sdwa v60, v52 dst_sel:DWORD dst_unused:UNUSED_PAD src0_sel:WORD_1
	v_cvt_f32_f16_e32 v52, v52
	v_and_b32_e32 v51, 0xffffff80, v51
	v_sub_u32_e32 v51, v51, v14
	v_not_b32_e32 v61, v60
	v_or_b32_e32 v62, 0x80000000, v60
	v_cmp_gt_i32_e32 vcc, 0, v60
	v_add_u32_e32 v59, 0x7e, v59
	v_add_u32_e32 v51, 0x7f, v51
	v_cndmask_b32_e32 v60, v62, v61, vcc
	v_not_b32_e32 v61, v52
	v_or_b32_e32 v62, 0x80000000, v52
	v_cmp_gt_i32_e32 vcc, 0, v52
	v_and_b32_e32 v60, 0xffffff80, v60
	v_sub_u32_e32 v60, v60, v12
	v_cndmask_b32_e32 v52, v62, v61, vcc
	v_cvt_f32_f16_sdwa v61, v53 dst_sel:DWORD dst_unused:UNUSED_PAD src0_sel:WORD_1
	v_cvt_f32_f16_e32 v53, v53
	v_and_b32_e32 v52, 0xffffff80, v52
	v_sub_u32_e32 v52, v52, v12
	v_not_b32_e32 v62, v61
	v_or_b32_e32 v63, 0x80000000, v61
	v_cmp_gt_i32_e32 vcc, 0, v61
	v_add_u32_e32 v60, 0x7e, v60
	v_add_u32_e32 v52, 0x7f, v52
	v_cndmask_b32_e32 v61, v63, v62, vcc
	v_not_b32_e32 v62, v53
	v_or_b32_e32 v63, 0x80000000, v53
	v_cmp_gt_i32_e32 vcc, 0, v53
	v_and_b32_e32 v61, 0xffffff80, v61
	v_sub_u32_e32 v61, v61, v10
	v_cndmask_b32_e32 v53, v63, v62, vcc
	v_cvt_f32_f16_sdwa v62, v46 dst_sel:DWORD dst_unused:UNUSED_PAD src0_sel:WORD_1
	v_cvt_f32_f16_e32 v46, v46
	v_and_b32_e32 v53, 0xffffff80, v53
	v_sub_u32_e32 v53, v53, v10
	v_not_b32_e32 v63, v62
	v_or_b32_e32 v64, 0x80000000, v62
	v_cmp_gt_i32_e32 vcc, 0, v62
	v_add_u32_e32 v61, 0x7e, v61
	v_add_u32_e32 v53, 0x7f, v53
	v_cndmask_b32_e32 v62, v64, v63, vcc
	v_not_b32_e32 v63, v46
	v_or_b32_e32 v64, 0x80000000, v46
	v_cmp_gt_i32_e32 vcc, 0, v46
	v_and_b32_e32 v62, 0xffffff80, v62
	v_sub_u32_e32 v62, v62, v8
	v_cndmask_b32_e32 v46, v64, v63, vcc
	v_cvt_f32_f16_sdwa v63, v47 dst_sel:DWORD dst_unused:UNUSED_PAD src0_sel:WORD_1
	v_cvt_f32_f16_e32 v47, v47
	v_and_b32_e32 v46, 0xffffff80, v46
	v_sub_u32_e32 v46, v46, v8
	v_not_b32_e32 v64, v63
	v_or_b32_e32 v65, 0x80000000, v63
	v_cmp_gt_i32_e32 vcc, 0, v63
	v_add_u32_e32 v62, 0x7e, v62
	v_add_u32_e32 v46, 0x7f, v46
	v_cndmask_b32_e32 v63, v65, v64, vcc
	v_not_b32_e32 v64, v47
	v_or_b32_e32 v65, 0x80000000, v47
	v_cmp_gt_i32_e32 vcc, 0, v47
	v_and_b32_e32 v63, 0xffffff80, v63
	v_sub_u32_e32 v63, v63, v16
	v_cndmask_b32_e32 v47, v65, v64, vcc
	v_cvt_f32_f16_sdwa v64, v48 dst_sel:DWORD dst_unused:UNUSED_PAD src0_sel:WORD_1
	v_cvt_f32_f16_e32 v48, v48
	v_and_b32_e32 v47, 0xffffff80, v47
	v_sub_u32_e32 v47, v47, v16
	v_not_b32_e32 v65, v64
	v_or_b32_e32 v66, 0x80000000, v64
	v_cmp_gt_i32_e32 vcc, 0, v64
	v_add_u32_e32 v63, 0x7e, v63
	v_add_u32_e32 v47, 0x7f, v47
	v_cndmask_b32_e32 v64, v66, v65, vcc
	v_not_b32_e32 v65, v48
	v_or_b32_e32 v66, 0x80000000, v48
	v_cmp_gt_i32_e32 vcc, 0, v48
	v_and_b32_e32 v64, 0xffffff80, v64
	v_sub_u32_e32 v64, v64, v17
	v_cndmask_b32_e32 v48, v66, v65, vcc
	v_cvt_f32_f16_sdwa v65, v49 dst_sel:DWORD dst_unused:UNUSED_PAD src0_sel:WORD_1
	v_cvt_f32_f16_e32 v49, v49
	v_and_b32_e32 v48, 0xffffff80, v48
	v_sub_u32_e32 v48, v48, v17
	v_not_b32_e32 v66, v65
	v_or_b32_e32 v67, 0x80000000, v65
	v_cmp_gt_i32_e32 vcc, 0, v65
	v_add_u32_e32 v64, 0x7e, v64
	v_add_u32_e32 v48, 0x7f, v48
	v_cndmask_b32_e32 v65, v67, v66, vcc
	v_not_b32_e32 v66, v49
	v_or_b32_e32 v67, 0x80000000, v49
	v_cmp_gt_i32_e32 vcc, 0, v49
	v_and_b32_e32 v65, 0xffffff80, v65
	v_sub_u32_e32 v65, v65, v18
	v_cndmask_b32_e32 v49, v67, v66, vcc
	s_waitcnt vmcnt(0)
; __device__ __forceinline__ unsigned f2key(float f) { const unsigned u = __float_as_uint(f); return (u & 0x80000000u) ? ~u : (u | 0x80000000u); }
; __device__ __forceinline__ void peer_tile(const Args& A, LAS unsigned char* lds, int tile) {
;     ...
;                 { const bf16_t* sp = QRY + m * 2048 + hp * 128 + 32 * g;
;                   const u32x4 s0 = *(const u32x4*)sp, s1 = *(const u32x4*)(sp + 8), s2 = *(const u32x4*)(sp + 16), s3 = *(const u32x4*)(sp + 24);
;                   const unsigned sw[16] = {s0.x, s0.y, s0.z, s0.w, s1.x, s1.y, s1.z, s1.w, s2.x, s2.y, s2.z, s2.w, s3.x, s3.y, s3.z, s3.w};
; #pragma unroll
;                   for (int i = 0; i < 16; ++i) {
;                       const float lo = (float)__builtin_bit_cast(_Float16, (unsigned short)(sw[i] & 0xffffu)), hi = (float)__builtin_bit_cast(_Float16, (unsigned short)(sw[i] >> 16));
;                       const unsigned klo = (f2key(lo) & ~127u) | (unsigned)(127 - (32 * g + 2 * i)), khi = (f2key(hi) & ~127u) | (unsigned)(127 - (32 * g + 2 * i + 1));
;                       if (i < 8) { k0[2 * i] = klo; k0[2 * i + 1] = khi; } else { k1[2 * (i - 8)] = klo; k1[2 * (i - 8) + 1] = khi; } } }
;                 sort16_desc(k0); sort16_desc(k1); merge16(k0, k1);
	v_cvt_f32_f16_sdwa v66, v54 dst_sel:DWORD dst_unused:UNUSED_PAD src0_sel:WORD_1
	v_cvt_f32_f16_e32 v54, v54
	v_and_b32_e32 v49, 0xffffff80, v49
	v_sub_u32_e32 v49, v49, v18
	v_not_b32_e32 v67, v66
	v_or_b32_e32 v68, 0x80000000, v66
	v_cmp_gt_i32_e32 vcc, 0, v66
	v_add_u32_e32 v65, 0x7e, v65
	v_add_u32_e32 v49, 0x7f, v49
	v_cndmask_b32_e32 v66, v68, v67, vcc
	v_not_b32_e32 v67, v54
	v_or_b32_e32 v68, 0x80000000, v54
	v_cmp_gt_i32_e32 vcc, 0, v54
	v_and_b32_e32 v66, 0xffffff80, v66
	v_sub_u32_e32 v66, v66, v20
	v_cndmask_b32_e32 v54, v68, v67, vcc
	v_cvt_f32_f16_sdwa v67, v55 dst_sel:DWORD dst_unused:UNUSED_PAD src0_sel:WORD_1
	v_cvt_f32_f16_e32 v55, v55
	v_and_b32_e32 v54, 0xffffff80, v54
	v_sub_u32_e32 v54, v54, v20
	v_not_b32_e32 v68, v67
	v_or_b32_e32 v69, 0x80000000, v67
	v_cmp_gt_i32_e32 vcc, 0, v67
	v_add_u32_e32 v66, 0x7e, v66
	v_add_u32_e32 v54, 0x7f, v54
	v_cndmask_b32_e32 v67, v69, v68, vcc
	v_not_b32_e32 v68, v55
	v_or_b32_e32 v69, 0x80000000, v55
	v_cmp_gt_i32_e32 vcc, 0, v55
	v_and_b32_e32 v67, 0xffffff80, v67
	v_sub_u32_e32 v67, v67, v21
	v_cndmask_b32_e32 v55, v69, v68, vcc
	v_cvt_f32_f16_sdwa v68, v56 dst_sel:DWORD dst_unused:UNUSED_PAD src0_sel:WORD_1
	v_cvt_f32_f16_e32 v56, v56
	v_and_b32_e32 v55, 0xffffff80, v55
	v_sub_u32_e32 v55, v55, v21
	v_not_b32_e32 v69, v68
	v_or_b32_e32 v70, 0x80000000, v68
	v_cmp_gt_i32_e32 vcc, 0, v68
	v_add_u32_e32 v67, 0x7e, v67
	v_add_u32_e32 v55, 0x7f, v55
	v_cndmask_b32_e32 v68, v70, v69, vcc
	v_not_b32_e32 v69, v56
	v_or_b32_e32 v70, 0x80000000, v56
	v_cmp_gt_i32_e32 vcc, 0, v56
	v_and_b32_e32 v68, 0xffffff80, v68
	v_sub_u32_e32 v68, v68, v22
	v_cndmask_b32_e32 v56, v70, v69, vcc
	v_cvt_f32_f16_sdwa v69, v57 dst_sel:DWORD dst_unused:UNUSED_PAD src0_sel:WORD_1
	v_cvt_f32_f16_e32 v57, v57
	v_and_b32_e32 v56, 0xffffff80, v56
	v_sub_u32_e32 v56, v56, v22
	v_not_b32_e32 v70, v69
	v_or_b32_e32 v71, 0x80000000, v69
	v_cmp_gt_i32_e32 vcc, 0, v69
	v_add_u32_e32 v68, 0x7e, v68
	v_add_u32_e32 v56, 0x7f, v56
	v_cndmask_b32_e32 v69, v71, v70, vcc
	v_not_b32_e32 v70, v57
	v_or_b32_e32 v71, 0x80000000, v57
	v_cmp_gt_i32_e32 vcc, 0, v57
	v_and_b32_e32 v69, 0xffffff80, v69
	v_sub_u32_e32 v69, v69, v23
	v_cndmask_b32_e32 v57, v71, v70, vcc
	v_cvt_f32_f16_sdwa v70, v0 dst_sel:DWORD dst_unused:UNUSED_PAD src0_sel:WORD_1
	v_cvt_f32_f16_e32 v0, v0
	v_and_b32_e32 v57, 0xffffff80, v57
	v_sub_u32_e32 v57, v57, v23
	v_not_b32_e32 v71, v70
	v_or_b32_e32 v72, 0x80000000, v70
	v_cmp_gt_i32_e32 vcc, 0, v70
	v_add_u32_e32 v69, 0x7e, v69
	v_add_u32_e32 v57, 0x7f, v57
	v_cndmask_b32_e32 v70, v72, v71, vcc
	v_not_b32_e32 v71, v0
	v_or_b32_e32 v72, 0x80000000, v0
	v_cmp_gt_i32_e32 vcc, 0, v0
	v_and_b32_e32 v70, 0xffffff80, v70
	v_sub_u32_e32 v70, v70, v24
	v_cndmask_b32_e32 v0, v72, v71, vcc
	v_cvt_f32_f16_sdwa v71, v1 dst_sel:DWORD dst_unused:UNUSED_PAD src0_sel:WORD_1
	v_cvt_f32_f16_e32 v1, v1
	v_and_b32_e32 v0, 0xffffff80, v0
	v_sub_u32_e32 v0, v0, v24
	v_not_b32_e32 v72, v71
	v_or_b32_e32 v73, 0x80000000, v71
	v_cmp_gt_i32_e32 vcc, 0, v71
	v_add_u32_e32 v70, 0x7e, v70
	v_add_u32_e32 v0, 0x7f, v0
	v_cndmask_b32_e32 v71, v73, v72, vcc
	v_not_b32_e32 v72, v1
	v_or_b32_e32 v73, 0x80000000, v1
	v_cmp_gt_i32_e32 vcc, 0, v1
	v_and_b32_e32 v71, 0xffffff80, v71
	v_sub_u32_e32 v71, v71, v25
	v_cndmask_b32_e32 v1, v73, v72, vcc
	v_cvt_f32_f16_sdwa v72, v2 dst_sel:DWORD dst_unused:UNUSED_PAD src0_sel:WORD_1
	v_cvt_f32_f16_e32 v2, v2
	v_and_b32_e32 v1, 0xffffff80, v1
	v_sub_u32_e32 v1, v1, v25
	v_not_b32_e32 v73, v72
	v_or_b32_e32 v74, 0x80000000, v72
	v_cmp_gt_i32_e32 vcc, 0, v72
	v_add_u32_e32 v71, 0x7e, v71
	v_add_u32_e32 v1, 0x7f, v1
	v_cndmask_b32_e32 v72, v74, v73, vcc
	v_not_b32_e32 v73, v2
	v_or_b32_e32 v74, 0x80000000, v2
	v_cmp_gt_i32_e32 vcc, 0, v2
	v_and_b32_e32 v72, 0xffffff80, v72
	v_sub_u32_e32 v72, v72, v26
	v_cndmask_b32_e32 v2, v74, v73, vcc
	v_cvt_f32_f16_sdwa v73, v3 dst_sel:DWORD dst_unused:UNUSED_PAD src0_sel:WORD_1
	v_cvt_f32_f16_e32 v3, v3
	v_and_b32_e32 v2, 0xffffff80, v2
	v_sub_u32_e32 v2, v2, v26
	v_not_b32_e32 v74, v73
	v_or_b32_e32 v75, 0x80000000, v73
	v_cmp_gt_i32_e32 vcc, 0, v73
	v_add_u32_e32 v72, 0x7e, v72
	v_add_u32_e32 v2, 0x7f, v2
	v_cndmask_b32_e32 v73, v75, v74, vcc
	v_not_b32_e32 v74, v3
	v_or_b32_e32 v75, 0x80000000, v3
	v_cmp_gt_i32_e32 vcc, 0, v3
	v_and_b32_e32 v73, 0xffffff80, v73
	v_sub_u32_e32 v73, v73, v28
	v_cndmask_b32_e32 v3, v75, v74, vcc
	v_and_b32_e32 v3, 0xffffff80, v3
	v_sub_u32_e32 v3, v3, v28
	v_add_u32_e32 v73, 0x7e, v73
	v_add_u32_e32 v3, 0x7f, v3
	v_max_u32_e32 v74, v50, v58
	v_min_u32_e32 v50, v50, v58
	v_max_u32_e32 v58, v59, v51
	v_min_u32_e32 v51, v59, v51
	v_max_u32_e32 v59, v52, v60
	v_min_u32_e32 v52, v52, v60
	v_max_u32_e32 v60, v61, v53
	v_min_u32_e32 v53, v61, v53
	v_max_u32_e32 v61, v46, v62
	v_min_u32_e32 v46, v46, v62
	v_max_u32_e32 v62, v63, v47
	v_min_u32_e32 v47, v63, v47
	v_max_u32_e32 v63, v48, v64
	v_min_u32_e32 v48, v48, v64
	v_max_u32_e32 v64, v65, v49
	v_min_u32_e32 v49, v65, v49
	v_max_u32_e32 v82, v54, v66
	v_min_u32_e32 v54, v54, v66
	v_max_u32_e32 v66, v67, v55
	v_min_u32_e32 v55, v67, v55
	v_max_u32_e32 v67, v56, v68
	v_min_u32_e32 v56, v56, v68
	v_max_u32_e32 v68, v69, v57
	v_min_u32_e32 v57, v69, v57
	v_max_u32_e32 v69, v0, v70
	v_min_u32_e32 v0, v0, v70
	v_max_u32_e32 v70, v71, v1
	v_min_u32_e32 v1, v71, v1
	v_max_u32_e32 v71, v2, v72
	v_min_u32_e32 v2, v2, v72
	v_max_u32_e32 v72, v73, v3
	v_min_u32_e32 v3, v73, v3
	v_max_u32_e32 v65, v74, v51
	v_min_u32_e32 v51, v74, v51
	v_max_u32_e32 v74, v50, v58
	v_min_u32_e32 v50, v50, v58
	v_max_u32_e32 v58, v53, v59
	v_min_u32_e32 v53, v53, v59
	v_max_u32_e32 v59, v60, v52
	v_min_u32_e32 v52, v60, v52
; #define CE_DESC(a, b) do { const unsigned _mx = (a) > (b) ? (a) : (b), _mn = (a) > (b) ? (b) : (a); (a) = _mx; (b) = _mn; } while (0)
; __device__ __forceinline__ void sort16_desc(unsigned (&k)[16]) {
; #pragma unroll
;     for (int size = 2; size <= 16; size <<= 1)
; #pragma unroll
;         for (int stride = size >> 1; stride > 0; stride >>= 1)
; #pragma unroll
;             for (int i = 0; i < 16; ++i) { const int j = i ^ stride;
;                 if (j > i) { if ((i & size) == 0) CE_DESC(k[i], k[j]); else CE_DESC(k[j], k[i]); } }
; }
	v_max_u32_e32 v60, v61, v47
	v_min_u32_e32 v47, v61, v47
	v_max_u32_e32 v61, v46, v62
	v_min_u32_e32 v46, v46, v62
	v_max_u32_e32 v62, v49, v63
	v_min_u32_e32 v49, v49, v63
	v_max_u32_e32 v63, v64, v48
	v_min_u32_e32 v48, v64, v48
	v_max_u32_e32 v73, v82, v55
	v_min_u32_e32 v55, v82, v55
	v_max_u32_e32 v82, v54, v66
	v_min_u32_e32 v54, v54, v66
	v_max_u32_e32 v66, v57, v67
	v_min_u32_e32 v57, v57, v67
	v_max_u32_e32 v67, v68, v56
	v_min_u32_e32 v56, v68, v56
	v_max_u32_e32 v68, v69, v1
	v_min_u32_e32 v1, v69, v1
	v_max_u32_e32 v69, v0, v70
	v_min_u32_e32 v0, v0, v70
	v_max_u32_e32 v70, v3, v71
	v_min_u32_e32 v3, v3, v71
	v_max_u32_e32 v71, v72, v2
	v_min_u32_e32 v2, v72, v2
	v_max_u32_e32 v64, v65, v74
	v_min_u32_e32 v65, v65, v74
	v_max_u32_e32 v74, v51, v50
	v_min_u32_e32 v50, v51, v50
	v_max_u32_e32 v51, v52, v53
	v_min_u32_e32 v52, v52, v53
	v_max_u32_e32 v53, v59, v58
	v_min_u32_e32 v58, v59, v58
	v_max_u32_e32 v59, v60, v61
	v_min_u32_e32 v60, v60, v61
	v_max_u32_e32 v61, v47, v46
	v_min_u32_e32 v46, v47, v46
	v_max_u32_e32 v47, v48, v49
	v_min_u32_e32 v48, v48, v49
	v_max_u32_e32 v49, v63, v62
	v_min_u32_e32 v62, v63, v62
	v_max_u32_e32 v72, v73, v82
	v_min_u32_e32 v73, v73, v82
	v_max_u32_e32 v82, v55, v54
	v_min_u32_e32 v54, v55, v54
	v_max_u32_e32 v55, v56, v57
	v_min_u32_e32 v56, v56, v57
	v_max_u32_e32 v57, v67, v66
	v_min_u32_e32 v66, v67, v66
	v_max_u32_e32 v67, v68, v69
	v_min_u32_e32 v68, v68, v69
	v_max_u32_e32 v69, v1, v0
	v_min_u32_e32 v0, v1, v0
	v_max_u32_e32 v1, v2, v3
	v_min_u32_e32 v2, v2, v3
	v_max_u32_e32 v3, v71, v70
	v_min_u32_e32 v70, v71, v70
	v_max_u32_e32 v63, v64, v52
	v_min_u32_e32 v52, v64, v52
	v_max_u32_e32 v64, v65, v51
	v_min_u32_e32 v51, v65, v51
	v_max_u32_e32 v65, v74, v58
	v_min_u32_e32 v58, v74, v58
	v_max_u32_e32 v74, v50, v53
	v_min_u32_e32 v50, v50, v53
	v_max_u32_e32 v53, v48, v59
	v_min_u32_e32 v48, v48, v59
	v_max_u32_e32 v59, v47, v60
	v_min_u32_e32 v47, v47, v60
	v_max_u32_e32 v60, v62, v61
	v_min_u32_e32 v61, v62, v61
	v_max_u32_e32 v62, v49, v46
	v_min_u32_e32 v46, v49, v46
	v_max_u32_e32 v71, v72, v56
	v_min_u32_e32 v56, v72, v56
	v_max_u32_e32 v72, v73, v55
	v_min_u32_e32 v55, v73, v55
	v_max_u32_e32 v73, v82, v66
	v_min_u32_e32 v66, v82, v66
	v_max_u32_e32 v82, v54, v57
	v_min_u32_e32 v54, v54, v57
	v_max_u32_e32 v57, v2, v67
	v_min_u32_e32 v2, v2, v67
	v_max_u32_e32 v67, v1, v68
	v_min_u32_e32 v1, v1, v68
	v_max_u32_e32 v68, v70, v69
	v_min_u32_e32 v69, v70, v69
	v_max_u32_e32 v70, v3, v0
	v_min_u32_e32 v0, v3, v0
	v_max_u32_e32 v49, v63, v65
	v_min_u32_e32 v63, v63, v65
	v_max_u32_e32 v65, v64, v74
	v_min_u32_e32 v64, v64, v74
	v_max_u32_e32 v74, v52, v58
	v_min_u32_e32 v52, v52, v58
	v_max_u32_e32 v58, v51, v50
	v_min_u32_e32 v50, v51, v50
	v_max_u32_e32 v51, v61, v48
	v_min_u32_e32 v48, v61, v48
	v_max_u32_e32 v61, v46, v47
	v_min_u32_e32 v46, v46, v47
	v_max_u32_e32 v47, v60, v53
	v_min_u32_e32 v53, v60, v53
	v_max_u32_e32 v60, v62, v59
	v_min_u32_e32 v59, v62, v59
	v_max_u32_e32 v3, v71, v73
	v_min_u32_e32 v71, v71, v73
	v_max_u32_e32 v73, v72, v82
	v_min_u32_e32 v72, v72, v82
	v_max_u32_e32 v82, v56, v66
	v_min_u32_e32 v56, v56, v66
	v_max_u32_e32 v66, v55, v54
	v_min_u32_e32 v54, v55, v54
	v_max_u32_e32 v55, v69, v2
	v_min_u32_e32 v2, v69, v2
	v_max_u32_e32 v69, v0, v1
	v_min_u32_e32 v0, v0, v1
	v_max_u32_e32 v1, v68, v57
	v_min_u32_e32 v57, v68, v57
	v_max_u32_e32 v68, v70, v67
	v_min_u32_e32 v67, v70, v67
	v_max_u32_e32 v62, v49, v65
	v_min_u32_e32 v49, v49, v65
	v_max_u32_e32 v65, v63, v64
	v_min_u32_e32 v63, v63, v64
	v_max_u32_e32 v64, v74, v58
	v_min_u32_e32 v58, v74, v58
	v_max_u32_e32 v74, v52, v50
	v_min_u32_e32 v50, v52, v50
	v_max_u32_e32 v52, v46, v48
	v_min_u32_e32 v46, v46, v48
	v_max_u32_e32 v48, v61, v51
	v_min_u32_e32 v51, v61, v51
	v_max_u32_e32 v61, v59, v53
	v_min_u32_e32 v53, v59, v53
	v_max_u32_e32 v59, v60, v47
	v_min_u32_e32 v47, v60, v47
	v_max_u32_e32 v70, v3, v73
	v_min_u32_e32 v3, v3, v73
	v_max_u32_e32 v73, v71, v72
	v_min_u32_e32 v71, v71, v72
	v_max_u32_e32 v72, v82, v66
	v_min_u32_e32 v66, v82, v66
	v_max_u32_e32 v82, v56, v54
	v_min_u32_e32 v54, v56, v54
	v_max_u32_e32 v56, v0, v2
	v_min_u32_e32 v0, v0, v2
	v_max_u32_e32 v2, v69, v55
	v_min_u32_e32 v55, v69, v55
	v_max_u32_e32 v69, v67, v57
	v_min_u32_e32 v57, v67, v57
	v_max_u32_e32 v67, v68, v1
	v_min_u32_e32 v1, v68, v1
	v_max_u32_e32 v60, v62, v46
	v_min_u32_e32 v46, v62, v46
	v_max_u32_e32 v62, v49, v52
	v_min_u32_e32 v49, v49, v52
	v_max_u32_e32 v52, v65, v51
	v_min_u32_e32 v51, v65, v51
	v_max_u32_e32 v65, v63, v48
	v_min_u32_e32 v48, v63, v48
	v_max_u32_e32 v63, v64, v53
	v_min_u32_e32 v53, v64, v53
	v_max_u32_e32 v64, v58, v61
	v_min_u32_e32 v58, v58, v61
	v_max_u32_e32 v61, v74, v47
	v_min_u32_e32 v47, v74, v47
	v_max_u32_e32 v74, v50, v59
	v_min_u32_e32 v50, v50, v59
	v_max_u32_e32 v68, v70, v0
	v_min_u32_e32 v0, v70, v0
	v_max_u32_e32 v70, v3, v56
	v_min_u32_e32 v3, v3, v56
	v_max_u32_e32 v56, v73, v55
	v_min_u32_e32 v55, v73, v55
	v_max_u32_e32 v73, v71, v2
	v_min_u32_e32 v2, v71, v2
	v_max_u32_e32 v71, v72, v57
	v_min_u32_e32 v57, v72, v57
	v_max_u32_e32 v72, v66, v69
	v_min_u32_e32 v66, v66, v69
	v_max_u32_e32 v69, v82, v1
	v_min_u32_e32 v1, v82, v1
	v_max_u32_e32 v82, v54, v67
	v_min_u32_e32 v54, v54, v67
	v_max_u32_e32 v59, v60, v63
	v_min_u32_e32 v60, v60, v63
	v_max_u32_e32 v63, v62, v64
	v_min_u32_e32 v62, v62, v64
	v_max_u32_e32 v64, v52, v61
	v_min_u32_e32 v52, v52, v61
	v_max_u32_e32 v61, v65, v74
	v_min_u32_e32 v65, v65, v74
	v_max_u32_e32 v74, v46, v53
	v_min_u32_e32 v46, v46, v53
	v_max_u32_e32 v53, v49, v58
	v_min_u32_e32 v49, v49, v58
	v_max_u32_e32 v58, v51, v47
; #define CE_DESC(a, b) do { const unsigned _mx = (a) > (b) ? (a) : (b), _mn = (a) > (b) ? (b) : (a); (a) = _mx; (b) = _mn; } while (0)
; __device__ __forceinline__ void merge16(unsigned (&a)[16], const unsigned (&b)[16]) {
; #pragma unroll
;     for (int i = 0; i < 16; ++i) a[i] = a[i] > b[15 - i] ? a[i] : b[15 - i];
; #pragma unroll
;     for (int stride = 8; stride > 0; stride >>= 1)
; #pragma unroll
;         for (int i = 0; i < 16; ++i) { const int j = i ^ stride; if (j > i) CE_DESC(a[i], a[j]); }
; }
; __device__ __forceinline__ void peer_tile(const Args& A, LAS unsigned char* lds, int tile) {
;     ...
;                 for (int msk = 16; msk <= 32; msk <<= 1) {
; #pragma unroll
;                     for (int i = 0; i < 16; ++i) k1[i] = (unsigned)__shfl_xor((int)k0[i], msk);
;                     merge16(k0, k1); }
	v_min_u32_e32 v47, v51, v47
	v_max_u32_e32 v51, v48, v50
	v_min_u32_e32 v48, v48, v50
	v_max_u32_e32 v67, v68, v71
	v_min_u32_e32 v68, v68, v71
	v_max_u32_e32 v71, v70, v72
	v_min_u32_e32 v70, v70, v72
	v_max_u32_e32 v72, v56, v69
	v_min_u32_e32 v56, v56, v69
	v_max_u32_e32 v69, v73, v82
	v_min_u32_e32 v73, v73, v82
	v_max_u32_e32 v82, v0, v57
	v_min_u32_e32 v0, v0, v57
	v_max_u32_e32 v57, v3, v66
	v_min_u32_e32 v3, v3, v66
	v_max_u32_e32 v66, v55, v1
	v_min_u32_e32 v1, v55, v1
	v_max_u32_e32 v55, v2, v54
	v_min_u32_e32 v2, v2, v54
	v_max_u32_e32 v50, v59, v64
	v_min_u32_e32 v59, v59, v64
	v_max_u32_e32 v64, v63, v61
	v_min_u32_e32 v61, v63, v61
	v_max_u32_e32 v63, v60, v52
	v_min_u32_e32 v52, v60, v52
	v_max_u32_e32 v60, v62, v65
	v_min_u32_e32 v62, v62, v65
	v_max_u32_e32 v65, v74, v58
	v_min_u32_e32 v58, v74, v58
	v_max_u32_e32 v74, v53, v51
	v_min_u32_e32 v51, v53, v51
	v_max_u32_e32 v53, v46, v47
	v_min_u32_e32 v46, v46, v47
	v_max_u32_e32 v47, v49, v48
	v_min_u32_e32 v48, v49, v48
	v_max_u32_e32 v54, v67, v72
	v_min_u32_e32 v67, v67, v72
	v_max_u32_e32 v72, v71, v69
	v_min_u32_e32 v69, v71, v69
	v_max_u32_e32 v71, v68, v56
	v_min_u32_e32 v56, v68, v56
	v_max_u32_e32 v68, v70, v73
	v_min_u32_e32 v70, v70, v73
	v_max_u32_e32 v73, v82, v66
	v_min_u32_e32 v66, v82, v66
	v_max_u32_e32 v82, v57, v55
	v_min_u32_e32 v55, v57, v55
	v_max_u32_e32 v57, v0, v1
	v_min_u32_e32 v0, v0, v1
	v_max_u32_e32 v1, v3, v2
	v_min_u32_e32 v2, v3, v2
	v_min_u32_e32 v49, v50, v64
	v_min_u32_e32 v75, v59, v61
	v_min_u32_e32 v76, v63, v60
	v_min_u32_e32 v77, v52, v62
	v_min_u32_e32 v78, v65, v74
	v_min_u32_e32 v79, v58, v51
	v_min_u32_e32 v80, v53, v47
	v_min_u32_e32 v81, v46, v48
	v_min_u32_e32 v3, v54, v72
	v_min_u32_e32 v83, v67, v69
	v_min_u32_e32 v84, v71, v68
	v_min_u32_e32 v85, v56, v70
	v_min_u32_e32 v86, v73, v82
	v_min_u32_e32 v87, v66, v55
	v_min_u32_e32 v88, v57, v1
	v_min_u32_e32 v89, v0, v2
	v_max3_u32 v50, v50, v64, v89
	v_max3_u32 v0, v49, v0, v2
	v_max3_u32 v2, v59, v61, v88
	v_max3_u32 v1, v75, v57, v1
	v_max3_u32 v49, v63, v60, v87
	v_max3_u32 v55, v76, v66, v55
	v_max3_u32 v52, v52, v62, v86
	v_max3_u32 v57, v77, v73, v82
	v_max3_u32 v59, v65, v74, v85
	v_max3_u32 v56, v78, v56, v70
	v_max3_u32 v51, v58, v51, v84
	v_max3_u32 v58, v79, v71, v68
	v_max3_u32 v47, v53, v47, v83
	v_max3_u32 v53, v80, v67, v69
	v_max3_u32 v3, v46, v48, v3
	v_max3_u32 v46, v81, v54, v72
	v_max_u32_e32 v48, v50, v59
	v_min_u32_e32 v50, v50, v59
	v_max_u32_e32 v54, v0, v56
	v_min_u32_e32 v0, v0, v56
	v_max_u32_e32 v56, v2, v51
	v_min_u32_e32 v2, v2, v51
	v_max_u32_e32 v51, v1, v58
	v_min_u32_e32 v1, v1, v58
	v_max_u32_e32 v58, v49, v47
	v_min_u32_e32 v47, v49, v47
	v_max_u32_e32 v49, v55, v53
	v_min_u32_e32 v53, v55, v53
	v_max_u32_e32 v55, v52, v3
	v_min_u32_e32 v3, v52, v3
	v_max_u32_e32 v52, v57, v46
	v_min_u32_e32 v46, v57, v46
	v_max_u32_e32 v57, v48, v58
	v_min_u32_e32 v48, v48, v58
	v_max_u32_e32 v58, v54, v49
	v_min_u32_e32 v49, v54, v49
	v_max_u32_e32 v54, v56, v55
	v_min_u32_e32 v55, v56, v55
	v_max_u32_e32 v56, v51, v52
	v_min_u32_e32 v51, v51, v52
	v_max_u32_e32 v52, v50, v47
	v_min_u32_e32 v47, v50, v47
	v_max_u32_e32 v50, v0, v53
	v_min_u32_e32 v0, v0, v53
	v_max_u32_e32 v53, v2, v3
	v_min_u32_e32 v2, v2, v3
	v_max_u32_e32 v3, v1, v46
	v_min_u32_e32 v1, v1, v46
	v_max_u32_e32 v46, v57, v54
	v_min_u32_e32 v54, v57, v54
	v_max_u32_e32 v57, v58, v56
	v_min_u32_e32 v56, v58, v56
	v_max_u32_e32 v58, v48, v55
	v_min_u32_e32 v48, v48, v55
	v_max_u32_e32 v55, v49, v51
	v_min_u32_e32 v49, v49, v51
	v_max_u32_e32 v51, v52, v53
	v_min_u32_e32 v52, v52, v53
	v_max_u32_e32 v53, v50, v3
	v_min_u32_e32 v3, v50, v3
	v_max_u32_e32 v50, v47, v2
	v_min_u32_e32 v2, v47, v2
	v_max_u32_e32 v47, v0, v1
	v_min_u32_e32 v0, v0, v1
	v_max_u32_e32 v1, v46, v57
	v_min_u32_e32 v46, v46, v57
	v_max_u32_e32 v57, v54, v56
	v_min_u32_e32 v54, v54, v56
	v_max_u32_e32 v56, v58, v55
	v_min_u32_e32 v55, v58, v55
	v_max_u32_e32 v58, v48, v49
	v_min_u32_e32 v48, v48, v49
	v_max_u32_e32 v49, v51, v53
	v_min_u32_e32 v51, v51, v53
	v_max_u32_e32 v53, v52, v3
	v_min_u32_e32 v3, v52, v3
	v_max_u32_e32 v52, v50, v47
	v_min_u32_e32 v47, v50, v47
	v_max_u32_e32 v50, v2, v0
	v_min_u32_e32 v0, v2, v0
	ds_bpermute_b32 v2, v27, v1
	ds_bpermute_b32 v59, v27, v46
	ds_bpermute_b32 v60, v27, v57
	ds_bpermute_b32 v61, v27, v54
	ds_bpermute_b32 v62, v27, v56
	ds_bpermute_b32 v63, v27, v55
	ds_bpermute_b32 v64, v27, v58
	ds_bpermute_b32 v65, v27, v48
	ds_bpermute_b32 v66, v27, v49
	ds_bpermute_b32 v67, v27, v51
	ds_bpermute_b32 v68, v27, v53
	ds_bpermute_b32 v69, v27, v0
	ds_bpermute_b32 v70, v27, v50
	ds_bpermute_b32 v71, v27, v47
	ds_bpermute_b32 v72, v27, v52
	ds_bpermute_b32 v73, v27, v3
	s_waitcnt lgkmcnt(4)
	v_max_u32_e32 v1, v1, v69
	s_waitcnt lgkmcnt(3)
	v_max_u32_e32 v46, v46, v70
	s_waitcnt lgkmcnt(2)
	v_max_u32_e32 v57, v57, v71
	s_waitcnt lgkmcnt(1)
	v_max_u32_e32 v54, v54, v72
	s_waitcnt lgkmcnt(0)
; __device__ __forceinline__ void peer_tile(const Args& A, LAS unsigned char* lds, int tile) {
;     ...
;                 sort16_desc(k0); sort16_desc(k1); merge16(k0, k1);
; #pragma unroll
;                 for (int msk = 16; msk <= 32; msk <<= 1) {
; #pragma unroll
;                     for (int i = 0; i < 16; ++i) k1[i] = (unsigned)__shfl_xor((int)k0[i], msk);
;                     merge16(k0, k1); }
; #pragma unroll
;                 for (int i = 0; i < 16; ++i) LA[hh][p][i] = k0[i];
;             }
	v_max_u32_e32 v56, v56, v73
	v_max_u32_e32 v55, v55, v68
	v_max_u32_e32 v58, v58, v67
	v_max_u32_e32 v48, v48, v66
	v_max_u32_e32 v49, v49, v65
	v_max_u32_e32 v51, v51, v64
	v_max_u32_e32 v53, v53, v63
	v_max_u32_e32 v3, v3, v62
	v_max_u32_e32 v52, v52, v61
	v_max_u32_e32 v47, v47, v60
	v_max_u32_e32 v50, v50, v59
	v_max_u32_e32 v0, v0, v2
	v_max_u32_e32 v2, v1, v49
	v_min_u32_e32 v1, v1, v49
	v_max_u32_e32 v49, v46, v51
	v_min_u32_e32 v46, v46, v51
	v_max_u32_e32 v51, v57, v53
	v_min_u32_e32 v53, v57, v53
	v_max_u32_e32 v57, v54, v3
	v_min_u32_e32 v3, v54, v3
	v_max_u32_e32 v54, v56, v52
	v_min_u32_e32 v52, v56, v52
	v_max_u32_e32 v56, v55, v47
	v_min_u32_e32 v47, v55, v47
	v_max_u32_e32 v55, v58, v50
	v_min_u32_e32 v50, v58, v50
	v_max_u32_e32 v58, v48, v0
	v_min_u32_e32 v0, v48, v0
	v_max_u32_e32 v48, v2, v54
	v_min_u32_e32 v2, v2, v54
	v_max_u32_e32 v54, v49, v56
	v_min_u32_e32 v49, v49, v56
	v_max_u32_e32 v56, v51, v55
	v_min_u32_e32 v51, v51, v55
	v_max_u32_e32 v55, v57, v58
	v_min_u32_e32 v57, v57, v58
	v_max_u32_e32 v58, v1, v52
	v_min_u32_e32 v1, v1, v52
	v_max_u32_e32 v52, v46, v47
	v_min_u32_e32 v46, v46, v47
	v_max_u32_e32 v47, v53, v50
	v_min_u32_e32 v50, v53, v50
	v_max_u32_e32 v53, v3, v0
	v_min_u32_e32 v0, v3, v0
	v_max_u32_e32 v3, v48, v56
	v_min_u32_e32 v48, v48, v56
	v_max_u32_e32 v56, v54, v55
	v_min_u32_e32 v54, v54, v55
	v_max_u32_e32 v55, v2, v51
	v_min_u32_e32 v2, v2, v51
	v_max_u32_e32 v51, v49, v57
	v_min_u32_e32 v49, v49, v57
	v_max_u32_e32 v57, v58, v47
	v_min_u32_e32 v47, v58, v47
	v_max_u32_e32 v58, v52, v53
	v_min_u32_e32 v52, v52, v53
	v_max_u32_e32 v53, v1, v50
	v_min_u32_e32 v1, v1, v50
	v_max_u32_e32 v50, v46, v0
	v_min_u32_e32 v0, v46, v0
	v_max_u32_e32 v46, v3, v56
	v_min_u32_e32 v3, v3, v56
	v_max_u32_e32 v56, v48, v54
	v_min_u32_e32 v48, v48, v54
	v_max_u32_e32 v54, v55, v51
	v_min_u32_e32 v51, v55, v51
	v_max_u32_e32 v55, v2, v49
	v_min_u32_e32 v2, v2, v49
	v_max_u32_e32 v49, v57, v58
	v_min_u32_e32 v57, v57, v58
	v_max_u32_e32 v58, v47, v52
	v_min_u32_e32 v47, v47, v52
	v_max_u32_e32 v52, v53, v50
	v_min_u32_e32 v50, v53, v50
	v_max_u32_e32 v53, v1, v0
	v_min_u32_e32 v0, v1, v0
	ds_bpermute_b32 v62, v29, v0
	ds_bpermute_b32 v1, v29, v46
	ds_bpermute_b32 v59, v29, v3
	ds_bpermute_b32 v60, v29, v56
	ds_bpermute_b32 v61, v29, v48
	s_waitcnt lgkmcnt(4)
	v_max_u32_e32 v46, v46, v62
	global_load_dwordx4 v[62:65], v[4:5], off offset:528
	global_load_dwordx4 v[66:69], v[4:5], off offset:512
	ds_bpermute_b32 v70, v29, v54
	ds_bpermute_b32 v71, v29, v51
	ds_bpermute_b32 v72, v29, v55
	ds_bpermute_b32 v73, v29, v2
	ds_bpermute_b32 v74, v29, v49
	ds_bpermute_b32 v75, v29, v57
	ds_bpermute_b32 v76, v29, v58
	ds_bpermute_b32 v77, v29, v47
	ds_bpermute_b32 v78, v29, v52
	ds_bpermute_b32 v79, v29, v53
	ds_bpermute_b32 v80, v29, v50
	s_waitcnt lgkmcnt(4)
	v_max_u32_e32 v51, v51, v76
	s_waitcnt lgkmcnt(3)
	v_max_u32_e32 v54, v54, v77
	s_waitcnt lgkmcnt(2)
	v_max_u32_e32 v48, v48, v78
	s_waitcnt lgkmcnt(1)
	v_max_u32_e32 v3, v3, v79
	s_waitcnt lgkmcnt(0)
	v_max_u32_e32 v56, v56, v80
	v_max_u32_e32 v55, v55, v75
	v_max_u32_e32 v2, v2, v74
	v_max_u32_e32 v49, v49, v73
	v_max_u32_e32 v57, v57, v72
	v_max_u32_e32 v58, v58, v71
	v_max_u32_e32 v47, v47, v70
	v_max_u32_e32 v52, v52, v61
	v_max_u32_e32 v50, v50, v60
	v_max_u32_e32 v53, v53, v59
	v_max_u32_e32 v0, v0, v1
	v_max_u32_e32 v1, v46, v49
	v_min_u32_e32 v46, v46, v49
	v_max_u32_e32 v49, v3, v57
	v_min_u32_e32 v3, v3, v57
	v_max_u32_e32 v57, v56, v58
	v_min_u32_e32 v56, v56, v58
	v_max_u32_e32 v58, v48, v47
	v_min_u32_e32 v47, v48, v47
	v_max_u32_e32 v48, v54, v52
	v_min_u32_e32 v52, v54, v52
	v_max_u32_e32 v54, v51, v50
	v_min_u32_e32 v50, v51, v50
	v_max_u32_e32 v51, v55, v53
	v_min_u32_e32 v53, v55, v53
	v_max_u32_e32 v55, v2, v0
	v_min_u32_e32 v0, v2, v0
	v_max_u32_e32 v2, v1, v48
	v_min_u32_e32 v1, v1, v48
	v_max_u32_e32 v48, v49, v54
	v_min_u32_e32 v49, v49, v54
	v_max_u32_e32 v54, v57, v51
	v_min_u32_e32 v51, v57, v51
	v_max_u32_e32 v57, v58, v55
	v_min_u32_e32 v55, v58, v55
	v_max_u32_e32 v58, v46, v52
	v_min_u32_e32 v46, v46, v52
	v_max_u32_e32 v52, v3, v50
	v_min_u32_e32 v3, v3, v50
	v_max_u32_e32 v50, v56, v53
	v_min_u32_e32 v53, v56, v53
	v_max_u32_e32 v56, v47, v0
	v_min_u32_e32 v0, v47, v0
	v_max_u32_e32 v47, v2, v54
	v_min_u32_e32 v2, v2, v54
	v_max_u32_e32 v54, v48, v57
	v_min_u32_e32 v48, v48, v57
	v_max_u32_e32 v70, v1, v51
	v_min_u32_e32 v1, v1, v51
	v_max_u32_e32 v51, v49, v55
	v_min_u32_e32 v49, v49, v55
	v_max_u32_e32 v71, v58, v50
	v_min_u32_e32 v50, v58, v50
	v_max_u32_e32 v72, v52, v56
	v_min_u32_e32 v73, v52, v56
	v_max_u32_e32 v74, v46, v53
	v_min_u32_e32 v46, v46, v53
	v_max_u32_e32 v75, v3, v0
	v_min_u32_e32 v0, v3, v0
	v_max_u32_e32 v61, v47, v54
	v_min_u32_e32 v60, v47, v54
	v_max_u32_e32 v59, v2, v48
	v_min_u32_e32 v58, v2, v48
	v_max_u32_e32 v57, v70, v51
	v_min_u32_e32 v56, v70, v51
	v_max_u32_e32 v55, v1, v49
	v_min_u32_e32 v54, v1, v49
	v_max_u32_e32 v53, v71, v72
	v_min_u32_e32 v52, v71, v72
	v_max_u32_e32 v51, v50, v73
	v_min_u32_e32 v50, v50, v73
	v_max_u32_e32 v47, v46, v0
	v_min_u32_e32 v46, v46, v0
	global_load_dwordx4 v[0:3], v[4:5], off offset:560
	global_load_dwordx4 v[70:73], v[4:5], off offset:544
	v_max_u32_e32 v49, v74, v75
	v_min_u32_e32 v48, v74, v75
	s_waitcnt vmcnt(2)
; __device__ __forceinline__ unsigned f2key(float f) { const unsigned u = __float_as_uint(f); return (u & 0x80000000u) ? ~u : (u | 0x80000000u); }
; __device__ __forceinline__ void peer_tile(const Args& A, LAS unsigned char* lds, int tile) {
;     ...
;                 const int hp = 2 * h + p;
;                 unsigned k0[16], k1[16];
;                 { const bf16_t* sp = QRY + m * 2048 + hp * 128 + 32 * g;
;                   const u32x4 s0 = *(const u32x4*)sp, s1 = *(const u32x4*)(sp + 8), s2 = *(const u32x4*)(sp + 16), s3 = *(const u32x4*)(sp + 24);
;                   const unsigned sw[16] = {s0.x, s0.y, s0.z, s0.w, s1.x, s1.y, s1.z, s1.w, s2.x, s2.y, s2.z, s2.w, s3.x, s3.y, s3.z, s3.w};
; #pragma unroll
;                   for (int i = 0; i < 16; ++i) {
;                       const float lo = (float)__builtin_bit_cast(_Float16, (unsigned short)(sw[i] & 0xffffu)), hi = (float)__builtin_bit_cast(_Float16, (unsigned short)(sw[i] >> 16));
;                       const unsigned klo = (f2key(lo) & ~127u) | (unsigned)(127 - (32 * g + 2 * i)), khi = (f2key(hi) & ~127u) | (unsigned)(127 - (32 * g + 2 * i + 1));
;                       if (i < 8) { k0[2 * i] = klo; k0[2 * i + 1] = khi; } else { k1[2 * (i - 8)] = klo; k1[2 * (i - 8) + 1] = khi; } } }
	v_cvt_f32_f16_sdwa v74, v66 dst_sel:DWORD dst_unused:UNUSED_PAD src0_sel:WORD_1
	v_cvt_f32_f16_e32 v66, v66
	v_not_b32_e32 v75, v74
	v_or_b32_e32 v76, 0x80000000, v74
	v_cmp_gt_i32_e32 vcc, 0, v74
	s_nop 1
	v_cndmask_b32_e32 v74, v76, v75, vcc
	v_not_b32_e32 v75, v66
	v_or_b32_e32 v76, 0x80000000, v66
	v_cmp_gt_i32_e32 vcc, 0, v66
	v_and_b32_e32 v74, 0xffffff80, v74
	v_sub_u32_e32 v74, v74, v15
	v_cndmask_b32_e32 v66, v76, v75, vcc
	v_cvt_f32_f16_sdwa v75, v67 dst_sel:DWORD dst_unused:UNUSED_PAD src0_sel:WORD_1
	v_cvt_f32_f16_e32 v67, v67
	v_and_b32_e32 v66, 0xffffff80, v66
	v_sub_u32_e32 v66, v66, v15
	v_not_b32_e32 v76, v75
	v_or_b32_e32 v77, 0x80000000, v75
	v_cmp_gt_i32_e32 vcc, 0, v75
	v_add_u32_e32 v74, 0x7e, v74
	v_add_u32_e32 v66, 0x7f, v66
	v_cndmask_b32_e32 v75, v77, v76, vcc
	v_not_b32_e32 v76, v67
	v_or_b32_e32 v77, 0x80000000, v67
	v_cmp_gt_i32_e32 vcc, 0, v67
	v_and_b32_e32 v75, 0xffffff80, v75
	v_sub_u32_e32 v75, v75, v14
	v_cndmask_b32_e32 v67, v77, v76, vcc
	v_cvt_f32_f16_sdwa v76, v68 dst_sel:DWORD dst_unused:UNUSED_PAD src0_sel:WORD_1
	v_cvt_f32_f16_e32 v68, v68
	v_and_b32_e32 v67, 0xffffff80, v67
	v_sub_u32_e32 v67, v67, v14
	v_not_b32_e32 v77, v76
	v_or_b32_e32 v78, 0x80000000, v76
	v_cmp_gt_i32_e32 vcc, 0, v76
	v_add_u32_e32 v75, 0x7e, v75
	v_add_u32_e32 v67, 0x7f, v67
	v_cndmask_b32_e32 v76, v78, v77, vcc
	v_not_b32_e32 v77, v68
	v_or_b32_e32 v78, 0x80000000, v68
	v_cmp_gt_i32_e32 vcc, 0, v68
	v_and_b32_e32 v76, 0xffffff80, v76
	v_sub_u32_e32 v76, v76, v12
	v_cndmask_b32_e32 v68, v78, v77, vcc
	v_cvt_f32_f16_sdwa v77, v69 dst_sel:DWORD dst_unused:UNUSED_PAD src0_sel:WORD_1
	v_cvt_f32_f16_e32 v69, v69
	v_and_b32_e32 v68, 0xffffff80, v68
	v_sub_u32_e32 v68, v68, v12
	v_not_b32_e32 v78, v77
	v_or_b32_e32 v79, 0x80000000, v77
	v_cmp_gt_i32_e32 vcc, 0, v77
	v_add_u32_e32 v76, 0x7e, v76
	v_add_u32_e32 v68, 0x7f, v68
	v_cndmask_b32_e32 v77, v79, v78, vcc
	v_not_b32_e32 v78, v69
	v_or_b32_e32 v79, 0x80000000, v69
	v_cmp_gt_i32_e32 vcc, 0, v69
	v_and_b32_e32 v77, 0xffffff80, v77
	v_sub_u32_e32 v77, v77, v10
	v_cndmask_b32_e32 v69, v79, v78, vcc
	v_cvt_f32_f16_sdwa v78, v62 dst_sel:DWORD dst_unused:UNUSED_PAD src0_sel:WORD_1
	v_cvt_f32_f16_e32 v62, v62
	v_and_b32_e32 v69, 0xffffff80, v69
	v_sub_u32_e32 v69, v69, v10
	v_not_b32_e32 v79, v78
	v_or_b32_e32 v80, 0x80000000, v78
	v_cmp_gt_i32_e32 vcc, 0, v78
	v_add_u32_e32 v77, 0x7e, v77
	v_add_u32_e32 v69, 0x7f, v69
	v_cndmask_b32_e32 v78, v80, v79, vcc
	v_not_b32_e32 v79, v62
	v_or_b32_e32 v80, 0x80000000, v62
	v_cmp_gt_i32_e32 vcc, 0, v62
	v_and_b32_e32 v78, 0xffffff80, v78
	v_sub_u32_e32 v78, v78, v8
	v_cndmask_b32_e32 v62, v80, v79, vcc
	v_cvt_f32_f16_sdwa v79, v63 dst_sel:DWORD dst_unused:UNUSED_PAD src0_sel:WORD_1
	v_cvt_f32_f16_e32 v63, v63
	v_and_b32_e32 v62, 0xffffff80, v62
	v_sub_u32_e32 v62, v62, v8
	v_not_b32_e32 v80, v79
	v_or_b32_e32 v81, 0x80000000, v79
	v_cmp_gt_i32_e32 vcc, 0, v79
	v_add_u32_e32 v78, 0x7e, v78
	v_add_u32_e32 v62, 0x7f, v62
	v_cndmask_b32_e32 v79, v81, v80, vcc
	v_not_b32_e32 v80, v63
	v_or_b32_e32 v81, 0x80000000, v63
	v_cmp_gt_i32_e32 vcc, 0, v63
	v_and_b32_e32 v79, 0xffffff80, v79
	v_sub_u32_e32 v79, v79, v16
	v_cndmask_b32_e32 v63, v81, v80, vcc
	v_cvt_f32_f16_sdwa v80, v64 dst_sel:DWORD dst_unused:UNUSED_PAD src0_sel:WORD_1
	v_cvt_f32_f16_e32 v64, v64
	v_and_b32_e32 v63, 0xffffff80, v63
	v_sub_u32_e32 v63, v63, v16
	v_not_b32_e32 v81, v80
	v_or_b32_e32 v82, 0x80000000, v80
	v_cmp_gt_i32_e32 vcc, 0, v80
	v_add_u32_e32 v79, 0x7e, v79
	v_add_u32_e32 v63, 0x7f, v63
	v_cndmask_b32_e32 v80, v82, v81, vcc
	v_not_b32_e32 v81, v64
	v_or_b32_e32 v82, 0x80000000, v64
	v_cmp_gt_i32_e32 vcc, 0, v64
	v_and_b32_e32 v80, 0xffffff80, v80
	v_sub_u32_e32 v80, v80, v17
	v_cndmask_b32_e32 v64, v82, v81, vcc
	v_cvt_f32_f16_sdwa v81, v65 dst_sel:DWORD dst_unused:UNUSED_PAD src0_sel:WORD_1
	v_cvt_f32_f16_e32 v65, v65
	v_and_b32_e32 v64, 0xffffff80, v64
	v_sub_u32_e32 v64, v64, v17
	v_not_b32_e32 v82, v81
	v_or_b32_e32 v83, 0x80000000, v81
	v_cmp_gt_i32_e32 vcc, 0, v81
	v_add_u32_e32 v80, 0x7e, v80
	v_add_u32_e32 v64, 0x7f, v64
	v_cndmask_b32_e32 v81, v83, v82, vcc
	v_not_b32_e32 v82, v65
	v_or_b32_e32 v83, 0x80000000, v65
	v_cmp_gt_i32_e32 vcc, 0, v65
	v_and_b32_e32 v81, 0xffffff80, v81
	v_sub_u32_e32 v81, v81, v18
	v_cndmask_b32_e32 v65, v83, v82, vcc
	s_waitcnt vmcnt(0)
; __device__ __forceinline__ unsigned f2key(float f) { const unsigned u = __float_as_uint(f); return (u & 0x80000000u) ? ~u : (u | 0x80000000u); }
; #define CE_DESC(a, b) do { const unsigned _mx = (a) > (b) ? (a) : (b), _mn = (a) > (b) ? (b) : (a); (a) = _mx; (b) = _mn; } while (0)
; __device__ __forceinline__ void sort16_desc(unsigned (&k)[16]) {
; #pragma unroll
;     for (int size = 2; size <= 16; size <<= 1)
; #pragma unroll
;         for (int stride = size >> 1; stride > 0; stride >>= 1)
; #pragma unroll
;             for (int i = 0; i < 16; ++i) { const int j = i ^ stride;
;                 if (j > i) { if ((i & size) == 0) CE_DESC(k[i], k[j]); else CE_DESC(k[j], k[i]); } }
; }
; __device__ __forceinline__ void peer_tile(const Args& A, LAS unsigned char* lds, int tile) {
;     ...
;                   for (int i = 0; i < 16; ++i) {
;                       const float lo = (float)__builtin_bit_cast(_Float16, (unsigned short)(sw[i] & 0xffffu)), hi = (float)__builtin_bit_cast(_Float16, (unsigned short)(sw[i] >> 16));
;                       const unsigned klo = (f2key(lo) & ~127u) | (unsigned)(127 - (32 * g + 2 * i)), khi = (f2key(hi) & ~127u) | (unsigned)(127 - (32 * g + 2 * i + 1));
;                       if (i < 8) { k0[2 * i] = klo; k0[2 * i + 1] = khi; } else { k1[2 * (i - 8)] = klo; k1[2 * (i - 8) + 1] = khi; } } }
	v_cvt_f32_f16_sdwa v82, v70 dst_sel:DWORD dst_unused:UNUSED_PAD src0_sel:WORD_1
	v_cvt_f32_f16_e32 v70, v70
	v_and_b32_e32 v65, 0xffffff80, v65
	v_sub_u32_e32 v65, v65, v18
	v_not_b32_e32 v83, v82
	v_or_b32_e32 v84, 0x80000000, v82
	v_cmp_gt_i32_e32 vcc, 0, v82
	v_add_u32_e32 v81, 0x7e, v81
	v_add_u32_e32 v65, 0x7f, v65
	v_cndmask_b32_e32 v82, v84, v83, vcc
	v_not_b32_e32 v83, v70
	v_or_b32_e32 v84, 0x80000000, v70
	v_cmp_gt_i32_e32 vcc, 0, v70
	v_and_b32_e32 v82, 0xffffff80, v82
	v_sub_u32_e32 v82, v82, v20
	v_cndmask_b32_e32 v70, v84, v83, vcc
	v_cvt_f32_f16_sdwa v83, v71 dst_sel:DWORD dst_unused:UNUSED_PAD src0_sel:WORD_1
	v_cvt_f32_f16_e32 v71, v71
	v_and_b32_e32 v70, 0xffffff80, v70
	v_sub_u32_e32 v70, v70, v20
	v_not_b32_e32 v84, v83
	v_or_b32_e32 v85, 0x80000000, v83
	v_cmp_gt_i32_e32 vcc, 0, v83
	v_add_u32_e32 v82, 0x7e, v82
	v_add_u32_e32 v70, 0x7f, v70
	v_cndmask_b32_e32 v83, v85, v84, vcc
	v_not_b32_e32 v84, v71
	v_or_b32_e32 v85, 0x80000000, v71
	v_cmp_gt_i32_e32 vcc, 0, v71
	v_and_b32_e32 v83, 0xffffff80, v83
	v_sub_u32_e32 v83, v83, v21
	v_cndmask_b32_e32 v71, v85, v84, vcc
	v_cvt_f32_f16_sdwa v84, v72 dst_sel:DWORD dst_unused:UNUSED_PAD src0_sel:WORD_1
	v_cvt_f32_f16_e32 v72, v72
	v_and_b32_e32 v71, 0xffffff80, v71
	v_sub_u32_e32 v71, v71, v21
	v_not_b32_e32 v85, v84
	v_or_b32_e32 v86, 0x80000000, v84
	v_cmp_gt_i32_e32 vcc, 0, v84
	v_add_u32_e32 v83, 0x7e, v83
	v_add_u32_e32 v71, 0x7f, v71
	v_cndmask_b32_e32 v84, v86, v85, vcc
	v_not_b32_e32 v85, v72
	v_or_b32_e32 v86, 0x80000000, v72
	v_cmp_gt_i32_e32 vcc, 0, v72
	v_and_b32_e32 v84, 0xffffff80, v84
	v_sub_u32_e32 v84, v84, v22
	v_cndmask_b32_e32 v72, v86, v85, vcc
	v_cvt_f32_f16_sdwa v85, v73 dst_sel:DWORD dst_unused:UNUSED_PAD src0_sel:WORD_1
	v_cvt_f32_f16_e32 v73, v73
	v_and_b32_e32 v72, 0xffffff80, v72
	v_sub_u32_e32 v72, v72, v22
	v_not_b32_e32 v86, v85
	v_or_b32_e32 v87, 0x80000000, v85
	v_cmp_gt_i32_e32 vcc, 0, v85
	v_add_u32_e32 v84, 0x7e, v84
	v_add_u32_e32 v72, 0x7f, v72
	v_cndmask_b32_e32 v85, v87, v86, vcc
	v_not_b32_e32 v86, v73
	v_or_b32_e32 v87, 0x80000000, v73
	v_cmp_gt_i32_e32 vcc, 0, v73
	v_and_b32_e32 v85, 0xffffff80, v85
	v_sub_u32_e32 v85, v85, v23
	v_cndmask_b32_e32 v73, v87, v86, vcc
	v_cvt_f32_f16_sdwa v86, v0 dst_sel:DWORD dst_unused:UNUSED_PAD src0_sel:WORD_1
	v_cvt_f32_f16_e32 v0, v0
	v_and_b32_e32 v73, 0xffffff80, v73
	v_sub_u32_e32 v73, v73, v23
	v_not_b32_e32 v87, v86
	v_or_b32_e32 v88, 0x80000000, v86
	v_cmp_gt_i32_e32 vcc, 0, v86
	v_add_u32_e32 v85, 0x7e, v85
	v_add_u32_e32 v73, 0x7f, v73
	v_cndmask_b32_e32 v86, v88, v87, vcc
	v_not_b32_e32 v87, v0
	v_or_b32_e32 v88, 0x80000000, v0
	v_cmp_gt_i32_e32 vcc, 0, v0
	v_and_b32_e32 v86, 0xffffff80, v86
	v_sub_u32_e32 v86, v86, v24
	v_cndmask_b32_e32 v0, v88, v87, vcc
	v_cvt_f32_f16_sdwa v87, v1 dst_sel:DWORD dst_unused:UNUSED_PAD src0_sel:WORD_1
	v_cvt_f32_f16_e32 v1, v1
	v_and_b32_e32 v0, 0xffffff80, v0
	v_sub_u32_e32 v0, v0, v24
	v_not_b32_e32 v88, v87
	v_or_b32_e32 v89, 0x80000000, v87
	v_cmp_gt_i32_e32 vcc, 0, v87
	v_add_u32_e32 v86, 0x7e, v86
	v_add_u32_e32 v0, 0x7f, v0
	v_cndmask_b32_e32 v87, v89, v88, vcc
	v_not_b32_e32 v88, v1
	v_or_b32_e32 v89, 0x80000000, v1
	v_cmp_gt_i32_e32 vcc, 0, v1
	v_and_b32_e32 v87, 0xffffff80, v87
	v_sub_u32_e32 v87, v87, v25
	v_cndmask_b32_e32 v1, v89, v88, vcc
	v_cvt_f32_f16_sdwa v88, v2 dst_sel:DWORD dst_unused:UNUSED_PAD src0_sel:WORD_1
	v_cvt_f32_f16_e32 v2, v2
	v_and_b32_e32 v1, 0xffffff80, v1
	v_sub_u32_e32 v1, v1, v25
	v_not_b32_e32 v89, v88
	v_or_b32_e32 v90, 0x80000000, v88
	v_cmp_gt_i32_e32 vcc, 0, v88
	v_add_u32_e32 v87, 0x7e, v87
	v_add_u32_e32 v1, 0x7f, v1
	v_cndmask_b32_e32 v88, v90, v89, vcc
	v_not_b32_e32 v89, v2
	v_or_b32_e32 v90, 0x80000000, v2
	v_cmp_gt_i32_e32 vcc, 0, v2
	v_and_b32_e32 v88, 0xffffff80, v88
	v_sub_u32_e32 v88, v88, v26
	v_cndmask_b32_e32 v2, v90, v89, vcc
	v_cvt_f32_f16_sdwa v89, v3 dst_sel:DWORD dst_unused:UNUSED_PAD src0_sel:WORD_1
	v_cvt_f32_f16_e32 v3, v3
	v_and_b32_e32 v2, 0xffffff80, v2
	v_sub_u32_e32 v2, v2, v26
	v_not_b32_e32 v90, v89
	v_or_b32_e32 v91, 0x80000000, v89
	v_cmp_gt_i32_e32 vcc, 0, v89
	v_add_u32_e32 v88, 0x7e, v88
	v_add_u32_e32 v2, 0x7f, v2
	v_cndmask_b32_e32 v89, v91, v90, vcc
	v_not_b32_e32 v90, v3
	v_or_b32_e32 v91, 0x80000000, v3
	v_cmp_gt_i32_e32 vcc, 0, v3
	v_and_b32_e32 v89, 0xffffff80, v89
	v_sub_u32_e32 v89, v89, v28
	v_cndmask_b32_e32 v3, v91, v90, vcc
	v_and_b32_e32 v3, 0xffffff80, v3
	v_sub_u32_e32 v3, v3, v28
	v_add_u32_e32 v89, 0x7e, v89
	v_add_u32_e32 v3, 0x7f, v3
	v_max_u32_e32 v90, v66, v74
	v_min_u32_e32 v66, v66, v74
	v_max_u32_e32 v74, v75, v67
	v_min_u32_e32 v67, v75, v67
	v_max_u32_e32 v75, v68, v76
	v_min_u32_e32 v68, v68, v76
	v_max_u32_e32 v76, v77, v69
	v_min_u32_e32 v69, v77, v69
	v_max_u32_e32 v77, v62, v78
	v_min_u32_e32 v62, v62, v78
	v_max_u32_e32 v78, v79, v63
	v_min_u32_e32 v63, v79, v63
	v_max_u32_e32 v79, v64, v80
	v_min_u32_e32 v64, v64, v80
	v_max_u32_e32 v80, v81, v65
	v_min_u32_e32 v65, v81, v65
	v_max_u32_e32 v98, v70, v82
	v_min_u32_e32 v70, v70, v82
	v_max_u32_e32 v82, v83, v71
	v_min_u32_e32 v71, v83, v71
	v_max_u32_e32 v83, v72, v84
	v_min_u32_e32 v72, v72, v84
	v_max_u32_e32 v84, v85, v73
	v_min_u32_e32 v73, v85, v73
	v_max_u32_e32 v85, v0, v86
	v_min_u32_e32 v0, v0, v86
	v_max_u32_e32 v86, v87, v1
	v_min_u32_e32 v1, v87, v1
	v_max_u32_e32 v87, v2, v88
	v_min_u32_e32 v2, v2, v88
	v_max_u32_e32 v88, v89, v3
	v_min_u32_e32 v3, v89, v3
	v_max_u32_e32 v81, v90, v67
	v_min_u32_e32 v67, v90, v67
	v_max_u32_e32 v90, v66, v74
	v_min_u32_e32 v66, v66, v74
	v_max_u32_e32 v74, v69, v75
	v_min_u32_e32 v69, v69, v75
	v_max_u32_e32 v75, v76, v68
	v_min_u32_e32 v68, v76, v68
; #define CE_DESC(a, b) do { const unsigned _mx = (a) > (b) ? (a) : (b), _mn = (a) > (b) ? (b) : (a); (a) = _mx; (b) = _mn; } while (0)
; __device__ __forceinline__ void sort16_desc(unsigned (&k)[16]) {
; #pragma unroll
;     for (int size = 2; size <= 16; size <<= 1)
; #pragma unroll
;         for (int stride = size >> 1; stride > 0; stride >>= 1)
; #pragma unroll
;             for (int i = 0; i < 16; ++i) { const int j = i ^ stride;
;                 if (j > i) { if ((i & size) == 0) CE_DESC(k[i], k[j]); else CE_DESC(k[j], k[i]); } }
; }
	v_max_u32_e32 v76, v77, v63
	v_min_u32_e32 v63, v77, v63
	v_max_u32_e32 v77, v62, v78
	v_min_u32_e32 v62, v62, v78
	v_max_u32_e32 v78, v65, v79
	v_min_u32_e32 v65, v65, v79
	v_max_u32_e32 v79, v80, v64
	v_min_u32_e32 v64, v80, v64
	v_max_u32_e32 v89, v98, v71
	v_min_u32_e32 v71, v98, v71
	v_max_u32_e32 v98, v70, v82
	v_min_u32_e32 v70, v70, v82
	v_max_u32_e32 v82, v73, v83
	v_min_u32_e32 v73, v73, v83
	v_max_u32_e32 v83, v84, v72
	v_min_u32_e32 v72, v84, v72
	v_max_u32_e32 v84, v85, v1
	v_min_u32_e32 v1, v85, v1
	v_max_u32_e32 v85, v0, v86
	v_min_u32_e32 v0, v0, v86
	v_max_u32_e32 v86, v3, v87
	v_min_u32_e32 v3, v3, v87
	v_max_u32_e32 v87, v88, v2
	v_min_u32_e32 v2, v88, v2
	v_max_u32_e32 v80, v81, v90
	v_min_u32_e32 v81, v81, v90
	v_max_u32_e32 v90, v67, v66
	v_min_u32_e32 v66, v67, v66
	v_max_u32_e32 v67, v68, v69
	v_min_u32_e32 v68, v68, v69
	v_max_u32_e32 v69, v75, v74
	v_min_u32_e32 v74, v75, v74
	v_max_u32_e32 v75, v76, v77
	v_min_u32_e32 v76, v76, v77
	v_max_u32_e32 v77, v63, v62
	v_min_u32_e32 v62, v63, v62
	v_max_u32_e32 v63, v64, v65
	v_min_u32_e32 v64, v64, v65
	v_max_u32_e32 v65, v79, v78
	v_min_u32_e32 v78, v79, v78
	v_max_u32_e32 v88, v89, v98
	v_min_u32_e32 v89, v89, v98
	v_max_u32_e32 v98, v71, v70
	v_min_u32_e32 v70, v71, v70
	v_max_u32_e32 v71, v72, v73
	v_min_u32_e32 v72, v72, v73
	v_max_u32_e32 v73, v83, v82
	v_min_u32_e32 v82, v83, v82
	v_max_u32_e32 v83, v84, v85
	v_min_u32_e32 v84, v84, v85
	v_max_u32_e32 v85, v1, v0
	v_min_u32_e32 v0, v1, v0
	v_max_u32_e32 v1, v2, v3
	v_min_u32_e32 v2, v2, v3
	v_max_u32_e32 v3, v87, v86
	v_min_u32_e32 v86, v87, v86
	v_max_u32_e32 v79, v80, v68
	v_min_u32_e32 v68, v80, v68
	v_max_u32_e32 v80, v81, v67
	v_min_u32_e32 v67, v81, v67
	v_max_u32_e32 v81, v90, v74
	v_min_u32_e32 v74, v90, v74
	v_max_u32_e32 v90, v66, v69
	v_min_u32_e32 v66, v66, v69
	v_max_u32_e32 v69, v64, v75
	v_min_u32_e32 v64, v64, v75
	v_max_u32_e32 v75, v63, v76
	v_min_u32_e32 v63, v63, v76
	v_max_u32_e32 v76, v78, v77
	v_min_u32_e32 v77, v78, v77
	v_max_u32_e32 v78, v65, v62
	v_min_u32_e32 v62, v65, v62
	v_max_u32_e32 v87, v88, v72
	v_min_u32_e32 v72, v88, v72
	v_max_u32_e32 v88, v89, v71
	v_min_u32_e32 v71, v89, v71
	v_max_u32_e32 v89, v98, v82
	v_min_u32_e32 v82, v98, v82
	v_max_u32_e32 v98, v70, v73
	v_min_u32_e32 v70, v70, v73
	v_max_u32_e32 v73, v2, v83
	v_min_u32_e32 v2, v2, v83
	v_max_u32_e32 v83, v1, v84
	v_min_u32_e32 v1, v1, v84
	v_max_u32_e32 v84, v86, v85
	v_min_u32_e32 v85, v86, v85
	v_max_u32_e32 v86, v3, v0
	v_min_u32_e32 v0, v3, v0
	v_max_u32_e32 v65, v79, v81
	v_min_u32_e32 v79, v79, v81
	v_max_u32_e32 v81, v80, v90
	v_min_u32_e32 v80, v80, v90
	v_max_u32_e32 v90, v68, v74
	v_min_u32_e32 v68, v68, v74
	v_max_u32_e32 v74, v67, v66
	v_min_u32_e32 v66, v67, v66
	v_max_u32_e32 v67, v77, v64
	v_min_u32_e32 v64, v77, v64
	v_max_u32_e32 v77, v62, v63
	v_min_u32_e32 v62, v62, v63
	v_max_u32_e32 v63, v76, v69
	v_min_u32_e32 v69, v76, v69
	v_max_u32_e32 v76, v78, v75
	v_min_u32_e32 v75, v78, v75
	v_max_u32_e32 v3, v87, v89
	v_min_u32_e32 v87, v87, v89
	v_max_u32_e32 v89, v88, v98
	v_min_u32_e32 v88, v88, v98
	v_max_u32_e32 v98, v72, v82
	v_min_u32_e32 v72, v72, v82
	v_max_u32_e32 v82, v71, v70
	v_min_u32_e32 v70, v71, v70
	v_max_u32_e32 v71, v85, v2
	v_min_u32_e32 v2, v85, v2
	v_max_u32_e32 v85, v0, v1
	v_min_u32_e32 v0, v0, v1
	v_max_u32_e32 v1, v84, v73
	v_min_u32_e32 v73, v84, v73
	v_max_u32_e32 v84, v86, v83
	v_min_u32_e32 v83, v86, v83
	v_max_u32_e32 v78, v65, v81
	v_min_u32_e32 v65, v65, v81
	v_max_u32_e32 v81, v79, v80
	v_min_u32_e32 v79, v79, v80
	v_max_u32_e32 v80, v90, v74
	v_min_u32_e32 v74, v90, v74
	v_max_u32_e32 v90, v68, v66
	v_min_u32_e32 v66, v68, v66
	v_max_u32_e32 v68, v62, v64
	v_min_u32_e32 v62, v62, v64
	v_max_u32_e32 v64, v77, v67
	v_min_u32_e32 v67, v77, v67
	v_max_u32_e32 v77, v75, v69
	v_min_u32_e32 v69, v75, v69
	v_max_u32_e32 v75, v76, v63
	v_min_u32_e32 v63, v76, v63
	v_max_u32_e32 v86, v3, v89
	v_min_u32_e32 v3, v3, v89
	v_max_u32_e32 v89, v87, v88
	v_min_u32_e32 v87, v87, v88
	v_max_u32_e32 v88, v98, v82
	v_min_u32_e32 v82, v98, v82
	v_max_u32_e32 v98, v72, v70
	v_min_u32_e32 v70, v72, v70
	v_max_u32_e32 v72, v0, v2
	v_min_u32_e32 v0, v0, v2
	v_max_u32_e32 v2, v85, v71
	v_min_u32_e32 v71, v85, v71
	v_max_u32_e32 v85, v83, v73
	v_min_u32_e32 v73, v83, v73
	v_max_u32_e32 v83, v84, v1
	v_min_u32_e32 v1, v84, v1
	v_max_u32_e32 v76, v78, v62
	v_min_u32_e32 v62, v78, v62
	v_max_u32_e32 v78, v65, v68
	v_min_u32_e32 v65, v65, v68
	v_max_u32_e32 v68, v81, v67
	v_min_u32_e32 v67, v81, v67
	v_max_u32_e32 v81, v79, v64
	v_min_u32_e32 v64, v79, v64
	v_max_u32_e32 v79, v80, v69
	v_min_u32_e32 v69, v80, v69
	v_max_u32_e32 v80, v74, v77
	v_min_u32_e32 v74, v74, v77
	v_max_u32_e32 v77, v90, v63
	v_min_u32_e32 v63, v90, v63
	v_max_u32_e32 v90, v66, v75
	v_min_u32_e32 v66, v66, v75
	v_max_u32_e32 v84, v86, v0
	v_min_u32_e32 v0, v86, v0
	v_max_u32_e32 v86, v3, v72
	v_min_u32_e32 v3, v3, v72
	v_max_u32_e32 v72, v89, v71
	v_min_u32_e32 v71, v89, v71
	v_max_u32_e32 v89, v87, v2
	v_min_u32_e32 v2, v87, v2
	v_max_u32_e32 v87, v88, v73
	v_min_u32_e32 v73, v88, v73
	v_max_u32_e32 v88, v82, v85
	v_min_u32_e32 v82, v82, v85
	v_max_u32_e32 v85, v98, v1
	v_min_u32_e32 v1, v98, v1
	v_max_u32_e32 v98, v70, v83
	v_min_u32_e32 v70, v70, v83
	v_max_u32_e32 v75, v76, v79
	v_min_u32_e32 v76, v76, v79
	v_max_u32_e32 v79, v78, v80
	v_min_u32_e32 v78, v78, v80
	v_max_u32_e32 v80, v68, v77
	v_min_u32_e32 v68, v68, v77
	v_max_u32_e32 v77, v81, v90
	v_min_u32_e32 v81, v81, v90
	v_max_u32_e32 v90, v62, v69
	v_min_u32_e32 v62, v62, v69
	v_max_u32_e32 v69, v65, v74
	v_min_u32_e32 v65, v65, v74
	v_max_u32_e32 v74, v67, v63
; #define CE_DESC(a, b) do { const unsigned _mx = (a) > (b) ? (a) : (b), _mn = (a) > (b) ? (b) : (a); (a) = _mx; (b) = _mn; } while (0)
; __device__ __forceinline__ void sort16_desc(unsigned (&k)[16]) {
; #pragma unroll
;     for (int size = 2; size <= 16; size <<= 1)
; #pragma unroll
;         for (int stride = size >> 1; stride > 0; stride >>= 1)
; #pragma unroll
;             for (int i = 0; i < 16; ++i) { const int j = i ^ stride;
;                 if (j > i) { if ((i & size) == 0) CE_DESC(k[i], k[j]); else CE_DESC(k[j], k[i]); } }
; }
; __device__ __forceinline__ void merge16(unsigned (&a)[16], const unsigned (&b)[16]) {
; #pragma unroll
;     for (int i = 0; i < 16; ++i) a[i] = a[i] > b[15 - i] ? a[i] : b[15 - i];
; #pragma unroll
;     for (int stride = 8; stride > 0; stride >>= 1)
; #pragma unroll
;         for (int i = 0; i < 16; ++i) { const int j = i ^ stride; if (j > i) CE_DESC(a[i], a[j]); }
; }
; __device__ __forceinline__ void peer_tile(const Args& A, LAS unsigned char* lds, int tile) {
;     ...
;                 for (int msk = 16; msk <= 32; msk <<= 1) {
; #pragma unroll
;                     for (int i = 0; i < 16; ++i) k1[i] = (unsigned)__shfl_xor((int)k0[i], msk);
;                     merge16(k0, k1); }
	v_min_u32_e32 v63, v67, v63
	v_max_u32_e32 v67, v64, v66
	v_min_u32_e32 v64, v64, v66
	v_max_u32_e32 v83, v84, v87
	v_min_u32_e32 v84, v84, v87
	v_max_u32_e32 v87, v86, v88
	v_min_u32_e32 v86, v86, v88
	v_max_u32_e32 v88, v72, v85
	v_min_u32_e32 v72, v72, v85
	v_max_u32_e32 v85, v89, v98
	v_min_u32_e32 v89, v89, v98
	v_max_u32_e32 v98, v0, v73
	v_min_u32_e32 v0, v0, v73
	v_max_u32_e32 v73, v3, v82
	v_min_u32_e32 v3, v3, v82
	v_max_u32_e32 v82, v71, v1
	v_min_u32_e32 v1, v71, v1
	v_max_u32_e32 v71, v2, v70
	v_min_u32_e32 v2, v2, v70
	v_max_u32_e32 v66, v75, v80
	v_min_u32_e32 v75, v75, v80
	v_max_u32_e32 v80, v79, v77
	v_min_u32_e32 v77, v79, v77
	v_max_u32_e32 v79, v76, v68
	v_min_u32_e32 v68, v76, v68
	v_max_u32_e32 v76, v78, v81
	v_min_u32_e32 v78, v78, v81
	v_max_u32_e32 v81, v90, v74
	v_min_u32_e32 v74, v90, v74
	v_max_u32_e32 v90, v69, v67
	v_min_u32_e32 v67, v69, v67
	v_max_u32_e32 v69, v62, v63
	v_min_u32_e32 v62, v62, v63
	v_max_u32_e32 v63, v65, v64
	v_min_u32_e32 v64, v65, v64
	v_max_u32_e32 v70, v83, v88
	v_min_u32_e32 v83, v83, v88
	v_max_u32_e32 v88, v87, v85
	v_min_u32_e32 v85, v87, v85
	v_max_u32_e32 v87, v84, v72
	v_min_u32_e32 v72, v84, v72
	v_max_u32_e32 v84, v86, v89
	v_min_u32_e32 v86, v86, v89
	v_max_u32_e32 v89, v98, v82
	v_min_u32_e32 v82, v98, v82
	v_max_u32_e32 v98, v73, v71
	v_min_u32_e32 v71, v73, v71
	v_max_u32_e32 v73, v0, v1
	v_min_u32_e32 v0, v0, v1
	v_max_u32_e32 v1, v3, v2
	v_min_u32_e32 v2, v3, v2
	v_min_u32_e32 v65, v66, v80
	v_min_u32_e32 v91, v75, v77
	v_min_u32_e32 v92, v79, v76
	v_min_u32_e32 v93, v68, v78
	v_min_u32_e32 v94, v81, v90
	v_min_u32_e32 v95, v74, v67
	v_min_u32_e32 v96, v69, v63
	v_min_u32_e32 v97, v62, v64
	v_min_u32_e32 v3, v70, v88
	v_min_u32_e32 v99, v83, v85
	v_min_u32_e32 v100, v87, v84
	v_min_u32_e32 v101, v72, v86
	v_min_u32_e32 v102, v89, v98
	v_min_u32_e32 v103, v82, v71
	v_min_u32_e32 v104, v73, v1
	v_min_u32_e32 v105, v0, v2
	v_max3_u32 v66, v66, v80, v105
	v_max3_u32 v0, v65, v0, v2
	v_max3_u32 v2, v75, v77, v104
	v_max3_u32 v1, v91, v73, v1
	v_max3_u32 v65, v79, v76, v103
	v_max3_u32 v71, v92, v82, v71
	v_max3_u32 v68, v68, v78, v102
	v_max3_u32 v73, v93, v89, v98
	v_max3_u32 v75, v81, v90, v101
	v_max3_u32 v72, v94, v72, v86
	v_max3_u32 v67, v74, v67, v100
	v_max3_u32 v74, v95, v87, v84
	v_max3_u32 v63, v69, v63, v99
	v_max3_u32 v69, v96, v83, v85
	v_max3_u32 v3, v62, v64, v3
	v_max3_u32 v62, v97, v70, v88
	v_max_u32_e32 v64, v66, v75
	v_min_u32_e32 v66, v66, v75
	v_max_u32_e32 v70, v0, v72
	v_min_u32_e32 v0, v0, v72
	v_max_u32_e32 v72, v2, v67
	v_min_u32_e32 v2, v2, v67
	v_max_u32_e32 v67, v1, v74
	v_min_u32_e32 v1, v1, v74
	v_max_u32_e32 v74, v65, v63
	v_min_u32_e32 v63, v65, v63
	v_max_u32_e32 v65, v71, v69
	v_min_u32_e32 v69, v71, v69
	v_max_u32_e32 v71, v68, v3
	v_min_u32_e32 v3, v68, v3
	v_max_u32_e32 v68, v73, v62
	v_min_u32_e32 v62, v73, v62
	v_max_u32_e32 v73, v64, v74
	v_min_u32_e32 v64, v64, v74
	v_max_u32_e32 v74, v70, v65
	v_min_u32_e32 v65, v70, v65
	v_max_u32_e32 v70, v72, v71
	v_min_u32_e32 v71, v72, v71
	v_max_u32_e32 v72, v67, v68
	v_min_u32_e32 v67, v67, v68
	v_max_u32_e32 v68, v66, v63
	v_min_u32_e32 v63, v66, v63
	v_max_u32_e32 v66, v0, v69
	v_min_u32_e32 v0, v0, v69
	v_max_u32_e32 v69, v2, v3
	v_min_u32_e32 v2, v2, v3
	v_max_u32_e32 v3, v1, v62
	v_min_u32_e32 v1, v1, v62
	v_max_u32_e32 v62, v73, v70
	v_min_u32_e32 v70, v73, v70
	v_max_u32_e32 v73, v74, v72
	v_min_u32_e32 v72, v74, v72
	v_max_u32_e32 v74, v64, v71
	v_min_u32_e32 v64, v64, v71
	v_max_u32_e32 v71, v65, v67
	v_min_u32_e32 v65, v65, v67
	v_max_u32_e32 v67, v68, v69
	v_min_u32_e32 v68, v68, v69
	v_max_u32_e32 v69, v66, v3
	v_min_u32_e32 v3, v66, v3
	v_max_u32_e32 v66, v63, v2
	v_min_u32_e32 v2, v63, v2
	v_max_u32_e32 v63, v0, v1
	v_min_u32_e32 v0, v0, v1
	v_max_u32_e32 v1, v62, v73
	v_min_u32_e32 v62, v62, v73
	v_max_u32_e32 v73, v70, v72
	v_min_u32_e32 v70, v70, v72
	v_max_u32_e32 v72, v74, v71
	v_min_u32_e32 v71, v74, v71
	v_max_u32_e32 v74, v64, v65
	v_min_u32_e32 v64, v64, v65
	v_max_u32_e32 v65, v67, v69
	v_min_u32_e32 v67, v67, v69
	v_max_u32_e32 v69, v68, v3
	v_min_u32_e32 v3, v68, v3
	v_max_u32_e32 v68, v66, v63
	v_min_u32_e32 v63, v66, v63
	v_max_u32_e32 v66, v2, v0
	v_min_u32_e32 v0, v2, v0
	ds_bpermute_b32 v2, v27, v1
	ds_bpermute_b32 v75, v27, v62
	ds_bpermute_b32 v76, v27, v73
	ds_bpermute_b32 v77, v27, v70
	ds_bpermute_b32 v78, v27, v72
	ds_bpermute_b32 v79, v27, v71
	ds_bpermute_b32 v80, v27, v74
	ds_bpermute_b32 v81, v27, v64
	ds_bpermute_b32 v82, v27, v65
	ds_bpermute_b32 v83, v27, v67
	ds_bpermute_b32 v84, v27, v69
	ds_bpermute_b32 v85, v27, v0
	ds_bpermute_b32 v86, v27, v66
	ds_bpermute_b32 v87, v27, v63
	ds_bpermute_b32 v88, v27, v68
	ds_bpermute_b32 v89, v27, v3
	s_waitcnt lgkmcnt(4)
	v_max_u32_e32 v1, v1, v85
	s_waitcnt lgkmcnt(3)
	v_max_u32_e32 v62, v62, v86
	s_waitcnt lgkmcnt(2)
	v_max_u32_e32 v73, v73, v87
	s_waitcnt lgkmcnt(1)
	v_max_u32_e32 v70, v70, v88
	s_waitcnt lgkmcnt(0)
; #define CE_DESC(a, b) do { const unsigned _mx = (a) > (b) ? (a) : (b), _mn = (a) > (b) ? (b) : (a); (a) = _mx; (b) = _mn; } while (0)
; __device__ __forceinline__ void merge16(unsigned (&a)[16], const unsigned (&b)[16]) {
; #pragma unroll
;     for (int i = 0; i < 16; ++i) a[i] = a[i] > b[15 - i] ? a[i] : b[15 - i];
; #pragma unroll
;     for (int stride = 8; stride > 0; stride >>= 1)
; #pragma unroll
;         for (int i = 0; i < 16; ++i) { const int j = i ^ stride; if (j > i) CE_DESC(a[i], a[j]); }
; }
; __device__ __forceinline__ void peer_tile(const Args& A, LAS unsigned char* lds, int tile) {
;     ...
;                 { const bf16_t* sp = QRY + m * 2048 + hp * 128 + 32 * g;
;                   const u32x4 s0 = *(const u32x4*)sp, s1 = *(const u32x4*)(sp + 8), s2 = *(const u32x4*)(sp + 16), s3 = *(const u32x4*)(sp + 24);
;     ...
;                 for (int msk = 16; msk <= 32; msk <<= 1) {
; #pragma unroll
;                     for (int i = 0; i < 16; ++i) k1[i] = (unsigned)__shfl_xor((int)k0[i], msk);
;                     merge16(k0, k1); }
	v_max_u32_e32 v72, v72, v89
	v_max_u32_e32 v71, v71, v84
	v_max_u32_e32 v74, v74, v83
	v_max_u32_e32 v64, v64, v82
	v_max_u32_e32 v65, v65, v81
	v_max_u32_e32 v67, v67, v80
	v_max_u32_e32 v69, v69, v79
	v_max_u32_e32 v3, v3, v78
	v_max_u32_e32 v68, v68, v77
	v_max_u32_e32 v63, v63, v76
	v_max_u32_e32 v66, v66, v75
	v_max_u32_e32 v0, v0, v2
	v_max_u32_e32 v2, v1, v65
	v_min_u32_e32 v1, v1, v65
	v_max_u32_e32 v65, v62, v67
	v_min_u32_e32 v62, v62, v67
	v_max_u32_e32 v67, v73, v69
	v_min_u32_e32 v69, v73, v69
	v_max_u32_e32 v73, v70, v3
	v_min_u32_e32 v3, v70, v3
	v_max_u32_e32 v70, v72, v68
	v_min_u32_e32 v68, v72, v68
	v_max_u32_e32 v72, v71, v63
	v_min_u32_e32 v63, v71, v63
	v_max_u32_e32 v71, v74, v66
	v_min_u32_e32 v66, v74, v66
	v_max_u32_e32 v74, v64, v0
	v_min_u32_e32 v0, v64, v0
	v_max_u32_e32 v64, v2, v70
	v_min_u32_e32 v2, v2, v70
	v_max_u32_e32 v70, v65, v72
	v_min_u32_e32 v65, v65, v72
	v_max_u32_e32 v72, v67, v71
	v_min_u32_e32 v67, v67, v71
	v_max_u32_e32 v71, v73, v74
	v_min_u32_e32 v73, v73, v74
	v_max_u32_e32 v74, v1, v68
	v_min_u32_e32 v1, v1, v68
	v_max_u32_e32 v68, v62, v63
	v_min_u32_e32 v62, v62, v63
	v_max_u32_e32 v63, v69, v66
	v_min_u32_e32 v66, v69, v66
	v_max_u32_e32 v69, v3, v0
	v_min_u32_e32 v0, v3, v0
	v_max_u32_e32 v3, v64, v72
	v_min_u32_e32 v64, v64, v72
	v_max_u32_e32 v72, v70, v71
	v_min_u32_e32 v70, v70, v71
	v_max_u32_e32 v71, v2, v67
	v_min_u32_e32 v2, v2, v67
	v_max_u32_e32 v67, v65, v73
	v_min_u32_e32 v65, v65, v73
	v_max_u32_e32 v73, v74, v63
	v_min_u32_e32 v63, v74, v63
	v_max_u32_e32 v74, v68, v69
	v_min_u32_e32 v68, v68, v69
	v_max_u32_e32 v69, v1, v66
	v_min_u32_e32 v1, v1, v66
	v_max_u32_e32 v66, v62, v0
	v_min_u32_e32 v0, v62, v0
	v_max_u32_e32 v62, v3, v72
	v_min_u32_e32 v3, v3, v72
	v_max_u32_e32 v72, v64, v70
	v_min_u32_e32 v64, v64, v70
	v_max_u32_e32 v70, v71, v67
	v_min_u32_e32 v67, v71, v67
	v_max_u32_e32 v71, v2, v65
	v_min_u32_e32 v2, v2, v65
	v_max_u32_e32 v65, v73, v74
	v_min_u32_e32 v73, v73, v74
	v_max_u32_e32 v74, v63, v68
	v_min_u32_e32 v63, v63, v68
	v_max_u32_e32 v68, v69, v66
	v_min_u32_e32 v66, v69, v66
	v_max_u32_e32 v69, v1, v0
	v_min_u32_e32 v0, v1, v0
	ds_bpermute_b32 v78, v29, v0
	ds_bpermute_b32 v1, v29, v62
	ds_bpermute_b32 v75, v29, v3
	ds_bpermute_b32 v76, v29, v72
	ds_bpermute_b32 v77, v29, v64
	s_waitcnt lgkmcnt(4)
	v_max_u32_e32 v62, v62, v78
	global_load_dwordx4 v[78:81], v[4:5], off offset:784
	global_load_dwordx4 v[82:85], v[4:5], off offset:768
	ds_bpermute_b32 v86, v29, v70
	ds_bpermute_b32 v87, v29, v67
	ds_bpermute_b32 v88, v29, v71
	ds_bpermute_b32 v89, v29, v2
	ds_bpermute_b32 v90, v29, v65
	ds_bpermute_b32 v91, v29, v73
	ds_bpermute_b32 v92, v29, v74
	ds_bpermute_b32 v93, v29, v63
	ds_bpermute_b32 v94, v29, v68
	ds_bpermute_b32 v95, v29, v69
	ds_bpermute_b32 v96, v29, v66
	s_waitcnt lgkmcnt(4)
	v_max_u32_e32 v67, v67, v92
	s_waitcnt lgkmcnt(3)
	v_max_u32_e32 v70, v70, v93
	s_waitcnt lgkmcnt(2)
	v_max_u32_e32 v64, v64, v94
	s_waitcnt lgkmcnt(1)
	v_max_u32_e32 v3, v3, v95
	s_waitcnt lgkmcnt(0)
	v_max_u32_e32 v72, v72, v96
	v_max_u32_e32 v71, v71, v91
	v_max_u32_e32 v2, v2, v90
	v_max_u32_e32 v65, v65, v89
	v_max_u32_e32 v73, v73, v88
	v_max_u32_e32 v74, v74, v87
	v_max_u32_e32 v63, v63, v86
	v_max_u32_e32 v68, v68, v77
	v_max_u32_e32 v66, v66, v76
	v_max_u32_e32 v69, v69, v75
	v_max_u32_e32 v0, v0, v1
	v_max_u32_e32 v1, v62, v65
	v_min_u32_e32 v62, v62, v65
	v_max_u32_e32 v65, v3, v73
	v_min_u32_e32 v3, v3, v73
	v_max_u32_e32 v73, v72, v74
	v_min_u32_e32 v72, v72, v74
	v_max_u32_e32 v74, v64, v63
	v_min_u32_e32 v63, v64, v63
	v_max_u32_e32 v64, v70, v68
	v_min_u32_e32 v68, v70, v68
	v_max_u32_e32 v70, v67, v66
	v_min_u32_e32 v66, v67, v66
	v_max_u32_e32 v67, v71, v69
	v_min_u32_e32 v69, v71, v69
	v_max_u32_e32 v71, v2, v0
	v_min_u32_e32 v0, v2, v0
	v_max_u32_e32 v2, v1, v64
	v_min_u32_e32 v1, v1, v64
	v_max_u32_e32 v64, v65, v70
	v_min_u32_e32 v65, v65, v70
	v_max_u32_e32 v70, v73, v67
	v_min_u32_e32 v67, v73, v67
	v_max_u32_e32 v73, v74, v71
	v_min_u32_e32 v71, v74, v71
	v_max_u32_e32 v74, v62, v68
	v_min_u32_e32 v62, v62, v68
	v_max_u32_e32 v68, v3, v66
	v_min_u32_e32 v3, v3, v66
	v_max_u32_e32 v66, v72, v69
	v_min_u32_e32 v69, v72, v69
	v_max_u32_e32 v72, v63, v0
	v_min_u32_e32 v0, v63, v0
	v_max_u32_e32 v63, v2, v70
	v_min_u32_e32 v2, v2, v70
	v_max_u32_e32 v70, v64, v73
	v_min_u32_e32 v64, v64, v73
	v_max_u32_e32 v86, v1, v67
	v_min_u32_e32 v1, v1, v67
	v_max_u32_e32 v67, v65, v71
	v_min_u32_e32 v65, v65, v71
	v_max_u32_e32 v87, v74, v66
	v_min_u32_e32 v66, v74, v66
	v_max_u32_e32 v88, v68, v72
	v_min_u32_e32 v89, v68, v72
	v_max_u32_e32 v90, v62, v69
	v_min_u32_e32 v62, v62, v69
	v_max_u32_e32 v91, v3, v0
	v_min_u32_e32 v0, v3, v0
	v_max_u32_e32 v77, v63, v70
	v_min_u32_e32 v76, v63, v70
	v_max_u32_e32 v75, v2, v64
	v_min_u32_e32 v74, v2, v64
	v_max_u32_e32 v73, v86, v67
	v_min_u32_e32 v72, v86, v67
	v_max_u32_e32 v71, v1, v65
	v_min_u32_e32 v70, v1, v65
	v_max_u32_e32 v69, v87, v88
	v_min_u32_e32 v68, v87, v88
	v_max_u32_e32 v67, v66, v89
	v_min_u32_e32 v66, v66, v89
	v_max_u32_e32 v63, v62, v0
	v_min_u32_e32 v62, v62, v0
	global_load_dwordx4 v[0:3], v[4:5], off offset:816
	global_load_dwordx4 v[86:89], v[4:5], off offset:800
	v_max_u32_e32 v65, v90, v91
	v_min_u32_e32 v64, v90, v91
	s_waitcnt vmcnt(2)
; __device__ __forceinline__ unsigned f2key(float f) { const unsigned u = __float_as_uint(f); return (u & 0x80000000u) ? ~u : (u | 0x80000000u); }
; __device__ __forceinline__ void peer_tile(const Args& A, LAS unsigned char* lds, int tile) {
;     ...
;                 { const bf16_t* sp = QRY + m * 2048 + hp * 128 + 32 * g;
;                   const u32x4 s0 = *(const u32x4*)sp, s1 = *(const u32x4*)(sp + 8), s2 = *(const u32x4*)(sp + 16), s3 = *(const u32x4*)(sp + 24);
;                   const unsigned sw[16] = {s0.x, s0.y, s0.z, s0.w, s1.x, s1.y, s1.z, s1.w, s2.x, s2.y, s2.z, s2.w, s3.x, s3.y, s3.z, s3.w};
; #pragma unroll
;                   for (int i = 0; i < 16; ++i) {
;                       const float lo = (float)__builtin_bit_cast(_Float16, (unsigned short)(sw[i] & 0xffffu)), hi = (float)__builtin_bit_cast(_Float16, (unsigned short)(sw[i] >> 16));
;                       const unsigned klo = (f2key(lo) & ~127u) | (unsigned)(127 - (32 * g + 2 * i)), khi = (f2key(hi) & ~127u) | (unsigned)(127 - (32 * g + 2 * i + 1));
;                       if (i < 8) { k0[2 * i] = klo; k0[2 * i + 1] = khi; } else { k1[2 * (i - 8)] = klo; k1[2 * (i - 8) + 1] = khi; } } }
;     ...
;                 for (int i = 0; i < 16; ++i) L2[p][i] = (g & 2) ? ((g & 1) ? LA[3][p][i] : LA[2][p][i]) : ((g & 1) ? LA[1][p][i] : LA[0][p][i]);
	v_cvt_f32_f16_sdwa v90, v82 dst_sel:DWORD dst_unused:UNUSED_PAD src0_sel:WORD_1
	v_cvt_f32_f16_e32 v82, v82
	v_cndmask_b32_e64 v38, v70, v38, s[0:1]
	v_cndmask_b32_e64 v37, v69, v37, s[0:1]
	v_not_b32_e32 v91, v90
	v_or_b32_e32 v92, 0x80000000, v90
	v_cmp_gt_i32_e32 vcc, 0, v90
	v_cndmask_b32_e64 v36, v68, v36, s[0:1]
	v_cndmask_b32_e64 v35, v67, v35, s[0:1]
	v_cndmask_b32_e32 v90, v92, v91, vcc
	v_not_b32_e32 v91, v82
	v_or_b32_e32 v92, 0x80000000, v82
	v_cmp_gt_i32_e32 vcc, 0, v82
	v_and_b32_e32 v90, 0xffffff80, v90
	v_sub_u32_e32 v90, v90, v15
	v_cndmask_b32_e32 v82, v92, v91, vcc
	v_cvt_f32_f16_sdwa v91, v83 dst_sel:DWORD dst_unused:UNUSED_PAD src0_sel:WORD_1
	v_cvt_f32_f16_e32 v83, v83
	v_and_b32_e32 v82, 0xffffff80, v82
	v_sub_u32_e32 v82, v82, v15
	v_not_b32_e32 v92, v91
	v_or_b32_e32 v93, 0x80000000, v91
	v_cmp_gt_i32_e32 vcc, 0, v91
	v_add_u32_e32 v90, 0x7e, v90
	v_add_u32_e32 v82, 0x7f, v82
	v_cndmask_b32_e32 v91, v93, v92, vcc
	v_not_b32_e32 v92, v83
	v_or_b32_e32 v93, 0x80000000, v83
	v_cmp_gt_i32_e32 vcc, 0, v83
	v_and_b32_e32 v91, 0xffffff80, v91
	v_sub_u32_e32 v91, v91, v14
	v_cndmask_b32_e32 v83, v93, v92, vcc
	v_cvt_f32_f16_sdwa v92, v84 dst_sel:DWORD dst_unused:UNUSED_PAD src0_sel:WORD_1
	v_cvt_f32_f16_e32 v84, v84
	v_and_b32_e32 v83, 0xffffff80, v83
	v_sub_u32_e32 v83, v83, v14
	v_not_b32_e32 v93, v92
	v_or_b32_e32 v94, 0x80000000, v92
	v_cmp_gt_i32_e32 vcc, 0, v92
	v_add_u32_e32 v91, 0x7e, v91
	v_add_u32_e32 v83, 0x7f, v83
	v_cndmask_b32_e32 v92, v94, v93, vcc
	v_not_b32_e32 v93, v84
	v_or_b32_e32 v94, 0x80000000, v84
	v_cmp_gt_i32_e32 vcc, 0, v84
	v_and_b32_e32 v92, 0xffffff80, v92
	v_sub_u32_e32 v92, v92, v12
	v_cndmask_b32_e32 v84, v94, v93, vcc
	v_cvt_f32_f16_sdwa v93, v85 dst_sel:DWORD dst_unused:UNUSED_PAD src0_sel:WORD_1
	v_cvt_f32_f16_e32 v85, v85
	v_and_b32_e32 v84, 0xffffff80, v84
	v_sub_u32_e32 v84, v84, v12
	v_not_b32_e32 v94, v93
	v_or_b32_e32 v95, 0x80000000, v93
	v_cmp_gt_i32_e32 vcc, 0, v93
	v_add_u32_e32 v92, 0x7e, v92
	v_add_u32_e32 v84, 0x7f, v84
	v_cndmask_b32_e32 v93, v95, v94, vcc
	v_not_b32_e32 v94, v85
	v_or_b32_e32 v95, 0x80000000, v85
	v_cmp_gt_i32_e32 vcc, 0, v85
	v_and_b32_e32 v93, 0xffffff80, v93
	v_sub_u32_e32 v93, v93, v10
	v_cndmask_b32_e32 v85, v95, v94, vcc
	v_cvt_f32_f16_sdwa v94, v78 dst_sel:DWORD dst_unused:UNUSED_PAD src0_sel:WORD_1
	v_cvt_f32_f16_e32 v78, v78
	v_and_b32_e32 v85, 0xffffff80, v85
	v_sub_u32_e32 v85, v85, v10
	v_not_b32_e32 v95, v94
	v_or_b32_e32 v96, 0x80000000, v94
	v_cmp_gt_i32_e32 vcc, 0, v94
	v_add_u32_e32 v93, 0x7e, v93
	v_add_u32_e32 v85, 0x7f, v85
	v_cndmask_b32_e32 v94, v96, v95, vcc
	v_not_b32_e32 v95, v78
	v_or_b32_e32 v96, 0x80000000, v78
	v_cmp_gt_i32_e32 vcc, 0, v78
	v_and_b32_e32 v94, 0xffffff80, v94
	v_sub_u32_e32 v94, v94, v8
	v_cndmask_b32_e32 v78, v96, v95, vcc
	v_cvt_f32_f16_sdwa v95, v79 dst_sel:DWORD dst_unused:UNUSED_PAD src0_sel:WORD_1
	v_cvt_f32_f16_e32 v79, v79
	v_and_b32_e32 v78, 0xffffff80, v78
	v_sub_u32_e32 v78, v78, v8
	v_not_b32_e32 v96, v95
	v_or_b32_e32 v97, 0x80000000, v95
	v_cmp_gt_i32_e32 vcc, 0, v95
	v_add_u32_e32 v94, 0x7e, v94
	v_add_u32_e32 v78, 0x7f, v78
	v_cndmask_b32_e32 v95, v97, v96, vcc
	v_not_b32_e32 v96, v79
	v_or_b32_e32 v97, 0x80000000, v79
	v_cmp_gt_i32_e32 vcc, 0, v79
	v_and_b32_e32 v95, 0xffffff80, v95
	v_sub_u32_e32 v95, v95, v16
	v_cndmask_b32_e32 v79, v97, v96, vcc
	v_cvt_f32_f16_sdwa v96, v80 dst_sel:DWORD dst_unused:UNUSED_PAD src0_sel:WORD_1
	v_cvt_f32_f16_e32 v80, v80
	v_and_b32_e32 v79, 0xffffff80, v79
	v_sub_u32_e32 v79, v79, v16
	v_not_b32_e32 v97, v96
	v_or_b32_e32 v98, 0x80000000, v96
	v_cmp_gt_i32_e32 vcc, 0, v96
	v_add_u32_e32 v95, 0x7e, v95
	v_add_u32_e32 v79, 0x7f, v79
	v_cndmask_b32_e32 v96, v98, v97, vcc
	v_not_b32_e32 v97, v80
	v_or_b32_e32 v98, 0x80000000, v80
	v_cmp_gt_i32_e32 vcc, 0, v80
	v_and_b32_e32 v96, 0xffffff80, v96
	v_sub_u32_e32 v96, v96, v17
	v_cndmask_b32_e32 v80, v98, v97, vcc
	v_cvt_f32_f16_sdwa v97, v81 dst_sel:DWORD dst_unused:UNUSED_PAD src0_sel:WORD_1
	v_cvt_f32_f16_e32 v81, v81
	v_and_b32_e32 v80, 0xffffff80, v80
	v_sub_u32_e32 v80, v80, v17
	v_not_b32_e32 v98, v97
	v_or_b32_e32 v99, 0x80000000, v97
	v_cmp_gt_i32_e32 vcc, 0, v97
	v_add_u32_e32 v96, 0x7e, v96
	v_add_u32_e32 v80, 0x7f, v80
	v_cndmask_b32_e32 v97, v99, v98, vcc
	v_not_b32_e32 v98, v81
	v_or_b32_e32 v99, 0x80000000, v81
	v_cmp_gt_i32_e32 vcc, 0, v81
	v_and_b32_e32 v97, 0xffffff80, v97
	v_sub_u32_e32 v97, v97, v18
	v_cndmask_b32_e32 v81, v99, v98, vcc
	s_waitcnt vmcnt(0)
; __device__ __forceinline__ unsigned f2key(float f) { const unsigned u = __float_as_uint(f); return (u & 0x80000000u) ? ~u : (u | 0x80000000u); }
; #define CE_DESC(a, b) do { const unsigned _mx = (a) > (b) ? (a) : (b), _mn = (a) > (b) ? (b) : (a); (a) = _mx; (b) = _mn; } while (0)
; __device__ __forceinline__ void sort16_desc(unsigned (&k)[16]) {
; #pragma unroll
;     for (int size = 2; size <= 16; size <<= 1)
; #pragma unroll
;         for (int stride = size >> 1; stride > 0; stride >>= 1)
; #pragma unroll
;             for (int i = 0; i < 16; ++i) { const int j = i ^ stride;
;                 if (j > i) { if ((i & size) == 0) CE_DESC(k[i], k[j]); else CE_DESC(k[j], k[i]); } }
; }
; __device__ __forceinline__ void peer_tile(const Args& A, LAS unsigned char* lds, int tile) {
;     ...
;                   for (int i = 0; i < 16; ++i) {
;                       const float lo = (float)__builtin_bit_cast(_Float16, (unsigned short)(sw[i] & 0xffffu)), hi = (float)__builtin_bit_cast(_Float16, (unsigned short)(sw[i] >> 16));
;                       const unsigned klo = (f2key(lo) & ~127u) | (unsigned)(127 - (32 * g + 2 * i)), khi = (f2key(hi) & ~127u) | (unsigned)(127 - (32 * g + 2 * i + 1));
;                       if (i < 8) { k0[2 * i] = klo; k0[2 * i + 1] = khi; } else { k1[2 * (i - 8)] = klo; k1[2 * (i - 8) + 1] = khi; } } }
	v_cvt_f32_f16_sdwa v98, v86 dst_sel:DWORD dst_unused:UNUSED_PAD src0_sel:WORD_1
	v_cvt_f32_f16_e32 v86, v86
	v_and_b32_e32 v81, 0xffffff80, v81
	v_sub_u32_e32 v81, v81, v18
	v_not_b32_e32 v99, v98
	v_or_b32_e32 v100, 0x80000000, v98
	v_cmp_gt_i32_e32 vcc, 0, v98
	v_add_u32_e32 v97, 0x7e, v97
	v_add_u32_e32 v81, 0x7f, v81
	v_cndmask_b32_e32 v98, v100, v99, vcc
	v_not_b32_e32 v99, v86
	v_or_b32_e32 v100, 0x80000000, v86
	v_cmp_gt_i32_e32 vcc, 0, v86
	v_and_b32_e32 v98, 0xffffff80, v98
	v_sub_u32_e32 v98, v98, v20
	v_cndmask_b32_e32 v86, v100, v99, vcc
	v_cvt_f32_f16_sdwa v99, v87 dst_sel:DWORD dst_unused:UNUSED_PAD src0_sel:WORD_1
	v_cvt_f32_f16_e32 v87, v87
	v_and_b32_e32 v86, 0xffffff80, v86
	v_sub_u32_e32 v86, v86, v20
	v_not_b32_e32 v100, v99
	v_or_b32_e32 v101, 0x80000000, v99
	v_cmp_gt_i32_e32 vcc, 0, v99
	v_add_u32_e32 v98, 0x7e, v98
	v_add_u32_e32 v86, 0x7f, v86
	v_cndmask_b32_e32 v99, v101, v100, vcc
	v_not_b32_e32 v100, v87
	v_or_b32_e32 v101, 0x80000000, v87
	v_cmp_gt_i32_e32 vcc, 0, v87
	v_and_b32_e32 v99, 0xffffff80, v99
	v_sub_u32_e32 v99, v99, v21
	v_cndmask_b32_e32 v87, v101, v100, vcc
	v_cvt_f32_f16_sdwa v100, v88 dst_sel:DWORD dst_unused:UNUSED_PAD src0_sel:WORD_1
	v_cvt_f32_f16_e32 v88, v88
	v_and_b32_e32 v87, 0xffffff80, v87
	v_sub_u32_e32 v87, v87, v21
	v_not_b32_e32 v101, v100
	v_or_b32_e32 v102, 0x80000000, v100
	v_cmp_gt_i32_e32 vcc, 0, v100
	v_add_u32_e32 v99, 0x7e, v99
	v_add_u32_e32 v87, 0x7f, v87
	v_cndmask_b32_e32 v100, v102, v101, vcc
	v_not_b32_e32 v101, v88
	v_or_b32_e32 v102, 0x80000000, v88
	v_cmp_gt_i32_e32 vcc, 0, v88
	v_and_b32_e32 v100, 0xffffff80, v100
	v_sub_u32_e32 v100, v100, v22
	v_cndmask_b32_e32 v88, v102, v101, vcc
	v_cvt_f32_f16_sdwa v101, v89 dst_sel:DWORD dst_unused:UNUSED_PAD src0_sel:WORD_1
	v_cvt_f32_f16_e32 v89, v89
	v_and_b32_e32 v88, 0xffffff80, v88
	v_sub_u32_e32 v88, v88, v22
	v_not_b32_e32 v102, v101
	v_or_b32_e32 v103, 0x80000000, v101
	v_cmp_gt_i32_e32 vcc, 0, v101
	v_add_u32_e32 v100, 0x7e, v100
	v_add_u32_e32 v88, 0x7f, v88
	v_cndmask_b32_e32 v101, v103, v102, vcc
	v_not_b32_e32 v102, v89
	v_or_b32_e32 v103, 0x80000000, v89
	v_cmp_gt_i32_e32 vcc, 0, v89
	v_and_b32_e32 v101, 0xffffff80, v101
	v_sub_u32_e32 v101, v101, v23
	v_cndmask_b32_e32 v89, v103, v102, vcc
	v_cvt_f32_f16_sdwa v102, v0 dst_sel:DWORD dst_unused:UNUSED_PAD src0_sel:WORD_1
	v_cvt_f32_f16_e32 v0, v0
	v_and_b32_e32 v89, 0xffffff80, v89
	v_sub_u32_e32 v89, v89, v23
	v_not_b32_e32 v103, v102
	v_or_b32_e32 v104, 0x80000000, v102
	v_cmp_gt_i32_e32 vcc, 0, v102
	v_add_u32_e32 v101, 0x7e, v101
	v_add_u32_e32 v89, 0x7f, v89
	v_cndmask_b32_e32 v102, v104, v103, vcc
	v_not_b32_e32 v103, v0
	v_or_b32_e32 v104, 0x80000000, v0
	v_cmp_gt_i32_e32 vcc, 0, v0
	v_and_b32_e32 v102, 0xffffff80, v102
	v_sub_u32_e32 v102, v102, v24
	v_cndmask_b32_e32 v0, v104, v103, vcc
	v_cvt_f32_f16_sdwa v103, v1 dst_sel:DWORD dst_unused:UNUSED_PAD src0_sel:WORD_1
	v_cvt_f32_f16_e32 v1, v1
	v_and_b32_e32 v0, 0xffffff80, v0
	v_sub_u32_e32 v0, v0, v24
	v_not_b32_e32 v104, v103
	v_or_b32_e32 v105, 0x80000000, v103
	v_cmp_gt_i32_e32 vcc, 0, v103
	v_add_u32_e32 v102, 0x7e, v102
	v_add_u32_e32 v0, 0x7f, v0
	v_cndmask_b32_e32 v103, v105, v104, vcc
	v_not_b32_e32 v104, v1
	v_or_b32_e32 v105, 0x80000000, v1
	v_cmp_gt_i32_e32 vcc, 0, v1
	v_and_b32_e32 v103, 0xffffff80, v103
	v_sub_u32_e32 v103, v103, v25
	v_cndmask_b32_e32 v1, v105, v104, vcc
	v_cvt_f32_f16_sdwa v104, v2 dst_sel:DWORD dst_unused:UNUSED_PAD src0_sel:WORD_1
	v_cvt_f32_f16_e32 v2, v2
	v_and_b32_e32 v1, 0xffffff80, v1
	v_sub_u32_e32 v1, v1, v25
	v_not_b32_e32 v105, v104
	v_or_b32_e32 v106, 0x80000000, v104
	v_cmp_gt_i32_e32 vcc, 0, v104
	v_add_u32_e32 v103, 0x7e, v103
	v_add_u32_e32 v1, 0x7f, v1
	v_cndmask_b32_e32 v104, v106, v105, vcc
	v_not_b32_e32 v105, v2
	v_or_b32_e32 v106, 0x80000000, v2
	v_cmp_gt_i32_e32 vcc, 0, v2
	v_and_b32_e32 v104, 0xffffff80, v104
	v_sub_u32_e32 v104, v104, v26
	v_cndmask_b32_e32 v2, v106, v105, vcc
	v_cvt_f32_f16_sdwa v105, v3 dst_sel:DWORD dst_unused:UNUSED_PAD src0_sel:WORD_1
	v_cvt_f32_f16_e32 v3, v3
	v_and_b32_e32 v2, 0xffffff80, v2
	v_sub_u32_e32 v2, v2, v26
	v_not_b32_e32 v106, v105
	v_or_b32_e32 v107, 0x80000000, v105
	v_cmp_gt_i32_e32 vcc, 0, v105
	v_add_u32_e32 v104, 0x7e, v104
	v_add_u32_e32 v2, 0x7f, v2
	v_cndmask_b32_e32 v105, v107, v106, vcc
	v_not_b32_e32 v106, v3
	v_or_b32_e32 v107, 0x80000000, v3
	v_cmp_gt_i32_e32 vcc, 0, v3
	v_and_b32_e32 v105, 0xffffff80, v105
	v_sub_u32_e32 v105, v105, v28
	v_cndmask_b32_e32 v3, v107, v106, vcc
	v_and_b32_e32 v3, 0xffffff80, v3
	v_sub_u32_e32 v3, v3, v28
	v_add_u32_e32 v105, 0x7e, v105
	v_add_u32_e32 v3, 0x7f, v3
	v_max_u32_e32 v106, v82, v90
	v_min_u32_e32 v82, v82, v90
	v_max_u32_e32 v90, v91, v83
	v_min_u32_e32 v83, v91, v83
	v_max_u32_e32 v91, v84, v92
	v_min_u32_e32 v84, v84, v92
	v_max_u32_e32 v92, v93, v85
	v_min_u32_e32 v85, v93, v85
	v_max_u32_e32 v93, v78, v94
	v_min_u32_e32 v78, v78, v94
	v_max_u32_e32 v94, v95, v79
	v_min_u32_e32 v79, v95, v79
	v_max_u32_e32 v95, v80, v96
	v_min_u32_e32 v80, v80, v96
	v_max_u32_e32 v96, v97, v81
	v_min_u32_e32 v81, v97, v81
	v_max_u32_e32 v115, v86, v98
	v_min_u32_e32 v86, v86, v98
	v_max_u32_e32 v98, v99, v87
	v_min_u32_e32 v87, v99, v87
	v_max_u32_e32 v99, v88, v100
	v_min_u32_e32 v88, v88, v100
	v_max_u32_e32 v100, v101, v89
	v_min_u32_e32 v89, v101, v89
	v_max_u32_e32 v101, v0, v102
	v_min_u32_e32 v0, v0, v102
	v_max_u32_e32 v102, v103, v1
	v_min_u32_e32 v1, v103, v1
	v_max_u32_e32 v103, v2, v104
	v_min_u32_e32 v2, v2, v104
	v_max_u32_e32 v104, v105, v3
	v_min_u32_e32 v3, v105, v3
	v_max_u32_e32 v97, v106, v83
	v_min_u32_e32 v83, v106, v83
	v_max_u32_e32 v106, v82, v90
; #define CE_DESC(a, b) do { const unsigned _mx = (a) > (b) ? (a) : (b), _mn = (a) > (b) ? (b) : (a); (a) = _mx; (b) = _mn; } while (0)
; __device__ __forceinline__ void sort16_desc(unsigned (&k)[16]) {
; #pragma unroll
;     for (int size = 2; size <= 16; size <<= 1)
; #pragma unroll
;         for (int stride = size >> 1; stride > 0; stride >>= 1)
; #pragma unroll
;             for (int i = 0; i < 16; ++i) { const int j = i ^ stride;
;                 if (j > i) { if ((i & size) == 0) CE_DESC(k[i], k[j]); else CE_DESC(k[j], k[i]); } }
; }
	v_min_u32_e32 v82, v82, v90
	v_max_u32_e32 v90, v85, v91
	v_min_u32_e32 v85, v85, v91
	v_max_u32_e32 v91, v92, v84
	v_min_u32_e32 v84, v92, v84
	v_max_u32_e32 v92, v93, v79
	v_min_u32_e32 v79, v93, v79
	v_max_u32_e32 v93, v78, v94
	v_min_u32_e32 v78, v78, v94
	v_max_u32_e32 v94, v81, v95
	v_min_u32_e32 v81, v81, v95
	v_max_u32_e32 v95, v96, v80
	v_min_u32_e32 v80, v96, v80
	v_max_u32_e32 v105, v115, v87
	v_min_u32_e32 v87, v115, v87
	v_max_u32_e32 v115, v86, v98
	v_min_u32_e32 v86, v86, v98
	v_max_u32_e32 v98, v89, v99
	v_min_u32_e32 v89, v89, v99
	v_max_u32_e32 v99, v100, v88
	v_min_u32_e32 v88, v100, v88
	v_max_u32_e32 v100, v101, v1
	v_min_u32_e32 v1, v101, v1
	v_max_u32_e32 v101, v0, v102
	v_min_u32_e32 v0, v0, v102
	v_max_u32_e32 v102, v3, v103
	v_min_u32_e32 v3, v3, v103
	v_max_u32_e32 v103, v104, v2
	v_min_u32_e32 v2, v104, v2
	v_max_u32_e32 v96, v97, v106
	v_min_u32_e32 v97, v97, v106
	v_max_u32_e32 v106, v83, v82
	v_min_u32_e32 v82, v83, v82
	v_max_u32_e32 v83, v84, v85
	v_min_u32_e32 v84, v84, v85
	v_max_u32_e32 v85, v91, v90
	v_min_u32_e32 v90, v91, v90
	v_max_u32_e32 v91, v92, v93
	v_min_u32_e32 v92, v92, v93
	v_max_u32_e32 v93, v79, v78
	v_min_u32_e32 v78, v79, v78
	v_max_u32_e32 v79, v80, v81
	v_min_u32_e32 v80, v80, v81
	v_max_u32_e32 v81, v95, v94
	v_min_u32_e32 v94, v95, v94
	v_max_u32_e32 v104, v105, v115
	v_min_u32_e32 v105, v105, v115
	v_max_u32_e32 v115, v87, v86
	v_min_u32_e32 v86, v87, v86
	v_max_u32_e32 v87, v88, v89
	v_min_u32_e32 v88, v88, v89
	v_max_u32_e32 v89, v99, v98
	v_min_u32_e32 v98, v99, v98
	v_max_u32_e32 v99, v100, v101
	v_min_u32_e32 v100, v100, v101
	v_max_u32_e32 v101, v1, v0
	v_min_u32_e32 v0, v1, v0
	v_max_u32_e32 v1, v2, v3
	v_min_u32_e32 v2, v2, v3
	v_max_u32_e32 v3, v103, v102
	v_min_u32_e32 v102, v103, v102
	v_max_u32_e32 v95, v96, v84
	v_min_u32_e32 v84, v96, v84
	v_max_u32_e32 v96, v97, v83
	v_min_u32_e32 v83, v97, v83
	v_max_u32_e32 v97, v106, v90
	v_min_u32_e32 v90, v106, v90
	v_max_u32_e32 v106, v82, v85
	v_min_u32_e32 v82, v82, v85
	v_max_u32_e32 v85, v80, v91
	v_min_u32_e32 v80, v80, v91
	v_max_u32_e32 v91, v79, v92
	v_min_u32_e32 v79, v79, v92
	v_max_u32_e32 v92, v94, v93
	v_min_u32_e32 v93, v94, v93
	v_max_u32_e32 v94, v81, v78
	v_min_u32_e32 v78, v81, v78
	v_max_u32_e32 v103, v104, v88
	v_min_u32_e32 v88, v104, v88
	v_max_u32_e32 v104, v105, v87
	v_min_u32_e32 v87, v105, v87
	v_max_u32_e32 v105, v115, v98
	v_min_u32_e32 v98, v115, v98
	v_max_u32_e32 v115, v86, v89
	v_min_u32_e32 v86, v86, v89
	v_max_u32_e32 v89, v2, v99
	v_min_u32_e32 v2, v2, v99
	v_max_u32_e32 v99, v1, v100
	v_min_u32_e32 v1, v1, v100
	v_max_u32_e32 v100, v102, v101
	v_min_u32_e32 v101, v102, v101
	v_max_u32_e32 v102, v3, v0
	v_min_u32_e32 v0, v3, v0
	v_max_u32_e32 v81, v95, v97
	v_min_u32_e32 v95, v95, v97
	v_max_u32_e32 v97, v96, v106
	v_min_u32_e32 v96, v96, v106
	v_max_u32_e32 v106, v84, v90
	v_min_u32_e32 v84, v84, v90
	v_max_u32_e32 v90, v83, v82
	v_min_u32_e32 v82, v83, v82
	v_max_u32_e32 v83, v93, v80
	v_min_u32_e32 v80, v93, v80
	v_max_u32_e32 v93, v78, v79
	v_min_u32_e32 v78, v78, v79
	v_max_u32_e32 v79, v92, v85
	v_min_u32_e32 v85, v92, v85
	v_max_u32_e32 v92, v94, v91
	v_min_u32_e32 v91, v94, v91
	v_max_u32_e32 v3, v103, v105
	v_min_u32_e32 v103, v103, v105
	v_max_u32_e32 v105, v104, v115
	v_min_u32_e32 v104, v104, v115
	v_max_u32_e32 v115, v88, v98
	v_min_u32_e32 v88, v88, v98
	v_max_u32_e32 v98, v87, v86
	v_min_u32_e32 v86, v87, v86
	v_max_u32_e32 v87, v101, v2
	v_min_u32_e32 v2, v101, v2
	v_max_u32_e32 v101, v0, v1
	v_min_u32_e32 v0, v0, v1
	v_max_u32_e32 v1, v100, v89
	v_min_u32_e32 v89, v100, v89
	v_max_u32_e32 v100, v102, v99
	v_min_u32_e32 v99, v102, v99
	v_max_u32_e32 v94, v81, v97
	v_min_u32_e32 v81, v81, v97
	v_max_u32_e32 v97, v95, v96
	v_min_u32_e32 v95, v95, v96
	v_max_u32_e32 v96, v106, v90
	v_min_u32_e32 v90, v106, v90
	v_max_u32_e32 v106, v84, v82
	v_min_u32_e32 v82, v84, v82
	v_max_u32_e32 v84, v78, v80
	v_min_u32_e32 v78, v78, v80
	v_max_u32_e32 v80, v93, v83
	v_min_u32_e32 v83, v93, v83
	v_max_u32_e32 v93, v91, v85
	v_min_u32_e32 v85, v91, v85
	v_max_u32_e32 v91, v92, v79
	v_min_u32_e32 v79, v92, v79
	v_max_u32_e32 v102, v3, v105
	v_min_u32_e32 v3, v3, v105
	v_max_u32_e32 v105, v103, v104
	v_min_u32_e32 v103, v103, v104
	v_max_u32_e32 v104, v115, v98
	v_min_u32_e32 v98, v115, v98
	v_max_u32_e32 v115, v88, v86
	v_min_u32_e32 v86, v88, v86
	v_max_u32_e32 v88, v0, v2
	v_min_u32_e32 v0, v0, v2
	v_max_u32_e32 v2, v101, v87
	v_min_u32_e32 v87, v101, v87
	v_max_u32_e32 v101, v99, v89
	v_min_u32_e32 v89, v99, v89
	v_max_u32_e32 v99, v100, v1
	v_min_u32_e32 v1, v100, v1
	v_max_u32_e32 v92, v94, v78
	v_min_u32_e32 v78, v94, v78
	v_max_u32_e32 v94, v81, v84
	v_min_u32_e32 v81, v81, v84
	v_max_u32_e32 v84, v97, v83
	v_min_u32_e32 v83, v97, v83
	v_max_u32_e32 v97, v95, v80
	v_min_u32_e32 v80, v95, v80
	v_max_u32_e32 v95, v96, v85
	v_min_u32_e32 v85, v96, v85
	v_max_u32_e32 v96, v90, v93
	v_min_u32_e32 v90, v90, v93
	v_max_u32_e32 v93, v106, v79
	v_min_u32_e32 v79, v106, v79
	v_max_u32_e32 v106, v82, v91
	v_min_u32_e32 v82, v82, v91
	v_max_u32_e32 v100, v102, v0
	v_min_u32_e32 v0, v102, v0
	v_max_u32_e32 v102, v3, v88
	v_min_u32_e32 v3, v3, v88
	v_max_u32_e32 v88, v105, v87
	v_min_u32_e32 v87, v105, v87
	v_max_u32_e32 v105, v103, v2
	v_min_u32_e32 v2, v103, v2
	v_max_u32_e32 v103, v104, v89
	v_min_u32_e32 v89, v104, v89
	v_max_u32_e32 v104, v98, v101
	v_min_u32_e32 v98, v98, v101
	v_max_u32_e32 v101, v115, v1
	v_min_u32_e32 v1, v115, v1
	v_max_u32_e32 v115, v86, v99
	v_min_u32_e32 v86, v86, v99
	v_max_u32_e32 v91, v92, v95
	v_min_u32_e32 v92, v92, v95
	v_max_u32_e32 v95, v94, v96
; #define CE_DESC(a, b) do { const unsigned _mx = (a) > (b) ? (a) : (b), _mn = (a) > (b) ? (b) : (a); (a) = _mx; (b) = _mn; } while (0)
; __device__ __forceinline__ void sort16_desc(unsigned (&k)[16]) {
; #pragma unroll
;     for (int size = 2; size <= 16; size <<= 1)
; #pragma unroll
;         for (int stride = size >> 1; stride > 0; stride >>= 1)
; #pragma unroll
;             for (int i = 0; i < 16; ++i) { const int j = i ^ stride;
;                 if (j > i) { if ((i & size) == 0) CE_DESC(k[i], k[j]); else CE_DESC(k[j], k[i]); } }
; }
; __device__ __forceinline__ void merge16(unsigned (&a)[16], const unsigned (&b)[16]) {
; #pragma unroll
;     for (int i = 0; i < 16; ++i) a[i] = a[i] > b[15 - i] ? a[i] : b[15 - i];
; #pragma unroll
;     for (int stride = 8; stride > 0; stride >>= 1)
; #pragma unroll
;         for (int i = 0; i < 16; ++i) { const int j = i ^ stride; if (j > i) CE_DESC(a[i], a[j]); }
; }
; __device__ __forceinline__ void peer_tile(const Args& A, LAS unsigned char* lds, int tile) {
;     ...
;                 for (int msk = 16; msk <= 32; msk <<= 1) {
; #pragma unroll
;                     for (int i = 0; i < 16; ++i) k1[i] = (unsigned)__shfl_xor((int)k0[i], msk);
;                     merge16(k0, k1); }
	v_min_u32_e32 v94, v94, v96
	v_max_u32_e32 v96, v84, v93
	v_min_u32_e32 v84, v84, v93
	v_max_u32_e32 v93, v97, v106
	v_min_u32_e32 v97, v97, v106
	v_max_u32_e32 v106, v78, v85
	v_min_u32_e32 v78, v78, v85
	v_max_u32_e32 v85, v81, v90
	v_min_u32_e32 v81, v81, v90
	v_max_u32_e32 v90, v83, v79
	v_min_u32_e32 v79, v83, v79
	v_max_u32_e32 v83, v80, v82
	v_min_u32_e32 v80, v80, v82
	v_max_u32_e32 v99, v100, v103
	v_min_u32_e32 v100, v100, v103
	v_max_u32_e32 v103, v102, v104
	v_min_u32_e32 v102, v102, v104
	v_max_u32_e32 v104, v88, v101
	v_min_u32_e32 v88, v88, v101
	v_max_u32_e32 v101, v105, v115
	v_min_u32_e32 v105, v105, v115
	v_max_u32_e32 v115, v0, v89
	v_min_u32_e32 v0, v0, v89
	v_max_u32_e32 v89, v3, v98
	v_min_u32_e32 v3, v3, v98
	v_max_u32_e32 v98, v87, v1
	v_min_u32_e32 v1, v87, v1
	v_max_u32_e32 v87, v2, v86
	v_min_u32_e32 v2, v2, v86
	v_max_u32_e32 v82, v91, v96
	v_min_u32_e32 v91, v91, v96
	v_max_u32_e32 v96, v95, v93
	v_min_u32_e32 v93, v95, v93
	v_max_u32_e32 v95, v92, v84
	v_min_u32_e32 v84, v92, v84
	v_max_u32_e32 v92, v94, v97
	v_min_u32_e32 v94, v94, v97
	v_max_u32_e32 v97, v106, v90
	v_min_u32_e32 v90, v106, v90
	v_max_u32_e32 v106, v85, v83
	v_min_u32_e32 v83, v85, v83
	v_max_u32_e32 v85, v78, v79
	v_min_u32_e32 v78, v78, v79
	v_max_u32_e32 v79, v81, v80
	v_min_u32_e32 v80, v81, v80
	v_max_u32_e32 v86, v99, v104
	v_min_u32_e32 v99, v99, v104
	v_max_u32_e32 v104, v103, v101
	v_min_u32_e32 v101, v103, v101
	v_max_u32_e32 v103, v100, v88
	v_min_u32_e32 v88, v100, v88
	v_max_u32_e32 v100, v102, v105
	v_min_u32_e32 v102, v102, v105
	v_max_u32_e32 v105, v115, v98
	v_min_u32_e32 v98, v115, v98
	v_max_u32_e32 v115, v89, v87
	v_min_u32_e32 v87, v89, v87
	v_max_u32_e32 v89, v0, v1
	v_min_u32_e32 v0, v0, v1
	v_max_u32_e32 v1, v3, v2
	v_min_u32_e32 v2, v3, v2
	v_min_u32_e32 v81, v82, v96
	v_min_u32_e32 v107, v91, v93
	v_min_u32_e32 v108, v95, v92
	v_min_u32_e32 v109, v84, v94
	v_min_u32_e32 v110, v97, v106
	v_min_u32_e32 v111, v90, v83
	v_min_u32_e32 v112, v85, v79
	v_min_u32_e32 v114, v78, v80
	v_min_u32_e32 v3, v86, v104
	v_min_u32_e32 v116, v99, v101
	v_min_u32_e32 v117, v103, v100
	v_min_u32_e32 v118, v88, v102
	v_min_u32_e32 v119, v105, v115
	v_min_u32_e32 v120, v98, v87
	v_min_u32_e32 v121, v89, v1
	v_min_u32_e32 v122, v0, v2
	v_max3_u32 v82, v82, v96, v122
	v_max3_u32 v0, v81, v0, v2
	v_max3_u32 v2, v91, v93, v121
	v_max3_u32 v1, v107, v89, v1
	v_max3_u32 v81, v95, v92, v120
	v_max3_u32 v87, v108, v98, v87
	v_max3_u32 v84, v84, v94, v119
	v_max3_u32 v89, v109, v105, v115
	v_max3_u32 v91, v97, v106, v118
	v_max3_u32 v88, v110, v88, v102
	v_max3_u32 v83, v90, v83, v117
	v_max3_u32 v90, v111, v103, v100
	v_max3_u32 v79, v85, v79, v116
	v_max3_u32 v85, v112, v99, v101
	v_max3_u32 v3, v78, v80, v3
	v_max3_u32 v78, v114, v86, v104
	v_max_u32_e32 v80, v82, v91
	v_min_u32_e32 v82, v82, v91
	v_max_u32_e32 v86, v0, v88
	v_min_u32_e32 v0, v0, v88
	v_max_u32_e32 v88, v2, v83
	v_min_u32_e32 v2, v2, v83
	v_max_u32_e32 v83, v1, v90
	v_min_u32_e32 v1, v1, v90
	v_max_u32_e32 v90, v81, v79
	v_min_u32_e32 v79, v81, v79
	v_max_u32_e32 v81, v87, v85
	v_min_u32_e32 v85, v87, v85
	v_max_u32_e32 v87, v84, v3
	v_min_u32_e32 v3, v84, v3
	v_max_u32_e32 v84, v89, v78
	v_min_u32_e32 v78, v89, v78
	v_max_u32_e32 v89, v80, v90
	v_min_u32_e32 v80, v80, v90
	v_max_u32_e32 v90, v86, v81
	v_min_u32_e32 v81, v86, v81
	v_max_u32_e32 v86, v88, v87
	v_min_u32_e32 v87, v88, v87
	v_max_u32_e32 v88, v83, v84
	v_min_u32_e32 v83, v83, v84
	v_max_u32_e32 v84, v82, v79
	v_min_u32_e32 v79, v82, v79
	v_max_u32_e32 v82, v0, v85
	v_min_u32_e32 v0, v0, v85
	v_max_u32_e32 v85, v2, v3
	v_min_u32_e32 v2, v2, v3
	v_max_u32_e32 v3, v1, v78
	v_min_u32_e32 v1, v1, v78
	v_max_u32_e32 v78, v89, v86
	v_min_u32_e32 v86, v89, v86
	v_max_u32_e32 v89, v90, v88
	v_min_u32_e32 v88, v90, v88
	v_max_u32_e32 v90, v80, v87
	v_min_u32_e32 v80, v80, v87
	v_max_u32_e32 v87, v81, v83
	v_min_u32_e32 v81, v81, v83
	v_max_u32_e32 v83, v84, v85
	v_min_u32_e32 v84, v84, v85
	v_max_u32_e32 v85, v82, v3
	v_min_u32_e32 v3, v82, v3
	v_max_u32_e32 v82, v79, v2
	v_min_u32_e32 v2, v79, v2
	v_max_u32_e32 v79, v0, v1
	v_min_u32_e32 v0, v0, v1
	v_max_u32_e32 v1, v78, v89
	v_min_u32_e32 v78, v78, v89
	v_max_u32_e32 v89, v86, v88
	v_min_u32_e32 v86, v86, v88
	v_max_u32_e32 v88, v90, v87
	v_min_u32_e32 v87, v90, v87
	v_max_u32_e32 v90, v80, v81
	v_min_u32_e32 v80, v80, v81
	v_max_u32_e32 v81, v83, v85
	v_min_u32_e32 v83, v83, v85
	v_max_u32_e32 v85, v84, v3
	v_min_u32_e32 v3, v84, v3
	v_max_u32_e32 v84, v82, v79
	v_min_u32_e32 v79, v82, v79
	v_max_u32_e32 v82, v2, v0
	v_min_u32_e32 v0, v2, v0
	ds_bpermute_b32 v2, v27, v1
	ds_bpermute_b32 v91, v27, v78
	ds_bpermute_b32 v92, v27, v89
	ds_bpermute_b32 v93, v27, v86
	ds_bpermute_b32 v94, v27, v88
	ds_bpermute_b32 v95, v27, v87
	ds_bpermute_b32 v96, v27, v90
	ds_bpermute_b32 v97, v27, v80
	ds_bpermute_b32 v98, v27, v81
	ds_bpermute_b32 v99, v27, v83
	ds_bpermute_b32 v100, v27, v85
	ds_bpermute_b32 v101, v27, v0
	ds_bpermute_b32 v102, v27, v82
	ds_bpermute_b32 v103, v27, v79
	ds_bpermute_b32 v104, v27, v84
	ds_bpermute_b32 v105, v27, v3
	s_waitcnt lgkmcnt(4)
	v_max_u32_e32 v1, v1, v101
	s_waitcnt lgkmcnt(3)
	v_max_u32_e32 v78, v78, v102
	s_waitcnt lgkmcnt(2)
	v_max_u32_e32 v89, v89, v103
	s_waitcnt lgkmcnt(1)
	v_max_u32_e32 v86, v86, v104
	s_waitcnt lgkmcnt(0)
; #define CE_DESC(a, b) do { const unsigned _mx = (a) > (b) ? (a) : (b), _mn = (a) > (b) ? (b) : (a); (a) = _mx; (b) = _mn; } while (0)
; __device__ __forceinline__ void merge16(unsigned (&a)[16], const unsigned (&b)[16]) {
; #pragma unroll
;     for (int i = 0; i < 16; ++i) a[i] = a[i] > b[15 - i] ? a[i] : b[15 - i];
; #pragma unroll
;     for (int stride = 8; stride > 0; stride >>= 1)
; #pragma unroll
;         for (int i = 0; i < 16; ++i) { const int j = i ^ stride; if (j > i) CE_DESC(a[i], a[j]); }
; }
; __device__ __forceinline__ void peer_tile(const Args& A, LAS unsigned char* lds, int tile) {
;     ...
;                 { const bf16_t* sp = QRY + m * 2048 + hp * 128 + 32 * g;
;                   const u32x4 s0 = *(const u32x4*)sp, s1 = *(const u32x4*)(sp + 8), s2 = *(const u32x4*)(sp + 16), s3 = *(const u32x4*)(sp + 24);
;     ...
;                 for (int msk = 16; msk <= 32; msk <<= 1) {
; #pragma unroll
;                     for (int i = 0; i < 16; ++i) k1[i] = (unsigned)__shfl_xor((int)k0[i], msk);
;                     merge16(k0, k1); }
	v_max_u32_e32 v88, v88, v105
	v_max_u32_e32 v87, v87, v100
	v_max_u32_e32 v90, v90, v99
	v_max_u32_e32 v80, v80, v98
	v_max_u32_e32 v81, v81, v97
	v_max_u32_e32 v83, v83, v96
	v_max_u32_e32 v85, v85, v95
	v_max_u32_e32 v3, v3, v94
	v_max_u32_e32 v84, v84, v93
	v_max_u32_e32 v79, v79, v92
	v_max_u32_e32 v82, v82, v91
	v_max_u32_e32 v0, v0, v2
	v_max_u32_e32 v2, v1, v81
	v_min_u32_e32 v1, v1, v81
	v_max_u32_e32 v81, v78, v83
	v_min_u32_e32 v78, v78, v83
	v_max_u32_e32 v83, v89, v85
	v_min_u32_e32 v85, v89, v85
	v_max_u32_e32 v89, v86, v3
	v_min_u32_e32 v3, v86, v3
	v_max_u32_e32 v86, v88, v84
	v_min_u32_e32 v84, v88, v84
	v_max_u32_e32 v88, v87, v79
	v_min_u32_e32 v79, v87, v79
	v_max_u32_e32 v87, v90, v82
	v_min_u32_e32 v82, v90, v82
	v_max_u32_e32 v90, v80, v0
	v_min_u32_e32 v0, v80, v0
	v_max_u32_e32 v80, v2, v86
	v_min_u32_e32 v2, v2, v86
	v_max_u32_e32 v86, v81, v88
	v_min_u32_e32 v81, v81, v88
	v_max_u32_e32 v88, v83, v87
	v_min_u32_e32 v83, v83, v87
	v_max_u32_e32 v87, v89, v90
	v_min_u32_e32 v89, v89, v90
	v_max_u32_e32 v90, v1, v84
	v_min_u32_e32 v1, v1, v84
	v_max_u32_e32 v84, v78, v79
	v_min_u32_e32 v78, v78, v79
	v_max_u32_e32 v79, v85, v82
	v_min_u32_e32 v82, v85, v82
	v_max_u32_e32 v85, v3, v0
	v_min_u32_e32 v0, v3, v0
	v_max_u32_e32 v3, v80, v88
	v_min_u32_e32 v80, v80, v88
	v_max_u32_e32 v88, v86, v87
	v_min_u32_e32 v86, v86, v87
	v_max_u32_e32 v87, v2, v83
	v_min_u32_e32 v2, v2, v83
	v_max_u32_e32 v83, v81, v89
	v_min_u32_e32 v81, v81, v89
	v_max_u32_e32 v89, v90, v79
	v_min_u32_e32 v79, v90, v79
	v_max_u32_e32 v90, v84, v85
	v_min_u32_e32 v84, v84, v85
	v_max_u32_e32 v85, v1, v82
	v_min_u32_e32 v1, v1, v82
	v_max_u32_e32 v82, v78, v0
	v_min_u32_e32 v0, v78, v0
	v_max_u32_e32 v78, v3, v88
	v_min_u32_e32 v3, v3, v88
	v_max_u32_e32 v88, v80, v86
	v_min_u32_e32 v80, v80, v86
	v_max_u32_e32 v86, v87, v83
	v_min_u32_e32 v83, v87, v83
	v_max_u32_e32 v87, v2, v81
	v_min_u32_e32 v2, v2, v81
	v_max_u32_e32 v81, v89, v90
	v_min_u32_e32 v89, v89, v90
	v_max_u32_e32 v90, v79, v84
	v_min_u32_e32 v79, v79, v84
	v_max_u32_e32 v84, v85, v82
	v_min_u32_e32 v82, v85, v82
	v_max_u32_e32 v85, v1, v0
	v_min_u32_e32 v0, v1, v0
	ds_bpermute_b32 v94, v29, v0
	ds_bpermute_b32 v1, v29, v78
	ds_bpermute_b32 v91, v29, v3
	ds_bpermute_b32 v92, v29, v88
	ds_bpermute_b32 v93, v29, v80
	s_waitcnt lgkmcnt(4)
	v_max_u32_e32 v78, v78, v94
	global_load_dwordx4 v[94:97], v[4:5], off offset:1040
	global_load_dwordx4 v[98:101], v[4:5], off offset:1024
	ds_bpermute_b32 v102, v29, v86
	ds_bpermute_b32 v103, v29, v83
	ds_bpermute_b32 v104, v29, v87
	ds_bpermute_b32 v105, v29, v2
	ds_bpermute_b32 v106, v29, v81
	ds_bpermute_b32 v107, v29, v89
	ds_bpermute_b32 v108, v29, v90
	ds_bpermute_b32 v109, v29, v79
	ds_bpermute_b32 v110, v29, v84
	ds_bpermute_b32 v111, v29, v85
	ds_bpermute_b32 v112, v29, v82
	s_waitcnt lgkmcnt(4)
	v_max_u32_e32 v83, v83, v108
	s_waitcnt lgkmcnt(3)
	v_max_u32_e32 v86, v86, v109
	s_waitcnt lgkmcnt(2)
	v_max_u32_e32 v80, v80, v110
	s_waitcnt lgkmcnt(1)
	v_max_u32_e32 v3, v3, v111
	s_waitcnt lgkmcnt(0)
	v_max_u32_e32 v88, v88, v112
	v_max_u32_e32 v87, v87, v107
	v_max_u32_e32 v2, v2, v106
	v_max_u32_e32 v81, v81, v105
	v_max_u32_e32 v89, v89, v104
	v_max_u32_e32 v90, v90, v103
	v_max_u32_e32 v79, v79, v102
	v_max_u32_e32 v84, v84, v93
	v_max_u32_e32 v82, v82, v92
	v_max_u32_e32 v85, v85, v91
	v_max_u32_e32 v0, v0, v1
	v_max_u32_e32 v1, v78, v81
	v_min_u32_e32 v78, v78, v81
	v_max_u32_e32 v81, v3, v89
	v_min_u32_e32 v3, v3, v89
	v_max_u32_e32 v89, v88, v90
	v_min_u32_e32 v88, v88, v90
	v_max_u32_e32 v90, v80, v79
	v_min_u32_e32 v79, v80, v79
	v_max_u32_e32 v80, v86, v84
	v_min_u32_e32 v84, v86, v84
	v_max_u32_e32 v86, v83, v82
	v_min_u32_e32 v82, v83, v82
	v_max_u32_e32 v83, v87, v85
	v_min_u32_e32 v85, v87, v85
	v_max_u32_e32 v87, v2, v0
	v_min_u32_e32 v0, v2, v0
	v_max_u32_e32 v2, v1, v80
	v_min_u32_e32 v1, v1, v80
	v_max_u32_e32 v80, v81, v86
	v_min_u32_e32 v81, v81, v86
	v_max_u32_e32 v86, v89, v83
	v_min_u32_e32 v83, v89, v83
	v_max_u32_e32 v89, v90, v87
	v_min_u32_e32 v87, v90, v87
	v_max_u32_e32 v90, v78, v84
	v_min_u32_e32 v78, v78, v84
	v_max_u32_e32 v84, v3, v82
	v_min_u32_e32 v3, v3, v82
	v_max_u32_e32 v82, v88, v85
	v_min_u32_e32 v85, v88, v85
	v_max_u32_e32 v88, v79, v0
	v_min_u32_e32 v0, v79, v0
	v_max_u32_e32 v79, v2, v86
	v_min_u32_e32 v2, v2, v86
	v_max_u32_e32 v86, v80, v89
	v_min_u32_e32 v80, v80, v89
	v_max_u32_e32 v102, v1, v83
	v_min_u32_e32 v1, v1, v83
	v_max_u32_e32 v83, v81, v87
	v_min_u32_e32 v81, v81, v87
	v_max_u32_e32 v103, v90, v82
	v_min_u32_e32 v82, v90, v82
	v_max_u32_e32 v104, v84, v88
	v_min_u32_e32 v105, v84, v88
	v_max_u32_e32 v106, v78, v85
	v_min_u32_e32 v78, v78, v85
	v_max_u32_e32 v107, v3, v0
	v_min_u32_e32 v0, v3, v0
	v_max_u32_e32 v93, v79, v86
	v_min_u32_e32 v92, v79, v86
	v_max_u32_e32 v91, v2, v80
	v_min_u32_e32 v90, v2, v80
	v_max_u32_e32 v89, v102, v83
	v_min_u32_e32 v88, v102, v83
	v_max_u32_e32 v87, v1, v81
	v_min_u32_e32 v86, v1, v81
	v_max_u32_e32 v85, v103, v104
	v_min_u32_e32 v84, v103, v104
	v_max_u32_e32 v83, v82, v105
	v_min_u32_e32 v82, v82, v105
	v_max_u32_e32 v79, v78, v0
	v_min_u32_e32 v78, v78, v0
	global_load_dwordx4 v[0:3], v[4:5], off offset:1072
	global_load_dwordx4 v[102:105], v[4:5], off offset:1056
	v_max_u32_e32 v81, v106, v107
	v_min_u32_e32 v80, v106, v107
	s_waitcnt vmcnt(2)
; __device__ __forceinline__ unsigned f2key(float f) { const unsigned u = __float_as_uint(f); return (u & 0x80000000u) ? ~u : (u | 0x80000000u); }
; __device__ __forceinline__ void peer_tile(const Args& A, LAS unsigned char* lds, int tile) {
;     ...
;                 { const bf16_t* sp = QRY + m * 2048 + hp * 128 + 32 * g;
;                   const u32x4 s0 = *(const u32x4*)sp, s1 = *(const u32x4*)(sp + 8), s2 = *(const u32x4*)(sp + 16), s3 = *(const u32x4*)(sp + 24);
;                   const unsigned sw[16] = {s0.x, s0.y, s0.z, s0.w, s1.x, s1.y, s1.z, s1.w, s2.x, s2.y, s2.z, s2.w, s3.x, s3.y, s3.z, s3.w};
; #pragma unroll
;                   for (int i = 0; i < 16; ++i) {
;                       const float lo = (float)__builtin_bit_cast(_Float16, (unsigned short)(sw[i] & 0xffffu)), hi = (float)__builtin_bit_cast(_Float16, (unsigned short)(sw[i] >> 16));
;                       const unsigned klo = (f2key(lo) & ~127u) | (unsigned)(127 - (32 * g + 2 * i)), khi = (f2key(hi) & ~127u) | (unsigned)(127 - (32 * g + 2 * i + 1));
;                       if (i < 8) { k0[2 * i] = klo; k0[2 * i + 1] = khi; } else { k1[2 * (i - 8)] = klo; k1[2 * (i - 8) + 1] = khi; } } }
;     ...
;                 for (int i = 0; i < 16; ++i) L2[p][i] = (g & 2) ? ((g & 1) ? LA[3][p][i] : LA[2][p][i]) : ((g & 1) ? LA[1][p][i] : LA[0][p][i]);
	v_cvt_f32_f16_sdwa v106, v98 dst_sel:DWORD dst_unused:UNUSED_PAD src0_sel:WORD_1
	v_cvt_f32_f16_e32 v98, v98
	v_cndmask_b32_e64 v34, v66, v34, s[0:1]
	v_cndmask_b32_e64 v33, v65, v33, s[0:1]
	v_not_b32_e32 v107, v106
	v_or_b32_e32 v108, 0x80000000, v106
	v_cmp_gt_i32_e32 vcc, 0, v106
	v_cndmask_b32_e64 v32, v64, v32, s[0:1]
	v_cndmask_b32_e64 v31, v63, v31, s[0:1]
	v_cndmask_b32_e32 v106, v108, v107, vcc
	v_not_b32_e32 v107, v98
	v_or_b32_e32 v108, 0x80000000, v98
	v_cmp_gt_i32_e32 vcc, 0, v98
	v_and_b32_e32 v106, 0xffffff80, v106
	v_sub_u32_e32 v106, v106, v15
	v_cndmask_b32_e32 v98, v108, v107, vcc
	v_cvt_f32_f16_sdwa v107, v99 dst_sel:DWORD dst_unused:UNUSED_PAD src0_sel:WORD_1
	v_cvt_f32_f16_e32 v99, v99
	v_and_b32_e32 v98, 0xffffff80, v98
	v_sub_u32_e32 v98, v98, v15
	v_not_b32_e32 v108, v107
	v_or_b32_e32 v109, 0x80000000, v107
	v_cmp_gt_i32_e32 vcc, 0, v107
	v_add_u32_e32 v106, 0x7e, v106
	v_add_u32_e32 v98, 0x7f, v98
	v_cndmask_b32_e32 v107, v109, v108, vcc
	v_not_b32_e32 v108, v99
	v_or_b32_e32 v109, 0x80000000, v99
	v_cmp_gt_i32_e32 vcc, 0, v99
	v_and_b32_e32 v107, 0xffffff80, v107
	v_sub_u32_e32 v107, v107, v14
	v_cndmask_b32_e32 v99, v109, v108, vcc
	v_cvt_f32_f16_sdwa v108, v100 dst_sel:DWORD dst_unused:UNUSED_PAD src0_sel:WORD_1
	v_cvt_f32_f16_e32 v100, v100
	v_and_b32_e32 v99, 0xffffff80, v99
	v_sub_u32_e32 v99, v99, v14
	v_not_b32_e32 v109, v108
	v_or_b32_e32 v110, 0x80000000, v108
	v_cmp_gt_i32_e32 vcc, 0, v108
	v_add_u32_e32 v107, 0x7e, v107
	v_add_u32_e32 v99, 0x7f, v99
	v_cndmask_b32_e32 v108, v110, v109, vcc
	v_not_b32_e32 v109, v100
	v_or_b32_e32 v110, 0x80000000, v100
	v_cmp_gt_i32_e32 vcc, 0, v100
	v_and_b32_e32 v108, 0xffffff80, v108
	v_sub_u32_e32 v108, v108, v12
	v_cndmask_b32_e32 v100, v110, v109, vcc
	v_cvt_f32_f16_sdwa v109, v101 dst_sel:DWORD dst_unused:UNUSED_PAD src0_sel:WORD_1
	v_cvt_f32_f16_e32 v101, v101
	v_and_b32_e32 v100, 0xffffff80, v100
	v_sub_u32_e32 v100, v100, v12
	v_not_b32_e32 v110, v109
	v_or_b32_e32 v111, 0x80000000, v109
	v_cmp_gt_i32_e32 vcc, 0, v109
	v_add_u32_e32 v108, 0x7e, v108
	v_add_u32_e32 v100, 0x7f, v100
	v_cndmask_b32_e32 v109, v111, v110, vcc
	v_not_b32_e32 v110, v101
	v_or_b32_e32 v111, 0x80000000, v101
	v_cmp_gt_i32_e32 vcc, 0, v101
	v_and_b32_e32 v109, 0xffffff80, v109
	v_sub_u32_e32 v109, v109, v10
	v_cndmask_b32_e32 v101, v111, v110, vcc
	v_cvt_f32_f16_sdwa v110, v94 dst_sel:DWORD dst_unused:UNUSED_PAD src0_sel:WORD_1
	v_cvt_f32_f16_e32 v94, v94
	v_and_b32_e32 v101, 0xffffff80, v101
	v_sub_u32_e32 v101, v101, v10
	v_not_b32_e32 v111, v110
	v_or_b32_e32 v112, 0x80000000, v110
	v_cmp_gt_i32_e32 vcc, 0, v110
	v_add_u32_e32 v109, 0x7e, v109
	v_add_u32_e32 v101, 0x7f, v101
	v_cndmask_b32_e32 v110, v112, v111, vcc
	v_not_b32_e32 v111, v94
	v_or_b32_e32 v112, 0x80000000, v94
	v_cmp_gt_i32_e32 vcc, 0, v94
	v_and_b32_e32 v110, 0xffffff80, v110
	v_sub_u32_e32 v110, v110, v8
	v_cndmask_b32_e32 v94, v112, v111, vcc
	v_cvt_f32_f16_sdwa v111, v95 dst_sel:DWORD dst_unused:UNUSED_PAD src0_sel:WORD_1
	v_cvt_f32_f16_e32 v95, v95
	v_and_b32_e32 v94, 0xffffff80, v94
	v_sub_u32_e32 v94, v94, v8
	v_not_b32_e32 v112, v111
	v_or_b32_e32 v114, 0x80000000, v111
	v_cmp_gt_i32_e32 vcc, 0, v111
	v_add_u32_e32 v110, 0x7e, v110
	v_add_u32_e32 v94, 0x7f, v94
	v_cndmask_b32_e32 v111, v114, v112, vcc
	v_not_b32_e32 v112, v95
	v_or_b32_e32 v114, 0x80000000, v95
	v_cmp_gt_i32_e32 vcc, 0, v95
	v_and_b32_e32 v111, 0xffffff80, v111
	v_sub_u32_e32 v111, v111, v16
	v_cndmask_b32_e32 v95, v114, v112, vcc
	v_cvt_f32_f16_sdwa v112, v96 dst_sel:DWORD dst_unused:UNUSED_PAD src0_sel:WORD_1
	v_cvt_f32_f16_e32 v96, v96
	v_and_b32_e32 v95, 0xffffff80, v95
	v_sub_u32_e32 v95, v95, v16
	v_not_b32_e32 v114, v112
	v_or_b32_e32 v115, 0x80000000, v112
	v_cmp_gt_i32_e32 vcc, 0, v112
	v_add_u32_e32 v111, 0x7e, v111
	v_add_u32_e32 v95, 0x7f, v95
	v_cndmask_b32_e32 v112, v115, v114, vcc
	v_not_b32_e32 v114, v96
	v_or_b32_e32 v115, 0x80000000, v96
	v_cmp_gt_i32_e32 vcc, 0, v96
	v_and_b32_e32 v112, 0xffffff80, v112
	v_sub_u32_e32 v112, v112, v17
	v_cndmask_b32_e32 v96, v115, v114, vcc
	v_cvt_f32_f16_sdwa v114, v97 dst_sel:DWORD dst_unused:UNUSED_PAD src0_sel:WORD_1
	v_cvt_f32_f16_e32 v97, v97
	v_and_b32_e32 v96, 0xffffff80, v96
	v_sub_u32_e32 v96, v96, v17
	v_not_b32_e32 v115, v114
	v_or_b32_e32 v116, 0x80000000, v114
	v_cmp_gt_i32_e32 vcc, 0, v114
	v_add_u32_e32 v112, 0x7e, v112
	v_add_u32_e32 v96, 0x7f, v96
	v_cndmask_b32_e32 v114, v116, v115, vcc
	v_not_b32_e32 v115, v97
	v_or_b32_e32 v116, 0x80000000, v97
	v_cmp_gt_i32_e32 vcc, 0, v97
	v_and_b32_e32 v114, 0xffffff80, v114
	v_sub_u32_e32 v114, v114, v18
	v_cndmask_b32_e32 v97, v116, v115, vcc
	s_waitcnt vmcnt(0)
; __device__ __forceinline__ unsigned f2key(float f) { const unsigned u = __float_as_uint(f); return (u & 0x80000000u) ? ~u : (u | 0x80000000u); }
; #define CE_DESC(a, b) do { const unsigned _mx = (a) > (b) ? (a) : (b), _mn = (a) > (b) ? (b) : (a); (a) = _mx; (b) = _mn; } while (0)
; __device__ __forceinline__ void sort16_desc(unsigned (&k)[16]) {
; #pragma unroll
;     for (int size = 2; size <= 16; size <<= 1)
; #pragma unroll
;         for (int stride = size >> 1; stride > 0; stride >>= 1)
; #pragma unroll
;             for (int i = 0; i < 16; ++i) { const int j = i ^ stride;
;                 if (j > i) { if ((i & size) == 0) CE_DESC(k[i], k[j]); else CE_DESC(k[j], k[i]); } }
; }
; __device__ __forceinline__ void peer_tile(const Args& A, LAS unsigned char* lds, int tile) {
;     ...
;                   for (int i = 0; i < 16; ++i) {
;                       const float lo = (float)__builtin_bit_cast(_Float16, (unsigned short)(sw[i] & 0xffffu)), hi = (float)__builtin_bit_cast(_Float16, (unsigned short)(sw[i] >> 16));
;                       const unsigned klo = (f2key(lo) & ~127u) | (unsigned)(127 - (32 * g + 2 * i)), khi = (f2key(hi) & ~127u) | (unsigned)(127 - (32 * g + 2 * i + 1));
;                       if (i < 8) { k0[2 * i] = klo; k0[2 * i + 1] = khi; } else { k1[2 * (i - 8)] = klo; k1[2 * (i - 8) + 1] = khi; } } }
	v_cvt_f32_f16_sdwa v115, v102 dst_sel:DWORD dst_unused:UNUSED_PAD src0_sel:WORD_1
	v_cvt_f32_f16_e32 v102, v102
	v_and_b32_e32 v97, 0xffffff80, v97
	v_sub_u32_e32 v97, v97, v18
	v_not_b32_e32 v116, v115
	v_or_b32_e32 v117, 0x80000000, v115
	v_cmp_gt_i32_e32 vcc, 0, v115
	v_add_u32_e32 v114, 0x7e, v114
	v_add_u32_e32 v97, 0x7f, v97
	v_cndmask_b32_e32 v115, v117, v116, vcc
	v_not_b32_e32 v116, v102
	v_or_b32_e32 v117, 0x80000000, v102
	v_cmp_gt_i32_e32 vcc, 0, v102
	v_and_b32_e32 v115, 0xffffff80, v115
	v_sub_u32_e32 v115, v115, v20
	v_cndmask_b32_e32 v102, v117, v116, vcc
	v_cvt_f32_f16_sdwa v116, v103 dst_sel:DWORD dst_unused:UNUSED_PAD src0_sel:WORD_1
	v_cvt_f32_f16_e32 v103, v103
	v_and_b32_e32 v102, 0xffffff80, v102
	v_sub_u32_e32 v102, v102, v20
	v_not_b32_e32 v117, v116
	v_or_b32_e32 v118, 0x80000000, v116
	v_cmp_gt_i32_e32 vcc, 0, v116
	v_add_u32_e32 v115, 0x7e, v115
	v_add_u32_e32 v102, 0x7f, v102
	v_cndmask_b32_e32 v116, v118, v117, vcc
	v_not_b32_e32 v117, v103
	v_or_b32_e32 v118, 0x80000000, v103
	v_cmp_gt_i32_e32 vcc, 0, v103
	v_and_b32_e32 v116, 0xffffff80, v116
	v_sub_u32_e32 v116, v116, v21
	v_cndmask_b32_e32 v103, v118, v117, vcc
	v_cvt_f32_f16_sdwa v117, v104 dst_sel:DWORD dst_unused:UNUSED_PAD src0_sel:WORD_1
	v_cvt_f32_f16_e32 v104, v104
	v_and_b32_e32 v103, 0xffffff80, v103
	v_sub_u32_e32 v103, v103, v21
	v_not_b32_e32 v118, v117
	v_or_b32_e32 v119, 0x80000000, v117
	v_cmp_gt_i32_e32 vcc, 0, v117
	v_add_u32_e32 v116, 0x7e, v116
	v_add_u32_e32 v103, 0x7f, v103
	v_cndmask_b32_e32 v117, v119, v118, vcc
	v_not_b32_e32 v118, v104
	v_or_b32_e32 v119, 0x80000000, v104
	v_cmp_gt_i32_e32 vcc, 0, v104
	v_and_b32_e32 v117, 0xffffff80, v117
	v_sub_u32_e32 v117, v117, v22
	v_cndmask_b32_e32 v104, v119, v118, vcc
	v_cvt_f32_f16_sdwa v118, v105 dst_sel:DWORD dst_unused:UNUSED_PAD src0_sel:WORD_1
	v_cvt_f32_f16_e32 v105, v105
	v_and_b32_e32 v104, 0xffffff80, v104
	v_sub_u32_e32 v104, v104, v22
	v_not_b32_e32 v119, v118
	v_or_b32_e32 v120, 0x80000000, v118
	v_cmp_gt_i32_e32 vcc, 0, v118
	v_add_u32_e32 v117, 0x7e, v117
	v_add_u32_e32 v104, 0x7f, v104
	v_cndmask_b32_e32 v118, v120, v119, vcc
	v_not_b32_e32 v119, v105
	v_or_b32_e32 v120, 0x80000000, v105
	v_cmp_gt_i32_e32 vcc, 0, v105
	v_and_b32_e32 v118, 0xffffff80, v118
	v_sub_u32_e32 v118, v118, v23
	v_cndmask_b32_e32 v105, v120, v119, vcc
	v_cvt_f32_f16_sdwa v119, v0 dst_sel:DWORD dst_unused:UNUSED_PAD src0_sel:WORD_1
	v_cvt_f32_f16_e32 v0, v0
	v_and_b32_e32 v105, 0xffffff80, v105
	v_sub_u32_e32 v105, v105, v23
	v_not_b32_e32 v120, v119
	v_or_b32_e32 v121, 0x80000000, v119
	v_cmp_gt_i32_e32 vcc, 0, v119
	v_add_u32_e32 v118, 0x7e, v118
	v_add_u32_e32 v105, 0x7f, v105
	v_cndmask_b32_e32 v119, v121, v120, vcc
	v_not_b32_e32 v120, v0
	v_or_b32_e32 v121, 0x80000000, v0
	v_cmp_gt_i32_e32 vcc, 0, v0
	v_and_b32_e32 v119, 0xffffff80, v119
	v_sub_u32_e32 v119, v119, v24
	v_cndmask_b32_e32 v0, v121, v120, vcc
	v_cvt_f32_f16_sdwa v120, v1 dst_sel:DWORD dst_unused:UNUSED_PAD src0_sel:WORD_1
	v_cvt_f32_f16_e32 v1, v1
	v_and_b32_e32 v0, 0xffffff80, v0
	v_sub_u32_e32 v0, v0, v24
	v_not_b32_e32 v121, v120
	v_or_b32_e32 v122, 0x80000000, v120
	v_cmp_gt_i32_e32 vcc, 0, v120
	v_add_u32_e32 v119, 0x7e, v119
	v_add_u32_e32 v0, 0x7f, v0
	v_cndmask_b32_e32 v120, v122, v121, vcc
	v_not_b32_e32 v121, v1
	v_or_b32_e32 v122, 0x80000000, v1
	v_cmp_gt_i32_e32 vcc, 0, v1
	v_and_b32_e32 v120, 0xffffff80, v120
	v_sub_u32_e32 v120, v120, v25
	v_cndmask_b32_e32 v1, v122, v121, vcc
	v_cvt_f32_f16_sdwa v121, v2 dst_sel:DWORD dst_unused:UNUSED_PAD src0_sel:WORD_1
	v_cvt_f32_f16_e32 v2, v2
	v_and_b32_e32 v1, 0xffffff80, v1
	v_sub_u32_e32 v1, v1, v25
	v_not_b32_e32 v122, v121
	v_or_b32_e32 v123, 0x80000000, v121
	v_cmp_gt_i32_e32 vcc, 0, v121
	v_add_u32_e32 v120, 0x7e, v120
	v_add_u32_e32 v1, 0x7f, v1
	v_cndmask_b32_e32 v121, v123, v122, vcc
	v_not_b32_e32 v122, v2
	v_or_b32_e32 v123, 0x80000000, v2
	v_cmp_gt_i32_e32 vcc, 0, v2
	v_and_b32_e32 v121, 0xffffff80, v121
	v_sub_u32_e32 v121, v121, v26
	v_cndmask_b32_e32 v2, v123, v122, vcc
	v_cvt_f32_f16_sdwa v122, v3 dst_sel:DWORD dst_unused:UNUSED_PAD src0_sel:WORD_1
	v_cvt_f32_f16_e32 v3, v3
	v_and_b32_e32 v2, 0xffffff80, v2
	v_sub_u32_e32 v2, v2, v26
	v_not_b32_e32 v123, v122
	v_or_b32_e32 v124, 0x80000000, v122
	v_cmp_gt_i32_e32 vcc, 0, v122
	v_add_u32_e32 v121, 0x7e, v121
	v_add_u32_e32 v2, 0x7f, v2
	v_cndmask_b32_e32 v122, v124, v123, vcc
	v_not_b32_e32 v123, v3
	v_or_b32_e32 v124, 0x80000000, v3
	v_cmp_gt_i32_e32 vcc, 0, v3
	v_and_b32_e32 v122, 0xffffff80, v122
	v_sub_u32_e32 v122, v122, v28
	v_cndmask_b32_e32 v3, v124, v123, vcc
	v_and_b32_e32 v3, 0xffffff80, v3
	v_sub_u32_e32 v3, v3, v28
	v_add_u32_e32 v122, 0x7e, v122
	v_add_u32_e32 v3, 0x7f, v3
	v_max_u32_e32 v123, v98, v106
	v_min_u32_e32 v98, v98, v106
	v_max_u32_e32 v106, v107, v99
	v_min_u32_e32 v99, v107, v99
	v_max_u32_e32 v107, v100, v108
	v_min_u32_e32 v100, v100, v108
	v_max_u32_e32 v108, v109, v101
	v_min_u32_e32 v101, v109, v101
	v_max_u32_e32 v109, v94, v110
	v_min_u32_e32 v94, v94, v110
	v_max_u32_e32 v110, v111, v95
	v_min_u32_e32 v95, v111, v95
	v_max_u32_e32 v111, v96, v112
	v_min_u32_e32 v96, v96, v112
	v_max_u32_e32 v112, v114, v97
	v_min_u32_e32 v97, v114, v97
	v_max_u32_e32 v131, v102, v115
	v_min_u32_e32 v102, v102, v115
	v_max_u32_e32 v115, v116, v103
	v_min_u32_e32 v103, v116, v103
	v_max_u32_e32 v116, v104, v117
	v_min_u32_e32 v104, v104, v117
	v_max_u32_e32 v117, v118, v105
	v_min_u32_e32 v105, v118, v105
	v_max_u32_e32 v118, v0, v119
	v_min_u32_e32 v0, v0, v119
	v_max_u32_e32 v119, v120, v1
	v_min_u32_e32 v1, v120, v1
	v_max_u32_e32 v120, v2, v121
	v_min_u32_e32 v2, v2, v121
; #define CE_DESC(a, b) do { const unsigned _mx = (a) > (b) ? (a) : (b), _mn = (a) > (b) ? (b) : (a); (a) = _mx; (b) = _mn; } while (0)
; __device__ __forceinline__ void sort16_desc(unsigned (&k)[16]) {
; #pragma unroll
;     for (int size = 2; size <= 16; size <<= 1)
; #pragma unroll
;         for (int stride = size >> 1; stride > 0; stride >>= 1)
; #pragma unroll
;             for (int i = 0; i < 16; ++i) { const int j = i ^ stride;
;                 if (j > i) { if ((i & size) == 0) CE_DESC(k[i], k[j]); else CE_DESC(k[j], k[i]); } }
; }
	v_max_u32_e32 v121, v122, v3
	v_min_u32_e32 v3, v122, v3
	v_max_u32_e32 v114, v123, v99
	v_min_u32_e32 v99, v123, v99
	v_max_u32_e32 v123, v98, v106
	v_min_u32_e32 v98, v98, v106
	v_max_u32_e32 v106, v101, v107
	v_min_u32_e32 v101, v101, v107
	v_max_u32_e32 v107, v108, v100
	v_min_u32_e32 v100, v108, v100
	v_max_u32_e32 v108, v109, v95
	v_min_u32_e32 v95, v109, v95
	v_max_u32_e32 v109, v94, v110
	v_min_u32_e32 v94, v94, v110
	v_max_u32_e32 v110, v97, v111
	v_min_u32_e32 v97, v97, v111
	v_max_u32_e32 v111, v112, v96
	v_min_u32_e32 v96, v112, v96
	v_max_u32_e32 v122, v131, v103
	v_min_u32_e32 v103, v131, v103
	v_max_u32_e32 v131, v102, v115
	v_min_u32_e32 v102, v102, v115
	v_max_u32_e32 v115, v105, v116
	v_min_u32_e32 v105, v105, v116
	v_max_u32_e32 v116, v117, v104
	v_min_u32_e32 v104, v117, v104
	v_max_u32_e32 v117, v118, v1
	v_min_u32_e32 v1, v118, v1
	v_max_u32_e32 v118, v0, v119
	v_min_u32_e32 v0, v0, v119
	v_max_u32_e32 v119, v3, v120
	v_min_u32_e32 v3, v3, v120
	v_max_u32_e32 v120, v121, v2
	v_min_u32_e32 v2, v121, v2
	v_max_u32_e32 v112, v114, v123
	v_min_u32_e32 v114, v114, v123
	v_max_u32_e32 v123, v99, v98
	v_min_u32_e32 v98, v99, v98
	v_max_u32_e32 v99, v100, v101
	v_min_u32_e32 v100, v100, v101
	v_max_u32_e32 v101, v107, v106
	v_min_u32_e32 v106, v107, v106
	v_max_u32_e32 v107, v108, v109
	v_min_u32_e32 v108, v108, v109
	v_max_u32_e32 v109, v95, v94
	v_min_u32_e32 v94, v95, v94
	v_max_u32_e32 v95, v96, v97
	v_min_u32_e32 v96, v96, v97
	v_max_u32_e32 v97, v111, v110
	v_min_u32_e32 v110, v111, v110
	v_max_u32_e32 v121, v122, v131
	v_min_u32_e32 v122, v122, v131
	v_max_u32_e32 v131, v103, v102
	v_min_u32_e32 v102, v103, v102
	v_max_u32_e32 v103, v104, v105
	v_min_u32_e32 v104, v104, v105
	v_max_u32_e32 v105, v116, v115
	v_min_u32_e32 v115, v116, v115
	v_max_u32_e32 v116, v117, v118
	v_min_u32_e32 v117, v117, v118
	v_max_u32_e32 v118, v1, v0
	v_min_u32_e32 v0, v1, v0
	v_max_u32_e32 v1, v2, v3
	v_min_u32_e32 v2, v2, v3
	v_max_u32_e32 v3, v120, v119
	v_min_u32_e32 v119, v120, v119
	v_max_u32_e32 v111, v112, v100
	v_min_u32_e32 v100, v112, v100
	v_max_u32_e32 v112, v114, v99
	v_min_u32_e32 v99, v114, v99
	v_max_u32_e32 v114, v123, v106
	v_min_u32_e32 v106, v123, v106
	v_max_u32_e32 v123, v98, v101
	v_min_u32_e32 v98, v98, v101
	v_max_u32_e32 v101, v96, v107
	v_min_u32_e32 v96, v96, v107
	v_max_u32_e32 v107, v95, v108
	v_min_u32_e32 v95, v95, v108
	v_max_u32_e32 v108, v110, v109
	v_min_u32_e32 v109, v110, v109
	v_max_u32_e32 v110, v97, v94
	v_min_u32_e32 v94, v97, v94
	v_max_u32_e32 v120, v121, v104
	v_min_u32_e32 v104, v121, v104
	v_max_u32_e32 v121, v122, v103
	v_min_u32_e32 v103, v122, v103
	v_max_u32_e32 v122, v131, v115
	v_min_u32_e32 v115, v131, v115
	v_max_u32_e32 v131, v102, v105
	v_min_u32_e32 v102, v102, v105
	v_max_u32_e32 v105, v2, v116
	v_min_u32_e32 v2, v2, v116
	v_max_u32_e32 v116, v1, v117
	v_min_u32_e32 v1, v1, v117
	v_max_u32_e32 v117, v119, v118
	v_min_u32_e32 v118, v119, v118
	v_max_u32_e32 v119, v3, v0
	v_min_u32_e32 v0, v3, v0
	v_max_u32_e32 v97, v111, v114
	v_min_u32_e32 v111, v111, v114
	v_max_u32_e32 v114, v112, v123
	v_min_u32_e32 v112, v112, v123
	v_max_u32_e32 v123, v100, v106
	v_min_u32_e32 v100, v100, v106
	v_max_u32_e32 v106, v99, v98
	v_min_u32_e32 v98, v99, v98
	v_max_u32_e32 v99, v109, v96
	v_min_u32_e32 v96, v109, v96
	v_max_u32_e32 v109, v94, v95
	v_min_u32_e32 v94, v94, v95
	v_max_u32_e32 v95, v108, v101
	v_min_u32_e32 v101, v108, v101
	v_max_u32_e32 v108, v110, v107
	v_min_u32_e32 v107, v110, v107
	v_max_u32_e32 v3, v120, v122
	v_min_u32_e32 v120, v120, v122
	v_max_u32_e32 v122, v121, v131
	v_min_u32_e32 v121, v121, v131
	v_max_u32_e32 v131, v104, v115
	v_min_u32_e32 v104, v104, v115
	v_max_u32_e32 v115, v103, v102
	v_min_u32_e32 v102, v103, v102
	v_max_u32_e32 v103, v118, v2
	v_min_u32_e32 v2, v118, v2
	v_max_u32_e32 v118, v0, v1
	v_min_u32_e32 v0, v0, v1
	v_max_u32_e32 v1, v117, v105
	v_min_u32_e32 v105, v117, v105
	v_max_u32_e32 v117, v119, v116
	v_min_u32_e32 v116, v119, v116
	v_max_u32_e32 v110, v97, v114
	v_min_u32_e32 v97, v97, v114
	v_max_u32_e32 v114, v111, v112
	v_min_u32_e32 v111, v111, v112
	v_max_u32_e32 v112, v123, v106
	v_min_u32_e32 v106, v123, v106
	v_max_u32_e32 v123, v100, v98
	v_min_u32_e32 v98, v100, v98
	v_max_u32_e32 v100, v94, v96
	v_min_u32_e32 v94, v94, v96
	v_max_u32_e32 v96, v109, v99
	v_min_u32_e32 v99, v109, v99
	v_max_u32_e32 v109, v107, v101
	v_min_u32_e32 v101, v107, v101
	v_max_u32_e32 v107, v108, v95
	v_min_u32_e32 v95, v108, v95
	v_max_u32_e32 v119, v3, v122
	v_min_u32_e32 v3, v3, v122
	v_max_u32_e32 v122, v120, v121
	v_min_u32_e32 v120, v120, v121
	v_max_u32_e32 v121, v131, v115
	v_min_u32_e32 v115, v131, v115
	v_max_u32_e32 v131, v104, v102
	v_min_u32_e32 v102, v104, v102
	v_max_u32_e32 v104, v0, v2
	v_min_u32_e32 v0, v0, v2
	v_max_u32_e32 v2, v118, v103
	v_min_u32_e32 v103, v118, v103
	v_max_u32_e32 v118, v116, v105
	v_min_u32_e32 v105, v116, v105
	v_max_u32_e32 v116, v117, v1
	v_min_u32_e32 v1, v117, v1
	v_max_u32_e32 v108, v110, v94
	v_min_u32_e32 v94, v110, v94
	v_max_u32_e32 v110, v97, v100
	v_min_u32_e32 v97, v97, v100
	v_max_u32_e32 v100, v114, v99
	v_min_u32_e32 v99, v114, v99
	v_max_u32_e32 v114, v111, v96
	v_min_u32_e32 v96, v111, v96
	v_max_u32_e32 v111, v112, v101
	v_min_u32_e32 v101, v112, v101
	v_max_u32_e32 v112, v106, v109
	v_min_u32_e32 v106, v106, v109
	v_max_u32_e32 v109, v123, v95
	v_min_u32_e32 v95, v123, v95
	v_max_u32_e32 v123, v98, v107
	v_min_u32_e32 v98, v98, v107
	v_max_u32_e32 v117, v119, v0
	v_min_u32_e32 v0, v119, v0
	v_max_u32_e32 v119, v3, v104
	v_min_u32_e32 v3, v3, v104
	v_max_u32_e32 v104, v122, v103
	v_min_u32_e32 v103, v122, v103
; #define CE_DESC(a, b) do { const unsigned _mx = (a) > (b) ? (a) : (b), _mn = (a) > (b) ? (b) : (a); (a) = _mx; (b) = _mn; } while (0)
; __device__ __forceinline__ void sort16_desc(unsigned (&k)[16]) {
; #pragma unroll
;     for (int size = 2; size <= 16; size <<= 1)
; #pragma unroll
;         for (int stride = size >> 1; stride > 0; stride >>= 1)
; #pragma unroll
;             for (int i = 0; i < 16; ++i) { const int j = i ^ stride;
;                 if (j > i) { if ((i & size) == 0) CE_DESC(k[i], k[j]); else CE_DESC(k[j], k[i]); } }
; }
; __device__ __forceinline__ void merge16(unsigned (&a)[16], const unsigned (&b)[16]) {
; #pragma unroll
;     for (int i = 0; i < 16; ++i) a[i] = a[i] > b[15 - i] ? a[i] : b[15 - i];
; #pragma unroll
;     for (int stride = 8; stride > 0; stride >>= 1)
; #pragma unroll
;         for (int i = 0; i < 16; ++i) { const int j = i ^ stride; if (j > i) CE_DESC(a[i], a[j]); }
; }
; __device__ __forceinline__ void peer_tile(const Args& A, LAS unsigned char* lds, int tile) {
;     ...
;                 for (int msk = 16; msk <= 32; msk <<= 1) {
; #pragma unroll
;                     for (int i = 0; i < 16; ++i) k1[i] = (unsigned)__shfl_xor((int)k0[i], msk);
;                     merge16(k0, k1); }
	v_max_u32_e32 v122, v120, v2
	v_min_u32_e32 v2, v120, v2
	v_max_u32_e32 v120, v121, v105
	v_min_u32_e32 v105, v121, v105
	v_max_u32_e32 v121, v115, v118
	v_min_u32_e32 v115, v115, v118
	v_max_u32_e32 v118, v131, v1
	v_min_u32_e32 v1, v131, v1
	v_max_u32_e32 v131, v102, v116
	v_min_u32_e32 v102, v102, v116
	v_max_u32_e32 v107, v108, v111
	v_min_u32_e32 v108, v108, v111
	v_max_u32_e32 v111, v110, v112
	v_min_u32_e32 v110, v110, v112
	v_max_u32_e32 v112, v100, v109
	v_min_u32_e32 v100, v100, v109
	v_max_u32_e32 v109, v114, v123
	v_min_u32_e32 v114, v114, v123
	v_max_u32_e32 v123, v94, v101
	v_min_u32_e32 v94, v94, v101
	v_max_u32_e32 v101, v97, v106
	v_min_u32_e32 v97, v97, v106
	v_max_u32_e32 v106, v99, v95
	v_min_u32_e32 v95, v99, v95
	v_max_u32_e32 v99, v96, v98
	v_min_u32_e32 v96, v96, v98
	v_max_u32_e32 v116, v117, v120
	v_min_u32_e32 v117, v117, v120
	v_max_u32_e32 v120, v119, v121
	v_min_u32_e32 v119, v119, v121
	v_max_u32_e32 v121, v104, v118
	v_min_u32_e32 v104, v104, v118
	v_max_u32_e32 v118, v122, v131
	v_min_u32_e32 v122, v122, v131
	v_max_u32_e32 v131, v0, v105
	v_min_u32_e32 v0, v0, v105
	v_max_u32_e32 v105, v3, v115
	v_min_u32_e32 v3, v3, v115
	v_max_u32_e32 v115, v103, v1
	v_min_u32_e32 v1, v103, v1
	v_max_u32_e32 v103, v2, v102
	v_min_u32_e32 v2, v2, v102
	v_max_u32_e32 v98, v107, v112
	v_min_u32_e32 v107, v107, v112
	v_max_u32_e32 v112, v111, v109
	v_min_u32_e32 v109, v111, v109
	v_max_u32_e32 v111, v108, v100
	v_min_u32_e32 v100, v108, v100
	v_max_u32_e32 v108, v110, v114
	v_min_u32_e32 v110, v110, v114
	v_max_u32_e32 v114, v123, v106
	v_min_u32_e32 v106, v123, v106
	v_max_u32_e32 v123, v101, v99
	v_min_u32_e32 v99, v101, v99
	v_max_u32_e32 v101, v94, v95
	v_min_u32_e32 v94, v94, v95
	v_max_u32_e32 v95, v97, v96
	v_min_u32_e32 v96, v97, v96
	v_max_u32_e32 v102, v116, v121
	v_min_u32_e32 v116, v116, v121
	v_max_u32_e32 v121, v120, v118
	v_min_u32_e32 v118, v120, v118
	v_max_u32_e32 v120, v117, v104
	v_min_u32_e32 v104, v117, v104
	v_max_u32_e32 v117, v119, v122
	v_min_u32_e32 v119, v119, v122
	v_max_u32_e32 v122, v131, v115
	v_min_u32_e32 v115, v131, v115
	v_max_u32_e32 v131, v105, v103
	v_min_u32_e32 v103, v105, v103
	v_max_u32_e32 v105, v0, v1
	v_min_u32_e32 v0, v0, v1
	v_max_u32_e32 v1, v3, v2
	v_min_u32_e32 v2, v3, v2
	v_min_u32_e32 v97, v98, v112
	v_min_u32_e32 v124, v107, v109
	v_min_u32_e32 v125, v111, v108
	v_min_u32_e32 v126, v100, v110
	v_min_u32_e32 v127, v114, v123
	v_min_u32_e32 v128, v106, v99
	v_min_u32_e32 v129, v101, v95
	v_min_u32_e32 v130, v94, v96
	v_min_u32_e32 v3, v102, v121
	v_min_u32_e32 v132, v116, v118
	v_min_u32_e32 v133, v120, v117
	v_min_u32_e32 v134, v104, v119
	v_min_u32_e32 v135, v122, v131
	v_min_u32_e32 v136, v115, v103
	v_min_u32_e32 v137, v105, v1
	v_min_u32_e32 v138, v0, v2
	v_max3_u32 v98, v98, v112, v138
	v_max3_u32 v0, v97, v0, v2
	v_max3_u32 v2, v107, v109, v137
	v_max3_u32 v1, v124, v105, v1
	v_max3_u32 v97, v111, v108, v136
	v_max3_u32 v103, v125, v115, v103
	v_max3_u32 v100, v100, v110, v135
	v_max3_u32 v105, v126, v122, v131
	v_max3_u32 v107, v114, v123, v134
	v_max3_u32 v104, v127, v104, v119
	v_max3_u32 v99, v106, v99, v133
	v_max3_u32 v106, v128, v120, v117
	v_max3_u32 v95, v101, v95, v132
	v_max3_u32 v101, v129, v116, v118
	v_max3_u32 v3, v94, v96, v3
	v_max3_u32 v94, v130, v102, v121
	v_max_u32_e32 v96, v98, v107
	v_min_u32_e32 v98, v98, v107
	v_max_u32_e32 v102, v0, v104
	v_min_u32_e32 v0, v0, v104
	v_max_u32_e32 v104, v2, v99
	v_min_u32_e32 v2, v2, v99
	v_max_u32_e32 v99, v1, v106
	v_min_u32_e32 v1, v1, v106
	v_max_u32_e32 v106, v97, v95
	v_min_u32_e32 v95, v97, v95
	v_max_u32_e32 v97, v103, v101
	v_min_u32_e32 v101, v103, v101
	v_max_u32_e32 v103, v100, v3
	v_min_u32_e32 v3, v100, v3
	v_max_u32_e32 v100, v105, v94
	v_min_u32_e32 v94, v105, v94
	v_max_u32_e32 v105, v96, v106
	v_min_u32_e32 v96, v96, v106
	v_max_u32_e32 v106, v102, v97
	v_min_u32_e32 v97, v102, v97
	v_max_u32_e32 v102, v104, v103
	v_min_u32_e32 v103, v104, v103
	v_max_u32_e32 v104, v99, v100
	v_min_u32_e32 v99, v99, v100
	v_max_u32_e32 v100, v98, v95
	v_min_u32_e32 v95, v98, v95
	v_max_u32_e32 v98, v0, v101
	v_min_u32_e32 v0, v0, v101
	v_max_u32_e32 v101, v2, v3
	v_min_u32_e32 v2, v2, v3
	v_max_u32_e32 v3, v1, v94
	v_min_u32_e32 v1, v1, v94
	v_max_u32_e32 v94, v105, v102
	v_min_u32_e32 v102, v105, v102
	v_max_u32_e32 v105, v106, v104
	v_min_u32_e32 v104, v106, v104
	v_max_u32_e32 v106, v96, v103
	v_min_u32_e32 v96, v96, v103
	v_max_u32_e32 v103, v97, v99
	v_min_u32_e32 v97, v97, v99
	v_max_u32_e32 v99, v100, v101
	v_min_u32_e32 v100, v100, v101
	v_max_u32_e32 v101, v98, v3
	v_min_u32_e32 v3, v98, v3
	v_max_u32_e32 v98, v95, v2
	v_min_u32_e32 v2, v95, v2
	v_max_u32_e32 v95, v0, v1
	v_min_u32_e32 v0, v0, v1
	v_max_u32_e32 v1, v94, v105
	v_min_u32_e32 v94, v94, v105
	v_max_u32_e32 v105, v102, v104
	v_min_u32_e32 v102, v102, v104
	v_max_u32_e32 v104, v106, v103
	v_min_u32_e32 v103, v106, v103
	v_max_u32_e32 v106, v96, v97
	v_min_u32_e32 v96, v96, v97
	v_max_u32_e32 v97, v99, v101
	v_min_u32_e32 v99, v99, v101
	v_max_u32_e32 v101, v100, v3
	v_min_u32_e32 v3, v100, v3
	v_max_u32_e32 v100, v98, v95
	v_min_u32_e32 v95, v98, v95
	v_max_u32_e32 v98, v2, v0
	v_min_u32_e32 v0, v2, v0
	ds_bpermute_b32 v2, v27, v1
	ds_bpermute_b32 v107, v27, v94
	ds_bpermute_b32 v108, v27, v105
	ds_bpermute_b32 v109, v27, v102
	ds_bpermute_b32 v110, v27, v104
	ds_bpermute_b32 v111, v27, v103
	ds_bpermute_b32 v112, v27, v106
	ds_bpermute_b32 v114, v27, v96
	ds_bpermute_b32 v115, v27, v97
	ds_bpermute_b32 v116, v27, v99
	ds_bpermute_b32 v117, v27, v101
	ds_bpermute_b32 v118, v27, v0
	ds_bpermute_b32 v119, v27, v98
	ds_bpermute_b32 v120, v27, v95
	ds_bpermute_b32 v121, v27, v100
	ds_bpermute_b32 v122, v27, v3
	s_waitcnt lgkmcnt(4)
; #define CE_DESC(a, b) do { const unsigned _mx = (a) > (b) ? (a) : (b), _mn = (a) > (b) ? (b) : (a); (a) = _mx; (b) = _mn; } while (0)
; __device__ __forceinline__ void merge16(unsigned (&a)[16], const unsigned (&b)[16]) {
; #pragma unroll
;     for (int i = 0; i < 16; ++i) a[i] = a[i] > b[15 - i] ? a[i] : b[15 - i];
; #pragma unroll
;     for (int stride = 8; stride > 0; stride >>= 1)
; #pragma unroll
;         for (int i = 0; i < 16; ++i) { const int j = i ^ stride; if (j > i) CE_DESC(a[i], a[j]); }
; }
; __device__ __forceinline__ void peer_tile(const Args& A, LAS unsigned char* lds, int tile) {
;     ...
;                 { const bf16_t* sp = QRY + m * 2048 + hp * 128 + 32 * g;
;                   const u32x4 s0 = *(const u32x4*)sp, s1 = *(const u32x4*)(sp + 8), s2 = *(const u32x4*)(sp + 16), s3 = *(const u32x4*)(sp + 24);
;     ...
;                 for (int msk = 16; msk <= 32; msk <<= 1) {
; #pragma unroll
;                     for (int i = 0; i < 16; ++i) k1[i] = (unsigned)__shfl_xor((int)k0[i], msk);
;                     merge16(k0, k1); }
	v_max_u32_e32 v1, v1, v118
	s_waitcnt lgkmcnt(3)
	v_max_u32_e32 v94, v94, v119
	s_waitcnt lgkmcnt(2)
	v_max_u32_e32 v105, v105, v120
	s_waitcnt lgkmcnt(1)
	v_max_u32_e32 v102, v102, v121
	s_waitcnt lgkmcnt(0)
	v_max_u32_e32 v104, v104, v122
	v_max_u32_e32 v103, v103, v117
	v_max_u32_e32 v106, v106, v116
	v_max_u32_e32 v96, v96, v115
	v_max_u32_e32 v97, v97, v114
	v_max_u32_e32 v99, v99, v112
	v_max_u32_e32 v101, v101, v111
	v_max_u32_e32 v3, v3, v110
	v_max_u32_e32 v100, v100, v109
	v_max_u32_e32 v95, v95, v108
	v_max_u32_e32 v98, v98, v107
	v_max_u32_e32 v0, v0, v2
	v_max_u32_e32 v2, v1, v97
	v_min_u32_e32 v1, v1, v97
	v_max_u32_e32 v97, v94, v99
	v_min_u32_e32 v94, v94, v99
	v_max_u32_e32 v99, v105, v101
	v_min_u32_e32 v101, v105, v101
	v_max_u32_e32 v105, v102, v3
	v_min_u32_e32 v3, v102, v3
	v_max_u32_e32 v102, v104, v100
	v_min_u32_e32 v100, v104, v100
	v_max_u32_e32 v104, v103, v95
	v_min_u32_e32 v95, v103, v95
	v_max_u32_e32 v103, v106, v98
	v_min_u32_e32 v98, v106, v98
	v_max_u32_e32 v106, v96, v0
	v_min_u32_e32 v0, v96, v0
	v_max_u32_e32 v96, v2, v102
	v_min_u32_e32 v2, v2, v102
	v_max_u32_e32 v102, v97, v104
	v_min_u32_e32 v97, v97, v104
	v_max_u32_e32 v104, v99, v103
	v_min_u32_e32 v99, v99, v103
	v_max_u32_e32 v103, v105, v106
	v_min_u32_e32 v105, v105, v106
	v_max_u32_e32 v106, v1, v100
	v_min_u32_e32 v1, v1, v100
	v_max_u32_e32 v100, v94, v95
	v_min_u32_e32 v94, v94, v95
	v_max_u32_e32 v95, v101, v98
	v_min_u32_e32 v98, v101, v98
	v_max_u32_e32 v101, v3, v0
	v_min_u32_e32 v0, v3, v0
	v_max_u32_e32 v3, v96, v104
	v_min_u32_e32 v96, v96, v104
	v_max_u32_e32 v104, v102, v103
	v_min_u32_e32 v102, v102, v103
	v_max_u32_e32 v103, v2, v99
	v_min_u32_e32 v2, v2, v99
	v_max_u32_e32 v99, v97, v105
	v_min_u32_e32 v97, v97, v105
	v_max_u32_e32 v105, v106, v95
	v_min_u32_e32 v95, v106, v95
	v_max_u32_e32 v106, v100, v101
	v_min_u32_e32 v100, v100, v101
	v_max_u32_e32 v101, v1, v98
	v_min_u32_e32 v1, v1, v98
	v_max_u32_e32 v98, v94, v0
	v_min_u32_e32 v0, v94, v0
	v_max_u32_e32 v94, v3, v104
	v_min_u32_e32 v3, v3, v104
	v_max_u32_e32 v104, v96, v102
	v_min_u32_e32 v96, v96, v102
	v_max_u32_e32 v102, v103, v99
	v_min_u32_e32 v99, v103, v99
	v_max_u32_e32 v103, v2, v97
	v_min_u32_e32 v2, v2, v97
	v_max_u32_e32 v97, v105, v106
	v_min_u32_e32 v105, v105, v106
	v_max_u32_e32 v106, v95, v100
	v_min_u32_e32 v95, v95, v100
	v_max_u32_e32 v100, v101, v98
	v_min_u32_e32 v98, v101, v98
	v_max_u32_e32 v101, v1, v0
	v_min_u32_e32 v0, v1, v0
	ds_bpermute_b32 v114, v29, v0
	ds_bpermute_b32 v1, v29, v94
	ds_bpermute_b32 v107, v29, v3
	ds_bpermute_b32 v108, v29, v104
	ds_bpermute_b32 v109, v29, v96
	s_waitcnt lgkmcnt(4)
	v_max_u32_e32 v94, v94, v114
	global_load_dwordx4 v[114:117], v[4:5], off offset:1296
	global_load_dwordx4 v[118:121], v[4:5], off offset:1280
	ds_bpermute_b32 v110, v29, v102
	ds_bpermute_b32 v111, v29, v99
	ds_bpermute_b32 v112, v29, v103
	ds_bpermute_b32 v122, v29, v2
	ds_bpermute_b32 v123, v29, v97
	ds_bpermute_b32 v124, v29, v105
	ds_bpermute_b32 v125, v29, v106
	ds_bpermute_b32 v126, v29, v95
	ds_bpermute_b32 v127, v29, v100
	ds_bpermute_b32 v128, v29, v101
	ds_bpermute_b32 v129, v29, v98
	s_waitcnt lgkmcnt(4)
	v_max_u32_e32 v99, v99, v125
	s_waitcnt lgkmcnt(3)
	v_max_u32_e32 v102, v102, v126
	s_waitcnt lgkmcnt(2)
	v_max_u32_e32 v96, v96, v127
	s_waitcnt lgkmcnt(1)
	v_max_u32_e32 v3, v3, v128
	s_waitcnt lgkmcnt(0)
	v_max_u32_e32 v104, v104, v129
	v_max_u32_e32 v103, v103, v124
	v_max_u32_e32 v2, v2, v123
	v_max_u32_e32 v97, v97, v122
	v_max_u32_e32 v105, v105, v112
	v_max_u32_e32 v106, v106, v111
	v_max_u32_e32 v95, v95, v110
	v_max_u32_e32 v100, v100, v109
	v_max_u32_e32 v98, v98, v108
	v_max_u32_e32 v101, v101, v107
	v_max_u32_e32 v0, v0, v1
	v_max_u32_e32 v1, v94, v97
	v_min_u32_e32 v94, v94, v97
	v_max_u32_e32 v97, v3, v105
	v_min_u32_e32 v3, v3, v105
	v_max_u32_e32 v105, v104, v106
	v_min_u32_e32 v104, v104, v106
	v_max_u32_e32 v106, v96, v95
	v_min_u32_e32 v95, v96, v95
	v_max_u32_e32 v96, v102, v100
	v_min_u32_e32 v100, v102, v100
	v_max_u32_e32 v102, v99, v98
	v_min_u32_e32 v98, v99, v98
	v_max_u32_e32 v99, v103, v101
	v_min_u32_e32 v101, v103, v101
	v_max_u32_e32 v103, v2, v0
	v_min_u32_e32 v0, v2, v0
	v_max_u32_e32 v2, v1, v96
	v_min_u32_e32 v1, v1, v96
	v_max_u32_e32 v96, v97, v102
	v_min_u32_e32 v97, v97, v102
	v_max_u32_e32 v102, v105, v99
	v_min_u32_e32 v99, v105, v99
	v_max_u32_e32 v105, v106, v103
	v_min_u32_e32 v103, v106, v103
	v_max_u32_e32 v106, v94, v100
	v_min_u32_e32 v94, v94, v100
	v_max_u32_e32 v100, v3, v98
	v_min_u32_e32 v3, v3, v98
	v_max_u32_e32 v98, v104, v101
	v_min_u32_e32 v101, v104, v101
	v_max_u32_e32 v104, v95, v0
	v_min_u32_e32 v0, v95, v0
	v_max_u32_e32 v95, v2, v102
	v_min_u32_e32 v2, v2, v102
	v_max_u32_e32 v102, v96, v105
	v_min_u32_e32 v96, v96, v105
	v_max_u32_e32 v110, v1, v99
	v_min_u32_e32 v1, v1, v99
	v_max_u32_e32 v99, v97, v103
	v_min_u32_e32 v97, v97, v103
	v_max_u32_e32 v111, v106, v98
	v_min_u32_e32 v98, v106, v98
	v_min_u32_e32 v122, v100, v104
	v_max_u32_e32 v123, v94, v101
	v_min_u32_e32 v94, v94, v101
	v_max_u32_e32 v124, v3, v0
	v_min_u32_e32 v0, v3, v0
	v_max_u32_e32 v112, v100, v104
	v_max_u32_e32 v109, v95, v102
	v_min_u32_e32 v108, v95, v102
	v_max_u32_e32 v107, v2, v96
	v_min_u32_e32 v106, v2, v96
	v_max_u32_e32 v105, v110, v99
	v_min_u32_e32 v104, v110, v99
	v_max_u32_e32 v103, v1, v97
	v_min_u32_e32 v102, v1, v97
	v_max_u32_e32 v99, v98, v122
	v_min_u32_e32 v98, v98, v122
	v_max_u32_e32 v97, v123, v124
	v_min_u32_e32 v96, v123, v124
	v_max_u32_e32 v95, v94, v0
	v_min_u32_e32 v94, v94, v0
	global_load_dwordx4 v[0:3], v[4:5], off offset:1328
	global_load_dwordx4 v[122:125], v[4:5], off offset:1312
	s_waitcnt vmcnt(2)
; __device__ __forceinline__ unsigned f2key(float f) { const unsigned u = __float_as_uint(f); return (u & 0x80000000u) ? ~u : (u | 0x80000000u); }
; __device__ __forceinline__ void peer_tile(const Args& A, LAS unsigned char* lds, int tile) {
;     ...
;                 { const bf16_t* sp = QRY + m * 2048 + hp * 128 + 32 * g;
;                   const u32x4 s0 = *(const u32x4*)sp, s1 = *(const u32x4*)(sp + 8), s2 = *(const u32x4*)(sp + 16), s3 = *(const u32x4*)(sp + 24);
;                   const unsigned sw[16] = {s0.x, s0.y, s0.z, s0.w, s1.x, s1.y, s1.z, s1.w, s2.x, s2.y, s2.z, s2.w, s3.x, s3.y, s3.z, s3.w};
; #pragma unroll
;                   for (int i = 0; i < 16; ++i) {
;                       const float lo = (float)__builtin_bit_cast(_Float16, (unsigned short)(sw[i] & 0xffffu)), hi = (float)__builtin_bit_cast(_Float16, (unsigned short)(sw[i] >> 16));
;                       const unsigned klo = (f2key(lo) & ~127u) | (unsigned)(127 - (32 * g + 2 * i)), khi = (f2key(hi) & ~127u) | (unsigned)(127 - (32 * g + 2 * i + 1));
;                       if (i < 8) { k0[2 * i] = klo; k0[2 * i + 1] = khi; } else { k1[2 * (i - 8)] = klo; k1[2 * (i - 8) + 1] = khi; } } }
;     ...
;                 for (int i = 0; i < 16; ++i) L2[p][i] = (g & 2) ? ((g & 1) ? LA[3][p][i] : LA[2][p][i]) : ((g & 1) ? LA[1][p][i] : LA[0][p][i]);
	v_cvt_f32_f16_sdwa v110, v118 dst_sel:DWORD dst_unused:UNUSED_PAD src0_sel:WORD_1
	v_max_u32_e32 v101, v111, v112
	v_min_u32_e32 v100, v111, v112
	v_cvt_f32_f16_e32 v111, v118
	v_not_b32_e32 v112, v110
	v_or_b32_e32 v118, 0x80000000, v110
	v_cmp_gt_i32_e32 vcc, 0, v110
	v_cndmask_b32_e64 v30, v62, v30, s[0:1]
	s_nop 0
	v_cndmask_b32_e32 v110, v118, v112, vcc
	v_not_b32_e32 v112, v111
	v_or_b32_e32 v118, 0x80000000, v111
	v_cmp_gt_i32_e32 vcc, 0, v111
	v_and_b32_e32 v110, 0xffffff80, v110
	v_sub_u32_e32 v110, v110, v15
	v_cndmask_b32_e32 v111, v118, v112, vcc
	v_cvt_f32_f16_sdwa v112, v119 dst_sel:DWORD dst_unused:UNUSED_PAD src0_sel:WORD_1
	v_cvt_f32_f16_e32 v118, v119
	v_and_b32_e32 v111, 0xffffff80, v111
	v_sub_u32_e32 v111, v111, v15
	v_not_b32_e32 v119, v112
	v_or_b32_e32 v126, 0x80000000, v112
	v_cmp_gt_i32_e32 vcc, 0, v112
	v_add_u32_e32 v110, 0x7e, v110
	v_add_u32_e32 v111, 0x7f, v111
	v_cndmask_b32_e32 v112, v126, v119, vcc
	v_not_b32_e32 v119, v118
	v_or_b32_e32 v126, 0x80000000, v118
	v_cmp_gt_i32_e32 vcc, 0, v118
	v_and_b32_e32 v112, 0xffffff80, v112
	v_sub_u32_e32 v112, v112, v14
	v_cndmask_b32_e32 v118, v126, v119, vcc
	v_cvt_f32_f16_sdwa v119, v120 dst_sel:DWORD dst_unused:UNUSED_PAD src0_sel:WORD_1
	v_cvt_f32_f16_e32 v120, v120
	v_and_b32_e32 v118, 0xffffff80, v118
	v_sub_u32_e32 v118, v118, v14
	v_not_b32_e32 v126, v119
	v_or_b32_e32 v127, 0x80000000, v119
	v_cmp_gt_i32_e32 vcc, 0, v119
	v_add_u32_e32 v112, 0x7e, v112
	v_add_u32_e32 v118, 0x7f, v118
	v_cndmask_b32_e32 v119, v127, v126, vcc
	v_not_b32_e32 v126, v120
	v_or_b32_e32 v127, 0x80000000, v120
	v_cmp_gt_i32_e32 vcc, 0, v120
	v_and_b32_e32 v119, 0xffffff80, v119
	v_sub_u32_e32 v119, v119, v12
	v_cndmask_b32_e32 v120, v127, v126, vcc
	v_cvt_f32_f16_sdwa v126, v121 dst_sel:DWORD dst_unused:UNUSED_PAD src0_sel:WORD_1
	v_cvt_f32_f16_e32 v121, v121
	v_and_b32_e32 v120, 0xffffff80, v120
	v_sub_u32_e32 v120, v120, v12
	v_not_b32_e32 v127, v126
	v_or_b32_e32 v128, 0x80000000, v126
	v_cmp_gt_i32_e32 vcc, 0, v126
	v_add_u32_e32 v119, 0x7e, v119
	v_add_u32_e32 v120, 0x7f, v120
	v_cndmask_b32_e32 v126, v128, v127, vcc
	v_not_b32_e32 v127, v121
	v_or_b32_e32 v128, 0x80000000, v121
	v_cmp_gt_i32_e32 vcc, 0, v121
	v_and_b32_e32 v126, 0xffffff80, v126
	v_sub_u32_e32 v126, v126, v10
	v_cndmask_b32_e32 v121, v128, v127, vcc
	v_cvt_f32_f16_sdwa v127, v114 dst_sel:DWORD dst_unused:UNUSED_PAD src0_sel:WORD_1
	v_cvt_f32_f16_e32 v114, v114
	v_and_b32_e32 v121, 0xffffff80, v121
	v_sub_u32_e32 v121, v121, v10
	v_not_b32_e32 v128, v127
	v_or_b32_e32 v129, 0x80000000, v127
	v_cmp_gt_i32_e32 vcc, 0, v127
	v_add_u32_e32 v126, 0x7e, v126
	v_add_u32_e32 v121, 0x7f, v121
	v_cndmask_b32_e32 v127, v129, v128, vcc
	v_not_b32_e32 v128, v114
	v_or_b32_e32 v129, 0x80000000, v114
	v_cmp_gt_i32_e32 vcc, 0, v114
	v_and_b32_e32 v127, 0xffffff80, v127
	v_sub_u32_e32 v127, v127, v8
	v_cndmask_b32_e32 v114, v129, v128, vcc
	v_cvt_f32_f16_sdwa v128, v115 dst_sel:DWORD dst_unused:UNUSED_PAD src0_sel:WORD_1
	v_cvt_f32_f16_e32 v115, v115
	v_and_b32_e32 v114, 0xffffff80, v114
	v_sub_u32_e32 v114, v114, v8
	v_not_b32_e32 v129, v128
	v_or_b32_e32 v130, 0x80000000, v128
	v_cmp_gt_i32_e32 vcc, 0, v128
	v_add_u32_e32 v127, 0x7e, v127
	v_add_u32_e32 v114, 0x7f, v114
	v_cndmask_b32_e32 v128, v130, v129, vcc
	v_not_b32_e32 v129, v115
	v_or_b32_e32 v130, 0x80000000, v115
	v_cmp_gt_i32_e32 vcc, 0, v115
	v_and_b32_e32 v128, 0xffffff80, v128
	v_sub_u32_e32 v128, v128, v16
	v_cndmask_b32_e32 v115, v130, v129, vcc
	v_cvt_f32_f16_sdwa v129, v116 dst_sel:DWORD dst_unused:UNUSED_PAD src0_sel:WORD_1
	v_cvt_f32_f16_e32 v116, v116
	v_and_b32_e32 v115, 0xffffff80, v115
	v_sub_u32_e32 v115, v115, v16
	v_not_b32_e32 v130, v129
	v_or_b32_e32 v131, 0x80000000, v129
	v_cmp_gt_i32_e32 vcc, 0, v129
	v_add_u32_e32 v128, 0x7e, v128
	v_add_u32_e32 v115, 0x7f, v115
	v_cndmask_b32_e32 v129, v131, v130, vcc
	v_not_b32_e32 v130, v116
	v_or_b32_e32 v131, 0x80000000, v116
	v_cmp_gt_i32_e32 vcc, 0, v116
	v_and_b32_e32 v129, 0xffffff80, v129
	v_sub_u32_e32 v129, v129, v17
	v_cndmask_b32_e32 v116, v131, v130, vcc
	v_cvt_f32_f16_sdwa v130, v117 dst_sel:DWORD dst_unused:UNUSED_PAD src0_sel:WORD_1
	v_cvt_f32_f16_e32 v117, v117
	v_and_b32_e32 v116, 0xffffff80, v116
	v_sub_u32_e32 v116, v116, v17
	v_not_b32_e32 v131, v130
	v_or_b32_e32 v132, 0x80000000, v130
	v_cmp_gt_i32_e32 vcc, 0, v130
	v_add_u32_e32 v129, 0x7e, v129
	v_add_u32_e32 v116, 0x7f, v116
	v_cndmask_b32_e32 v130, v132, v131, vcc
	v_not_b32_e32 v131, v117
	v_or_b32_e32 v132, 0x80000000, v117
	v_cmp_gt_i32_e32 vcc, 0, v117
	v_and_b32_e32 v130, 0xffffff80, v130
	v_sub_u32_e32 v130, v130, v18
	v_cndmask_b32_e32 v117, v132, v131, vcc
	s_waitcnt vmcnt(0)
; __device__ __forceinline__ unsigned f2key(float f) { const unsigned u = __float_as_uint(f); return (u & 0x80000000u) ? ~u : (u | 0x80000000u); }
; #define CE_DESC(a, b) do { const unsigned _mx = (a) > (b) ? (a) : (b), _mn = (a) > (b) ? (b) : (a); (a) = _mx; (b) = _mn; } while (0)
; __device__ __forceinline__ void sort16_desc(unsigned (&k)[16]) {
; #pragma unroll
;     for (int size = 2; size <= 16; size <<= 1)
; #pragma unroll
;         for (int stride = size >> 1; stride > 0; stride >>= 1)
; #pragma unroll
;             for (int i = 0; i < 16; ++i) { const int j = i ^ stride;
;                 if (j > i) { if ((i & size) == 0) CE_DESC(k[i], k[j]); else CE_DESC(k[j], k[i]); } }
; }
; __device__ __forceinline__ void peer_tile(const Args& A, LAS unsigned char* lds, int tile) {
;     ...
;                   for (int i = 0; i < 16; ++i) {
;                       const float lo = (float)__builtin_bit_cast(_Float16, (unsigned short)(sw[i] & 0xffffu)), hi = (float)__builtin_bit_cast(_Float16, (unsigned short)(sw[i] >> 16));
;                       const unsigned klo = (f2key(lo) & ~127u) | (unsigned)(127 - (32 * g + 2 * i)), khi = (f2key(hi) & ~127u) | (unsigned)(127 - (32 * g + 2 * i + 1));
;                       if (i < 8) { k0[2 * i] = klo; k0[2 * i + 1] = khi; } else { k1[2 * (i - 8)] = klo; k1[2 * (i - 8) + 1] = khi; } } }
	v_cvt_f32_f16_sdwa v131, v122 dst_sel:DWORD dst_unused:UNUSED_PAD src0_sel:WORD_1
	v_cvt_f32_f16_e32 v122, v122
	v_and_b32_e32 v117, 0xffffff80, v117
	v_sub_u32_e32 v117, v117, v18
	v_not_b32_e32 v132, v131
	v_or_b32_e32 v133, 0x80000000, v131
	v_cmp_gt_i32_e32 vcc, 0, v131
	v_add_u32_e32 v130, 0x7e, v130
	v_add_u32_e32 v117, 0x7f, v117
	v_cndmask_b32_e32 v131, v133, v132, vcc
	v_not_b32_e32 v132, v122
	v_or_b32_e32 v133, 0x80000000, v122
	v_cmp_gt_i32_e32 vcc, 0, v122
	v_and_b32_e32 v131, 0xffffff80, v131
	v_sub_u32_e32 v131, v131, v20
	v_cndmask_b32_e32 v122, v133, v132, vcc
	v_cvt_f32_f16_sdwa v132, v123 dst_sel:DWORD dst_unused:UNUSED_PAD src0_sel:WORD_1
	v_cvt_f32_f16_e32 v123, v123
	v_and_b32_e32 v122, 0xffffff80, v122
	v_sub_u32_e32 v122, v122, v20
	v_not_b32_e32 v133, v132
	v_or_b32_e32 v134, 0x80000000, v132
	v_cmp_gt_i32_e32 vcc, 0, v132
	v_add_u32_e32 v131, 0x7e, v131
	v_add_u32_e32 v122, 0x7f, v122
	v_cndmask_b32_e32 v132, v134, v133, vcc
	v_not_b32_e32 v133, v123
	v_or_b32_e32 v134, 0x80000000, v123
	v_cmp_gt_i32_e32 vcc, 0, v123
	v_and_b32_e32 v132, 0xffffff80, v132
	v_sub_u32_e32 v132, v132, v21
	v_cndmask_b32_e32 v123, v134, v133, vcc
	v_cvt_f32_f16_sdwa v133, v124 dst_sel:DWORD dst_unused:UNUSED_PAD src0_sel:WORD_1
	v_cvt_f32_f16_e32 v124, v124
	v_and_b32_e32 v123, 0xffffff80, v123
	v_sub_u32_e32 v123, v123, v21
	v_not_b32_e32 v134, v133
	v_or_b32_e32 v135, 0x80000000, v133
	v_cmp_gt_i32_e32 vcc, 0, v133
	v_add_u32_e32 v132, 0x7e, v132
	v_add_u32_e32 v123, 0x7f, v123
	v_cndmask_b32_e32 v133, v135, v134, vcc
	v_not_b32_e32 v134, v124
	v_or_b32_e32 v135, 0x80000000, v124
	v_cmp_gt_i32_e32 vcc, 0, v124
	v_and_b32_e32 v133, 0xffffff80, v133
	v_sub_u32_e32 v133, v133, v22
	v_cndmask_b32_e32 v124, v135, v134, vcc
	v_cvt_f32_f16_sdwa v134, v125 dst_sel:DWORD dst_unused:UNUSED_PAD src0_sel:WORD_1
	v_cvt_f32_f16_e32 v125, v125
	v_and_b32_e32 v124, 0xffffff80, v124
	v_sub_u32_e32 v124, v124, v22
	v_not_b32_e32 v135, v134
	v_or_b32_e32 v136, 0x80000000, v134
	v_cmp_gt_i32_e32 vcc, 0, v134
	v_add_u32_e32 v133, 0x7e, v133
	v_add_u32_e32 v124, 0x7f, v124
	v_cndmask_b32_e32 v134, v136, v135, vcc
	v_not_b32_e32 v135, v125
	v_or_b32_e32 v136, 0x80000000, v125
	v_cmp_gt_i32_e32 vcc, 0, v125
	v_and_b32_e32 v134, 0xffffff80, v134
	v_sub_u32_e32 v134, v134, v23
	v_cndmask_b32_e32 v125, v136, v135, vcc
	v_cvt_f32_f16_sdwa v135, v0 dst_sel:DWORD dst_unused:UNUSED_PAD src0_sel:WORD_1
	v_cvt_f32_f16_e32 v0, v0
	v_and_b32_e32 v125, 0xffffff80, v125
	v_sub_u32_e32 v125, v125, v23
	v_not_b32_e32 v136, v135
	v_or_b32_e32 v137, 0x80000000, v135
	v_cmp_gt_i32_e32 vcc, 0, v135
	v_add_u32_e32 v134, 0x7e, v134
	v_add_u32_e32 v125, 0x7f, v125
	v_cndmask_b32_e32 v135, v137, v136, vcc
	v_not_b32_e32 v136, v0
	v_or_b32_e32 v137, 0x80000000, v0
	v_cmp_gt_i32_e32 vcc, 0, v0
	v_and_b32_e32 v135, 0xffffff80, v135
	v_sub_u32_e32 v135, v135, v24
	v_cndmask_b32_e32 v0, v137, v136, vcc
	v_cvt_f32_f16_sdwa v136, v1 dst_sel:DWORD dst_unused:UNUSED_PAD src0_sel:WORD_1
	v_cvt_f32_f16_e32 v1, v1
	v_and_b32_e32 v0, 0xffffff80, v0
	v_sub_u32_e32 v0, v0, v24
	v_not_b32_e32 v137, v136
	v_or_b32_e32 v138, 0x80000000, v136
	v_cmp_gt_i32_e32 vcc, 0, v136
	v_add_u32_e32 v135, 0x7e, v135
	v_add_u32_e32 v0, 0x7f, v0
	v_cndmask_b32_e32 v136, v138, v137, vcc
	v_not_b32_e32 v137, v1
	v_or_b32_e32 v138, 0x80000000, v1
	v_cmp_gt_i32_e32 vcc, 0, v1
	v_and_b32_e32 v136, 0xffffff80, v136
	v_sub_u32_e32 v136, v136, v25
	v_cndmask_b32_e32 v1, v138, v137, vcc
	v_cvt_f32_f16_sdwa v137, v2 dst_sel:DWORD dst_unused:UNUSED_PAD src0_sel:WORD_1
	v_cvt_f32_f16_e32 v2, v2
	v_and_b32_e32 v1, 0xffffff80, v1
	v_sub_u32_e32 v1, v1, v25
	v_not_b32_e32 v138, v137
	v_or_b32_e32 v139, 0x80000000, v137
	v_cmp_gt_i32_e32 vcc, 0, v137
	v_add_u32_e32 v136, 0x7e, v136
	v_add_u32_e32 v1, 0x7f, v1
	v_cndmask_b32_e32 v137, v139, v138, vcc
	v_not_b32_e32 v138, v2
	v_or_b32_e32 v139, 0x80000000, v2
	v_cmp_gt_i32_e32 vcc, 0, v2
	v_and_b32_e32 v137, 0xffffff80, v137
	v_sub_u32_e32 v137, v137, v26
	v_cndmask_b32_e32 v2, v139, v138, vcc
	v_cvt_f32_f16_sdwa v138, v3 dst_sel:DWORD dst_unused:UNUSED_PAD src0_sel:WORD_1
	v_cvt_f32_f16_e32 v3, v3
	v_and_b32_e32 v2, 0xffffff80, v2
	v_sub_u32_e32 v2, v2, v26
	v_not_b32_e32 v139, v138
	v_or_b32_e32 v140, 0x80000000, v138
	v_cmp_gt_i32_e32 vcc, 0, v138
	v_add_u32_e32 v137, 0x7e, v137
	v_add_u32_e32 v2, 0x7f, v2
	v_cndmask_b32_e32 v138, v140, v139, vcc
	v_not_b32_e32 v139, v3
	v_or_b32_e32 v140, 0x80000000, v3
	v_cmp_gt_i32_e32 vcc, 0, v3
	v_and_b32_e32 v138, 0xffffff80, v138
	v_sub_u32_e32 v138, v138, v28
	v_cndmask_b32_e32 v3, v140, v139, vcc
	v_and_b32_e32 v3, 0xffffff80, v3
	v_sub_u32_e32 v3, v3, v28
	v_add_u32_e32 v138, 0x7e, v138
	v_add_u32_e32 v3, 0x7f, v3
	v_max_u32_e32 v139, v111, v110
	v_min_u32_e32 v110, v111, v110
	v_max_u32_e32 v111, v112, v118
	v_min_u32_e32 v112, v112, v118
	v_max_u32_e32 v118, v120, v119
	v_min_u32_e32 v119, v120, v119
	v_max_u32_e32 v120, v126, v121
	v_min_u32_e32 v121, v126, v121
	v_max_u32_e32 v126, v114, v127
	v_min_u32_e32 v114, v114, v127
	v_max_u32_e32 v127, v128, v115
	v_min_u32_e32 v115, v128, v115
	v_max_u32_e32 v128, v116, v129
	v_min_u32_e32 v116, v116, v129
	v_max_u32_e32 v129, v130, v117
	v_min_u32_e32 v117, v130, v117
	v_max_u32_e32 v147, v122, v131
	v_min_u32_e32 v122, v122, v131
	v_max_u32_e32 v131, v132, v123
	v_min_u32_e32 v123, v132, v123
	v_max_u32_e32 v132, v124, v133
	v_min_u32_e32 v124, v124, v133
	v_max_u32_e32 v133, v134, v125
	v_min_u32_e32 v125, v134, v125
	v_max_u32_e32 v134, v0, v135
	v_min_u32_e32 v0, v0, v135
	v_max_u32_e32 v135, v136, v1
	v_min_u32_e32 v1, v136, v1
	v_max_u32_e32 v136, v2, v137
	v_min_u32_e32 v2, v2, v137
; #define CE_DESC(a, b) do { const unsigned _mx = (a) > (b) ? (a) : (b), _mn = (a) > (b) ? (b) : (a); (a) = _mx; (b) = _mn; } while (0)
; __device__ __forceinline__ void sort16_desc(unsigned (&k)[16]) {
; #pragma unroll
;     for (int size = 2; size <= 16; size <<= 1)
; #pragma unroll
;         for (int stride = size >> 1; stride > 0; stride >>= 1)
; #pragma unroll
;             for (int i = 0; i < 16; ++i) { const int j = i ^ stride;
;                 if (j > i) { if ((i & size) == 0) CE_DESC(k[i], k[j]); else CE_DESC(k[j], k[i]); } }
; }
	v_max_u32_e32 v137, v138, v3
	v_min_u32_e32 v3, v138, v3
	v_max_u32_e32 v130, v139, v112
	v_min_u32_e32 v112, v139, v112
	v_max_u32_e32 v139, v110, v111
	v_min_u32_e32 v110, v110, v111
	v_max_u32_e32 v111, v121, v118
	v_min_u32_e32 v118, v121, v118
	v_max_u32_e32 v121, v120, v119
	v_min_u32_e32 v119, v120, v119
	v_max_u32_e32 v120, v126, v115
	v_min_u32_e32 v115, v126, v115
	v_max_u32_e32 v126, v114, v127
	v_min_u32_e32 v114, v114, v127
	v_max_u32_e32 v127, v117, v128
	v_min_u32_e32 v117, v117, v128
	v_max_u32_e32 v128, v129, v116
	v_min_u32_e32 v116, v129, v116
	v_max_u32_e32 v138, v147, v123
	v_min_u32_e32 v123, v147, v123
	v_max_u32_e32 v147, v122, v131
	v_min_u32_e32 v122, v122, v131
	v_max_u32_e32 v131, v125, v132
	v_min_u32_e32 v125, v125, v132
	v_max_u32_e32 v132, v133, v124
	v_min_u32_e32 v124, v133, v124
	v_max_u32_e32 v133, v134, v1
	v_min_u32_e32 v1, v134, v1
	v_max_u32_e32 v134, v0, v135
	v_min_u32_e32 v0, v0, v135
	v_max_u32_e32 v135, v3, v136
	v_min_u32_e32 v3, v3, v136
	v_max_u32_e32 v136, v137, v2
	v_min_u32_e32 v2, v137, v2
	v_max_u32_e32 v129, v130, v139
	v_min_u32_e32 v130, v130, v139
	v_max_u32_e32 v139, v112, v110
	v_min_u32_e32 v110, v112, v110
	v_max_u32_e32 v112, v119, v118
	v_min_u32_e32 v118, v119, v118
	v_max_u32_e32 v119, v121, v111
	v_min_u32_e32 v111, v121, v111
	v_max_u32_e32 v121, v120, v126
	v_min_u32_e32 v120, v120, v126
	v_max_u32_e32 v126, v115, v114
	v_min_u32_e32 v114, v115, v114
	v_max_u32_e32 v115, v116, v117
	v_min_u32_e32 v116, v116, v117
	v_max_u32_e32 v117, v128, v127
	v_min_u32_e32 v127, v128, v127
	v_max_u32_e32 v137, v138, v147
	v_min_u32_e32 v138, v138, v147
	v_max_u32_e32 v147, v123, v122
	v_min_u32_e32 v122, v123, v122
	v_max_u32_e32 v123, v124, v125
	v_min_u32_e32 v124, v124, v125
	v_max_u32_e32 v125, v132, v131
	v_min_u32_e32 v131, v132, v131
	v_max_u32_e32 v132, v133, v134
	v_min_u32_e32 v133, v133, v134
	v_max_u32_e32 v134, v1, v0
	v_min_u32_e32 v0, v1, v0
	v_max_u32_e32 v1, v2, v3
	v_min_u32_e32 v2, v2, v3
	v_max_u32_e32 v3, v136, v135
	v_min_u32_e32 v135, v136, v135
	v_max_u32_e32 v128, v129, v118
	v_min_u32_e32 v118, v129, v118
	v_max_u32_e32 v129, v130, v112
	v_min_u32_e32 v112, v130, v112
	v_max_u32_e32 v130, v139, v111
	v_min_u32_e32 v111, v139, v111
	v_max_u32_e32 v139, v110, v119
	v_min_u32_e32 v110, v110, v119
	v_max_u32_e32 v119, v116, v121
	v_min_u32_e32 v116, v116, v121
	v_max_u32_e32 v121, v115, v120
	v_min_u32_e32 v115, v115, v120
	v_max_u32_e32 v120, v127, v126
	v_min_u32_e32 v126, v127, v126
	v_max_u32_e32 v127, v117, v114
	v_min_u32_e32 v114, v117, v114
	v_max_u32_e32 v136, v137, v124
	v_min_u32_e32 v124, v137, v124
	v_max_u32_e32 v137, v138, v123
	v_min_u32_e32 v123, v138, v123
	v_max_u32_e32 v138, v147, v131
	v_min_u32_e32 v131, v147, v131
	v_max_u32_e32 v147, v122, v125
	v_min_u32_e32 v122, v122, v125
	v_max_u32_e32 v125, v2, v132
	v_min_u32_e32 v2, v2, v132
	v_max_u32_e32 v132, v1, v133
	v_min_u32_e32 v1, v1, v133
	v_max_u32_e32 v133, v135, v134
	v_min_u32_e32 v134, v135, v134
	v_max_u32_e32 v135, v3, v0
	v_min_u32_e32 v0, v3, v0
	v_max_u32_e32 v117, v128, v130
	v_min_u32_e32 v128, v128, v130
	v_max_u32_e32 v130, v129, v139
	v_min_u32_e32 v129, v129, v139
	v_max_u32_e32 v139, v118, v111
	v_min_u32_e32 v111, v118, v111
	v_max_u32_e32 v118, v112, v110
	v_min_u32_e32 v110, v112, v110
	v_max_u32_e32 v112, v126, v116
	v_min_u32_e32 v116, v126, v116
	v_max_u32_e32 v126, v114, v115
	v_min_u32_e32 v114, v114, v115
	v_max_u32_e32 v115, v120, v119
	v_min_u32_e32 v119, v120, v119
	v_max_u32_e32 v120, v127, v121
	v_min_u32_e32 v121, v127, v121
	v_max_u32_e32 v3, v136, v138
	v_min_u32_e32 v136, v136, v138
	v_max_u32_e32 v138, v137, v147
	v_min_u32_e32 v137, v137, v147
	v_max_u32_e32 v147, v124, v131
	v_min_u32_e32 v124, v124, v131
	v_max_u32_e32 v131, v123, v122
	v_min_u32_e32 v122, v123, v122
	v_max_u32_e32 v123, v134, v2
	v_min_u32_e32 v2, v134, v2
	v_max_u32_e32 v134, v0, v1
	v_min_u32_e32 v0, v0, v1
	v_max_u32_e32 v1, v133, v125
	v_min_u32_e32 v125, v133, v125
	v_max_u32_e32 v133, v135, v132
	v_min_u32_e32 v132, v135, v132
	v_max_u32_e32 v127, v117, v130
	v_min_u32_e32 v117, v117, v130
	v_max_u32_e32 v130, v128, v129
	v_min_u32_e32 v128, v128, v129
	v_max_u32_e32 v129, v139, v118
	v_min_u32_e32 v118, v139, v118
	v_max_u32_e32 v139, v111, v110
	v_min_u32_e32 v110, v111, v110
	v_max_u32_e32 v111, v114, v116
	v_min_u32_e32 v114, v114, v116
	v_max_u32_e32 v116, v126, v112
	v_min_u32_e32 v112, v126, v112
	v_max_u32_e32 v126, v121, v119
	v_min_u32_e32 v119, v121, v119
	v_max_u32_e32 v121, v120, v115
	v_min_u32_e32 v115, v120, v115
	v_max_u32_e32 v135, v3, v138
	v_min_u32_e32 v3, v3, v138
	v_max_u32_e32 v138, v136, v137
	v_min_u32_e32 v136, v136, v137
	v_max_u32_e32 v137, v147, v131
	v_min_u32_e32 v131, v147, v131
	v_max_u32_e32 v147, v124, v122
	v_min_u32_e32 v122, v124, v122
	v_max_u32_e32 v124, v0, v2
	v_min_u32_e32 v0, v0, v2
	v_max_u32_e32 v2, v134, v123
	v_min_u32_e32 v123, v134, v123
	v_max_u32_e32 v134, v132, v125
	v_min_u32_e32 v125, v132, v125
	v_max_u32_e32 v132, v133, v1
	v_min_u32_e32 v1, v133, v1
	v_max_u32_e32 v120, v127, v114
	v_min_u32_e32 v114, v127, v114
	v_max_u32_e32 v127, v117, v111
	v_min_u32_e32 v111, v117, v111
	v_max_u32_e32 v117, v130, v112
	v_min_u32_e32 v112, v130, v112
	v_max_u32_e32 v130, v128, v116
	v_min_u32_e32 v116, v128, v116
	v_max_u32_e32 v128, v129, v119
	v_min_u32_e32 v119, v129, v119
	v_max_u32_e32 v129, v118, v126
	v_min_u32_e32 v118, v118, v126
	v_max_u32_e32 v126, v139, v115
	v_min_u32_e32 v115, v139, v115
	v_max_u32_e32 v139, v110, v121
	v_min_u32_e32 v110, v110, v121
	v_max_u32_e32 v133, v135, v0
	v_min_u32_e32 v0, v135, v0
; #define CE_DESC(a, b) do { const unsigned _mx = (a) > (b) ? (a) : (b), _mn = (a) > (b) ? (b) : (a); (a) = _mx; (b) = _mn; } while (0)
; __device__ __forceinline__ void sort16_desc(unsigned (&k)[16]) {
; #pragma unroll
;     for (int size = 2; size <= 16; size <<= 1)
; #pragma unroll
;         for (int stride = size >> 1; stride > 0; stride >>= 1)
; #pragma unroll
;             for (int i = 0; i < 16; ++i) { const int j = i ^ stride;
;                 if (j > i) { if ((i & size) == 0) CE_DESC(k[i], k[j]); else CE_DESC(k[j], k[i]); } }
; }
; __device__ __forceinline__ void merge16(unsigned (&a)[16], const unsigned (&b)[16]) {
; #pragma unroll
;     for (int i = 0; i < 16; ++i) a[i] = a[i] > b[15 - i] ? a[i] : b[15 - i];
; #pragma unroll
;     for (int stride = 8; stride > 0; stride >>= 1)
; #pragma unroll
;         for (int i = 0; i < 16; ++i) { const int j = i ^ stride; if (j > i) CE_DESC(a[i], a[j]); }
; }
; __device__ __forceinline__ void peer_tile(const Args& A, LAS unsigned char* lds, int tile) {
;     ...
;                 for (int msk = 16; msk <= 32; msk <<= 1) {
; #pragma unroll
;                     for (int i = 0; i < 16; ++i) k1[i] = (unsigned)__shfl_xor((int)k0[i], msk);
;                     merge16(k0, k1); }
	v_max_u32_e32 v135, v3, v124
	v_min_u32_e32 v3, v3, v124
	v_max_u32_e32 v124, v138, v123
	v_min_u32_e32 v123, v138, v123
	v_max_u32_e32 v138, v136, v2
	v_min_u32_e32 v2, v136, v2
	v_max_u32_e32 v136, v137, v125
	v_min_u32_e32 v125, v137, v125
	v_max_u32_e32 v137, v131, v134
	v_min_u32_e32 v131, v131, v134
	v_max_u32_e32 v134, v147, v1
	v_min_u32_e32 v1, v147, v1
	v_max_u32_e32 v147, v122, v132
	v_min_u32_e32 v122, v122, v132
	v_max_u32_e32 v121, v120, v128
	v_min_u32_e32 v120, v120, v128
	v_max_u32_e32 v128, v127, v129
	v_min_u32_e32 v127, v127, v129
	v_max_u32_e32 v129, v117, v126
	v_min_u32_e32 v117, v117, v126
	v_max_u32_e32 v126, v130, v139
	v_min_u32_e32 v130, v130, v139
	v_max_u32_e32 v139, v114, v119
	v_min_u32_e32 v114, v114, v119
	v_max_u32_e32 v119, v111, v118
	v_min_u32_e32 v111, v111, v118
	v_max_u32_e32 v118, v112, v115
	v_min_u32_e32 v112, v112, v115
	v_max_u32_e32 v115, v116, v110
	v_min_u32_e32 v110, v116, v110
	v_max_u32_e32 v132, v133, v136
	v_min_u32_e32 v133, v133, v136
	v_max_u32_e32 v136, v135, v137
	v_min_u32_e32 v135, v135, v137
	v_max_u32_e32 v137, v124, v134
	v_min_u32_e32 v124, v124, v134
	v_max_u32_e32 v134, v138, v147
	v_min_u32_e32 v138, v138, v147
	v_max_u32_e32 v147, v0, v125
	v_min_u32_e32 v0, v0, v125
	v_max_u32_e32 v125, v3, v131
	v_min_u32_e32 v3, v3, v131
	v_max_u32_e32 v131, v123, v1
	v_min_u32_e32 v1, v123, v1
	v_max_u32_e32 v123, v2, v122
	v_min_u32_e32 v2, v2, v122
	v_max_u32_e32 v116, v121, v129
	v_min_u32_e32 v121, v121, v129
	v_max_u32_e32 v129, v128, v126
	v_min_u32_e32 v126, v128, v126
	v_max_u32_e32 v128, v120, v117
	v_min_u32_e32 v117, v120, v117
	v_max_u32_e32 v120, v127, v130
	v_min_u32_e32 v127, v127, v130
	v_max_u32_e32 v130, v139, v118
	v_min_u32_e32 v118, v139, v118
	v_max_u32_e32 v139, v119, v115
	v_min_u32_e32 v115, v119, v115
	v_max_u32_e32 v119, v114, v112
	v_min_u32_e32 v112, v114, v112
	v_max_u32_e32 v114, v111, v110
	v_min_u32_e32 v110, v111, v110
	v_max_u32_e32 v122, v132, v137
	v_min_u32_e32 v132, v132, v137
	v_max_u32_e32 v137, v136, v134
	v_min_u32_e32 v134, v136, v134
	v_max_u32_e32 v136, v133, v124
	v_min_u32_e32 v124, v133, v124
	v_max_u32_e32 v133, v135, v138
	v_min_u32_e32 v135, v135, v138
	v_max_u32_e32 v138, v147, v131
	v_min_u32_e32 v131, v147, v131
	v_max_u32_e32 v147, v125, v123
	v_min_u32_e32 v123, v125, v123
	v_max_u32_e32 v125, v0, v1
	v_min_u32_e32 v0, v0, v1
	v_max_u32_e32 v1, v3, v2
	v_min_u32_e32 v2, v3, v2
	v_min_u32_e32 v111, v116, v129
	v_min_u32_e32 v140, v121, v126
	v_min_u32_e32 v141, v128, v120
	v_min_u32_e32 v142, v117, v127
	v_min_u32_e32 v143, v130, v139
	v_min_u32_e32 v144, v118, v115
	v_min_u32_e32 v145, v119, v114
	v_min_u32_e32 v146, v112, v110
	v_min_u32_e32 v3, v122, v137
	v_min_u32_e32 v148, v132, v134
	v_min_u32_e32 v149, v136, v133
	v_min_u32_e32 v150, v124, v135
	v_min_u32_e32 v151, v138, v147
	v_min_u32_e32 v152, v131, v123
	v_min_u32_e32 v153, v125, v1
	v_min_u32_e32 v154, v0, v2
	v_max3_u32 v116, v116, v129, v154
	v_max3_u32 v0, v111, v0, v2
	v_max3_u32 v2, v121, v126, v153
	v_max3_u32 v1, v140, v125, v1
	v_max3_u32 v111, v128, v120, v152
	v_max3_u32 v120, v141, v131, v123
	v_max3_u32 v117, v117, v127, v151
	v_max3_u32 v121, v142, v138, v147
	v_max3_u32 v123, v130, v139, v150
	v_max3_u32 v124, v143, v124, v135
	v_max3_u32 v115, v118, v115, v149
	v_max3_u32 v118, v144, v136, v133
	v_max3_u32 v114, v119, v114, v148
	v_max3_u32 v119, v145, v132, v134
	v_max3_u32 v3, v112, v110, v3
	v_max3_u32 v110, v146, v122, v137
	v_max_u32_e32 v112, v116, v123
	v_min_u32_e32 v116, v116, v123
	v_max_u32_e32 v122, v0, v124
	v_min_u32_e32 v0, v0, v124
	v_max_u32_e32 v123, v2, v115
	v_min_u32_e32 v2, v2, v115
	v_max_u32_e32 v115, v1, v118
	v_min_u32_e32 v1, v1, v118
	v_max_u32_e32 v118, v111, v114
	v_min_u32_e32 v111, v111, v114
	v_max_u32_e32 v114, v120, v119
	v_min_u32_e32 v119, v120, v119
	v_max_u32_e32 v120, v117, v3
	v_min_u32_e32 v3, v117, v3
	v_max_u32_e32 v117, v121, v110
	v_min_u32_e32 v110, v121, v110
	v_max_u32_e32 v121, v112, v118
	v_min_u32_e32 v112, v112, v118
	v_max_u32_e32 v118, v122, v114
	v_min_u32_e32 v114, v122, v114
	v_max_u32_e32 v122, v123, v120
	v_min_u32_e32 v120, v123, v120
	v_max_u32_e32 v123, v115, v117
	v_min_u32_e32 v115, v115, v117
	v_max_u32_e32 v117, v116, v111
	v_min_u32_e32 v111, v116, v111
	v_max_u32_e32 v116, v0, v119
	v_min_u32_e32 v0, v0, v119
	v_max_u32_e32 v119, v2, v3
	v_min_u32_e32 v2, v2, v3
	v_max_u32_e32 v3, v1, v110
	v_min_u32_e32 v1, v1, v110
	v_max_u32_e32 v110, v121, v122
	v_min_u32_e32 v121, v121, v122
	v_max_u32_e32 v122, v118, v123
	v_min_u32_e32 v118, v118, v123
	v_max_u32_e32 v123, v112, v120
	v_min_u32_e32 v112, v112, v120
	v_max_u32_e32 v120, v114, v115
	v_min_u32_e32 v114, v114, v115
	v_max_u32_e32 v115, v117, v119
	v_min_u32_e32 v117, v117, v119
	v_max_u32_e32 v119, v116, v3
	v_min_u32_e32 v3, v116, v3
	v_max_u32_e32 v116, v111, v2
	v_min_u32_e32 v2, v111, v2
	v_max_u32_e32 v111, v0, v1
	v_min_u32_e32 v0, v0, v1
	v_max_u32_e32 v1, v110, v122
	v_min_u32_e32 v110, v110, v122
	v_max_u32_e32 v122, v121, v118
	v_min_u32_e32 v118, v121, v118
	v_max_u32_e32 v121, v123, v120
	v_min_u32_e32 v120, v123, v120
	v_max_u32_e32 v123, v112, v114
	v_min_u32_e32 v112, v112, v114
	v_max_u32_e32 v114, v115, v119
	v_min_u32_e32 v115, v115, v119
	v_max_u32_e32 v119, v117, v3
	v_min_u32_e32 v3, v117, v3
	v_max_u32_e32 v117, v116, v111
	v_min_u32_e32 v111, v116, v111
	v_max_u32_e32 v116, v2, v0
	v_min_u32_e32 v0, v2, v0
	ds_bpermute_b32 v2, v27, v1
	ds_bpermute_b32 v124, v27, v110
	ds_bpermute_b32 v125, v27, v122
	ds_bpermute_b32 v126, v27, v118
	ds_bpermute_b32 v127, v27, v121
	ds_bpermute_b32 v128, v27, v120
	ds_bpermute_b32 v129, v27, v123
	ds_bpermute_b32 v130, v27, v112
	ds_bpermute_b32 v131, v27, v114
	ds_bpermute_b32 v132, v27, v115
	ds_bpermute_b32 v133, v27, v119
	ds_bpermute_b32 v134, v27, v0
	ds_bpermute_b32 v135, v27, v116
	ds_bpermute_b32 v136, v27, v111
	ds_bpermute_b32 v137, v27, v117
	ds_bpermute_b32 v138, v27, v3
	s_waitcnt lgkmcnt(4)
; #define CE_DESC(a, b) do { const unsigned _mx = (a) > (b) ? (a) : (b), _mn = (a) > (b) ? (b) : (a); (a) = _mx; (b) = _mn; } while (0)
; __device__ __forceinline__ void merge16(unsigned (&a)[16], const unsigned (&b)[16]) {
; #pragma unroll
;     for (int i = 0; i < 16; ++i) a[i] = a[i] > b[15 - i] ? a[i] : b[15 - i];
; #pragma unroll
;     for (int stride = 8; stride > 0; stride >>= 1)
; #pragma unroll
;         for (int i = 0; i < 16; ++i) { const int j = i ^ stride; if (j > i) CE_DESC(a[i], a[j]); }
; }
; __device__ __forceinline__ void peer_tile(const Args& A, LAS unsigned char* lds, int tile) {
;     ...
;                 { const bf16_t* sp = QRY + m * 2048 + hp * 128 + 32 * g;
;                   const u32x4 s0 = *(const u32x4*)sp, s1 = *(const u32x4*)(sp + 8), s2 = *(const u32x4*)(sp + 16), s3 = *(const u32x4*)(sp + 24);
;     ...
;                 for (int msk = 16; msk <= 32; msk <<= 1) {
; #pragma unroll
;                     for (int i = 0; i < 16; ++i) k1[i] = (unsigned)__shfl_xor((int)k0[i], msk);
;                     merge16(k0, k1); }
	v_max_u32_e32 v1, v1, v134
	s_waitcnt lgkmcnt(3)
	v_max_u32_e32 v110, v110, v135
	s_waitcnt lgkmcnt(2)
	v_max_u32_e32 v122, v122, v136
	s_waitcnt lgkmcnt(1)
	v_max_u32_e32 v118, v118, v137
	s_waitcnt lgkmcnt(0)
	v_max_u32_e32 v121, v121, v138
	v_max_u32_e32 v120, v120, v133
	v_max_u32_e32 v123, v123, v132
	v_max_u32_e32 v112, v112, v131
	v_max_u32_e32 v114, v114, v130
	v_max_u32_e32 v115, v115, v129
	v_max_u32_e32 v119, v119, v128
	v_max_u32_e32 v3, v3, v127
	v_max_u32_e32 v117, v117, v126
	v_max_u32_e32 v111, v111, v125
	v_max_u32_e32 v116, v116, v124
	v_max_u32_e32 v0, v0, v2
	v_max_u32_e32 v2, v1, v114
	v_min_u32_e32 v1, v1, v114
	v_max_u32_e32 v114, v110, v115
	v_min_u32_e32 v110, v110, v115
	v_max_u32_e32 v115, v122, v119
	v_min_u32_e32 v119, v122, v119
	v_max_u32_e32 v122, v118, v3
	v_min_u32_e32 v3, v118, v3
	v_max_u32_e32 v118, v121, v117
	v_min_u32_e32 v117, v121, v117
	v_max_u32_e32 v121, v120, v111
	v_min_u32_e32 v111, v120, v111
	v_max_u32_e32 v120, v123, v116
	v_min_u32_e32 v116, v123, v116
	v_max_u32_e32 v123, v112, v0
	v_min_u32_e32 v0, v112, v0
	v_max_u32_e32 v112, v2, v118
	v_min_u32_e32 v2, v2, v118
	v_max_u32_e32 v118, v114, v121
	v_min_u32_e32 v114, v114, v121
	v_max_u32_e32 v121, v115, v120
	v_min_u32_e32 v115, v115, v120
	v_max_u32_e32 v120, v122, v123
	v_min_u32_e32 v122, v122, v123
	v_max_u32_e32 v123, v1, v117
	v_min_u32_e32 v1, v1, v117
	v_max_u32_e32 v117, v110, v111
	v_min_u32_e32 v110, v110, v111
	v_max_u32_e32 v111, v119, v116
	v_min_u32_e32 v116, v119, v116
	v_max_u32_e32 v119, v3, v0
	v_min_u32_e32 v0, v3, v0
	v_max_u32_e32 v3, v112, v121
	v_min_u32_e32 v112, v112, v121
	v_max_u32_e32 v121, v118, v120
	v_min_u32_e32 v118, v118, v120
	v_max_u32_e32 v120, v2, v115
	v_min_u32_e32 v2, v2, v115
	v_max_u32_e32 v115, v114, v122
	v_min_u32_e32 v114, v114, v122
	v_max_u32_e32 v122, v123, v111
	v_min_u32_e32 v111, v123, v111
	v_max_u32_e32 v123, v117, v119
	v_min_u32_e32 v117, v117, v119
	v_max_u32_e32 v119, v1, v116
	v_min_u32_e32 v1, v1, v116
	v_max_u32_e32 v116, v110, v0
	v_min_u32_e32 v0, v110, v0
	v_max_u32_e32 v110, v3, v121
	v_min_u32_e32 v3, v3, v121
	v_max_u32_e32 v121, v112, v118
	v_min_u32_e32 v112, v112, v118
	v_max_u32_e32 v118, v120, v115
	v_min_u32_e32 v115, v120, v115
	v_max_u32_e32 v120, v2, v114
	v_min_u32_e32 v2, v2, v114
	v_max_u32_e32 v114, v122, v123
	v_min_u32_e32 v122, v122, v123
	v_max_u32_e32 v123, v111, v117
	v_min_u32_e32 v111, v111, v117
	v_max_u32_e32 v117, v119, v116
	v_min_u32_e32 v116, v119, v116
	v_max_u32_e32 v119, v1, v0
	v_min_u32_e32 v0, v1, v0
	ds_bpermute_b32 v128, v29, v0
	ds_bpermute_b32 v1, v29, v110
	ds_bpermute_b32 v124, v29, v3
	ds_bpermute_b32 v125, v29, v121
	ds_bpermute_b32 v126, v29, v112
	s_waitcnt lgkmcnt(4)
	v_max_u32_e32 v110, v110, v128
	global_load_dwordx4 v[128:131], v[4:5], off offset:1552
	global_load_dwordx4 v[132:135], v[4:5], off offset:1536
	ds_bpermute_b32 v127, v29, v118
	ds_bpermute_b32 v136, v29, v115
	ds_bpermute_b32 v137, v29, v120
	ds_bpermute_b32 v138, v29, v2
	ds_bpermute_b32 v139, v29, v114
	ds_bpermute_b32 v140, v29, v122
	ds_bpermute_b32 v141, v29, v123
	ds_bpermute_b32 v142, v29, v111
	ds_bpermute_b32 v143, v29, v117
	ds_bpermute_b32 v144, v29, v119
	ds_bpermute_b32 v145, v29, v116
	s_waitcnt lgkmcnt(4)
	v_max_u32_e32 v115, v115, v141
	s_waitcnt lgkmcnt(3)
	v_max_u32_e32 v118, v118, v142
	s_waitcnt lgkmcnt(2)
	v_max_u32_e32 v112, v112, v143
	s_waitcnt lgkmcnt(1)
	v_max_u32_e32 v3, v3, v144
	s_waitcnt lgkmcnt(0)
	v_max_u32_e32 v121, v121, v145
	v_max_u32_e32 v120, v120, v140
	v_max_u32_e32 v2, v2, v139
	v_max_u32_e32 v114, v114, v138
	v_max_u32_e32 v122, v122, v137
	v_max_u32_e32 v123, v123, v136
	v_max_u32_e32 v111, v111, v127
	v_max_u32_e32 v117, v117, v126
	v_max_u32_e32 v116, v116, v125
	v_max_u32_e32 v119, v119, v124
	v_max_u32_e32 v0, v0, v1
	v_max_u32_e32 v1, v110, v114
	v_min_u32_e32 v110, v110, v114
	v_max_u32_e32 v114, v3, v122
	v_min_u32_e32 v3, v3, v122
	v_max_u32_e32 v122, v121, v123
	v_min_u32_e32 v121, v121, v123
	v_max_u32_e32 v123, v112, v111
	v_min_u32_e32 v111, v112, v111
	v_max_u32_e32 v112, v118, v117
	v_min_u32_e32 v117, v118, v117
	v_max_u32_e32 v118, v115, v116
	v_min_u32_e32 v115, v115, v116
	v_max_u32_e32 v116, v120, v119
	v_min_u32_e32 v119, v120, v119
	v_max_u32_e32 v120, v2, v0
	v_min_u32_e32 v0, v2, v0
	v_max_u32_e32 v2, v1, v112
	v_min_u32_e32 v1, v1, v112
	v_max_u32_e32 v112, v114, v118
	v_min_u32_e32 v114, v114, v118
	v_max_u32_e32 v118, v122, v116
	v_min_u32_e32 v116, v122, v116
	v_max_u32_e32 v122, v123, v120
	v_min_u32_e32 v120, v123, v120
	v_max_u32_e32 v123, v110, v117
	v_min_u32_e32 v110, v110, v117
	v_max_u32_e32 v117, v3, v115
	v_min_u32_e32 v3, v3, v115
	v_max_u32_e32 v115, v121, v119
	v_min_u32_e32 v119, v121, v119
	v_max_u32_e32 v121, v111, v0
	v_min_u32_e32 v0, v111, v0
	v_max_u32_e32 v111, v2, v118
	v_min_u32_e32 v2, v2, v118
	v_max_u32_e32 v118, v112, v122
	v_min_u32_e32 v112, v112, v122
	v_max_u32_e32 v127, v1, v116
	v_min_u32_e32 v1, v1, v116
	v_max_u32_e32 v116, v114, v120
	v_min_u32_e32 v114, v114, v120
	v_max_u32_e32 v136, v123, v115
	v_min_u32_e32 v115, v123, v115
	v_max_u32_e32 v137, v117, v121
	v_min_u32_e32 v138, v117, v121
	v_max_u32_e32 v139, v110, v119
	v_min_u32_e32 v110, v110, v119
	v_max_u32_e32 v140, v3, v0
	v_min_u32_e32 v0, v3, v0
	v_max_u32_e32 v126, v111, v118
	v_min_u32_e32 v125, v111, v118
	v_max_u32_e32 v124, v2, v112
	v_min_u32_e32 v123, v2, v112
	v_max_u32_e32 v122, v127, v116
	v_min_u32_e32 v121, v127, v116
	v_max_u32_e32 v120, v1, v114
	v_min_u32_e32 v119, v1, v114
	v_max_u32_e32 v118, v136, v137
	v_min_u32_e32 v117, v136, v137
	v_max_u32_e32 v116, v115, v138
	v_min_u32_e32 v115, v115, v138
	v_max_u32_e32 v114, v139, v140
	v_min_u32_e32 v112, v139, v140
	v_max_u32_e32 v111, v110, v0
	v_min_u32_e32 v110, v110, v0
	global_load_dwordx4 v[0:3], v[4:5], off offset:1584
	global_load_dwordx4 v[136:139], v[4:5], off offset:1568
	s_waitcnt vmcnt(2)
; __device__ __forceinline__ unsigned f2key(float f) { const unsigned u = __float_as_uint(f); return (u & 0x80000000u) ? ~u : (u | 0x80000000u); }
; __device__ __forceinline__ void peer_tile(const Args& A, LAS unsigned char* lds, int tile) {
;     ...
;                 { const bf16_t* sp = QRY + m * 2048 + hp * 128 + 32 * g;
;                   const u32x4 s0 = *(const u32x4*)sp, s1 = *(const u32x4*)(sp + 8), s2 = *(const u32x4*)(sp + 16), s3 = *(const u32x4*)(sp + 24);
;                   const unsigned sw[16] = {s0.x, s0.y, s0.z, s0.w, s1.x, s1.y, s1.z, s1.w, s2.x, s2.y, s2.z, s2.w, s3.x, s3.y, s3.z, s3.w};
; #pragma unroll
;                   for (int i = 0; i < 16; ++i) {
;                       const float lo = (float)__builtin_bit_cast(_Float16, (unsigned short)(sw[i] & 0xffffu)), hi = (float)__builtin_bit_cast(_Float16, (unsigned short)(sw[i] >> 16));
;                       const unsigned klo = (f2key(lo) & ~127u) | (unsigned)(127 - (32 * g + 2 * i)), khi = (f2key(hi) & ~127u) | (unsigned)(127 - (32 * g + 2 * i + 1));
;                       if (i < 8) { k0[2 * i] = klo; k0[2 * i + 1] = khi; } else { k1[2 * (i - 8)] = klo; k1[2 * (i - 8) + 1] = khi; } } }
	v_cvt_f32_f16_sdwa v127, v132 dst_sel:DWORD dst_unused:UNUSED_PAD src0_sel:WORD_1
	v_cvt_f32_f16_e32 v132, v132
	v_not_b32_e32 v140, v127
	v_or_b32_e32 v141, 0x80000000, v127
	v_cmp_gt_i32_e32 vcc, 0, v127
	s_nop 1
	v_cndmask_b32_e32 v127, v141, v140, vcc
	v_not_b32_e32 v140, v132
	v_or_b32_e32 v141, 0x80000000, v132
	v_cmp_gt_i32_e32 vcc, 0, v132
	v_and_b32_e32 v127, 0xffffff80, v127
	v_sub_u32_e32 v127, v127, v15
	v_cndmask_b32_e32 v132, v141, v140, vcc
	v_cvt_f32_f16_sdwa v140, v133 dst_sel:DWORD dst_unused:UNUSED_PAD src0_sel:WORD_1
	v_cvt_f32_f16_e32 v133, v133
	v_and_b32_e32 v132, 0xffffff80, v132
	v_sub_u32_e32 v132, v132, v15
	v_not_b32_e32 v141, v140
	v_or_b32_e32 v142, 0x80000000, v140
	v_cmp_gt_i32_e32 vcc, 0, v140
	v_add_u32_e32 v127, 0x7e, v127
	v_add_u32_e32 v132, 0x7f, v132
	v_cndmask_b32_e32 v140, v142, v141, vcc
	v_not_b32_e32 v141, v133
	v_or_b32_e32 v142, 0x80000000, v133
	v_cmp_gt_i32_e32 vcc, 0, v133
	v_and_b32_e32 v140, 0xffffff80, v140
	v_sub_u32_e32 v140, v140, v14
	v_cndmask_b32_e32 v133, v142, v141, vcc
	v_cvt_f32_f16_sdwa v141, v134 dst_sel:DWORD dst_unused:UNUSED_PAD src0_sel:WORD_1
	v_cvt_f32_f16_e32 v134, v134
	v_and_b32_e32 v133, 0xffffff80, v133
	v_sub_u32_e32 v133, v133, v14
	v_not_b32_e32 v142, v141
	v_or_b32_e32 v143, 0x80000000, v141
	v_cmp_gt_i32_e32 vcc, 0, v141
	v_add_u32_e32 v140, 0x7e, v140
	v_add_u32_e32 v133, 0x7f, v133
	v_cndmask_b32_e32 v141, v143, v142, vcc
	v_not_b32_e32 v142, v134
	v_or_b32_e32 v143, 0x80000000, v134
	v_cmp_gt_i32_e32 vcc, 0, v134
	v_and_b32_e32 v141, 0xffffff80, v141
	v_sub_u32_e32 v141, v141, v12
	v_cndmask_b32_e32 v134, v143, v142, vcc
	v_cvt_f32_f16_sdwa v142, v135 dst_sel:DWORD dst_unused:UNUSED_PAD src0_sel:WORD_1
	v_cvt_f32_f16_e32 v135, v135
	v_and_b32_e32 v134, 0xffffff80, v134
	v_sub_u32_e32 v134, v134, v12
	v_not_b32_e32 v143, v142
	v_or_b32_e32 v144, 0x80000000, v142
	v_cmp_gt_i32_e32 vcc, 0, v142
	v_add_u32_e32 v141, 0x7e, v141
	v_add_u32_e32 v134, 0x7f, v134
	v_cndmask_b32_e32 v142, v144, v143, vcc
	v_not_b32_e32 v143, v135
	v_or_b32_e32 v144, 0x80000000, v135
	v_cmp_gt_i32_e32 vcc, 0, v135
	v_and_b32_e32 v142, 0xffffff80, v142
	v_sub_u32_e32 v142, v142, v10
	v_cndmask_b32_e32 v135, v144, v143, vcc
	v_cvt_f32_f16_sdwa v143, v128 dst_sel:DWORD dst_unused:UNUSED_PAD src0_sel:WORD_1
	v_cvt_f32_f16_e32 v128, v128
	v_and_b32_e32 v135, 0xffffff80, v135
	v_sub_u32_e32 v135, v135, v10
	v_not_b32_e32 v144, v143
	v_or_b32_e32 v145, 0x80000000, v143
	v_cmp_gt_i32_e32 vcc, 0, v143
	v_add_u32_e32 v142, 0x7e, v142
	v_add_u32_e32 v135, 0x7f, v135
	v_cndmask_b32_e32 v143, v145, v144, vcc
	v_not_b32_e32 v144, v128
	v_or_b32_e32 v145, 0x80000000, v128
	v_cmp_gt_i32_e32 vcc, 0, v128
	v_and_b32_e32 v143, 0xffffff80, v143
	v_sub_u32_e32 v143, v143, v8
	v_cndmask_b32_e32 v128, v145, v144, vcc
	v_cvt_f32_f16_sdwa v144, v129 dst_sel:DWORD dst_unused:UNUSED_PAD src0_sel:WORD_1
	v_cvt_f32_f16_e32 v129, v129
	v_and_b32_e32 v128, 0xffffff80, v128
	v_sub_u32_e32 v128, v128, v8
	v_not_b32_e32 v145, v144
	v_or_b32_e32 v146, 0x80000000, v144
	v_cmp_gt_i32_e32 vcc, 0, v144
	v_add_u32_e32 v143, 0x7e, v143
	v_add_u32_e32 v128, 0x7f, v128
	v_cndmask_b32_e32 v144, v146, v145, vcc
	v_not_b32_e32 v145, v129
	v_or_b32_e32 v146, 0x80000000, v129
	v_cmp_gt_i32_e32 vcc, 0, v129
	v_and_b32_e32 v144, 0xffffff80, v144
	v_sub_u32_e32 v144, v144, v16
	v_cndmask_b32_e32 v129, v146, v145, vcc
	v_cvt_f32_f16_sdwa v145, v130 dst_sel:DWORD dst_unused:UNUSED_PAD src0_sel:WORD_1
	v_cvt_f32_f16_e32 v130, v130
	v_and_b32_e32 v129, 0xffffff80, v129
	v_sub_u32_e32 v129, v129, v16
	v_not_b32_e32 v146, v145
	v_or_b32_e32 v147, 0x80000000, v145
	v_cmp_gt_i32_e32 vcc, 0, v145
	v_add_u32_e32 v144, 0x7e, v144
	v_add_u32_e32 v129, 0x7f, v129
	v_cndmask_b32_e32 v145, v147, v146, vcc
	v_not_b32_e32 v146, v130
	v_or_b32_e32 v147, 0x80000000, v130
	v_cmp_gt_i32_e32 vcc, 0, v130
	v_and_b32_e32 v145, 0xffffff80, v145
	v_sub_u32_e32 v145, v145, v17
	v_cndmask_b32_e32 v130, v147, v146, vcc
	v_cvt_f32_f16_sdwa v146, v131 dst_sel:DWORD dst_unused:UNUSED_PAD src0_sel:WORD_1
	v_cvt_f32_f16_e32 v131, v131
	v_and_b32_e32 v130, 0xffffff80, v130
	v_sub_u32_e32 v130, v130, v17
	v_not_b32_e32 v147, v146
	v_or_b32_e32 v148, 0x80000000, v146
	v_cmp_gt_i32_e32 vcc, 0, v146
	v_add_u32_e32 v145, 0x7e, v145
	v_add_u32_e32 v130, 0x7f, v130
	v_cndmask_b32_e32 v146, v148, v147, vcc
	v_not_b32_e32 v147, v131
	v_or_b32_e32 v148, 0x80000000, v131
	v_cmp_gt_i32_e32 vcc, 0, v131
	v_and_b32_e32 v146, 0xffffff80, v146
	v_sub_u32_e32 v146, v146, v18
	v_cndmask_b32_e32 v131, v148, v147, vcc
	s_waitcnt vmcnt(0)
; __device__ __forceinline__ unsigned f2key(float f) { const unsigned u = __float_as_uint(f); return (u & 0x80000000u) ? ~u : (u | 0x80000000u); }
; #define CE_DESC(a, b) do { const unsigned _mx = (a) > (b) ? (a) : (b), _mn = (a) > (b) ? (b) : (a); (a) = _mx; (b) = _mn; } while (0)
; __device__ __forceinline__ void sort16_desc(unsigned (&k)[16]) {
; #pragma unroll
;     for (int size = 2; size <= 16; size <<= 1)
; #pragma unroll
;         for (int stride = size >> 1; stride > 0; stride >>= 1)
; #pragma unroll
;             for (int i = 0; i < 16; ++i) { const int j = i ^ stride;
;                 if (j > i) { if ((i & size) == 0) CE_DESC(k[i], k[j]); else CE_DESC(k[j], k[i]); } }
; }
; __device__ __forceinline__ void peer_tile(const Args& A, LAS unsigned char* lds, int tile) {
;     ...
;                   for (int i = 0; i < 16; ++i) {
;                       const float lo = (float)__builtin_bit_cast(_Float16, (unsigned short)(sw[i] & 0xffffu)), hi = (float)__builtin_bit_cast(_Float16, (unsigned short)(sw[i] >> 16));
;                       const unsigned klo = (f2key(lo) & ~127u) | (unsigned)(127 - (32 * g + 2 * i)), khi = (f2key(hi) & ~127u) | (unsigned)(127 - (32 * g + 2 * i + 1));
;                       if (i < 8) { k0[2 * i] = klo; k0[2 * i + 1] = khi; } else { k1[2 * (i - 8)] = klo; k1[2 * (i - 8) + 1] = khi; } } }
	v_cvt_f32_f16_sdwa v147, v136 dst_sel:DWORD dst_unused:UNUSED_PAD src0_sel:WORD_1
	v_cvt_f32_f16_e32 v136, v136
	v_and_b32_e32 v131, 0xffffff80, v131
	v_sub_u32_e32 v131, v131, v18
	v_not_b32_e32 v148, v147
	v_or_b32_e32 v149, 0x80000000, v147
	v_cmp_gt_i32_e32 vcc, 0, v147
	v_add_u32_e32 v146, 0x7e, v146
	v_add_u32_e32 v131, 0x7f, v131
	v_cndmask_b32_e32 v147, v149, v148, vcc
	v_not_b32_e32 v148, v136
	v_or_b32_e32 v149, 0x80000000, v136
	v_cmp_gt_i32_e32 vcc, 0, v136
	v_and_b32_e32 v147, 0xffffff80, v147
	v_sub_u32_e32 v147, v147, v20
	v_cndmask_b32_e32 v136, v149, v148, vcc
	v_cvt_f32_f16_sdwa v148, v137 dst_sel:DWORD dst_unused:UNUSED_PAD src0_sel:WORD_1
	v_cvt_f32_f16_e32 v137, v137
	v_and_b32_e32 v136, 0xffffff80, v136
	v_sub_u32_e32 v136, v136, v20
	v_not_b32_e32 v149, v148
	v_or_b32_e32 v150, 0x80000000, v148
	v_cmp_gt_i32_e32 vcc, 0, v148
	v_add_u32_e32 v147, 0x7e, v147
	v_add_u32_e32 v136, 0x7f, v136
	v_cndmask_b32_e32 v148, v150, v149, vcc
	v_not_b32_e32 v149, v137
	v_or_b32_e32 v150, 0x80000000, v137
	v_cmp_gt_i32_e32 vcc, 0, v137
	v_and_b32_e32 v148, 0xffffff80, v148
	v_sub_u32_e32 v148, v148, v21
	v_cndmask_b32_e32 v137, v150, v149, vcc
	v_cvt_f32_f16_sdwa v149, v138 dst_sel:DWORD dst_unused:UNUSED_PAD src0_sel:WORD_1
	v_cvt_f32_f16_e32 v138, v138
	v_and_b32_e32 v137, 0xffffff80, v137
	v_sub_u32_e32 v137, v137, v21
	v_not_b32_e32 v150, v149
	v_or_b32_e32 v151, 0x80000000, v149
	v_cmp_gt_i32_e32 vcc, 0, v149
	v_add_u32_e32 v148, 0x7e, v148
	v_add_u32_e32 v137, 0x7f, v137
	v_cndmask_b32_e32 v149, v151, v150, vcc
	v_not_b32_e32 v150, v138
	v_or_b32_e32 v151, 0x80000000, v138
	v_cmp_gt_i32_e32 vcc, 0, v138
	v_and_b32_e32 v149, 0xffffff80, v149
	v_sub_u32_e32 v149, v149, v22
	v_cndmask_b32_e32 v138, v151, v150, vcc
	v_cvt_f32_f16_sdwa v150, v139 dst_sel:DWORD dst_unused:UNUSED_PAD src0_sel:WORD_1
	v_cvt_f32_f16_e32 v139, v139
	v_and_b32_e32 v138, 0xffffff80, v138
	v_sub_u32_e32 v138, v138, v22
	v_not_b32_e32 v151, v150
	v_or_b32_e32 v152, 0x80000000, v150
	v_cmp_gt_i32_e32 vcc, 0, v150
	v_add_u32_e32 v149, 0x7e, v149
	v_add_u32_e32 v138, 0x7f, v138
	v_cndmask_b32_e32 v150, v152, v151, vcc
	v_not_b32_e32 v151, v139
	v_or_b32_e32 v152, 0x80000000, v139
	v_cmp_gt_i32_e32 vcc, 0, v139
	v_and_b32_e32 v150, 0xffffff80, v150
	v_sub_u32_e32 v150, v150, v23
	v_cndmask_b32_e32 v139, v152, v151, vcc
	v_cvt_f32_f16_sdwa v151, v0 dst_sel:DWORD dst_unused:UNUSED_PAD src0_sel:WORD_1
	v_cvt_f32_f16_e32 v0, v0
	v_and_b32_e32 v139, 0xffffff80, v139
	v_sub_u32_e32 v139, v139, v23
	v_not_b32_e32 v152, v151
	v_or_b32_e32 v153, 0x80000000, v151
	v_cmp_gt_i32_e32 vcc, 0, v151
	v_add_u32_e32 v150, 0x7e, v150
	v_add_u32_e32 v139, 0x7f, v139
	v_cndmask_b32_e32 v151, v153, v152, vcc
	v_not_b32_e32 v152, v0
	v_or_b32_e32 v153, 0x80000000, v0
	v_cmp_gt_i32_e32 vcc, 0, v0
	v_and_b32_e32 v151, 0xffffff80, v151
	v_sub_u32_e32 v151, v151, v24
	v_cndmask_b32_e32 v0, v153, v152, vcc
	v_cvt_f32_f16_sdwa v152, v1 dst_sel:DWORD dst_unused:UNUSED_PAD src0_sel:WORD_1
	v_cvt_f32_f16_e32 v1, v1
	v_and_b32_e32 v0, 0xffffff80, v0
	v_sub_u32_e32 v0, v0, v24
	v_not_b32_e32 v153, v152
	v_or_b32_e32 v154, 0x80000000, v152
	v_cmp_gt_i32_e32 vcc, 0, v152
	v_add_u32_e32 v151, 0x7e, v151
	v_add_u32_e32 v0, 0x7f, v0
	v_cndmask_b32_e32 v152, v154, v153, vcc
	v_not_b32_e32 v153, v1
	v_or_b32_e32 v154, 0x80000000, v1
	v_cmp_gt_i32_e32 vcc, 0, v1
	v_and_b32_e32 v152, 0xffffff80, v152
	v_sub_u32_e32 v152, v152, v25
	v_cndmask_b32_e32 v1, v154, v153, vcc
	v_cvt_f32_f16_sdwa v153, v2 dst_sel:DWORD dst_unused:UNUSED_PAD src0_sel:WORD_1
	v_cvt_f32_f16_e32 v2, v2
	v_and_b32_e32 v1, 0xffffff80, v1
	v_sub_u32_e32 v1, v1, v25
	v_not_b32_e32 v154, v153
	v_or_b32_e32 v155, 0x80000000, v153
	v_cmp_gt_i32_e32 vcc, 0, v153
	v_add_u32_e32 v152, 0x7e, v152
	v_add_u32_e32 v1, 0x7f, v1
	v_cndmask_b32_e32 v153, v155, v154, vcc
	v_not_b32_e32 v154, v2
	v_or_b32_e32 v155, 0x80000000, v2
	v_cmp_gt_i32_e32 vcc, 0, v2
	v_and_b32_e32 v153, 0xffffff80, v153
	v_sub_u32_e32 v153, v153, v26
	v_cndmask_b32_e32 v2, v155, v154, vcc
	v_cvt_f32_f16_sdwa v154, v3 dst_sel:DWORD dst_unused:UNUSED_PAD src0_sel:WORD_1
	v_cvt_f32_f16_e32 v3, v3
	v_and_b32_e32 v2, 0xffffff80, v2
	v_sub_u32_e32 v2, v2, v26
	v_not_b32_e32 v155, v154
	v_or_b32_e32 v156, 0x80000000, v154
	v_cmp_gt_i32_e32 vcc, 0, v154
	v_add_u32_e32 v153, 0x7e, v153
	v_add_u32_e32 v2, 0x7f, v2
	v_cndmask_b32_e32 v154, v156, v155, vcc
	v_not_b32_e32 v155, v3
	v_or_b32_e32 v156, 0x80000000, v3
	v_cmp_gt_i32_e32 vcc, 0, v3
	v_and_b32_e32 v154, 0xffffff80, v154
	v_sub_u32_e32 v154, v154, v28
	v_cndmask_b32_e32 v3, v156, v155, vcc
	v_and_b32_e32 v3, 0xffffff80, v3
	v_sub_u32_e32 v3, v3, v28
	v_add_u32_e32 v154, 0x7e, v154
	v_add_u32_e32 v3, 0x7f, v3
	v_max_u32_e32 v155, v132, v127
	v_min_u32_e32 v127, v132, v127
	v_max_u32_e32 v132, v140, v133
	v_min_u32_e32 v133, v140, v133
	v_max_u32_e32 v140, v134, v141
	v_min_u32_e32 v134, v134, v141
	v_max_u32_e32 v141, v142, v135
	v_min_u32_e32 v135, v142, v135
	v_max_u32_e32 v142, v128, v143
	v_min_u32_e32 v128, v128, v143
	v_max_u32_e32 v143, v144, v129
	v_min_u32_e32 v129, v144, v129
	v_max_u32_e32 v144, v130, v145
	v_min_u32_e32 v130, v130, v145
	v_max_u32_e32 v145, v146, v131
	v_min_u32_e32 v131, v146, v131
	v_max_u32_e32 v163, v136, v147
	v_min_u32_e32 v136, v136, v147
	v_max_u32_e32 v147, v148, v137
	v_min_u32_e32 v137, v148, v137
	v_max_u32_e32 v148, v138, v149
	v_min_u32_e32 v138, v138, v149
	v_max_u32_e32 v149, v150, v139
	v_min_u32_e32 v139, v150, v139
	v_max_u32_e32 v150, v0, v151
	v_min_u32_e32 v0, v0, v151
	v_max_u32_e32 v151, v152, v1
	v_min_u32_e32 v1, v152, v1
	v_max_u32_e32 v152, v2, v153
	v_min_u32_e32 v2, v2, v153
; #define CE_DESC(a, b) do { const unsigned _mx = (a) > (b) ? (a) : (b), _mn = (a) > (b) ? (b) : (a); (a) = _mx; (b) = _mn; } while (0)
; __device__ __forceinline__ void sort16_desc(unsigned (&k)[16]) {
; #pragma unroll
;     for (int size = 2; size <= 16; size <<= 1)
; #pragma unroll
;         for (int stride = size >> 1; stride > 0; stride >>= 1)
; #pragma unroll
;             for (int i = 0; i < 16; ++i) { const int j = i ^ stride;
;                 if (j > i) { if ((i & size) == 0) CE_DESC(k[i], k[j]); else CE_DESC(k[j], k[i]); } }
; }
	v_max_u32_e32 v153, v154, v3
	v_min_u32_e32 v3, v154, v3
	v_max_u32_e32 v146, v155, v133
	v_min_u32_e32 v133, v155, v133
	v_max_u32_e32 v155, v127, v132
	v_min_u32_e32 v127, v127, v132
	v_max_u32_e32 v132, v135, v140
	v_min_u32_e32 v135, v135, v140
	v_max_u32_e32 v140, v141, v134
	v_min_u32_e32 v134, v141, v134
	v_max_u32_e32 v141, v142, v129
	v_min_u32_e32 v129, v142, v129
	v_max_u32_e32 v142, v128, v143
	v_min_u32_e32 v128, v128, v143
	v_max_u32_e32 v143, v131, v144
	v_min_u32_e32 v131, v131, v144
	v_max_u32_e32 v144, v145, v130
	v_min_u32_e32 v130, v145, v130
	v_max_u32_e32 v154, v163, v137
	v_min_u32_e32 v137, v163, v137
	v_max_u32_e32 v163, v136, v147
	v_min_u32_e32 v136, v136, v147
	v_max_u32_e32 v147, v139, v148
	v_min_u32_e32 v139, v139, v148
	v_max_u32_e32 v148, v149, v138
	v_min_u32_e32 v138, v149, v138
	v_max_u32_e32 v149, v150, v1
	v_min_u32_e32 v1, v150, v1
	v_max_u32_e32 v150, v0, v151
	v_min_u32_e32 v0, v0, v151
	v_max_u32_e32 v151, v3, v152
	v_min_u32_e32 v3, v3, v152
	v_max_u32_e32 v152, v153, v2
	v_min_u32_e32 v2, v153, v2
	v_max_u32_e32 v145, v146, v155
	v_min_u32_e32 v146, v146, v155
	v_max_u32_e32 v155, v133, v127
	v_min_u32_e32 v127, v133, v127
	v_max_u32_e32 v133, v134, v135
	v_min_u32_e32 v134, v134, v135
	v_max_u32_e32 v135, v140, v132
	v_min_u32_e32 v132, v140, v132
	v_max_u32_e32 v140, v141, v142
	v_min_u32_e32 v141, v141, v142
	v_max_u32_e32 v142, v129, v128
	v_min_u32_e32 v128, v129, v128
	v_max_u32_e32 v129, v130, v131
	v_min_u32_e32 v130, v130, v131
	v_max_u32_e32 v131, v144, v143
	v_min_u32_e32 v143, v144, v143
	v_max_u32_e32 v153, v154, v163
	v_min_u32_e32 v154, v154, v163
	v_max_u32_e32 v163, v137, v136
	v_min_u32_e32 v136, v137, v136
	v_max_u32_e32 v137, v138, v139
	v_min_u32_e32 v138, v138, v139
	v_max_u32_e32 v139, v148, v147
	v_min_u32_e32 v147, v148, v147
	v_max_u32_e32 v148, v149, v150
	v_min_u32_e32 v149, v149, v150
	v_max_u32_e32 v150, v1, v0
	v_min_u32_e32 v0, v1, v0
	v_max_u32_e32 v1, v2, v3
	v_min_u32_e32 v2, v2, v3
	v_max_u32_e32 v3, v152, v151
	v_min_u32_e32 v151, v152, v151
	v_max_u32_e32 v144, v145, v134
	v_min_u32_e32 v134, v145, v134
	v_max_u32_e32 v145, v146, v133
	v_min_u32_e32 v133, v146, v133
	v_max_u32_e32 v146, v155, v132
	v_min_u32_e32 v132, v155, v132
	v_max_u32_e32 v155, v127, v135
	v_min_u32_e32 v127, v127, v135
	v_max_u32_e32 v135, v130, v140
	v_min_u32_e32 v130, v130, v140
	v_max_u32_e32 v140, v129, v141
	v_min_u32_e32 v129, v129, v141
	v_max_u32_e32 v141, v143, v142
	v_min_u32_e32 v142, v143, v142
	v_max_u32_e32 v143, v131, v128
	v_min_u32_e32 v128, v131, v128
	v_max_u32_e32 v152, v153, v138
	v_min_u32_e32 v138, v153, v138
	v_max_u32_e32 v153, v154, v137
	v_min_u32_e32 v137, v154, v137
	v_max_u32_e32 v154, v163, v147
	v_min_u32_e32 v147, v163, v147
	v_max_u32_e32 v163, v136, v139
	v_min_u32_e32 v136, v136, v139
	v_max_u32_e32 v139, v2, v148
	v_min_u32_e32 v2, v2, v148
	v_max_u32_e32 v148, v1, v149
	v_min_u32_e32 v1, v1, v149
	v_max_u32_e32 v149, v151, v150
	v_min_u32_e32 v150, v151, v150
	v_max_u32_e32 v151, v3, v0
	v_min_u32_e32 v0, v3, v0
	v_max_u32_e32 v131, v144, v146
	v_min_u32_e32 v144, v144, v146
	v_max_u32_e32 v146, v145, v155
	v_min_u32_e32 v145, v145, v155
	v_max_u32_e32 v155, v134, v132
	v_min_u32_e32 v132, v134, v132
	v_max_u32_e32 v134, v133, v127
	v_min_u32_e32 v127, v133, v127
	v_max_u32_e32 v133, v142, v130
	v_min_u32_e32 v130, v142, v130
	v_max_u32_e32 v142, v128, v129
	v_min_u32_e32 v128, v128, v129
	v_max_u32_e32 v129, v141, v135
	v_min_u32_e32 v135, v141, v135
	v_max_u32_e32 v141, v143, v140
	v_min_u32_e32 v140, v143, v140
	v_max_u32_e32 v3, v152, v154
	v_min_u32_e32 v152, v152, v154
	v_max_u32_e32 v154, v153, v163
	v_min_u32_e32 v153, v153, v163
	v_max_u32_e32 v163, v138, v147
	v_min_u32_e32 v138, v138, v147
	v_max_u32_e32 v147, v137, v136
	v_min_u32_e32 v136, v137, v136
	v_max_u32_e32 v137, v150, v2
	v_min_u32_e32 v2, v150, v2
	v_max_u32_e32 v150, v0, v1
	v_min_u32_e32 v0, v0, v1
	v_max_u32_e32 v1, v149, v139
	v_min_u32_e32 v139, v149, v139
	v_max_u32_e32 v149, v151, v148
	v_min_u32_e32 v148, v151, v148
	v_max_u32_e32 v143, v131, v146
	v_min_u32_e32 v131, v131, v146
	v_max_u32_e32 v146, v144, v145
	v_min_u32_e32 v144, v144, v145
	v_max_u32_e32 v145, v155, v134
	v_min_u32_e32 v134, v155, v134
	v_max_u32_e32 v155, v132, v127
	v_min_u32_e32 v127, v132, v127
	v_max_u32_e32 v132, v128, v130
	v_min_u32_e32 v128, v128, v130
	v_max_u32_e32 v130, v142, v133
	v_min_u32_e32 v133, v142, v133
	v_max_u32_e32 v142, v140, v135
	v_min_u32_e32 v135, v140, v135
	v_max_u32_e32 v140, v141, v129
	v_min_u32_e32 v129, v141, v129
	v_max_u32_e32 v151, v3, v154
	v_min_u32_e32 v3, v3, v154
	v_max_u32_e32 v154, v152, v153
	v_min_u32_e32 v152, v152, v153
	v_max_u32_e32 v153, v163, v147
	v_min_u32_e32 v147, v163, v147
	v_max_u32_e32 v163, v138, v136
	v_min_u32_e32 v136, v138, v136
	v_max_u32_e32 v138, v0, v2
	v_min_u32_e32 v0, v0, v2
	v_max_u32_e32 v2, v150, v137
	v_min_u32_e32 v137, v150, v137
	v_max_u32_e32 v150, v148, v139
	v_min_u32_e32 v139, v148, v139
	v_max_u32_e32 v148, v149, v1
	v_min_u32_e32 v1, v149, v1
	v_max_u32_e32 v141, v143, v128
	v_min_u32_e32 v128, v143, v128
	v_max_u32_e32 v143, v131, v132
	v_min_u32_e32 v131, v131, v132
	v_max_u32_e32 v132, v146, v133
	v_min_u32_e32 v133, v146, v133
	v_max_u32_e32 v146, v144, v130
	v_min_u32_e32 v130, v144, v130
	v_max_u32_e32 v144, v145, v135
	v_min_u32_e32 v135, v145, v135
	v_max_u32_e32 v145, v134, v142
	v_min_u32_e32 v134, v134, v142
	v_max_u32_e32 v142, v155, v129
	v_min_u32_e32 v129, v155, v129
	v_max_u32_e32 v155, v127, v140
	v_min_u32_e32 v127, v127, v140
	v_max_u32_e32 v149, v151, v0
	v_min_u32_e32 v0, v151, v0
; #define CE_DESC(a, b) do { const unsigned _mx = (a) > (b) ? (a) : (b), _mn = (a) > (b) ? (b) : (a); (a) = _mx; (b) = _mn; } while (0)
; __device__ __forceinline__ void sort16_desc(unsigned (&k)[16]) {
; #pragma unroll
;     for (int size = 2; size <= 16; size <<= 1)
; #pragma unroll
;         for (int stride = size >> 1; stride > 0; stride >>= 1)
; #pragma unroll
;             for (int i = 0; i < 16; ++i) { const int j = i ^ stride;
;                 if (j > i) { if ((i & size) == 0) CE_DESC(k[i], k[j]); else CE_DESC(k[j], k[i]); } }
; }
; __device__ __forceinline__ void merge16(unsigned (&a)[16], const unsigned (&b)[16]) {
; #pragma unroll
;     for (int i = 0; i < 16; ++i) a[i] = a[i] > b[15 - i] ? a[i] : b[15 - i];
; #pragma unroll
;     for (int stride = 8; stride > 0; stride >>= 1)
; #pragma unroll
;         for (int i = 0; i < 16; ++i) { const int j = i ^ stride; if (j > i) CE_DESC(a[i], a[j]); }
; }
; __device__ __forceinline__ void peer_tile(const Args& A, LAS unsigned char* lds, int tile) {
;     ...
;                 for (int msk = 16; msk <= 32; msk <<= 1) {
; #pragma unroll
;                     for (int i = 0; i < 16; ++i) k1[i] = (unsigned)__shfl_xor((int)k0[i], msk);
;                     merge16(k0, k1); }
	v_max_u32_e32 v151, v3, v138
	v_min_u32_e32 v3, v3, v138
	v_max_u32_e32 v138, v154, v137
	v_min_u32_e32 v137, v154, v137
	v_max_u32_e32 v154, v152, v2
	v_min_u32_e32 v2, v152, v2
	v_max_u32_e32 v152, v153, v139
	v_min_u32_e32 v139, v153, v139
	v_max_u32_e32 v153, v147, v150
	v_min_u32_e32 v147, v147, v150
	v_max_u32_e32 v150, v163, v1
	v_min_u32_e32 v1, v163, v1
	v_max_u32_e32 v163, v136, v148
	v_min_u32_e32 v136, v136, v148
	v_max_u32_e32 v140, v141, v144
	v_min_u32_e32 v141, v141, v144
	v_max_u32_e32 v144, v143, v145
	v_min_u32_e32 v143, v143, v145
	v_max_u32_e32 v145, v132, v142
	v_min_u32_e32 v132, v132, v142
	v_max_u32_e32 v142, v146, v155
	v_min_u32_e32 v146, v146, v155
	v_max_u32_e32 v155, v128, v135
	v_min_u32_e32 v128, v128, v135
	v_max_u32_e32 v135, v131, v134
	v_min_u32_e32 v131, v131, v134
	v_max_u32_e32 v134, v133, v129
	v_min_u32_e32 v129, v133, v129
	v_max_u32_e32 v133, v130, v127
	v_min_u32_e32 v127, v130, v127
	v_max_u32_e32 v148, v149, v152
	v_min_u32_e32 v149, v149, v152
	v_max_u32_e32 v152, v151, v153
	v_min_u32_e32 v151, v151, v153
	v_max_u32_e32 v153, v138, v150
	v_min_u32_e32 v138, v138, v150
	v_max_u32_e32 v150, v154, v163
	v_min_u32_e32 v154, v154, v163
	v_max_u32_e32 v163, v0, v139
	v_min_u32_e32 v0, v0, v139
	v_max_u32_e32 v139, v3, v147
	v_min_u32_e32 v3, v3, v147
	v_max_u32_e32 v147, v137, v1
	v_min_u32_e32 v1, v137, v1
	v_max_u32_e32 v137, v2, v136
	v_min_u32_e32 v2, v2, v136
	v_max_u32_e32 v130, v140, v145
	v_min_u32_e32 v140, v140, v145
	v_max_u32_e32 v145, v144, v142
	v_min_u32_e32 v142, v144, v142
	v_max_u32_e32 v144, v141, v132
	v_min_u32_e32 v132, v141, v132
	v_max_u32_e32 v141, v143, v146
	v_min_u32_e32 v143, v143, v146
	v_max_u32_e32 v146, v155, v134
	v_min_u32_e32 v134, v155, v134
	v_max_u32_e32 v155, v135, v133
	v_min_u32_e32 v133, v135, v133
	v_max_u32_e32 v135, v128, v129
	v_min_u32_e32 v128, v128, v129
	v_max_u32_e32 v129, v131, v127
	v_min_u32_e32 v127, v131, v127
	v_max_u32_e32 v136, v148, v153
	v_min_u32_e32 v148, v148, v153
	v_max_u32_e32 v153, v152, v150
	v_min_u32_e32 v150, v152, v150
	v_max_u32_e32 v152, v149, v138
	v_min_u32_e32 v138, v149, v138
	v_max_u32_e32 v149, v151, v154
	v_min_u32_e32 v151, v151, v154
	v_max_u32_e32 v154, v163, v147
	v_min_u32_e32 v147, v163, v147
	v_max_u32_e32 v163, v139, v137
	v_min_u32_e32 v137, v139, v137
	v_max_u32_e32 v139, v0, v1
	v_min_u32_e32 v0, v0, v1
	v_max_u32_e32 v1, v3, v2
	v_min_u32_e32 v2, v3, v2
	v_min_u32_e32 v131, v130, v145
	v_min_u32_e32 v156, v140, v142
	v_min_u32_e32 v157, v144, v141
	v_min_u32_e32 v158, v132, v143
	v_min_u32_e32 v159, v146, v155
	v_min_u32_e32 v160, v134, v133
	v_min_u32_e32 v161, v135, v129
	v_min_u32_e32 v162, v128, v127
	v_min_u32_e32 v3, v136, v153
	v_min_u32_e32 v164, v148, v150
	v_min_u32_e32 v165, v152, v149
	v_min_u32_e32 v166, v138, v151
	v_min_u32_e32 v167, v154, v163
	v_min_u32_e32 v168, v147, v137
	v_min_u32_e32 v169, v139, v1
	v_min_u32_e32 v170, v0, v2
	v_max3_u32 v130, v130, v145, v170
	v_max3_u32 v0, v131, v0, v2
	v_max3_u32 v2, v140, v142, v169
	v_max3_u32 v1, v156, v139, v1
	v_max3_u32 v131, v144, v141, v168
	v_max3_u32 v137, v157, v147, v137
	v_max3_u32 v132, v132, v143, v167
	v_max3_u32 v139, v158, v154, v163
	v_max3_u32 v140, v146, v155, v166
	v_max3_u32 v138, v159, v138, v151
	v_max3_u32 v133, v134, v133, v165
	v_max3_u32 v134, v160, v152, v149
	v_max3_u32 v129, v135, v129, v164
	v_max3_u32 v135, v161, v148, v150
	v_max3_u32 v3, v128, v127, v3
	v_max3_u32 v127, v162, v136, v153
	v_max_u32_e32 v128, v130, v140
	v_min_u32_e32 v130, v130, v140
	v_max_u32_e32 v136, v0, v138
	v_min_u32_e32 v0, v0, v138
	v_max_u32_e32 v138, v2, v133
	v_min_u32_e32 v2, v2, v133
	v_max_u32_e32 v133, v1, v134
	v_min_u32_e32 v1, v1, v134
	v_max_u32_e32 v134, v131, v129
	v_min_u32_e32 v129, v131, v129
	v_max_u32_e32 v131, v137, v135
	v_min_u32_e32 v135, v137, v135
	v_max_u32_e32 v137, v132, v3
	v_min_u32_e32 v3, v132, v3
	v_max_u32_e32 v132, v139, v127
	v_min_u32_e32 v127, v139, v127
	v_max_u32_e32 v139, v128, v134
	v_min_u32_e32 v128, v128, v134
	v_max_u32_e32 v134, v136, v131
	v_min_u32_e32 v131, v136, v131
	v_max_u32_e32 v136, v138, v137
	v_min_u32_e32 v137, v138, v137
	v_max_u32_e32 v138, v133, v132
	v_min_u32_e32 v132, v133, v132
	v_max_u32_e32 v133, v130, v129
	v_min_u32_e32 v129, v130, v129
	v_max_u32_e32 v130, v0, v135
	v_min_u32_e32 v0, v0, v135
	v_max_u32_e32 v135, v2, v3
	v_min_u32_e32 v2, v2, v3
	v_max_u32_e32 v3, v1, v127
	v_min_u32_e32 v1, v1, v127
	v_max_u32_e32 v127, v139, v136
	v_min_u32_e32 v136, v139, v136
	v_max_u32_e32 v139, v134, v138
	v_min_u32_e32 v134, v134, v138
	v_max_u32_e32 v138, v128, v137
	v_min_u32_e32 v128, v128, v137
	v_max_u32_e32 v137, v131, v132
	v_min_u32_e32 v131, v131, v132
	v_max_u32_e32 v132, v133, v135
	v_min_u32_e32 v133, v133, v135
	v_max_u32_e32 v135, v130, v3
	v_min_u32_e32 v3, v130, v3
	v_max_u32_e32 v130, v129, v2
	v_min_u32_e32 v2, v129, v2
	v_max_u32_e32 v129, v0, v1
	v_min_u32_e32 v0, v0, v1
	v_max_u32_e32 v1, v127, v139
	v_min_u32_e32 v127, v127, v139
	v_max_u32_e32 v139, v136, v134
	v_min_u32_e32 v134, v136, v134
	v_max_u32_e32 v136, v138, v137
	v_min_u32_e32 v137, v138, v137
	v_max_u32_e32 v138, v128, v131
	v_min_u32_e32 v128, v128, v131
	v_max_u32_e32 v131, v132, v135
	v_min_u32_e32 v132, v132, v135
	v_max_u32_e32 v135, v133, v3
	v_min_u32_e32 v3, v133, v3
	v_max_u32_e32 v133, v130, v129
	v_min_u32_e32 v129, v130, v129
	v_max_u32_e32 v130, v2, v0
	v_min_u32_e32 v0, v2, v0
	ds_bpermute_b32 v2, v27, v1
	ds_bpermute_b32 v140, v27, v127
	ds_bpermute_b32 v141, v27, v139
	ds_bpermute_b32 v142, v27, v134
	ds_bpermute_b32 v143, v27, v136
	ds_bpermute_b32 v144, v27, v137
	ds_bpermute_b32 v145, v27, v138
	ds_bpermute_b32 v146, v27, v128
	ds_bpermute_b32 v147, v27, v131
	ds_bpermute_b32 v148, v27, v132
	ds_bpermute_b32 v149, v27, v135
	ds_bpermute_b32 v150, v27, v0
	ds_bpermute_b32 v151, v27, v130
	ds_bpermute_b32 v152, v27, v129
	ds_bpermute_b32 v153, v27, v133
	ds_bpermute_b32 v154, v27, v3
	s_waitcnt lgkmcnt(4)
; #define CE_DESC(a, b) do { const unsigned _mx = (a) > (b) ? (a) : (b), _mn = (a) > (b) ? (b) : (a); (a) = _mx; (b) = _mn; } while (0)
; __device__ __forceinline__ void merge16(unsigned (&a)[16], const unsigned (&b)[16]) {
; #pragma unroll
;     for (int i = 0; i < 16; ++i) a[i] = a[i] > b[15 - i] ? a[i] : b[15 - i];
; #pragma unroll
;     for (int stride = 8; stride > 0; stride >>= 1)
; #pragma unroll
;         for (int i = 0; i < 16; ++i) { const int j = i ^ stride; if (j > i) CE_DESC(a[i], a[j]); }
; }
; __device__ __forceinline__ void peer_tile(const Args& A, LAS unsigned char* lds, int tile) {
;     ...
;                 for (int msk = 16; msk <= 32; msk <<= 1) {
; #pragma unroll
;                     for (int i = 0; i < 16; ++i) k1[i] = (unsigned)__shfl_xor((int)k0[i], msk);
;                     merge16(k0, k1); }
	v_max_u32_e32 v1, v1, v150
	s_waitcnt lgkmcnt(3)
	v_max_u32_e32 v127, v127, v151
	s_waitcnt lgkmcnt(2)
	v_max_u32_e32 v139, v139, v152
	s_waitcnt lgkmcnt(1)
	v_max_u32_e32 v134, v134, v153
	s_waitcnt lgkmcnt(0)
	v_max_u32_e32 v136, v136, v154
	v_max_u32_e32 v137, v137, v149
	v_max_u32_e32 v138, v138, v148
	v_max_u32_e32 v128, v128, v147
	v_max_u32_e32 v131, v131, v146
	v_max_u32_e32 v132, v132, v145
	v_max_u32_e32 v135, v135, v144
	v_max_u32_e32 v3, v3, v143
	v_max_u32_e32 v133, v133, v142
	v_max_u32_e32 v129, v129, v141
	v_max_u32_e32 v130, v130, v140
	v_max_u32_e32 v0, v0, v2
	v_max_u32_e32 v2, v1, v131
	v_min_u32_e32 v1, v1, v131
	v_max_u32_e32 v131, v127, v132
	v_min_u32_e32 v127, v127, v132
	v_max_u32_e32 v132, v139, v135
	v_min_u32_e32 v135, v139, v135
	v_max_u32_e32 v139, v134, v3
	v_min_u32_e32 v3, v134, v3
	v_max_u32_e32 v134, v136, v133
	v_min_u32_e32 v133, v136, v133
	v_max_u32_e32 v136, v137, v129
	v_min_u32_e32 v129, v137, v129
	v_max_u32_e32 v137, v138, v130
	v_min_u32_e32 v130, v138, v130
	v_max_u32_e32 v138, v128, v0
	v_min_u32_e32 v0, v128, v0
	v_max_u32_e32 v128, v2, v134
	v_min_u32_e32 v2, v2, v134
	v_max_u32_e32 v134, v131, v136
	v_min_u32_e32 v131, v131, v136
	v_max_u32_e32 v136, v132, v137
	v_min_u32_e32 v132, v132, v137
	v_max_u32_e32 v137, v139, v138
	v_min_u32_e32 v138, v139, v138
	v_max_u32_e32 v139, v1, v133
	v_min_u32_e32 v1, v1, v133
	v_max_u32_e32 v133, v127, v129
	v_min_u32_e32 v127, v127, v129
	v_max_u32_e32 v129, v135, v130
	v_min_u32_e32 v130, v135, v130
	v_max_u32_e32 v135, v3, v0
	v_min_u32_e32 v0, v3, v0
	v_max_u32_e32 v3, v128, v136
	v_min_u32_e32 v128, v128, v136
	v_max_u32_e32 v136, v134, v137
	v_min_u32_e32 v134, v134, v137
	v_max_u32_e32 v137, v2, v132
	v_min_u32_e32 v2, v2, v132
	v_max_u32_e32 v132, v131, v138
	v_min_u32_e32 v131, v131, v138
	v_max_u32_e32 v138, v139, v129
	v_min_u32_e32 v129, v139, v129
	v_max_u32_e32 v139, v133, v135
	v_min_u32_e32 v133, v133, v135
	v_max_u32_e32 v135, v1, v130
	v_min_u32_e32 v1, v1, v130
	v_max_u32_e32 v130, v127, v0
	v_min_u32_e32 v0, v127, v0
	v_max_u32_e32 v127, v3, v136
	v_min_u32_e32 v3, v3, v136
	v_max_u32_e32 v136, v128, v134
	v_min_u32_e32 v128, v128, v134
	v_max_u32_e32 v134, v137, v132
	v_min_u32_e32 v132, v137, v132
	v_max_u32_e32 v137, v2, v131
	v_min_u32_e32 v2, v2, v131
	v_max_u32_e32 v131, v138, v139
	v_min_u32_e32 v138, v138, v139
	v_max_u32_e32 v139, v129, v133
	v_min_u32_e32 v129, v129, v133
	v_max_u32_e32 v133, v135, v130
	v_min_u32_e32 v130, v135, v130
	v_max_u32_e32 v135, v1, v0
	v_min_u32_e32 v0, v1, v0
	ds_bpermute_b32 v144, v29, v0
	ds_bpermute_b32 v1, v29, v127
	ds_bpermute_b32 v140, v29, v3
	ds_bpermute_b32 v141, v29, v136
	ds_bpermute_b32 v142, v29, v128
	s_waitcnt lgkmcnt(4)
	v_max_u32_e32 v127, v127, v144
	global_load_dwordx4 v[144:147], v[4:5], off offset:1808
	global_load_dwordx4 v[148:151], v[4:5], off offset:1792
	ds_bpermute_b32 v143, v29, v134
	ds_bpermute_b32 v152, v29, v132
	ds_bpermute_b32 v153, v29, v137
	ds_bpermute_b32 v154, v29, v2
	ds_bpermute_b32 v155, v29, v131
	ds_bpermute_b32 v156, v29, v138
	ds_bpermute_b32 v157, v29, v139
	ds_bpermute_b32 v158, v29, v129
	ds_bpermute_b32 v159, v29, v133
	ds_bpermute_b32 v160, v29, v135
	ds_bpermute_b32 v161, v29, v130
	s_waitcnt lgkmcnt(4)
	v_max_u32_e32 v132, v132, v157
	s_waitcnt lgkmcnt(3)
	v_max_u32_e32 v134, v134, v158
	s_waitcnt lgkmcnt(2)
	v_max_u32_e32 v128, v128, v159
	s_waitcnt lgkmcnt(1)
	v_max_u32_e32 v3, v3, v160
	s_waitcnt lgkmcnt(0)
	v_max_u32_e32 v136, v136, v161
	v_max_u32_e32 v137, v137, v156
	v_max_u32_e32 v2, v2, v155
	v_max_u32_e32 v131, v131, v154
	v_max_u32_e32 v138, v138, v153
	v_max_u32_e32 v139, v139, v152
	v_max_u32_e32 v129, v129, v143
	v_max_u32_e32 v133, v133, v142
	v_max_u32_e32 v130, v130, v141
	v_max_u32_e32 v135, v135, v140
	v_max_u32_e32 v0, v0, v1
	v_max_u32_e32 v1, v127, v131
	v_min_u32_e32 v127, v127, v131
	v_max_u32_e32 v131, v3, v138
	v_min_u32_e32 v3, v3, v138
	v_max_u32_e32 v138, v136, v139
	v_min_u32_e32 v136, v136, v139
	v_max_u32_e32 v139, v128, v129
	v_min_u32_e32 v128, v128, v129
	v_max_u32_e32 v129, v134, v133
	v_min_u32_e32 v133, v134, v133
	v_max_u32_e32 v134, v132, v130
	v_min_u32_e32 v130, v132, v130
	v_max_u32_e32 v132, v137, v135
	v_min_u32_e32 v135, v137, v135
	v_max_u32_e32 v137, v2, v0
	v_min_u32_e32 v0, v2, v0
	v_max_u32_e32 v2, v1, v129
	v_min_u32_e32 v1, v1, v129
	v_max_u32_e32 v129, v131, v134
	v_min_u32_e32 v131, v131, v134
	v_max_u32_e32 v134, v138, v132
	v_min_u32_e32 v132, v138, v132
	v_max_u32_e32 v138, v139, v137
	v_min_u32_e32 v137, v139, v137
	v_max_u32_e32 v139, v127, v133
	v_min_u32_e32 v127, v127, v133
	v_max_u32_e32 v133, v3, v130
	v_min_u32_e32 v3, v3, v130
	v_max_u32_e32 v130, v136, v135
	v_min_u32_e32 v135, v136, v135
	v_max_u32_e32 v136, v128, v0
	v_min_u32_e32 v0, v128, v0
	v_max_u32_e32 v128, v2, v134
	v_min_u32_e32 v2, v2, v134
	v_max_u32_e32 v134, v129, v138
	v_min_u32_e32 v129, v129, v138
	v_max_u32_e32 v143, v1, v132
	v_min_u32_e32 v1, v1, v132
	v_max_u32_e32 v132, v131, v137
	v_min_u32_e32 v131, v131, v137
	v_max_u32_e32 v152, v139, v130
	v_min_u32_e32 v130, v139, v130
	v_max_u32_e32 v153, v133, v136
	v_min_u32_e32 v154, v133, v136
	v_max_u32_e32 v155, v127, v135
	v_min_u32_e32 v127, v127, v135
	v_max_u32_e32 v156, v3, v0
	v_min_u32_e32 v0, v3, v0
	v_max_u32_e32 v142, v128, v134
	v_min_u32_e32 v141, v128, v134
	v_max_u32_e32 v140, v2, v129
	v_min_u32_e32 v139, v2, v129
	v_max_u32_e32 v138, v143, v132
	v_min_u32_e32 v137, v143, v132
	v_max_u32_e32 v136, v1, v131
	v_min_u32_e32 v135, v1, v131
	v_max_u32_e32 v134, v152, v153
	v_min_u32_e32 v133, v152, v153
	v_max_u32_e32 v132, v130, v154
	v_min_u32_e32 v131, v130, v154
	v_max_u32_e32 v130, v155, v156
	v_min_u32_e32 v129, v155, v156
	v_max_u32_e32 v128, v127, v0
	v_min_u32_e32 v127, v127, v0
	global_load_dwordx4 v[0:3], v[4:5], off offset:1840
	global_load_dwordx4 v[152:155], v[4:5], off offset:1824
	s_waitcnt vmcnt(2)
; __device__ __forceinline__ unsigned f2key(float f) { const unsigned u = __float_as_uint(f); return (u & 0x80000000u) ? ~u : (u | 0x80000000u); }
; __device__ __forceinline__ void peer_tile(const Args& A, LAS unsigned char* lds, int tile) {
;     ...
;                 { const bf16_t* sp = QRY + m * 2048 + hp * 128 + 32 * g;
;                   const u32x4 s0 = *(const u32x4*)sp, s1 = *(const u32x4*)(sp + 8), s2 = *(const u32x4*)(sp + 16), s3 = *(const u32x4*)(sp + 24);
;                   const unsigned sw[16] = {s0.x, s0.y, s0.z, s0.w, s1.x, s1.y, s1.z, s1.w, s2.x, s2.y, s2.z, s2.w, s3.x, s3.y, s3.z, s3.w};
; #pragma unroll
;                   for (int i = 0; i < 16; ++i) {
;                       const float lo = (float)__builtin_bit_cast(_Float16, (unsigned short)(sw[i] & 0xffffu)), hi = (float)__builtin_bit_cast(_Float16, (unsigned short)(sw[i] >> 16));
;                       const unsigned klo = (f2key(lo) & ~127u) | (unsigned)(127 - (32 * g + 2 * i)), khi = (f2key(hi) & ~127u) | (unsigned)(127 - (32 * g + 2 * i + 1));
;                       if (i < 8) { k0[2 * i] = klo; k0[2 * i + 1] = khi; } else { k1[2 * (i - 8)] = klo; k1[2 * (i - 8) + 1] = khi; } } }
	v_cvt_f32_f16_sdwa v143, v148 dst_sel:DWORD dst_unused:UNUSED_PAD src0_sel:WORD_1
	v_cvt_f32_f16_e32 v4, v148
	v_not_b32_e32 v5, v143
	v_or_b32_e32 v148, 0x80000000, v143
	v_cmp_gt_i32_e32 vcc, 0, v143
	v_not_b32_e32 v143, v4
	s_nop 0
	v_cndmask_b32_e32 v5, v148, v5, vcc
	v_or_b32_e32 v148, 0x80000000, v4
	v_cmp_gt_i32_e32 vcc, 0, v4
	v_and_b32_e32 v5, 0xffffff80, v5
	v_sub_u32_e32 v5, v5, v15
	v_cndmask_b32_e32 v4, v148, v143, vcc
	v_and_b32_e32 v4, 0xffffff80, v4
	v_cvt_f32_f16_sdwa v143, v149 dst_sel:DWORD dst_unused:UNUSED_PAD src0_sel:WORD_1
	v_sub_u32_e32 v4, v4, v15
	v_cvt_f32_f16_e32 v15, v149
	v_add_u32_e32 v5, 0x7e, v5
	v_not_b32_e32 v148, v143
	v_or_b32_e32 v149, 0x80000000, v143
	v_cmp_gt_i32_e32 vcc, 0, v143
	v_add_u32_e32 v4, 0x7f, v4
	s_nop 0
	v_cndmask_b32_e32 v143, v149, v148, vcc
	v_not_b32_e32 v148, v15
	v_or_b32_e32 v149, 0x80000000, v15
	v_cmp_gt_i32_e32 vcc, 0, v15
	v_and_b32_e32 v143, 0xffffff80, v143
	v_sub_u32_e32 v143, v143, v14
	v_cndmask_b32_e32 v15, v149, v148, vcc
	v_and_b32_e32 v15, 0xffffff80, v15
	v_cvt_f32_f16_sdwa v148, v150 dst_sel:DWORD dst_unused:UNUSED_PAD src0_sel:WORD_1
	v_sub_u32_e32 v14, v15, v14
	v_cvt_f32_f16_e32 v15, v150
	v_add_u32_e32 v143, 0x7e, v143
	v_not_b32_e32 v149, v148
	v_or_b32_e32 v150, 0x80000000, v148
	v_cmp_gt_i32_e32 vcc, 0, v148
	v_add_u32_e32 v14, 0x7f, v14
	s_nop 0
	v_cndmask_b32_e32 v148, v150, v149, vcc
	v_not_b32_e32 v149, v15
	v_or_b32_e32 v150, 0x80000000, v15
	v_cmp_gt_i32_e32 vcc, 0, v15
	v_and_b32_e32 v148, 0xffffff80, v148
	v_sub_u32_e32 v148, v148, v12
	v_cndmask_b32_e32 v15, v150, v149, vcc
	v_and_b32_e32 v15, 0xffffff80, v15
	v_cvt_f32_f16_sdwa v149, v151 dst_sel:DWORD dst_unused:UNUSED_PAD src0_sel:WORD_1
	v_sub_u32_e32 v12, v15, v12
	v_cvt_f32_f16_e32 v15, v151
	v_add_u32_e32 v148, 0x7e, v148
	v_not_b32_e32 v150, v149
	v_or_b32_e32 v151, 0x80000000, v149
	v_cmp_gt_i32_e32 vcc, 0, v149
	v_add_u32_e32 v12, 0x7f, v12
	s_nop 0
	v_cndmask_b32_e32 v149, v151, v150, vcc
	v_not_b32_e32 v150, v15
	v_or_b32_e32 v151, 0x80000000, v15
	v_cmp_gt_i32_e32 vcc, 0, v15
	v_and_b32_e32 v149, 0xffffff80, v149
	v_sub_u32_e32 v149, v149, v10
	v_cndmask_b32_e32 v15, v151, v150, vcc
	v_and_b32_e32 v15, 0xffffff80, v15
	v_cvt_f32_f16_sdwa v150, v144 dst_sel:DWORD dst_unused:UNUSED_PAD src0_sel:WORD_1
	v_sub_u32_e32 v10, v15, v10
	v_cvt_f32_f16_e32 v15, v144
	v_add_u32_e32 v149, 0x7e, v149
	v_not_b32_e32 v144, v150
	v_or_b32_e32 v151, 0x80000000, v150
	v_cmp_gt_i32_e32 vcc, 0, v150
	v_not_b32_e32 v150, v15
	v_add_u32_e32 v10, 0x7f, v10
	v_cndmask_b32_e32 v144, v151, v144, vcc
	v_or_b32_e32 v151, 0x80000000, v15
	v_cmp_gt_i32_e32 vcc, 0, v15
	v_and_b32_e32 v144, 0xffffff80, v144
	v_sub_u32_e32 v144, v144, v8
	v_cndmask_b32_e32 v15, v151, v150, vcc
	v_and_b32_e32 v15, 0xffffff80, v15
	v_cvt_f32_f16_sdwa v150, v145 dst_sel:DWORD dst_unused:UNUSED_PAD src0_sel:WORD_1
	v_sub_u32_e32 v8, v15, v8
	v_cvt_f32_f16_e32 v15, v145
	v_add_u32_e32 v144, 0x7e, v144
	v_not_b32_e32 v145, v150
	v_or_b32_e32 v151, 0x80000000, v150
	v_cmp_gt_i32_e32 vcc, 0, v150
	v_not_b32_e32 v150, v15
	v_add_u32_e32 v8, 0x7f, v8
	v_cndmask_b32_e32 v145, v151, v145, vcc
	v_or_b32_e32 v151, 0x80000000, v15
	v_cmp_gt_i32_e32 vcc, 0, v15
	v_and_b32_e32 v145, 0xffffff80, v145
	v_sub_u32_e32 v145, v145, v16
	v_cndmask_b32_e32 v15, v151, v150, vcc
	v_and_b32_e32 v15, 0xffffff80, v15
	v_cvt_f32_f16_sdwa v150, v146 dst_sel:DWORD dst_unused:UNUSED_PAD src0_sel:WORD_1
	v_sub_u32_e32 v15, v15, v16
	v_cvt_f32_f16_e32 v16, v146
	v_add_u32_e32 v145, 0x7e, v145
	v_not_b32_e32 v146, v150
	v_or_b32_e32 v151, 0x80000000, v150
	v_cmp_gt_i32_e32 vcc, 0, v150
	v_not_b32_e32 v150, v16
	v_add_u32_e32 v15, 0x7f, v15
	v_cndmask_b32_e32 v146, v151, v146, vcc
	v_or_b32_e32 v151, 0x80000000, v16
	v_cmp_gt_i32_e32 vcc, 0, v16
	v_and_b32_e32 v146, 0xffffff80, v146
	v_sub_u32_e32 v146, v146, v17
	v_cndmask_b32_e32 v16, v151, v150, vcc
	v_and_b32_e32 v16, 0xffffff80, v16
	v_cvt_f32_f16_sdwa v150, v147 dst_sel:DWORD dst_unused:UNUSED_PAD src0_sel:WORD_1
	v_sub_u32_e32 v16, v16, v17
	v_cvt_f32_f16_e32 v17, v147
	v_add_u32_e32 v146, 0x7e, v146
	v_not_b32_e32 v147, v150
	v_or_b32_e32 v151, 0x80000000, v150
	v_cmp_gt_i32_e32 vcc, 0, v150
	v_not_b32_e32 v150, v17
	v_add_u32_e32 v16, 0x7f, v16
	v_cndmask_b32_e32 v147, v151, v147, vcc
	v_or_b32_e32 v151, 0x80000000, v17
	v_cmp_gt_i32_e32 vcc, 0, v17
	v_and_b32_e32 v147, 0xffffff80, v147
	v_sub_u32_e32 v147, v147, v18
	v_cndmask_b32_e32 v17, v151, v150, vcc
	v_and_b32_e32 v17, 0xffffff80, v17
	s_waitcnt vmcnt(0)
; __device__ __forceinline__ unsigned f2key(float f) { const unsigned u = __float_as_uint(f); return (u & 0x80000000u) ? ~u : (u | 0x80000000u); }
; #define CE_DESC(a, b) do { const unsigned _mx = (a) > (b) ? (a) : (b), _mn = (a) > (b) ? (b) : (a); (a) = _mx; (b) = _mn; } while (0)
; __device__ __forceinline__ void sort16_desc(unsigned (&k)[16]) {
; #pragma unroll
;     for (int size = 2; size <= 16; size <<= 1)
; #pragma unroll
;         for (int stride = size >> 1; stride > 0; stride >>= 1)
; #pragma unroll
;             for (int i = 0; i < 16; ++i) { const int j = i ^ stride;
;                 if (j > i) { if ((i & size) == 0) CE_DESC(k[i], k[j]); else CE_DESC(k[j], k[i]); } }
; }
; __device__ __forceinline__ void peer_tile(const Args& A, LAS unsigned char* lds, int tile) {
;     ...
;                 { const bf16_t* sp = QRY + m * 2048 + hp * 128 + 32 * g;
;                   const u32x4 s0 = *(const u32x4*)sp, s1 = *(const u32x4*)(sp + 8), s2 = *(const u32x4*)(sp + 16), s3 = *(const u32x4*)(sp + 24);
;                   const unsigned sw[16] = {s0.x, s0.y, s0.z, s0.w, s1.x, s1.y, s1.z, s1.w, s2.x, s2.y, s2.z, s2.w, s3.x, s3.y, s3.z, s3.w};
; #pragma unroll
;                   for (int i = 0; i < 16; ++i) {
;                       const float lo = (float)__builtin_bit_cast(_Float16, (unsigned short)(sw[i] & 0xffffu)), hi = (float)__builtin_bit_cast(_Float16, (unsigned short)(sw[i] >> 16));
;                       const unsigned klo = (f2key(lo) & ~127u) | (unsigned)(127 - (32 * g + 2 * i)), khi = (f2key(hi) & ~127u) | (unsigned)(127 - (32 * g + 2 * i + 1));
;                       if (i < 8) { k0[2 * i] = klo; k0[2 * i + 1] = khi; } else { k1[2 * (i - 8)] = klo; k1[2 * (i - 8) + 1] = khi; } } }
	v_cvt_f32_f16_sdwa v150, v152 dst_sel:DWORD dst_unused:UNUSED_PAD src0_sel:WORD_1
	v_sub_u32_e32 v17, v17, v18
	v_cvt_f32_f16_e32 v18, v152
	v_add_u32_e32 v147, 0x7e, v147
	v_not_b32_e32 v151, v150
	v_or_b32_e32 v152, 0x80000000, v150
	v_cmp_gt_i32_e32 vcc, 0, v150
	v_add_u32_e32 v17, 0x7f, v17
	s_nop 0
	v_cndmask_b32_e32 v150, v152, v151, vcc
	v_not_b32_e32 v151, v18
	v_or_b32_e32 v152, 0x80000000, v18
	v_cmp_gt_i32_e32 vcc, 0, v18
	v_and_b32_e32 v150, 0xffffff80, v150
	v_sub_u32_e32 v150, v150, v20
	v_cndmask_b32_e32 v18, v152, v151, vcc
	v_and_b32_e32 v18, 0xffffff80, v18
	v_cvt_f32_f16_sdwa v151, v153 dst_sel:DWORD dst_unused:UNUSED_PAD src0_sel:WORD_1
	v_sub_u32_e32 v18, v18, v20
	v_cvt_f32_f16_e32 v20, v153
	v_add_u32_e32 v150, 0x7e, v150
	v_not_b32_e32 v152, v151
	v_or_b32_e32 v153, 0x80000000, v151
	v_cmp_gt_i32_e32 vcc, 0, v151
	v_add_u32_e32 v18, 0x7f, v18
	v_max_u32_e32 v161, v18, v150
	v_cndmask_b32_e32 v151, v153, v152, vcc
	v_not_b32_e32 v152, v20
	v_or_b32_e32 v153, 0x80000000, v20
	v_cmp_gt_i32_e32 vcc, 0, v20
	v_and_b32_e32 v151, 0xffffff80, v151
	v_sub_u32_e32 v151, v151, v21
	v_cndmask_b32_e32 v20, v153, v152, vcc
	v_and_b32_e32 v20, 0xffffff80, v20
	v_cvt_f32_f16_sdwa v152, v154 dst_sel:DWORD dst_unused:UNUSED_PAD src0_sel:WORD_1
	v_sub_u32_e32 v20, v20, v21
	v_cvt_f32_f16_e32 v21, v154
	v_add_u32_e32 v151, 0x7e, v151
	v_not_b32_e32 v153, v152
	v_or_b32_e32 v154, 0x80000000, v152
	v_cmp_gt_i32_e32 vcc, 0, v152
	v_add_u32_e32 v20, 0x7f, v20
	v_min_u32_e32 v18, v18, v150
	v_cndmask_b32_e32 v152, v154, v153, vcc
	v_not_b32_e32 v153, v21
	v_or_b32_e32 v154, 0x80000000, v21
	v_cmp_gt_i32_e32 vcc, 0, v21
	v_and_b32_e32 v152, 0xffffff80, v152
	v_sub_u32_e32 v152, v152, v22
	v_cndmask_b32_e32 v21, v154, v153, vcc
	v_and_b32_e32 v21, 0xffffff80, v21
	v_cvt_f32_f16_sdwa v153, v155 dst_sel:DWORD dst_unused:UNUSED_PAD src0_sel:WORD_1
	v_sub_u32_e32 v21, v21, v22
	v_cvt_f32_f16_e32 v22, v155
	v_add_u32_e32 v152, 0x7e, v152
	v_not_b32_e32 v154, v153
	v_or_b32_e32 v155, 0x80000000, v153
	v_cmp_gt_i32_e32 vcc, 0, v153
	v_add_u32_e32 v21, 0x7f, v21
	v_max_u32_e32 v150, v151, v20
	v_cndmask_b32_e32 v153, v155, v154, vcc
	v_not_b32_e32 v154, v22
	v_or_b32_e32 v155, 0x80000000, v22
	v_cmp_gt_i32_e32 vcc, 0, v22
	v_and_b32_e32 v153, 0xffffff80, v153
	v_sub_u32_e32 v153, v153, v23
	v_cndmask_b32_e32 v22, v155, v154, vcc
	v_cvt_f32_f16_sdwa v154, v0 dst_sel:DWORD dst_unused:UNUSED_PAD src0_sel:WORD_1
	v_cvt_f32_f16_e32 v0, v0
	v_and_b32_e32 v22, 0xffffff80, v22
	v_sub_u32_e32 v22, v22, v23
	v_not_b32_e32 v23, v154
	v_or_b32_e32 v155, 0x80000000, v154
	v_cmp_gt_i32_e32 vcc, 0, v154
	v_not_b32_e32 v154, v0
	v_add_u32_e32 v153, 0x7e, v153
	v_cndmask_b32_e32 v23, v155, v23, vcc
	v_or_b32_e32 v155, 0x80000000, v0
	v_cmp_gt_i32_e32 vcc, 0, v0
	v_and_b32_e32 v23, 0xffffff80, v23
	v_sub_u32_e32 v23, v23, v24
	v_cndmask_b32_e32 v0, v155, v154, vcc
	v_cvt_f32_f16_sdwa v154, v1 dst_sel:DWORD dst_unused:UNUSED_PAD src0_sel:WORD_1
	v_cvt_f32_f16_e32 v1, v1
	v_and_b32_e32 v0, 0xffffff80, v0
	v_sub_u32_e32 v0, v0, v24
	v_not_b32_e32 v24, v154
	v_or_b32_e32 v155, 0x80000000, v154
	v_cmp_gt_i32_e32 vcc, 0, v154
	v_not_b32_e32 v154, v1
	v_add_u32_e32 v22, 0x7f, v22
	v_cndmask_b32_e32 v24, v155, v24, vcc
	v_or_b32_e32 v155, 0x80000000, v1
	v_cmp_gt_i32_e32 vcc, 0, v1
	v_and_b32_e32 v24, 0xffffff80, v24
	v_sub_u32_e32 v24, v24, v25
	v_cndmask_b32_e32 v1, v155, v154, vcc
	v_cvt_f32_f16_sdwa v154, v2 dst_sel:DWORD dst_unused:UNUSED_PAD src0_sel:WORD_1
	v_cvt_f32_f16_e32 v2, v2
	v_and_b32_e32 v1, 0xffffff80, v1
	v_sub_u32_e32 v1, v1, v25
	v_not_b32_e32 v25, v154
	v_or_b32_e32 v155, 0x80000000, v154
	v_cmp_gt_i32_e32 vcc, 0, v154
	v_not_b32_e32 v154, v2
	v_add_u32_e32 v23, 0x7e, v23
	v_cndmask_b32_e32 v25, v155, v25, vcc
	v_or_b32_e32 v155, 0x80000000, v2
	v_cmp_gt_i32_e32 vcc, 0, v2
	v_and_b32_e32 v25, 0xffffff80, v25
	v_sub_u32_e32 v25, v25, v26
	v_cndmask_b32_e32 v2, v155, v154, vcc
	v_cvt_f32_f16_sdwa v154, v3 dst_sel:DWORD dst_unused:UNUSED_PAD src0_sel:WORD_1
	v_cvt_f32_f16_e32 v3, v3
	v_and_b32_e32 v2, 0xffffff80, v2
	v_sub_u32_e32 v2, v2, v26
	v_not_b32_e32 v26, v154
	v_or_b32_e32 v155, 0x80000000, v154
	v_cmp_gt_i32_e32 vcc, 0, v154
	v_not_b32_e32 v154, v3
	v_add_u32_e32 v0, 0x7f, v0
	v_cndmask_b32_e32 v26, v155, v26, vcc
	v_or_b32_e32 v155, 0x80000000, v3
	v_cmp_gt_i32_e32 vcc, 0, v3
	v_and_b32_e32 v26, 0xffffff80, v26
	v_sub_u32_e32 v26, v26, v28
	v_cndmask_b32_e32 v3, v155, v154, vcc
	v_and_b32_e32 v3, 0xffffff80, v3
	v_sub_u32_e32 v3, v3, v28
	v_add_u32_e32 v24, 0x7e, v24
	v_add_u32_e32 v1, 0x7f, v1
	v_add_u32_e32 v25, 0x7e, v25
	v_add_u32_e32 v2, 0x7f, v2
	v_add_u32_e32 v26, 0x7e, v26
	v_add_u32_e32 v3, 0x7f, v3
	v_max_u32_e32 v28, v4, v5
	v_min_u32_e32 v4, v4, v5
	v_max_u32_e32 v5, v143, v14
	v_min_u32_e32 v14, v143, v14
	v_max_u32_e32 v143, v12, v148
	v_min_u32_e32 v12, v12, v148
	v_max_u32_e32 v148, v149, v10
	v_min_u32_e32 v10, v149, v10
	v_max_u32_e32 v149, v8, v144
	v_min_u32_e32 v8, v8, v144
	v_max_u32_e32 v144, v145, v15
	v_min_u32_e32 v15, v145, v15
	v_max_u32_e32 v145, v16, v146
	v_min_u32_e32 v16, v16, v146
	v_max_u32_e32 v146, v147, v17
	v_min_u32_e32 v17, v147, v17
	v_min_u32_e32 v20, v151, v20
	v_max_u32_e32 v151, v21, v152
	v_min_u32_e32 v21, v21, v152
	v_max_u32_e32 v152, v153, v22
	v_min_u32_e32 v22, v153, v22
	v_max_u32_e32 v153, v0, v23
	v_min_u32_e32 v0, v0, v23
	v_max_u32_e32 v23, v24, v1
	v_min_u32_e32 v1, v24, v1
	v_max_u32_e32 v24, v2, v25
	v_min_u32_e32 v2, v2, v25
	v_max_u32_e32 v25, v26, v3
	v_min_u32_e32 v3, v26, v3
	v_max_u32_e32 v147, v28, v14
	v_min_u32_e32 v14, v28, v14
	v_max_u32_e32 v28, v4, v5
	v_min_u32_e32 v4, v4, v5
; #define CE_DESC(a, b) do { const unsigned _mx = (a) > (b) ? (a) : (b), _mn = (a) > (b) ? (b) : (a); (a) = _mx; (b) = _mn; } while (0)
; __device__ __forceinline__ void sort16_desc(unsigned (&k)[16]) {
; #pragma unroll
;     for (int size = 2; size <= 16; size <<= 1)
; #pragma unroll
;         for (int stride = size >> 1; stride > 0; stride >>= 1)
; #pragma unroll
;             for (int i = 0; i < 16; ++i) { const int j = i ^ stride;
;                 if (j > i) { if ((i & size) == 0) CE_DESC(k[i], k[j]); else CE_DESC(k[j], k[i]); } }
; }
	v_max_u32_e32 v5, v10, v143
	v_min_u32_e32 v10, v10, v143
	v_max_u32_e32 v143, v148, v12
	v_min_u32_e32 v12, v148, v12
	v_max_u32_e32 v148, v149, v15
	v_min_u32_e32 v15, v149, v15
	v_max_u32_e32 v149, v8, v144
	v_min_u32_e32 v8, v8, v144
	v_max_u32_e32 v144, v17, v145
	v_min_u32_e32 v17, v17, v145
	v_max_u32_e32 v145, v146, v16
	v_min_u32_e32 v16, v146, v16
	v_max_u32_e32 v26, v161, v20
	v_min_u32_e32 v20, v161, v20
	v_max_u32_e32 v161, v18, v150
	v_min_u32_e32 v18, v18, v150
	v_max_u32_e32 v150, v22, v151
	v_min_u32_e32 v22, v22, v151
	v_max_u32_e32 v151, v152, v21
	v_min_u32_e32 v21, v152, v21
	v_max_u32_e32 v152, v153, v1
	v_min_u32_e32 v1, v153, v1
	v_max_u32_e32 v153, v0, v23
	v_min_u32_e32 v0, v0, v23
	v_max_u32_e32 v23, v3, v24
	v_min_u32_e32 v3, v3, v24
	v_max_u32_e32 v24, v25, v2
	v_min_u32_e32 v2, v25, v2
	v_max_u32_e32 v146, v147, v28
	v_min_u32_e32 v28, v147, v28
	v_max_u32_e32 v147, v14, v4
	v_min_u32_e32 v4, v14, v4
	v_max_u32_e32 v14, v12, v10
	v_min_u32_e32 v10, v12, v10
	v_max_u32_e32 v12, v143, v5
	v_min_u32_e32 v5, v143, v5
	v_max_u32_e32 v143, v148, v149
	v_min_u32_e32 v148, v148, v149
	v_max_u32_e32 v149, v15, v8
	v_min_u32_e32 v8, v15, v8
	v_max_u32_e32 v15, v16, v17
	v_min_u32_e32 v16, v16, v17
	v_max_u32_e32 v17, v145, v144
	v_min_u32_e32 v144, v145, v144
	v_max_u32_e32 v25, v26, v161
	v_min_u32_e32 v26, v26, v161
	v_max_u32_e32 v161, v20, v18
	v_min_u32_e32 v18, v20, v18
	v_max_u32_e32 v20, v21, v22
	v_min_u32_e32 v21, v21, v22
	v_max_u32_e32 v22, v151, v150
	v_min_u32_e32 v150, v151, v150
	v_max_u32_e32 v151, v152, v153
	v_min_u32_e32 v152, v152, v153
	v_max_u32_e32 v153, v1, v0
	v_min_u32_e32 v0, v1, v0
	v_max_u32_e32 v1, v2, v3
	v_min_u32_e32 v2, v2, v3
	v_max_u32_e32 v3, v24, v23
	v_min_u32_e32 v23, v24, v23
	v_max_u32_e32 v145, v146, v10
	v_min_u32_e32 v10, v146, v10
	v_max_u32_e32 v146, v28, v14
	v_min_u32_e32 v14, v28, v14
	v_max_u32_e32 v28, v147, v5
	v_min_u32_e32 v5, v147, v5
	v_max_u32_e32 v147, v4, v12
	v_min_u32_e32 v4, v4, v12
	v_max_u32_e32 v12, v16, v143
	v_min_u32_e32 v16, v16, v143
	v_max_u32_e32 v143, v15, v148
	v_min_u32_e32 v15, v15, v148
	v_max_u32_e32 v148, v144, v149
	v_min_u32_e32 v144, v144, v149
	v_max_u32_e32 v149, v17, v8
	v_min_u32_e32 v8, v17, v8
	v_max_u32_e32 v24, v25, v21
	v_min_u32_e32 v21, v25, v21
	v_max_u32_e32 v25, v26, v20
	v_min_u32_e32 v20, v26, v20
	v_max_u32_e32 v26, v161, v150
	v_min_u32_e32 v150, v161, v150
	v_max_u32_e32 v161, v18, v22
	v_min_u32_e32 v18, v18, v22
	v_max_u32_e32 v22, v2, v151
	v_min_u32_e32 v2, v2, v151
	v_max_u32_e32 v151, v1, v152
	v_min_u32_e32 v1, v1, v152
	v_max_u32_e32 v152, v23, v153
	v_min_u32_e32 v23, v23, v153
	v_max_u32_e32 v153, v3, v0
	v_min_u32_e32 v0, v3, v0
	v_max_u32_e32 v17, v145, v28
	v_min_u32_e32 v28, v145, v28
	v_max_u32_e32 v145, v146, v147
	v_min_u32_e32 v146, v146, v147
	v_max_u32_e32 v147, v10, v5
	v_min_u32_e32 v5, v10, v5
	v_max_u32_e32 v10, v14, v4
	v_min_u32_e32 v4, v14, v4
	v_max_u32_e32 v14, v144, v16
	v_min_u32_e32 v16, v144, v16
	v_max_u32_e32 v144, v8, v15
	v_min_u32_e32 v8, v8, v15
	v_max_u32_e32 v15, v148, v12
	v_min_u32_e32 v12, v148, v12
	v_max_u32_e32 v148, v149, v143
	v_min_u32_e32 v143, v149, v143
	v_max_u32_e32 v3, v24, v26
	v_min_u32_e32 v24, v24, v26
	v_max_u32_e32 v26, v25, v161
	v_min_u32_e32 v25, v25, v161
	v_max_u32_e32 v161, v21, v150
	v_min_u32_e32 v21, v21, v150
	v_max_u32_e32 v150, v20, v18
	v_min_u32_e32 v18, v20, v18
	v_max_u32_e32 v20, v23, v2
	v_min_u32_e32 v2, v23, v2
	v_max_u32_e32 v23, v0, v1
	v_min_u32_e32 v0, v0, v1
	v_max_u32_e32 v1, v152, v22
	v_min_u32_e32 v22, v152, v22
	v_max_u32_e32 v152, v153, v151
	v_min_u32_e32 v151, v153, v151
	v_max_u32_e32 v149, v17, v145
	v_min_u32_e32 v17, v17, v145
	v_max_u32_e32 v145, v28, v146
	v_min_u32_e32 v28, v28, v146
	v_max_u32_e32 v146, v147, v10
	v_min_u32_e32 v10, v147, v10
	v_max_u32_e32 v147, v5, v4
	v_min_u32_e32 v4, v5, v4
	v_max_u32_e32 v5, v8, v16
	v_min_u32_e32 v8, v8, v16
	v_max_u32_e32 v16, v144, v14
	v_min_u32_e32 v14, v144, v14
	v_max_u32_e32 v144, v143, v12
	v_min_u32_e32 v12, v143, v12
	v_max_u32_e32 v143, v148, v15
	v_min_u32_e32 v15, v148, v15
	v_max_u32_e32 v153, v3, v26
	v_min_u32_e32 v3, v3, v26
	v_max_u32_e32 v26, v24, v25
	v_min_u32_e32 v24, v24, v25
	v_max_u32_e32 v25, v161, v150
	v_min_u32_e32 v150, v161, v150
	v_max_u32_e32 v161, v21, v18
	v_min_u32_e32 v18, v21, v18
	v_max_u32_e32 v21, v0, v2
	v_min_u32_e32 v0, v0, v2
	v_max_u32_e32 v2, v23, v20
	v_min_u32_e32 v20, v23, v20
	v_max_u32_e32 v23, v151, v22
	v_min_u32_e32 v22, v151, v22
	v_max_u32_e32 v151, v152, v1
	v_min_u32_e32 v1, v152, v1
	v_max_u32_e32 v148, v149, v8
	v_min_u32_e32 v8, v149, v8
	v_max_u32_e32 v149, v17, v5
	v_min_u32_e32 v5, v17, v5
	v_max_u32_e32 v17, v145, v14
	v_min_u32_e32 v14, v145, v14
	v_max_u32_e32 v145, v28, v16
	v_min_u32_e32 v16, v28, v16
	v_max_u32_e32 v28, v146, v12
	v_min_u32_e32 v12, v146, v12
	v_max_u32_e32 v146, v10, v144
	v_min_u32_e32 v10, v10, v144
	v_max_u32_e32 v144, v147, v15
	v_min_u32_e32 v15, v147, v15
	v_max_u32_e32 v147, v4, v143
	v_min_u32_e32 v4, v4, v143
	v_max_u32_e32 v152, v153, v0
	v_min_u32_e32 v0, v153, v0
	v_max_u32_e32 v153, v3, v21
	v_min_u32_e32 v3, v3, v21
	v_max_u32_e32 v21, v26, v20
	v_min_u32_e32 v20, v26, v20
	v_max_u32_e32 v26, v24, v2
	v_min_u32_e32 v2, v24, v2
	v_max_u32_e32 v24, v25, v22
	v_min_u32_e32 v22, v25, v22
	v_max_u32_e32 v25, v150, v23
	v_min_u32_e32 v23, v150, v23
	v_max_u32_e32 v150, v161, v1
	v_min_u32_e32 v1, v161, v1
	v_max_u32_e32 v161, v18, v151
	v_min_u32_e32 v18, v18, v151
	v_max_u32_e32 v143, v148, v28
	v_min_u32_e32 v28, v148, v28
	v_max_u32_e32 v148, v149, v146
	v_min_u32_e32 v146, v149, v146
; #define CE_DESC(a, b) do { const unsigned _mx = (a) > (b) ? (a) : (b), _mn = (a) > (b) ? (b) : (a); (a) = _mx; (b) = _mn; } while (0)
; __device__ __forceinline__ void merge16(unsigned (&a)[16], const unsigned (&b)[16]) {
; #pragma unroll
;     for (int i = 0; i < 16; ++i) a[i] = a[i] > b[15 - i] ? a[i] : b[15 - i];
; #pragma unroll
;     for (int stride = 8; stride > 0; stride >>= 1)
; #pragma unroll
;         for (int i = 0; i < 16; ++i) { const int j = i ^ stride; if (j > i) CE_DESC(a[i], a[j]); }
; }
; __device__ __forceinline__ void peer_tile(const Args& A, LAS unsigned char* lds, int tile) {
;     ...
;                 for (int msk = 16; msk <= 32; msk <<= 1) {
; #pragma unroll
;                     for (int i = 0; i < 16; ++i) k1[i] = (unsigned)__shfl_xor((int)k0[i], msk);
;                     merge16(k0, k1); }
	v_max_u32_e32 v149, v17, v144
	v_min_u32_e32 v17, v17, v144
	v_max_u32_e32 v144, v145, v147
	v_min_u32_e32 v145, v145, v147
	v_max_u32_e32 v147, v8, v12
	v_min_u32_e32 v8, v8, v12
	v_max_u32_e32 v12, v5, v10
	v_min_u32_e32 v5, v5, v10
	v_max_u32_e32 v10, v14, v15
	v_min_u32_e32 v14, v14, v15
	v_max_u32_e32 v15, v16, v4
	v_min_u32_e32 v4, v16, v4
	v_max_u32_e32 v151, v152, v24
	v_min_u32_e32 v24, v152, v24
	v_max_u32_e32 v152, v153, v25
	v_min_u32_e32 v25, v153, v25
	v_max_u32_e32 v153, v21, v150
	v_min_u32_e32 v21, v21, v150
	v_max_u32_e32 v150, v26, v161
	v_min_u32_e32 v26, v26, v161
	v_max_u32_e32 v161, v0, v22
	v_min_u32_e32 v0, v0, v22
	v_max_u32_e32 v22, v3, v23
	v_min_u32_e32 v3, v3, v23
	v_max_u32_e32 v23, v20, v1
	v_min_u32_e32 v1, v20, v1
	v_max_u32_e32 v20, v2, v18
	v_min_u32_e32 v2, v2, v18
	v_max_u32_e32 v16, v143, v149
	v_min_u32_e32 v143, v143, v149
	v_max_u32_e32 v149, v148, v144
	v_min_u32_e32 v144, v148, v144
	v_max_u32_e32 v148, v28, v17
	v_min_u32_e32 v17, v28, v17
	v_max_u32_e32 v28, v146, v145
	v_min_u32_e32 v145, v146, v145
	v_max_u32_e32 v146, v147, v10
	v_min_u32_e32 v10, v147, v10
	v_max_u32_e32 v147, v12, v15
	v_min_u32_e32 v12, v12, v15
	v_max_u32_e32 v15, v8, v14
	v_min_u32_e32 v8, v8, v14
	v_max_u32_e32 v14, v5, v4
	v_min_u32_e32 v4, v5, v4
	v_max_u32_e32 v18, v151, v153
	v_min_u32_e32 v151, v151, v153
	v_max_u32_e32 v153, v152, v150
	v_min_u32_e32 v150, v152, v150
	v_max_u32_e32 v152, v24, v21
	v_min_u32_e32 v21, v24, v21
	v_max_u32_e32 v24, v25, v26
	v_min_u32_e32 v25, v25, v26
	v_max_u32_e32 v26, v161, v23
	v_min_u32_e32 v23, v161, v23
	v_max_u32_e32 v161, v22, v20
	v_min_u32_e32 v20, v22, v20
	v_max_u32_e32 v22, v0, v1
	v_min_u32_e32 v0, v0, v1
	v_max_u32_e32 v1, v3, v2
	v_min_u32_e32 v2, v3, v2
	v_min_u32_e32 v5, v16, v149
	v_min_u32_e32 v154, v143, v144
	v_min_u32_e32 v155, v148, v28
	v_min_u32_e32 v156, v17, v145
	v_min_u32_e32 v157, v146, v147
	v_min_u32_e32 v158, v10, v12
	v_min_u32_e32 v159, v15, v14
	v_min_u32_e32 v160, v8, v4
	v_min_u32_e32 v3, v18, v153
	v_min_u32_e32 v162, v151, v150
	v_min_u32_e32 v163, v152, v24
	v_min_u32_e32 v164, v21, v25
	v_min_u32_e32 v165, v26, v161
	v_min_u32_e32 v166, v23, v20
	v_min_u32_e32 v167, v22, v1
	v_min_u32_e32 v168, v0, v2
	v_max3_u32 v16, v16, v149, v168
	v_max3_u32 v0, v5, v0, v2
	v_max3_u32 v2, v143, v144, v167
	v_max3_u32 v1, v154, v22, v1
	v_max3_u32 v5, v148, v28, v166
	v_max3_u32 v20, v155, v23, v20
	v_max3_u32 v17, v17, v145, v165
	v_max3_u32 v22, v156, v26, v161
	v_max3_u32 v23, v146, v147, v164
	v_max3_u32 v21, v157, v21, v25
	v_max3_u32 v10, v10, v12, v163
	v_max3_u32 v12, v158, v152, v24
	v_max3_u32 v14, v15, v14, v162
	v_max3_u32 v15, v159, v151, v150
	v_max3_u32 v3, v8, v4, v3
	v_max3_u32 v4, v160, v18, v153
	v_max_u32_e32 v8, v16, v23
	v_min_u32_e32 v16, v16, v23
	v_max_u32_e32 v18, v0, v21
	v_min_u32_e32 v0, v0, v21
	v_max_u32_e32 v21, v2, v10
	v_min_u32_e32 v2, v2, v10
	v_max_u32_e32 v10, v1, v12
	v_min_u32_e32 v1, v1, v12
	v_max_u32_e32 v12, v5, v14
	v_min_u32_e32 v5, v5, v14
	v_max_u32_e32 v14, v20, v15
	v_min_u32_e32 v15, v20, v15
	v_max_u32_e32 v20, v17, v3
	v_min_u32_e32 v3, v17, v3
	v_max_u32_e32 v17, v22, v4
	v_min_u32_e32 v4, v22, v4
	v_max_u32_e32 v22, v8, v12
	v_min_u32_e32 v8, v8, v12
	v_max_u32_e32 v12, v18, v14
	v_min_u32_e32 v14, v18, v14
	v_max_u32_e32 v18, v21, v20
	v_min_u32_e32 v20, v21, v20
	v_max_u32_e32 v21, v10, v17
	v_min_u32_e32 v10, v10, v17
	v_max_u32_e32 v17, v16, v5
	v_min_u32_e32 v5, v16, v5
	v_max_u32_e32 v16, v0, v15
	v_min_u32_e32 v0, v0, v15
	v_max_u32_e32 v15, v2, v3
	v_min_u32_e32 v2, v2, v3
	v_max_u32_e32 v3, v1, v4
	v_min_u32_e32 v1, v1, v4
	v_max_u32_e32 v4, v22, v18
	v_min_u32_e32 v18, v22, v18
	v_max_u32_e32 v22, v12, v21
	v_min_u32_e32 v12, v12, v21
	v_max_u32_e32 v21, v8, v20
	v_min_u32_e32 v8, v8, v20
	v_max_u32_e32 v20, v14, v10
	v_min_u32_e32 v10, v14, v10
	v_max_u32_e32 v14, v17, v15
	v_min_u32_e32 v15, v17, v15
	v_max_u32_e32 v17, v16, v3
	v_min_u32_e32 v3, v16, v3
	v_max_u32_e32 v16, v5, v2
	v_min_u32_e32 v2, v5, v2
	v_max_u32_e32 v5, v0, v1
	v_min_u32_e32 v0, v0, v1
	v_max_u32_e32 v1, v4, v22
	v_min_u32_e32 v4, v4, v22
	v_max_u32_e32 v22, v18, v12
	v_min_u32_e32 v12, v18, v12
	v_max_u32_e32 v18, v21, v20
	v_min_u32_e32 v20, v21, v20
	v_max_u32_e32 v21, v8, v10
	v_min_u32_e32 v8, v8, v10
	v_max_u32_e32 v10, v14, v17
	v_min_u32_e32 v14, v14, v17
	v_max_u32_e32 v17, v15, v3
	v_min_u32_e32 v3, v15, v3
	v_max_u32_e32 v15, v16, v5
	v_min_u32_e32 v5, v16, v5
	v_max_u32_e32 v16, v2, v0
	v_min_u32_e32 v0, v2, v0
	ds_bpermute_b32 v2, v27, v1
	ds_bpermute_b32 v23, v27, v4
	ds_bpermute_b32 v24, v27, v22
	ds_bpermute_b32 v25, v27, v12
	ds_bpermute_b32 v26, v27, v18
	ds_bpermute_b32 v28, v27, v20
	ds_bpermute_b32 v143, v27, v21
	ds_bpermute_b32 v144, v27, v8
	ds_bpermute_b32 v145, v27, v10
	ds_bpermute_b32 v146, v27, v14
	ds_bpermute_b32 v147, v27, v17
	ds_bpermute_b32 v148, v27, v0
	ds_bpermute_b32 v149, v27, v16
	ds_bpermute_b32 v150, v27, v5
	ds_bpermute_b32 v151, v27, v15
	ds_bpermute_b32 v27, v27, v3
	s_waitcnt lgkmcnt(4)
	v_max_u32_e32 v1, v1, v148
	s_waitcnt lgkmcnt(3)
	v_max_u32_e32 v4, v4, v149
	s_waitcnt lgkmcnt(2)
	v_max_u32_e32 v22, v22, v150
	s_waitcnt lgkmcnt(1)
	v_max_u32_e32 v12, v12, v151
	s_waitcnt lgkmcnt(0)
; __device__ __forceinline__ void peer_tile(const Args& A, LAS unsigned char* lds, int tile) {
;     ...
;                 for (int msk = 16; msk <= 32; msk <<= 1) {
; #pragma unroll
;                     for (int i = 0; i < 16; ++i) k1[i] = (unsigned)__shfl_xor((int)k0[i], msk);
;                     merge16(k0, k1); }
;     ...
;                 for (int i = 0; i < 16; ++i) L2[p][i] = (g & 2) ? ((g & 1) ? LA[3][p][i] : LA[2][p][i]) : ((g & 1) ? LA[1][p][i] : LA[0][p][i]);
	v_max_u32_e32 v18, v18, v27
	v_max_u32_e32 v20, v20, v147
	v_max_u32_e32 v21, v21, v146
	v_max_u32_e32 v8, v8, v145
	v_max_u32_e32 v10, v10, v144
	v_max_u32_e32 v14, v14, v143
	v_max_u32_e32 v17, v17, v28
	v_max_u32_e32 v3, v3, v26
	v_max_u32_e32 v15, v15, v25
	v_max_u32_e32 v5, v5, v24
	v_max_u32_e32 v16, v16, v23
	v_max_u32_e32 v0, v0, v2
	v_max_u32_e32 v2, v1, v10
	v_min_u32_e32 v1, v1, v10
	v_max_u32_e32 v10, v4, v14
	v_min_u32_e32 v4, v4, v14
	v_max_u32_e32 v14, v22, v17
	v_min_u32_e32 v17, v22, v17
	v_max_u32_e32 v22, v12, v3
	v_min_u32_e32 v3, v12, v3
	v_max_u32_e32 v12, v18, v15
	v_min_u32_e32 v15, v18, v15
	v_max_u32_e32 v18, v20, v5
	v_min_u32_e32 v5, v20, v5
	v_max_u32_e32 v20, v21, v16
	v_min_u32_e32 v16, v21, v16
	v_max_u32_e32 v21, v8, v0
	v_min_u32_e32 v0, v8, v0
	v_max_u32_e32 v8, v2, v12
	v_min_u32_e32 v2, v2, v12
	v_max_u32_e32 v12, v10, v18
	v_min_u32_e32 v10, v10, v18
	v_max_u32_e32 v18, v14, v20
	v_min_u32_e32 v14, v14, v20
	v_max_u32_e32 v20, v22, v21
	v_min_u32_e32 v21, v22, v21
	v_max_u32_e32 v22, v1, v15
	v_min_u32_e32 v1, v1, v15
	v_max_u32_e32 v15, v4, v5
	v_min_u32_e32 v4, v4, v5
	v_max_u32_e32 v5, v17, v16
	v_min_u32_e32 v16, v17, v16
	v_max_u32_e32 v17, v3, v0
	v_min_u32_e32 v0, v3, v0
	v_max_u32_e32 v3, v8, v18
	v_min_u32_e32 v8, v8, v18
	v_max_u32_e32 v18, v12, v20
	v_min_u32_e32 v12, v12, v20
	v_max_u32_e32 v20, v2, v14
	v_min_u32_e32 v2, v2, v14
	v_max_u32_e32 v14, v10, v21
	v_min_u32_e32 v10, v10, v21
	v_max_u32_e32 v21, v22, v5
	v_min_u32_e32 v5, v22, v5
	v_max_u32_e32 v22, v15, v17
	v_min_u32_e32 v15, v15, v17
	v_max_u32_e32 v17, v1, v16
	v_min_u32_e32 v1, v1, v16
	v_max_u32_e32 v16, v4, v0
	v_min_u32_e32 v0, v4, v0
	v_max_u32_e32 v4, v3, v18
	v_min_u32_e32 v3, v3, v18
	v_max_u32_e32 v18, v8, v12
	v_min_u32_e32 v8, v8, v12
	v_max_u32_e32 v12, v20, v14
	v_min_u32_e32 v14, v20, v14
	v_max_u32_e32 v20, v2, v10
	v_min_u32_e32 v2, v2, v10
	v_max_u32_e32 v10, v21, v22
	v_min_u32_e32 v21, v21, v22
	v_max_u32_e32 v22, v5, v15
	v_min_u32_e32 v5, v5, v15
	v_max_u32_e32 v15, v17, v16
	v_min_u32_e32 v16, v17, v16
	v_max_u32_e32 v17, v1, v0
	v_min_u32_e32 v0, v1, v0
	ds_bpermute_b32 v1, v29, v4
	ds_bpermute_b32 v23, v29, v3
	ds_bpermute_b32 v24, v29, v18
	ds_bpermute_b32 v25, v29, v8
	ds_bpermute_b32 v26, v29, v12
	ds_bpermute_b32 v27, v29, v14
	ds_bpermute_b32 v28, v29, v20
	ds_bpermute_b32 v143, v29, v2
	ds_bpermute_b32 v144, v29, v10
	ds_bpermute_b32 v145, v29, v21
	ds_bpermute_b32 v146, v29, v22
	ds_bpermute_b32 v147, v29, v0
	ds_bpermute_b32 v148, v29, v17
	ds_bpermute_b32 v149, v29, v16
	ds_bpermute_b32 v150, v29, v15
	ds_bpermute_b32 v29, v29, v5
	s_waitcnt lgkmcnt(4)
	v_max_u32_e32 v4, v4, v147
	s_waitcnt lgkmcnt(3)
	v_max_u32_e32 v3, v3, v148
	s_waitcnt lgkmcnt(2)
	v_max_u32_e32 v18, v18, v149
	s_waitcnt lgkmcnt(1)
	v_max_u32_e32 v8, v8, v150
	s_waitcnt lgkmcnt(0)
	v_max_u32_e32 v12, v12, v29
	v_max_u32_e32 v14, v14, v146
	v_max_u32_e32 v20, v20, v145
	v_max_u32_e32 v2, v2, v144
	v_max_u32_e32 v10, v10, v143
	v_max_u32_e32 v21, v21, v28
	v_max_u32_e32 v22, v22, v27
	v_max_u32_e32 v5, v5, v26
	v_max_u32_e32 v15, v15, v25
	v_max_u32_e32 v16, v16, v24
	v_max_u32_e32 v17, v17, v23
	v_max_u32_e32 v0, v0, v1
	v_max_u32_e32 v1, v4, v10
	v_min_u32_e32 v4, v4, v10
	v_max_u32_e32 v10, v3, v21
	v_min_u32_e32 v3, v3, v21
	v_max_u32_e32 v21, v18, v22
	v_min_u32_e32 v18, v18, v22
	v_max_u32_e32 v22, v8, v5
	v_min_u32_e32 v5, v8, v5
	v_max_u32_e32 v8, v12, v15
	v_min_u32_e32 v12, v12, v15
	v_max_u32_e32 v15, v14, v16
	v_min_u32_e32 v14, v14, v16
	v_max_u32_e32 v16, v20, v17
	v_min_u32_e32 v17, v20, v17
	v_max_u32_e32 v20, v2, v0
	v_min_u32_e32 v0, v2, v0
	v_max_u32_e32 v2, v1, v8
	v_min_u32_e32 v1, v1, v8
	v_max_u32_e32 v8, v10, v15
	v_min_u32_e32 v10, v10, v15
	v_max_u32_e32 v15, v21, v16
	v_min_u32_e32 v16, v21, v16
	v_max_u32_e32 v21, v22, v20
	v_min_u32_e32 v20, v22, v20
	v_max_u32_e32 v22, v4, v12
	v_min_u32_e32 v4, v4, v12
	v_max_u32_e32 v12, v3, v14
	v_min_u32_e32 v3, v3, v14
	v_max_u32_e32 v14, v18, v17
	v_min_u32_e32 v17, v18, v17
	v_max_u32_e32 v18, v5, v0
	v_min_u32_e32 v0, v5, v0
	v_max_u32_e32 v5, v2, v15
	v_min_u32_e32 v2, v2, v15
	v_max_u32_e32 v15, v8, v21
	v_min_u32_e32 v8, v8, v21
	v_max_u32_e32 v21, v1, v16
	v_min_u32_e32 v1, v1, v16
	v_max_u32_e32 v16, v10, v20
	v_min_u32_e32 v10, v10, v20
	v_max_u32_e32 v20, v22, v14
	v_min_u32_e32 v14, v22, v14
	v_max_u32_e32 v22, v12, v18
	v_min_u32_e32 v12, v12, v18
	v_max_u32_e32 v18, v4, v17
	v_min_u32_e32 v4, v4, v17
	v_max_u32_e32 v17, v3, v0
	v_min_u32_e32 v0, v3, v0
	v_max_u32_e32 v3, v5, v15
	v_min_u32_e32 v5, v5, v15
	v_max_u32_e32 v15, v2, v8
	v_min_u32_e32 v2, v2, v8
	v_max_u32_e32 v8, v21, v16
	v_min_u32_e32 v16, v21, v16
	v_max_u32_e32 v21, v1, v10
	v_min_u32_e32 v1, v1, v10
	v_max_u32_e32 v10, v20, v22
	v_min_u32_e32 v20, v20, v22
	v_max_u32_e32 v22, v14, v12
	v_min_u32_e32 v12, v14, v12
	v_max_u32_e32 v14, v18, v17
	v_min_u32_e32 v17, v18, v17
	v_max_u32_e32 v18, v4, v0
	v_min_u32_e32 v0, v4, v0
	v_and_b32_e32 v4, 16, v19
	v_cmp_eq_u32_e32 vcc, 0, v4
	v_cndmask_b32_e64 v23, v77, v45, s[0:1]
	v_cndmask_b32_e64 v24, v76, v44, s[0:1]
	v_cndmask_b32_e32 v4, v142, v109, vcc
	v_cndmask_b32_e64 v4, v4, v23, s[4:5]
	v_cndmask_b32_e32 v23, v141, v108, vcc
	v_cndmask_b32_e64 v23, v23, v24, s[4:5]
	v_cndmask_b32_e32 v24, v140, v107, vcc
	v_cndmask_b32_e64 v25, v75, v43, s[0:1]
	v_cndmask_b32_e64 v24, v24, v25, s[4:5]
	v_cndmask_b32_e32 v25, v139, v106, vcc
	v_cndmask_b32_e64 v26, v74, v42, s[0:1]
	v_cndmask_b32_e64 v25, v25, v26, s[4:5]
	v_cndmask_b32_e32 v26, v138, v105, vcc
	v_cndmask_b32_e64 v27, v73, v41, s[0:1]
	v_cndmask_b32_e64 v26, v26, v27, s[4:5]
; __device__ __forceinline__ float key2f(unsigned k) { const unsigned u = (k & 0x80000000u) ? (k & 0x7fffffffu) : ~k; return __uint_as_float(u); }
; __device__ __forceinline__ void peer_tile(const Args& A, LAS unsigned char* lds, int tile) {
;     ...
;                 for (int i = 0; i < 16; ++i) L2[p][i] = (g & 2) ? ((g & 1) ? LA[3][p][i] : LA[2][p][i]) : ((g & 1) ? LA[1][p][i] : LA[0][p][i]);
;             float va[16], vb[16];
; #pragma unroll
;             for (int i = 0; i < 16; ++i) { va[i] = key2f(L2[0][i] & ~127u); vb[i] = key2f(L2[1][i] & ~127u); idx[i] = 127u - (L2[0][i] & 127u); idx[16 + i] = 127u - (L2[1][i] & 127u); }
	v_cndmask_b32_e32 v27, v137, v104, vcc
	v_cndmask_b32_e64 v28, v72, v40, s[0:1]
	v_cndmask_b32_e64 v27, v27, v28, s[4:5]
	v_cndmask_b32_e32 v28, v136, v103, vcc
	v_cndmask_b32_e64 v29, v71, v39, s[0:1]
	v_cndmask_b32_e64 v28, v28, v29, s[4:5]
	v_cndmask_b32_e32 v29, v135, v102, vcc
	v_cndmask_b32_e64 v29, v29, v38, s[4:5]
	v_cndmask_b32_e32 v38, v134, v101, vcc
	v_cndmask_b32_e64 v37, v38, v37, s[4:5]
	v_cndmask_b32_e32 v38, v133, v100, vcc
	v_cndmask_b32_e64 v36, v38, v36, s[4:5]
	v_cndmask_b32_e32 v38, v132, v99, vcc
	v_cndmask_b32_e64 v38, v38, v35, s[4:5]
	v_cndmask_b32_e32 v35, v131, v98, vcc
	v_cndmask_b32_e64 v39, v35, v34, s[4:5]
	v_cndmask_b32_e32 v34, v130, v97, vcc
	v_cndmask_b32_e64 v33, v34, v33, s[4:5]
	v_cndmask_b32_e32 v34, v129, v96, vcc
	v_cndmask_b32_e64 v40, v34, v32, s[4:5]
	v_cndmask_b32_e32 v32, v128, v95, vcc
	v_cndmask_b32_e64 v42, v32, v31, s[4:5]
	v_cndmask_b32_e32 v31, v127, v94, vcc
	v_cndmask_b32_e64 v43, v31, v30, s[4:5]
	v_cndmask_b32_e32 v3, v3, v126, vcc
	v_cndmask_b32_e64 v30, v93, v61, s[0:1]
	v_cndmask_b32_e64 v3, v3, v30, s[4:5]
	v_cndmask_b32_e32 v5, v5, v125, vcc
	v_cndmask_b32_e64 v30, v92, v60, s[0:1]
	v_cndmask_b32_e64 v30, v5, v30, s[4:5]
	v_cndmask_b32_e32 v5, v15, v124, vcc
	v_cndmask_b32_e64 v15, v91, v59, s[0:1]
	v_cndmask_b32_e64 v15, v5, v15, s[4:5]
	v_cndmask_b32_e32 v2, v2, v123, vcc
	v_cndmask_b32_e64 v5, v90, v58, s[0:1]
	v_cndmask_b32_e64 v31, v2, v5, s[4:5]
	v_cndmask_b32_e32 v2, v8, v122, vcc
	v_cndmask_b32_e64 v5, v89, v57, s[0:1]
	v_cndmask_b32_e64 v8, v2, v5, s[4:5]
	v_cndmask_b32_e32 v2, v16, v121, vcc
	v_cndmask_b32_e64 v5, v88, v56, s[0:1]
	v_cndmask_b32_e64 v32, v2, v5, s[4:5]
	v_cndmask_b32_e32 v2, v21, v120, vcc
	v_cndmask_b32_e64 v5, v87, v55, s[0:1]
	v_cndmask_b32_e64 v21, v2, v5, s[4:5]
	v_cndmask_b32_e32 v1, v1, v119, vcc
	v_cndmask_b32_e64 v2, v86, v54, s[0:1]
	v_cndmask_b32_e64 v34, v1, v2, s[4:5]
	v_cndmask_b32_e32 v1, v10, v118, vcc
	v_cndmask_b32_e64 v2, v85, v53, s[0:1]
	v_cndmask_b32_e64 v41, v1, v2, s[4:5]
	v_cndmask_b32_e32 v1, v20, v117, vcc
	v_cndmask_b32_e64 v2, v84, v52, s[0:1]
	v_cndmask_b32_e64 v44, v1, v2, s[4:5]
	v_cndmask_b32_e32 v1, v22, v116, vcc
	v_cndmask_b32_e64 v2, v83, v51, s[0:1]
	v_cndmask_b32_e64 v45, v1, v2, s[4:5]
	v_cndmask_b32_e32 v1, v12, v115, vcc
	v_cndmask_b32_e64 v2, v82, v50, s[0:1]
	v_cndmask_b32_e64 v50, v1, v2, s[4:5]
	v_cndmask_b32_e32 v1, v14, v114, vcc
	v_cndmask_b32_e64 v2, v81, v49, s[0:1]
	v_cndmask_b32_e64 v49, v1, v2, s[4:5]
	v_cndmask_b32_e32 v1, v17, v112, vcc
	v_cndmask_b32_e64 v2, v80, v48, s[0:1]
	v_cndmask_b32_e64 v48, v1, v2, s[4:5]
	v_cndmask_b32_e32 v1, v18, v111, vcc
	v_cndmask_b32_e64 v2, v79, v47, s[0:1]
	v_cndmask_b32_e64 v47, v1, v2, s[4:5]
	v_cndmask_b32_e32 v0, v0, v110, vcc
	v_cndmask_b32_e64 v1, v78, v46, s[0:1]
	v_cndmask_b32_e64 v46, v0, v1, s[4:5]
	v_and_b32_e32 v0, 0x7fffff80, v4
	v_bitop3_b32 v1, v4, s19, v4 bitop3:0xcf
	v_cmp_gt_i32_e32 vcc, 0, v4
	v_bitop3_b32 v2, v4, s19, v4 bitop3:0xc
	v_bitop3_b32 v4, v23, s19, v23 bitop3:0xcf
	v_cndmask_b32_e32 v20, v1, v0, vcc
	v_and_b32_e32 v0, 0x7fffff80, v3
	v_bitop3_b32 v1, v3, s19, v3 bitop3:0xcf
	v_cmp_gt_i32_e32 vcc, 0, v3
	v_add_u32_e32 v5, 0, v6
	v_bitop3_b32 v3, v3, s19, v3 bitop3:0xc
	v_cndmask_b32_e32 v1, v1, v0, vcc
	v_and_b32_e32 v0, 0x7fffff80, v23
	v_cmp_gt_i32_e32 vcc, 0, v23
	v_bitop3_b32 v14, v31, s19, v31 bitop3:0xcf
	v_bitop3_b32 v6, v24, s19, v24 bitop3:0xc
	v_cndmask_b32_e32 v18, v4, v0, vcc
	v_and_b32_e32 v0, 0x7fffff80, v30
	v_bitop3_b32 v4, v30, s19, v30 bitop3:0xcf
	v_cmp_gt_i32_e32 vcc, 0, v30
	v_bitop3_b32 v10, v15, s19, v15 bitop3:0xc
	v_bitop3_b32 v16, v32, s19, v32 bitop3:0xcf
	v_cndmask_b32_e32 v0, v4, v0, vcc
	v_bitop3_b32 v4, v23, s19, v23 bitop3:0xc
	ds_write2_b32 v5, v2, v4 offset1:1
	v_bitop3_b32 v2, v30, s19, v30 bitop3:0xc
	ds_write2_b32 v5, v3, v2 offset0:16 offset1:17
	v_and_b32_e32 v2, 0x7fffff80, v24
	v_bitop3_b32 v3, v24, s19, v24 bitop3:0xcf
	v_cmp_gt_i32_e32 vcc, 0, v24
	v_bitop3_b32 v4, v25, s19, v25 bitop3:0xcf
	v_bitop3_b32 v22, v29, s19, v29 bitop3:0xcf
	v_cndmask_b32_e32 v12, v3, v2, vcc
	v_and_b32_e32 v2, 0x7fffff80, v15
	v_bitop3_b32 v3, v15, s19, v15 bitop3:0xcf
	v_cmp_gt_i32_e32 vcc, 0, v15
	v_bitop3_b32 v15, v27, s19, v27 bitop3:0xcf
	v_bitop3_b32 v24, v34, s19, v34 bitop3:0xcf
	v_cndmask_b32_e32 v3, v3, v2, vcc
	v_and_b32_e32 v2, 0x7fffff80, v25
	v_cmp_gt_i32_e32 vcc, 0, v25
	s_nop 1
	v_cndmask_b32_e32 v4, v4, v2, vcc
	v_and_b32_e32 v2, 0x7fffff80, v31
	v_cmp_gt_i32_e32 vcc, 0, v31
	s_nop 1
	v_cndmask_b32_e32 v2, v14, v2, vcc
	v_bitop3_b32 v14, v25, s19, v25 bitop3:0xc
	ds_write2_b32 v5, v6, v14 offset0:2 offset1:3
	v_bitop3_b32 v6, v31, s19, v31 bitop3:0xc
	ds_write2_b32 v5, v10, v6 offset0:18 offset1:19
	v_and_b32_e32 v6, 0x7fffff80, v26
	v_bitop3_b32 v10, v26, s19, v26 bitop3:0xcf
	v_cmp_gt_i32_e32 vcc, 0, v26
	v_bitop3_b32 v25, v36, s19, v36 bitop3:0xcf
	s_nop 0
	v_cndmask_b32_e32 v14, v10, v6, vcc
	v_and_b32_e32 v6, 0x7fffff80, v8
	v_bitop3_b32 v10, v8, s19, v8 bitop3:0xcf
	v_cmp_gt_i32_e32 vcc, 0, v8
	v_bitop3_b32 v8, v8, s19, v8 bitop3:0xc
	s_nop 0
	v_cndmask_b32_e32 v17, v10, v6, vcc
	v_and_b32_e32 v10, 0x7fffff80, v27
	v_cmp_gt_i32_e32 vcc, 0, v27
	v_bitop3_b32 v6, v26, s19, v26 bitop3:0xc
	v_bitop3_b32 v26, v43, s19, v43 bitop3:0xcf
	v_cndmask_b32_e32 v10, v15, v10, vcc
	v_and_b32_e32 v15, 0x7fffff80, v32
	v_cmp_gt_i32_e32 vcc, 0, v32
	s_nop 1
	v_cndmask_b32_e32 v16, v16, v15, vcc
	v_bitop3_b32 v15, v27, s19, v27 bitop3:0xc
	ds_write2_b32 v5, v6, v15 offset0:4 offset1:5
	v_bitop3_b32 v6, v32, s19, v32 bitop3:0xc
	ds_write2_b32 v5, v8, v6 offset0:20 offset1:21
	v_and_b32_e32 v6, 0x7fffff80, v28
; __device__ __forceinline__ float key2f(unsigned k) { const unsigned u = (k & 0x80000000u) ? (k & 0x7fffffffu) : ~k; return __uint_as_float(u); }
; #define CK(i, j) ((f2key(va[i] + vb[j]) & ~255u) | (unsigned)(255 - (16 * (i) + (j))))
; __device__ __forceinline__ void peer_tile(const Args& A, LAS unsigned char* lds, int tile) {
;     ...
;             for (int i = 0; i < 16; ++i) { va[i] = key2f(L2[0][i] & ~127u); vb[i] = key2f(L2[1][i] & ~127u); idx[i] = 127u - (L2[0][i] & 127u); idx[16 + i] = 127u - (L2[1][i] & 127u); }
;     ...
;             unsigned Lf[16], Bt[16];
; #pragma unroll
;             for (int j = 0; j < 16; ++j) Lf[j] = CK(0, j);
	v_bitop3_b32 v8, v28, s19, v28 bitop3:0xcf
	v_cmp_gt_i32_e32 vcc, 0, v28
	v_bitop3_b32 v15, v21, s19, v21 bitop3:0xcf
	s_nop 0
	v_cndmask_b32_e32 v8, v8, v6, vcc
	v_and_b32_e32 v6, 0x7fffff80, v21
	v_cmp_gt_i32_e32 vcc, 0, v21
	v_bitop3_b32 v21, v21, s19, v21 bitop3:0xc
	s_nop 0
	v_cndmask_b32_e32 v23, v15, v6, vcc
	v_and_b32_e32 v6, 0x7fffff80, v29
	v_cmp_gt_i32_e32 vcc, 0, v29
	v_bitop3_b32 v15, v28, s19, v28 bitop3:0xc
	s_nop 0
	v_cndmask_b32_e32 v6, v22, v6, vcc
	v_and_b32_e32 v22, 0x7fffff80, v34
	v_cmp_gt_i32_e32 vcc, 0, v34
	s_nop 1
	v_cndmask_b32_e32 v22, v24, v22, vcc
	v_bitop3_b32 v24, v29, s19, v29 bitop3:0xc
	ds_write2_b32 v5, v15, v24 offset0:6 offset1:7
	v_bitop3_b32 v15, v34, s19, v34 bitop3:0xc
	ds_write2_b32 v5, v21, v15 offset0:22 offset1:23
	v_and_b32_e32 v15, 0x7fffff80, v37
	v_bitop3_b32 v21, v37, s19, v37 bitop3:0xcf
	v_cmp_gt_i32_e32 vcc, 0, v37
	v_and_b32_e32 v24, 0x7fffff80, v36
	s_nop 0
	v_cndmask_b32_e32 v27, v21, v15, vcc
	v_and_b32_e32 v15, 0x7fffff80, v41
	v_bitop3_b32 v21, v41, s19, v41 bitop3:0xcf
	v_cmp_gt_i32_e32 vcc, 0, v41
	s_nop 1
	v_cndmask_b32_e32 v35, v21, v15, vcc
	v_cmp_gt_i32_e32 vcc, 0, v36
	v_bitop3_b32 v15, v37, s19, v37 bitop3:0xc
	v_bitop3_b32 v21, v41, s19, v41 bitop3:0xc
	v_cndmask_b32_e32 v28, v25, v24, vcc
	v_and_b32_e32 v24, 0x7fffff80, v44
	v_bitop3_b32 v25, v44, s19, v44 bitop3:0xcf
	v_cmp_gt_i32_e32 vcc, 0, v44
	s_nop 1
	v_cndmask_b32_e32 v34, v25, v24, vcc
	v_bitop3_b32 v24, v36, s19, v36 bitop3:0xc
	ds_write2_b32 v5, v15, v24 offset0:8 offset1:9
	v_bitop3_b32 v15, v44, s19, v44 bitop3:0xc
	ds_write2_b32 v5, v21, v15 offset0:24 offset1:25
	v_and_b32_e32 v15, 0x7fffff80, v38
	v_bitop3_b32 v21, v38, s19, v38 bitop3:0xcf
	v_cmp_gt_i32_e32 vcc, 0, v38
	v_and_b32_e32 v24, 0x7fffff80, v39
	v_bitop3_b32 v25, v39, s19, v39 bitop3:0xcf
	v_cndmask_b32_e32 v29, v21, v15, vcc
	v_and_b32_e32 v15, 0x7fffff80, v45
	v_bitop3_b32 v21, v45, s19, v45 bitop3:0xcf
	v_cmp_gt_i32_e32 vcc, 0, v45
	s_nop 1
	v_cndmask_b32_e32 v37, v21, v15, vcc
	v_cmp_gt_i32_e32 vcc, 0, v39
	v_bitop3_b32 v15, v38, s19, v38 bitop3:0xc
	v_bitop3_b32 v21, v45, s19, v45 bitop3:0xc
	v_cndmask_b32_e32 v30, v25, v24, vcc
	v_and_b32_e32 v24, 0x7fffff80, v50
	v_bitop3_b32 v25, v50, s19, v50 bitop3:0xcf
	v_cmp_gt_i32_e32 vcc, 0, v50
	s_nop 1
	v_cndmask_b32_e32 v36, v25, v24, vcc
	v_bitop3_b32 v24, v39, s19, v39 bitop3:0xc
	ds_write2_b32 v5, v15, v24 offset0:10 offset1:11
	v_bitop3_b32 v15, v50, s19, v50 bitop3:0xc
	ds_write2_b32 v5, v21, v15 offset0:26 offset1:27
	v_and_b32_e32 v15, 0x7fffff80, v33
	v_bitop3_b32 v21, v33, s19, v33 bitop3:0xcf
	v_cmp_gt_i32_e32 vcc, 0, v33
	v_and_b32_e32 v24, 0x7fffff80, v40
	v_bitop3_b32 v25, v40, s19, v40 bitop3:0xcf
	v_cndmask_b32_e32 v31, v21, v15, vcc
	v_and_b32_e32 v15, 0x7fffff80, v49
	v_bitop3_b32 v21, v49, s19, v49 bitop3:0xcf
	v_cmp_gt_i32_e32 vcc, 0, v49
	s_nop 1
	v_cndmask_b32_e32 v39, v21, v15, vcc
	v_cmp_gt_i32_e32 vcc, 0, v40
	v_bitop3_b32 v15, v33, s19, v33 bitop3:0xc
	v_bitop3_b32 v21, v49, s19, v49 bitop3:0xc
	v_cndmask_b32_e32 v32, v25, v24, vcc
	v_and_b32_e32 v24, 0x7fffff80, v48
	v_bitop3_b32 v25, v48, s19, v48 bitop3:0xcf
	v_cmp_gt_i32_e32 vcc, 0, v48
	v_bitop3_b32 v33, v46, s19, v46 bitop3:0xcf
	s_nop 0
	v_cndmask_b32_e32 v38, v25, v24, vcc
	v_bitop3_b32 v24, v40, s19, v40 bitop3:0xc
	ds_write2_b32 v5, v15, v24 offset0:12 offset1:13
	v_bitop3_b32 v15, v48, s19, v48 bitop3:0xc
	ds_write2_b32 v5, v21, v15 offset0:28 offset1:29
	v_and_b32_e32 v15, 0x7fffff80, v42
	v_bitop3_b32 v21, v42, s19, v42 bitop3:0xcf
	v_cmp_gt_i32_e32 vcc, 0, v42
	v_and_b32_e32 v24, 0x7fffff80, v43
	s_nop 0
	v_cndmask_b32_e32 v25, v21, v15, vcc
	v_and_b32_e32 v15, 0x7fffff80, v47
	v_bitop3_b32 v21, v47, s19, v47 bitop3:0xcf
	v_cmp_gt_i32_e32 vcc, 0, v47
	s_nop 1
	v_cndmask_b32_e32 v41, v21, v15, vcc
	v_cmp_gt_i32_e32 vcc, 0, v43
	v_bitop3_b32 v21, v47, s19, v47 bitop3:0xc
	v_bitop3_b32 v15, v42, s19, v42 bitop3:0xc
	v_cndmask_b32_e32 v26, v26, v24, vcc
	v_and_b32_e32 v24, 0x7fffff80, v46
	v_cmp_gt_i32_e32 vcc, 0, v46
	v_pk_add_f32 v[34:35], v[20:21], v[34:35] op_sel_hi:[0,1]
	s_nop 0
	v_cndmask_b32_e32 v40, v33, v24, vcc
	v_bitop3_b32 v24, v43, s19, v43 bitop3:0xc
	v_pk_add_f32 v[42:43], v[20:21], v[0:1] op_sel_hi:[0,1]
	ds_write2_b32 v5, v15, v24 offset0:14 offset1:15
	v_not_b32_e32 v15, v43
	v_or_b32_e32 v33, 0x80000000, v43
	v_cmp_gt_i32_e32 vcc, 0, v43
	v_or_b32_e32 v43, 0x80000000, v42
	v_bitop3_b32 v24, v46, s19, v46 bitop3:0xc
	v_cndmask_b32_e32 v15, v33, v15, vcc
	v_or_b32_e32 v33, 0xff, v15
	v_not_b32_e32 v15, v42
	v_cmp_gt_i32_e32 vcc, 0, v42
	ds_write2_b32 v5, v21, v24 offset0:30 offset1:31
	s_waitcnt lgkmcnt(0)
; #define CK(i, j) ((f2key(va[i] + vb[j]) & ~255u) | (unsigned)(255 - (16 * (i) + (j))))
; __device__ __forceinline__ void peer_tile(const Args& A, LAS unsigned char* lds, int tile) {
;     ...
;             unsigned Lf[16], Bt[16];
; #pragma unroll
;             for (int j = 0; j < 16; ++j) Lf[j] = CK(0, j);
; #pragma unroll
;             for (int j = 0; j < 8; ++j) Bt[j] = CK(1, j);
; #pragma unroll
;             for (int j = 0; j < 5; ++j) Bt[8 + j] = CK(2, j);
; #pragma unroll
;             for (int j = 0; j < 3; ++j) Bt[13 + j] = CK(4, j);
	s_nop 0
	v_cndmask_b32_e32 v15, v43, v15, vcc
	v_and_b32_e32 v15, 0xffffff00, v15
	v_pk_add_f32 v[42:43], v[20:21], v[2:3] op_sel_hi:[0,1]
	v_or_b32_e32 v44, 0xfe, v15
	v_not_b32_e32 v15, v43
	v_or_b32_e32 v45, 0x80000000, v43
	v_cmp_gt_i32_e32 vcc, 0, v43
	v_or_b32_e32 v43, 0x80000000, v42
	s_nop 0
	v_cndmask_b32_e32 v15, v45, v15, vcc
	v_and_b32_e32 v15, 0xffffff00, v15
	v_or_b32_e32 v45, 0xfd, v15
	v_not_b32_e32 v15, v42
	v_cmp_gt_i32_e32 vcc, 0, v42
	s_nop 1
	v_cndmask_b32_e32 v15, v43, v15, vcc
	v_and_b32_e32 v15, 0xffffff00, v15
	v_pk_add_f32 v[42:43], v[20:21], v[16:17] op_sel_hi:[0,1]
	v_or_b32_e32 v46, 0xfc, v15
	v_not_b32_e32 v15, v43
	v_or_b32_e32 v47, 0x80000000, v43
	v_cmp_gt_i32_e32 vcc, 0, v43
	v_or_b32_e32 v43, 0x80000000, v42
	s_nop 0
	v_cndmask_b32_e32 v15, v47, v15, vcc
	v_and_b32_e32 v15, 0xffffff00, v15
	v_or_b32_e32 v47, 0xfb, v15
	v_not_b32_e32 v15, v42
	v_cmp_gt_i32_e32 vcc, 0, v42
	s_nop 1
	v_cndmask_b32_e32 v15, v43, v15, vcc
	v_and_b32_e32 v15, 0xffffff00, v15
	v_pk_add_f32 v[42:43], v[20:21], v[22:23] op_sel_hi:[0,1]
	v_or_b32_e32 v48, 0xfa, v15
	v_not_b32_e32 v15, v43
	v_or_b32_e32 v49, 0x80000000, v43
	v_cmp_gt_i32_e32 vcc, 0, v43
	v_pk_add_f32 v[22:23], v[18:19], v[22:23] op_sel_hi:[0,1]
	s_nop 0
	v_cndmask_b32_e32 v15, v49, v15, vcc
	v_and_b32_e32 v15, 0xffffff00, v15
	v_or_b32_e32 v43, 0xf9, v15
	v_not_b32_e32 v15, v42
	v_or_b32_e32 v49, 0x80000000, v42
	v_cmp_gt_i32_e32 vcc, 0, v42
	s_nop 1
	v_cndmask_b32_e32 v15, v49, v15, vcc
	v_and_b32_e32 v15, 0xffffff00, v15
	v_or_b32_e32 v42, 0xf8, v15
	v_not_b32_e32 v15, v35
	v_or_b32_e32 v49, 0x80000000, v35
	v_cmp_gt_i32_e32 vcc, 0, v35
	v_or_b32_e32 v35, 0x80000000, v34
	s_nop 0
	v_cndmask_b32_e32 v15, v49, v15, vcc
	v_and_b32_e32 v15, 0xffffff00, v15
	v_or_b32_e32 v49, 0xf7, v15
	v_not_b32_e32 v15, v34
	v_cmp_gt_i32_e32 vcc, 0, v34
	s_nop 1
	v_cndmask_b32_e32 v15, v35, v15, vcc
	v_and_b32_e32 v15, 0xffffff00, v15
	v_pk_add_f32 v[34:35], v[20:21], v[36:37] op_sel_hi:[0,1]
	v_or_b32_e32 v50, 0xf6, v15
	v_not_b32_e32 v15, v35
	v_or_b32_e32 v36, 0x80000000, v35
	v_cmp_gt_i32_e32 vcc, 0, v35
	v_or_b32_e32 v35, 0x80000000, v34
	s_nop 0
	v_cndmask_b32_e32 v15, v36, v15, vcc
	v_and_b32_e32 v15, 0xffffff00, v15
	v_or_b32_e32 v36, 0xf5, v15
	v_not_b32_e32 v15, v34
	v_cmp_gt_i32_e32 vcc, 0, v34
	s_nop 1
	v_cndmask_b32_e32 v15, v35, v15, vcc
	v_and_b32_e32 v15, 0xffffff00, v15
	v_pk_add_f32 v[34:35], v[20:21], v[38:39] op_sel_hi:[0,1]
	v_or_b32_e32 v37, 0xf4, v15
	v_not_b32_e32 v15, v35
	v_or_b32_e32 v38, 0x80000000, v35
	v_cmp_gt_i32_e32 vcc, 0, v35
	v_or_b32_e32 v35, 0x80000000, v34
	s_nop 0
	v_cndmask_b32_e32 v15, v38, v15, vcc
	v_and_b32_e32 v15, 0xffffff00, v15
	v_or_b32_e32 v38, 0xf3, v15
	v_not_b32_e32 v15, v34
	v_cmp_gt_i32_e32 vcc, 0, v34
	s_nop 1
	v_cndmask_b32_e32 v15, v35, v15, vcc
	v_and_b32_e32 v15, 0xffffff00, v15
	v_pk_add_f32 v[34:35], v[20:21], v[40:41] op_sel_hi:[0,1]
	v_or_b32_e32 v39, 0xf2, v15
	v_not_b32_e32 v15, v35
	v_or_b32_e32 v20, 0x80000000, v35
	v_cmp_gt_i32_e32 vcc, 0, v35
	v_or_b32_e32 v35, 0x80000000, v34
	s_nop 0
	v_cndmask_b32_e32 v15, v20, v15, vcc
	v_and_b32_e32 v15, 0xffffff00, v15
	v_or_b32_e32 v20, 0xf1, v15
	v_not_b32_e32 v15, v34
	v_cmp_gt_i32_e32 vcc, 0, v34
	s_nop 1
	v_cndmask_b32_e32 v15, v35, v15, vcc
	v_and_b32_e32 v15, 0xffffff00, v15
	v_pk_add_f32 v[34:35], v[18:19], v[0:1] op_sel_hi:[0,1]
	v_or_b32_e32 v40, 0xf0, v15
	v_not_b32_e32 v15, v35
	v_or_b32_e32 v41, 0x80000000, v35
	v_cmp_gt_i32_e32 vcc, 0, v35
	v_or_b32_e32 v35, 0x80000000, v34
	s_nop 0
	v_cndmask_b32_e32 v15, v41, v15, vcc
	v_and_b32_e32 v15, 0xffffff00, v15
	v_or_b32_e32 v41, 0xef, v15
	v_not_b32_e32 v15, v34
	v_cmp_gt_i32_e32 vcc, 0, v34
	s_nop 1
	v_cndmask_b32_e32 v15, v35, v15, vcc
	v_and_b32_e32 v15, 0xffffff00, v15
	v_pk_add_f32 v[34:35], v[18:19], v[2:3] op_sel_hi:[0,1]
	v_or_b32_e32 v51, 0xee, v15
	v_not_b32_e32 v15, v35
	v_or_b32_e32 v52, 0x80000000, v35
	v_cmp_gt_i32_e32 vcc, 0, v35
	v_or_b32_e32 v35, 0x80000000, v34
	s_nop 0
	v_cndmask_b32_e32 v15, v52, v15, vcc
	v_and_b32_e32 v15, 0xffffff00, v15
	v_or_b32_e32 v52, 0xed, v15
	v_not_b32_e32 v15, v34
	v_cmp_gt_i32_e32 vcc, 0, v34
	s_nop 1
	v_cndmask_b32_e32 v15, v35, v15, vcc
	v_and_b32_e32 v15, 0xffffff00, v15
	v_pk_add_f32 v[34:35], v[18:19], v[16:17] op_sel_hi:[0,1]
	v_or_b32_e32 v53, 0xec, v15
	v_not_b32_e32 v15, v35
	v_or_b32_e32 v16, 0x80000000, v35
	v_cmp_gt_i32_e32 vcc, 0, v35
	s_nop 1
	v_cndmask_b32_e32 v15, v16, v15, vcc
	v_and_b32_e32 v15, 0xffffff00, v15
	v_or_b32_e32 v35, 0xeb, v15
	v_not_b32_e32 v15, v34
	v_or_b32_e32 v16, 0x80000000, v34
	v_cmp_gt_i32_e32 vcc, 0, v34
	s_nop 1
	v_cndmask_b32_e32 v15, v16, v15, vcc
	v_and_b32_e32 v15, 0xffffff00, v15
	v_or_b32_e32 v34, 0xea, v15
	v_not_b32_e32 v15, v23
	v_or_b32_e32 v16, 0x80000000, v23
	v_cmp_gt_i32_e32 vcc, 0, v23
	s_nop 1
	v_cndmask_b32_e32 v15, v16, v15, vcc
	v_and_b32_e32 v15, 0xffffff00, v15
	v_or_b32_e32 v18, 0xe9, v15
	v_not_b32_e32 v15, v22
	v_or_b32_e32 v16, 0x80000000, v22
	v_cmp_gt_i32_e32 vcc, 0, v22
	v_pk_add_f32 v[22:23], v[12:13], v[0:1] op_sel_hi:[0,1]
	s_nop 0
	v_cndmask_b32_e32 v15, v16, v15, vcc
	v_and_b32_e32 v15, 0xffffff00, v15
	v_or_b32_e32 v54, 0xe8, v15
	v_not_b32_e32 v15, v23
	v_or_b32_e32 v16, 0x80000000, v23
	v_cmp_gt_i32_e32 vcc, 0, v23
	s_nop 1
	v_cndmask_b32_e32 v15, v16, v15, vcc
	v_and_b32_e32 v15, 0xffffff00, v15
	v_or_b32_e32 v55, 0xdf, v15
	v_not_b32_e32 v15, v22
	v_or_b32_e32 v16, 0x80000000, v22
	v_cmp_gt_i32_e32 vcc, 0, v22
	v_pk_add_f32 v[22:23], v[12:13], v[2:3] op_sel_hi:[0,1]
	v_lshl_add_u32 v13, v13, 10, s35
	v_cndmask_b32_e32 v15, v16, v15, vcc
	v_and_b32_e32 v15, 0xffffff00, v15
; #define CE_DESC(a, b) do { const unsigned _mx = (a) > (b) ? (a) : (b), _mn = (a) > (b) ? (b) : (a); (a) = _mx; (b) = _mn; } while (0)
; #define CK(i, j) ((f2key(va[i] + vb[j]) & ~255u) | (unsigned)(255 - (16 * (i) + (j))))
; __device__ __forceinline__ void sort16_desc(unsigned (&k)[16]) {
; #pragma unroll
;     for (int size = 2; size <= 16; size <<= 1)
; #pragma unroll
;         for (int stride = size >> 1; stride > 0; stride >>= 1)
; #pragma unroll
;             for (int i = 0; i < 16; ++i) { const int j = i ^ stride;
;                 if (j > i) { if ((i & size) == 0) CE_DESC(k[i], k[j]); else CE_DESC(k[j], k[i]); } }
; }
; __device__ __forceinline__ void peer_tile(const Args& A, LAS unsigned char* lds, int tile) {
;     ...
;             for (int j = 0; j < 8; ++j) Bt[j] = CK(1, j);
; #pragma unroll
;             for (int j = 0; j < 5; ++j) Bt[8 + j] = CK(2, j);
; #pragma unroll
;             for (int j = 0; j < 3; ++j) Bt[13 + j] = CK(4, j);
;             sort16_desc(Bt); merge16(Lf, Bt);
	v_or_b32_e32 v56, 0xde, v15
	v_not_b32_e32 v15, v23
	v_or_b32_e32 v16, 0x80000000, v23
	v_cmp_gt_i32_e32 vcc, 0, v23
	s_nop 1
	v_cndmask_b32_e32 v15, v16, v15, vcc
	v_and_b32_e32 v15, 0xffffff00, v15
	v_or_b32_e32 v23, 0xdd, v15
	v_not_b32_e32 v15, v22
	v_or_b32_e32 v16, 0x80000000, v22
	v_cmp_gt_i32_e32 vcc, 0, v22
	s_nop 1
	v_cndmask_b32_e32 v15, v16, v15, vcc
	v_and_b32_e32 v15, 0xffffff00, v15
	v_or_b32_e32 v22, 0xdc, v15
	v_mov_b32_e32 v15, v12
	v_mov_b32_e32 v16, v1
	v_pk_add_f32 v[16:17], v[14:15], v[16:17]
	s_nop 0
	v_not_b32_e32 v12, v17
	v_or_b32_e32 v15, 0x80000000, v17
	v_cmp_gt_i32_e32 vcc, 0, v17
	v_or_b32_e32 v17, 0x80000000, v16
	s_nop 0
	v_cndmask_b32_e32 v12, v15, v12, vcc
	v_not_b32_e32 v15, v16
	v_cmp_gt_i32_e32 vcc, 0, v16
	v_mov_b32_e32 v16, v3
	v_and_b32_e32 v12, 0xffffff00, v12
	v_cndmask_b32_e32 v15, v17, v15, vcc
	v_and_b32_e32 v15, 0xffffff00, v15
	v_mov_b32_e32 v17, v0
	v_or_b32_e32 v57, 0xbf, v15
	v_pk_add_f32 v[14:15], v[14:15], v[16:17] op_sel_hi:[0,1]
	v_not_b32_e32 v16, v15
	v_or_b32_e32 v17, 0x80000000, v15
	v_cmp_gt_i32_e32 vcc, 0, v15
	v_or_b32_e32 v12, 0xdb, v12
	v_pk_add_f32 v[2:3], v[4:5], v[2:3] op_sel_hi:[0,1]
	v_cndmask_b32_e32 v15, v17, v16, vcc
	v_not_b32_e32 v16, v14
	v_or_b32_e32 v17, 0x80000000, v14
	v_cmp_gt_i32_e32 vcc, 0, v14
	v_and_b32_e32 v15, 0xffffff00, v15
	v_or_b32_e32 v15, 0xbe, v15
	v_cndmask_b32_e32 v14, v17, v16, vcc
	v_and_b32_e32 v14, 0xffffff00, v14
	v_or_b32_e32 v14, 0xbd, v14
	v_max_u32_e32 v16, v41, v51
	v_min_u32_e32 v17, v41, v51
	v_max_u32_e32 v41, v53, v52
	v_min_u32_e32 v51, v53, v52
	v_max_u32_e32 v52, v35, v34
	v_min_u32_e32 v34, v35, v34
	v_max_u32_e32 v35, v54, v18
	v_min_u32_e32 v18, v54, v18
	v_max_u32_e32 v53, v55, v56
	v_min_u32_e32 v54, v55, v56
	v_max_u32_e32 v55, v22, v23
	v_min_u32_e32 v22, v22, v23
	v_max_u32_e32 v23, v12, v57
	v_min_u32_e32 v12, v12, v57
	v_max_u32_e32 v56, v14, v15
	v_min_u32_e32 v14, v14, v15
	v_max_u32_e32 v15, v16, v51
	v_min_u32_e32 v16, v16, v51
	v_max_u32_e32 v51, v17, v41
	v_min_u32_e32 v17, v17, v41
	v_max_u32_e32 v41, v18, v52
	v_min_u32_e32 v18, v18, v52
	v_max_u32_e32 v52, v35, v34
	v_min_u32_e32 v34, v35, v34
	v_max_u32_e32 v35, v53, v22
	v_min_u32_e32 v22, v53, v22
	v_max_u32_e32 v53, v54, v55
	v_min_u32_e32 v54, v54, v55
	v_max_u32_e32 v55, v14, v23
	v_min_u32_e32 v14, v14, v23
	v_max_u32_e32 v23, v56, v12
	v_min_u32_e32 v12, v56, v12
	v_max_u32_e32 v56, v15, v51
	v_min_u32_e32 v15, v15, v51
	v_max_u32_e32 v51, v16, v17
	v_min_u32_e32 v16, v16, v17
	v_max_u32_e32 v17, v34, v18
	v_min_u32_e32 v18, v34, v18
	v_max_u32_e32 v34, v52, v41
	v_min_u32_e32 v41, v52, v41
	v_max_u32_e32 v52, v35, v53
	v_min_u32_e32 v35, v35, v53
	v_max_u32_e32 v53, v22, v54
	v_min_u32_e32 v22, v22, v54
	v_max_u32_e32 v54, v12, v14
	v_min_u32_e32 v12, v12, v14
	v_max_u32_e32 v14, v23, v55
	v_min_u32_e32 v23, v23, v55
	v_max_u32_e32 v55, v56, v18
	v_min_u32_e32 v18, v56, v18
	v_max_u32_e32 v56, v15, v17
	v_min_u32_e32 v15, v15, v17
	v_max_u32_e32 v17, v51, v41
	v_min_u32_e32 v41, v51, v41
	v_max_u32_e32 v51, v16, v34
	v_min_u32_e32 v16, v16, v34
	v_max_u32_e32 v34, v12, v52
	v_min_u32_e32 v12, v12, v52
	v_max_u32_e32 v52, v54, v35
	v_min_u32_e32 v35, v54, v35
	v_max_u32_e32 v54, v23, v53
	v_min_u32_e32 v23, v23, v53
	v_max_u32_e32 v53, v14, v22
	v_min_u32_e32 v14, v14, v22
	v_max_u32_e32 v22, v55, v17
	v_min_u32_e32 v17, v55, v17
	v_max_u32_e32 v55, v56, v51
	v_min_u32_e32 v51, v56, v51
	v_max_u32_e32 v56, v18, v41
	v_min_u32_e32 v18, v18, v41
	v_max_u32_e32 v41, v15, v16
	v_min_u32_e32 v15, v15, v16
	v_max_u32_e32 v16, v23, v12
	v_min_u32_e32 v12, v23, v12
	v_max_u32_e32 v23, v14, v35
	v_min_u32_e32 v14, v14, v35
	v_max_u32_e32 v35, v54, v34
	v_min_u32_e32 v34, v54, v34
	v_max_u32_e32 v54, v53, v52
	v_min_u32_e32 v52, v53, v52
	v_max_u32_e32 v53, v22, v55
	v_min_u32_e32 v22, v22, v55
	v_max_u32_e32 v55, v17, v51
	v_min_u32_e32 v17, v17, v51
	v_max_u32_e32 v51, v56, v41
	v_min_u32_e32 v41, v56, v41
	v_max_u32_e32 v56, v18, v15
	v_min_u32_e32 v15, v18, v15
	v_max_u32_e32 v18, v14, v12
	v_min_u32_e32 v12, v14, v12
	v_max_u32_e32 v14, v23, v16
	v_min_u32_e32 v16, v23, v16
	v_max_u32_e32 v23, v52, v34
	v_min_u32_e32 v34, v52, v34
	v_max_u32_e32 v52, v54, v35
	v_min_u32_e32 v35, v54, v35
	v_max_u32_e32 v54, v53, v12
	v_min_u32_e32 v12, v53, v12
	v_max_u32_e32 v53, v22, v18
	v_min_u32_e32 v18, v22, v18
	v_max_u32_e32 v22, v55, v16
	v_min_u32_e32 v16, v55, v16
	v_max_u32_e32 v55, v17, v14
	v_min_u32_e32 v14, v17, v14
	v_max_u32_e32 v17, v51, v34
	v_min_u32_e32 v34, v51, v34
	v_max_u32_e32 v51, v41, v23
	v_min_u32_e32 v23, v41, v23
	v_max_u32_e32 v41, v56, v35
	v_min_u32_e32 v35, v56, v35
	v_max_u32_e32 v56, v15, v52
	v_min_u32_e32 v15, v15, v52
	v_max_u32_e32 v52, v54, v17
	v_min_u32_e32 v17, v54, v17
	v_max_u32_e32 v54, v53, v51
	v_min_u32_e32 v51, v53, v51
	v_max_u32_e32 v53, v22, v41
	v_min_u32_e32 v22, v22, v41
	v_max_u32_e32 v41, v55, v56
	v_min_u32_e32 v55, v55, v56
	v_max_u32_e32 v56, v12, v34
	v_min_u32_e32 v12, v12, v34
	v_max_u32_e32 v34, v18, v23
	v_min_u32_e32 v18, v18, v23
	v_max_u32_e32 v23, v16, v35
	v_min_u32_e32 v16, v16, v35
	v_max_u32_e32 v35, v14, v15
	v_min_u32_e32 v14, v14, v15
	v_max_u32_e32 v15, v52, v53
	v_min_u32_e32 v52, v52, v53
	v_max_u32_e32 v53, v54, v41
	v_min_u32_e32 v41, v54, v41
	v_max_u32_e32 v54, v17, v22
	v_min_u32_e32 v17, v17, v22
	v_max_u32_e32 v22, v51, v55
	v_min_u32_e32 v51, v51, v55
	v_max_u32_e32 v55, v56, v23
	v_min_u32_e32 v23, v56, v23
	v_max_u32_e32 v56, v34, v35
	v_min_u32_e32 v34, v34, v35
	v_max_u32_e32 v35, v12, v16
	v_min_u32_e32 v12, v12, v16
	v_max_u32_e32 v16, v18, v14
	v_min_u32_e32 v14, v18, v14
; #define CE_DESC(a, b) do { const unsigned _mx = (a) > (b) ? (a) : (b), _mn = (a) > (b) ? (b) : (a); (a) = _mx; (b) = _mn; } while (0)
; #define CK(i, j) ((f2key(va[i] + vb[j]) & ~255u) | (unsigned)(255 - (16 * (i) + (j))))
; __device__ __forceinline__ void merge16(unsigned (&a)[16], const unsigned (&b)[16]) {
; #pragma unroll
;     for (int i = 0; i < 16; ++i) a[i] = a[i] > b[15 - i] ? a[i] : b[15 - i];
; #pragma unroll
;     for (int stride = 8; stride > 0; stride >>= 1)
; #pragma unroll
;         for (int i = 0; i < 16; ++i) { const int j = i ^ stride; if (j > i) CE_DESC(a[i], a[j]); }
; }
; __device__ __forceinline__ void peer_tile(const Args& A, LAS unsigned char* lds, int tile) {
;     ...
;             for (int j = 0; j < 4; ++j) Bt[j] = CK(3, j);
;             Bt[4] = CK(5, 0); Bt[5] = CK(5, 1); Bt[6] = CK(6, 0); Bt[7] = CK(6, 1); Bt[8] = CK(7, 0); Bt[9] = CK(7, 1);
;             Bt[10] = CK(8, 0); Bt[11] = CK(9, 0); Bt[12] = CK(10, 0); Bt[13] = CK(11, 0); Bt[14] = CK(12, 0); Bt[15] = CK(13, 0);
	v_min_u32_e32 v18, v15, v53
	v_min_u32_e32 v57, v52, v41
	v_min_u32_e32 v58, v54, v22
	v_min_u32_e32 v59, v17, v51
	v_min_u32_e32 v60, v55, v56
	v_min_u32_e32 v61, v23, v34
	v_min_u32_e32 v62, v35, v16
	v_min_u32_e32 v63, v12, v14
	v_max_u32_e32 v33, v33, v63
	v_max3_u32 v12, v44, v12, v14
	v_max_u32_e32 v14, v45, v62
	v_max3_u32 v16, v46, v35, v16
	v_max_u32_e32 v35, v47, v61
	v_max3_u32 v23, v48, v23, v34
	v_max_u32_e32 v34, v43, v60
	v_max3_u32 v42, v42, v55, v56
	v_max_u32_e32 v43, v49, v59
	v_max3_u32 v17, v50, v17, v51
	v_max_u32_e32 v36, v36, v58
	v_max3_u32 v22, v37, v54, v22
	v_max_u32_e32 v37, v38, v57
	v_max3_u32 v38, v39, v52, v41
	v_max_u32_e32 v18, v20, v18
	v_max3_u32 v15, v40, v15, v53
	v_max_u32_e32 v20, v33, v43
	v_min_u32_e32 v33, v33, v43
	v_max_u32_e32 v39, v12, v17
	v_min_u32_e32 v12, v12, v17
	v_max_u32_e32 v17, v14, v36
	v_min_u32_e32 v14, v14, v36
	v_max_u32_e32 v36, v16, v22
	v_min_u32_e32 v16, v16, v22
	v_max_u32_e32 v22, v35, v37
	v_min_u32_e32 v35, v35, v37
	v_max_u32_e32 v37, v23, v38
	v_min_u32_e32 v23, v23, v38
	v_max_u32_e32 v38, v34, v18
	v_min_u32_e32 v18, v34, v18
	v_max_u32_e32 v34, v42, v15
	v_min_u32_e32 v15, v42, v15
	v_max_u32_e32 v40, v20, v22
	v_min_u32_e32 v20, v20, v22
	v_max_u32_e32 v22, v39, v37
	v_min_u32_e32 v37, v39, v37
	v_max_u32_e32 v39, v17, v38
	v_min_u32_e32 v17, v17, v38
	v_max_u32_e32 v38, v36, v34
	v_min_u32_e32 v34, v36, v34
	v_max_u32_e32 v36, v33, v35
	v_min_u32_e32 v33, v33, v35
	v_max_u32_e32 v35, v12, v23
	v_min_u32_e32 v12, v12, v23
	v_max_u32_e32 v23, v14, v18
	v_min_u32_e32 v14, v14, v18
	v_max_u32_e32 v18, v16, v15
	v_min_u32_e32 v15, v16, v15
	v_max_u32_e32 v16, v40, v39
	v_min_u32_e32 v39, v40, v39
	v_max_u32_e32 v40, v22, v38
	v_min_u32_e32 v22, v22, v38
	v_max_u32_e32 v38, v20, v17
	v_min_u32_e32 v17, v20, v17
	v_max_u32_e32 v20, v37, v34
	v_min_u32_e32 v34, v37, v34
	v_max_u32_e32 v37, v36, v23
	v_min_u32_e32 v23, v36, v23
	v_max_u32_e32 v36, v35, v18
	v_min_u32_e32 v18, v35, v18
	v_max_u32_e32 v35, v33, v14
	v_min_u32_e32 v33, v33, v14
	v_max_u32_e32 v41, v12, v15
	v_min_u32_e32 v12, v12, v15
	v_pk_add_f32 v[14:15], v[4:5], v[0:1] op_sel_hi:[0,1]
	v_not_b32_e32 v50, v15
	v_or_b32_e32 v51, 0x80000000, v15
	v_cmp_gt_i32_e32 vcc, 0, v15
	v_not_b32_e32 v4, v3
	v_min_u32_e32 v42, v16, v40
	v_cndmask_b32_e32 v15, v51, v50, vcc
	v_not_b32_e32 v50, v14
	v_or_b32_e32 v51, 0x80000000, v14
	v_cmp_gt_i32_e32 vcc, 0, v14
	v_and_b32_e32 v15, 0xffffff00, v15
	v_or_b32_e32 v15, 0xcf, v15
	v_cndmask_b32_e32 v14, v51, v50, vcc
	v_or_b32_e32 v50, 0x80000000, v3
	v_cmp_gt_i32_e32 vcc, 0, v3
	v_and_b32_e32 v14, 0xffffff00, v14
	v_or_b32_e32 v14, 0xce, v14
	v_cndmask_b32_e32 v3, v50, v4, vcc
	v_and_b32_e32 v3, 0xffffff00, v3
	v_or_b32_e32 v4, 0xcd, v3
	v_not_b32_e32 v3, v2
	v_or_b32_e32 v50, 0x80000000, v2
	v_cmp_gt_i32_e32 vcc, 0, v2
	v_min_u32_e32 v43, v39, v22
	v_min_u32_e32 v44, v38, v20
	v_cndmask_b32_e32 v2, v50, v3, vcc
	v_and_b32_e32 v2, 0xffffff00, v2
	v_or_b32_e32 v50, 0xcc, v2
	v_pk_add_f32 v[2:3], v[10:11], v[0:1] op_sel_hi:[0,1]
	v_not_b32_e32 v10, v3
	v_or_b32_e32 v51, 0x80000000, v3
	v_cmp_gt_i32_e32 vcc, 0, v3
	v_min_u32_e32 v45, v17, v34
	v_min_u32_e32 v46, v37, v36
	v_cndmask_b32_e32 v3, v51, v10, vcc
	v_and_b32_e32 v3, 0xffffff00, v3
	v_or_b32_e32 v10, 0xaf, v3
	v_not_b32_e32 v3, v2
	v_or_b32_e32 v51, 0x80000000, v2
	v_cmp_gt_i32_e32 vcc, 0, v2
	v_min_u32_e32 v47, v23, v18
	v_min_u32_e32 v48, v35, v41
	v_cndmask_b32_e32 v2, v51, v3, vcc
	v_and_b32_e32 v2, 0xffffff00, v2
	v_or_b32_e32 v51, 0xae, v2
	v_pk_add_f32 v[2:3], v[8:9], v[0:1] op_sel_hi:[0,1]
	v_not_b32_e32 v8, v3
	v_or_b32_e32 v52, 0x80000000, v3
	v_cmp_gt_i32_e32 vcc, 0, v3
	v_min_u32_e32 v49, v33, v12
	v_lshlrev_b32_e32 v11, 9, v11
	v_cndmask_b32_e32 v3, v52, v8, vcc
	v_and_b32_e32 v3, 0xffffff00, v3
	v_or_b32_e32 v8, 0x9f, v3
	v_not_b32_e32 v3, v2
	v_or_b32_e32 v52, 0x80000000, v2
	v_cmp_gt_i32_e32 vcc, 0, v2
	s_nop 1
	v_cndmask_b32_e32 v2, v52, v3, vcc
	v_and_b32_e32 v2, 0xffffff00, v2
	v_or_b32_e32 v52, 0x9e, v2
	v_pk_add_f32 v[2:3], v[6:7], v[0:1] op_sel_hi:[0,1]
	v_not_b32_e32 v0, v3
	v_or_b32_e32 v6, 0x80000000, v3
	v_cmp_gt_i32_e32 vcc, 0, v3
	v_not_b32_e32 v3, v2
	s_nop 0
	v_cndmask_b32_e32 v0, v6, v0, vcc
	v_or_b32_e32 v6, 0x80000000, v2
	v_cmp_gt_i32_e32 vcc, 0, v2
	v_and_b32_e32 v0, 0xffffff00, v0
	v_or_b32_e32 v0, 0x8f, v0
	v_cndmask_b32_e32 v2, v6, v3, vcc
	v_add_f32_e32 v3, v27, v1
	v_not_b32_e32 v6, v3
	v_or_b32_e32 v27, 0x80000000, v3
	v_cmp_gt_i32_e32 vcc, 0, v3
	v_and_b32_e32 v2, 0xffffff00, v2
	v_or_b32_e32 v2, 0x8e, v2
	v_cndmask_b32_e32 v3, v27, v6, vcc
	v_add_f32_e32 v6, v28, v1
	v_not_b32_e32 v27, v6
	v_or_b32_e32 v28, 0x80000000, v6
	v_cmp_gt_i32_e32 vcc, 0, v6
	v_and_b32_e32 v3, 0xffffff00, v3
	v_or_b32_e32 v3, 0x7f, v3
	v_cndmask_b32_e32 v6, v28, v27, vcc
	v_add_f32_e32 v27, v29, v1
	v_not_b32_e32 v28, v27
	v_or_b32_e32 v29, 0x80000000, v27
	v_cmp_gt_i32_e32 vcc, 0, v27
	v_and_b32_e32 v6, 0xffffff00, v6
	v_or_b32_e32 v6, 0x6f, v6
	v_cndmask_b32_e32 v27, v29, v28, vcc
	v_add_f32_e32 v28, v30, v1
	v_not_b32_e32 v29, v28
	v_or_b32_e32 v30, 0x80000000, v28
	v_cmp_gt_i32_e32 vcc, 0, v28
	v_and_b32_e32 v27, 0xffffff00, v27
	v_or_b32_e32 v27, 0x5f, v27
	v_cndmask_b32_e32 v28, v30, v29, vcc
	v_add_f32_e32 v29, v31, v1
	v_not_b32_e32 v30, v29
	v_or_b32_e32 v31, 0x80000000, v29
	v_cmp_gt_i32_e32 vcc, 0, v29
	v_and_b32_e32 v28, 0xffffff00, v28
	v_or_b32_e32 v28, 0x4f, v28
	v_cndmask_b32_e32 v29, v31, v30, vcc
	v_add_f32_e32 v30, v32, v1
	v_not_b32_e32 v31, v30
	v_or_b32_e32 v32, 0x80000000, v30
	v_cmp_gt_i32_e32 vcc, 0, v30
	v_and_or_b32 v29, v29, s34, 63
	s_nop 0
	v_cndmask_b32_e32 v30, v32, v31, vcc
; #define CE_DESC(a, b) do { const unsigned _mx = (a) > (b) ? (a) : (b), _mn = (a) > (b) ? (b) : (a); (a) = _mx; (b) = _mn; } while (0)
; __device__ __forceinline__ void sort16_desc(unsigned (&k)[16]) {
; #pragma unroll
;     for (int size = 2; size <= 16; size <<= 1)
; #pragma unroll
;         for (int stride = size >> 1; stride > 0; stride >>= 1)
; #pragma unroll
;             for (int i = 0; i < 16; ++i) { const int j = i ^ stride;
;                 if (j > i) { if ((i & size) == 0) CE_DESC(k[i], k[j]); else CE_DESC(k[j], k[i]); } }
; }
; __device__ __forceinline__ void merge16(unsigned (&a)[16], const unsigned (&b)[16]) {
; #pragma unroll
;     for (int i = 0; i < 16; ++i) a[i] = a[i] > b[15 - i] ? a[i] : b[15 - i];
; #pragma unroll
;     for (int stride = 8; stride > 0; stride >>= 1)
; #pragma unroll
;         for (int i = 0; i < 16; ++i) { const int j = i ^ stride; if (j > i) CE_DESC(a[i], a[j]); }
; }
; __device__ __forceinline__ void peer_tile(const Args& A, LAS unsigned char* lds, int tile) {
;     ...
;             sort16_desc(Bt); merge16(Lf, Bt);
	v_and_or_b32 v30, v30, s34, 47
	v_max_u32_e32 v31, v15, v14
	v_min_u32_e32 v14, v15, v14
	v_max_u32_e32 v15, v50, v4
	v_min_u32_e32 v4, v50, v4
	v_max_u32_e32 v32, v10, v51
	v_min_u32_e32 v10, v10, v51
	v_max_u32_e32 v50, v52, v8
	v_min_u32_e32 v8, v52, v8
	v_max_u32_e32 v51, v0, v2
	v_min_u32_e32 v0, v0, v2
	v_max_u32_e32 v2, v6, v3
	v_min_u32_e32 v3, v6, v3
	v_max_u32_e32 v6, v27, v28
	v_min_u32_e32 v27, v27, v28
	v_max_u32_e32 v28, v30, v29
	v_min_u32_e32 v29, v30, v29
	v_max_u32_e32 v30, v31, v4
	v_min_u32_e32 v4, v31, v4
	v_max_u32_e32 v31, v14, v15
	v_min_u32_e32 v14, v14, v15
	v_max_u32_e32 v15, v8, v32
	v_min_u32_e32 v8, v8, v32
	v_max_u32_e32 v32, v50, v10
	v_min_u32_e32 v10, v50, v10
	v_max_u32_e32 v50, v51, v3
	v_min_u32_e32 v3, v51, v3
	v_max_u32_e32 v51, v0, v2
	v_min_u32_e32 v0, v0, v2
	v_max_u32_e32 v2, v29, v6
	v_min_u32_e32 v6, v29, v6
	v_max_u32_e32 v29, v28, v27
	v_min_u32_e32 v27, v28, v27
	v_max_u32_e32 v28, v30, v31
	v_min_u32_e32 v30, v30, v31
	v_max_u32_e32 v31, v4, v14
	v_min_u32_e32 v4, v4, v14
	v_max_u32_e32 v14, v10, v8
	v_min_u32_e32 v8, v10, v8
	v_max_u32_e32 v10, v32, v15
	v_min_u32_e32 v15, v32, v15
	v_max_u32_e32 v32, v50, v51
	v_min_u32_e32 v50, v50, v51
	v_max_u32_e32 v51, v3, v0
	v_min_u32_e32 v0, v3, v0
	v_max_u32_e32 v3, v27, v6
	v_min_u32_e32 v6, v27, v6
	v_max_u32_e32 v27, v29, v2
	v_min_u32_e32 v2, v29, v2
	v_max_u32_e32 v29, v28, v8
	v_min_u32_e32 v8, v28, v8
	v_max_u32_e32 v28, v30, v14
	v_min_u32_e32 v14, v30, v14
	v_max_u32_e32 v30, v31, v15
	v_min_u32_e32 v15, v31, v15
	v_max_u32_e32 v31, v4, v10
	v_min_u32_e32 v4, v4, v10
	v_max_u32_e32 v10, v6, v32
	v_min_u32_e32 v6, v6, v32
	v_max_u32_e32 v32, v3, v50
	v_min_u32_e32 v3, v3, v50
	v_max_u32_e32 v50, v2, v51
	v_min_u32_e32 v2, v2, v51
	v_max_u32_e32 v51, v27, v0
	v_min_u32_e32 v0, v27, v0
	v_max_u32_e32 v27, v29, v30
	v_min_u32_e32 v29, v29, v30
	v_max_u32_e32 v30, v28, v31
	v_min_u32_e32 v28, v28, v31
	v_max_u32_e32 v31, v8, v15
	v_min_u32_e32 v8, v8, v15
	v_max_u32_e32 v15, v14, v4
	v_min_u32_e32 v4, v14, v4
	v_max_u32_e32 v14, v2, v6
	v_min_u32_e32 v2, v2, v6
	v_max_u32_e32 v6, v0, v3
	v_min_u32_e32 v0, v0, v3
	v_max_u32_e32 v3, v50, v10
	v_min_u32_e32 v10, v50, v10
	v_max_u32_e32 v50, v51, v32
	v_min_u32_e32 v32, v51, v32
	v_max_u32_e32 v51, v27, v30
	v_min_u32_e32 v27, v27, v30
	v_max_u32_e32 v30, v29, v28
	v_min_u32_e32 v28, v29, v28
	v_max_u32_e32 v29, v31, v15
	v_min_u32_e32 v15, v31, v15
	v_max_u32_e32 v31, v8, v4
	v_min_u32_e32 v4, v8, v4
	v_max_u32_e32 v8, v0, v2
	v_min_u32_e32 v0, v0, v2
	v_max_u32_e32 v2, v6, v14
	v_min_u32_e32 v6, v6, v14
	v_max_u32_e32 v14, v32, v10
	v_min_u32_e32 v10, v32, v10
	v_max_u32_e32 v32, v50, v3
	v_min_u32_e32 v3, v50, v3
	v_max_u32_e32 v50, v51, v0
	v_min_u32_e32 v0, v51, v0
	v_max_u32_e32 v51, v27, v8
	v_min_u32_e32 v8, v27, v8
	v_max_u32_e32 v27, v30, v6
	v_min_u32_e32 v6, v30, v6
	v_max_u32_e32 v30, v28, v2
	v_min_u32_e32 v2, v28, v2
	v_max_u32_e32 v28, v29, v10
	v_min_u32_e32 v10, v29, v10
	v_max_u32_e32 v29, v15, v14
	v_min_u32_e32 v14, v15, v14
	v_max_u32_e32 v15, v31, v3
	v_min_u32_e32 v3, v31, v3
	v_max_u32_e32 v31, v4, v32
	v_min_u32_e32 v4, v4, v32
	v_max_u32_e32 v32, v50, v28
	v_min_u32_e32 v28, v50, v28
	v_max_u32_e32 v50, v51, v29
	v_min_u32_e32 v29, v51, v29
	v_max_u32_e32 v51, v27, v15
	v_min_u32_e32 v15, v27, v15
	v_max_u32_e32 v27, v30, v31
	v_min_u32_e32 v30, v30, v31
	v_max_u32_e32 v31, v0, v10
	v_min_u32_e32 v0, v0, v10
	v_max_u32_e32 v10, v8, v14
	v_min_u32_e32 v8, v8, v14
	v_max_u32_e32 v14, v6, v3
	v_min_u32_e32 v3, v6, v3
	v_max_u32_e32 v6, v2, v4
	v_min_u32_e32 v2, v2, v4
	v_max_u32_e32 v4, v32, v51
	v_min_u32_e32 v32, v32, v51
	v_max_u32_e32 v51, v50, v27
	v_min_u32_e32 v27, v50, v27
	v_max_u32_e32 v50, v28, v15
	v_min_u32_e32 v15, v28, v15
	v_max_u32_e32 v28, v29, v30
	v_min_u32_e32 v29, v29, v30
	v_max_u32_e32 v30, v31, v14
	v_min_u32_e32 v14, v31, v14
	v_max_u32_e32 v31, v10, v6
	v_min_u32_e32 v6, v10, v6
	v_max_u32_e32 v10, v0, v3
	v_min_u32_e32 v0, v0, v3
	v_max_u32_e32 v3, v8, v2
	v_min_u32_e32 v2, v8, v2
	v_min_u32_e32 v8, v4, v51
	v_min_u32_e32 v52, v32, v27
	v_min_u32_e32 v53, v50, v28
	v_min_u32_e32 v54, v15, v29
	v_min_u32_e32 v55, v30, v31
	v_min_u32_e32 v56, v14, v6
	v_min_u32_e32 v57, v10, v3
	v_min_u32_e32 v58, v0, v2
	v_max3_u32 v16, v16, v40, v58
	v_max3_u32 v0, v42, v0, v2
	v_max3_u32 v2, v39, v22, v57
	v_max3_u32 v3, v43, v10, v3
	v_max3_u32 v10, v38, v20, v56
	v_max3_u32 v6, v44, v14, v6
	v_max3_u32 v14, v17, v34, v55
	v_max3_u32 v17, v45, v30, v31
	v_max3_u32 v20, v37, v36, v54
	v_max3_u32 v15, v46, v15, v29
	v_max3_u32 v18, v23, v18, v53
	v_max3_u32 v22, v47, v50, v28
	v_max3_u32 v23, v35, v41, v52
	v_max3_u32 v27, v48, v32, v27
	v_max3_u32 v8, v33, v12, v8
	v_max3_u32 v4, v49, v4, v51
	v_max_u32_e32 v12, v16, v20
	v_min_u32_e32 v16, v16, v20
	v_max_u32_e32 v20, v0, v15
	v_min_u32_e32 v0, v0, v15
	v_max_u32_e32 v15, v2, v18
	v_min_u32_e32 v2, v2, v18
	v_max_u32_e32 v18, v3, v22
	v_min_u32_e32 v3, v3, v22
	v_max_u32_e32 v22, v10, v23
	v_min_u32_e32 v10, v10, v23
	v_max_u32_e32 v23, v6, v27
	v_min_u32_e32 v6, v6, v27
	v_max_u32_e32 v27, v14, v8
	v_min_u32_e32 v8, v14, v8
	v_max_u32_e32 v14, v17, v4
	v_min_u32_e32 v4, v17, v4
	v_max_u32_e32 v17, v12, v22
	v_min_u32_e32 v12, v12, v22
	v_max_u32_e32 v22, v20, v23
	v_min_u32_e32 v20, v20, v23
	v_max_u32_e32 v23, v15, v27
	v_min_u32_e32 v15, v15, v27
	v_max_u32_e32 v27, v18, v14
	v_min_u32_e32 v14, v18, v14
	v_max_u32_e32 v18, v16, v10
	v_min_u32_e32 v10, v16, v10
	v_max_u32_e32 v16, v0, v6
	v_min_u32_e32 v0, v0, v6
	v_max_u32_e32 v6, v2, v8
	v_min_u32_e32 v2, v2, v8
	v_max_u32_e32 v8, v3, v4
; __device__ __forceinline__ float key2f(unsigned k) { const unsigned u = (k & 0x80000000u) ? (k & 0x7fffffffu) : ~k; return __uint_as_float(u); }
; #define CE_DESC(a, b) do { const unsigned _mx = (a) > (b) ? (a) : (b), _mn = (a) > (b) ? (b) : (a); (a) = _mx; (b) = _mn; } while (0)
; #define CK(i, j) ((f2key(va[i] + vb[j]) & ~255u) | (unsigned)(255 - (16 * (i) + (j))))
; __device__ __forceinline__ void peer_tile(const Args& A, LAS unsigned char* lds, int tile) {
;     ...
;             sort16_desc(Bt); merge16(Lf, Bt);
;             { unsigned x0 = CK(14, 0), x1 = CK(15, 0);
; #pragma unroll
;               for (int i = 0; i < 16; ++i) CE_DESC(Lf[i], x0);
; #pragma unroll
;               for (int i = 0; i < 16; ++i) CE_DESC(Lf[i], x1); }
;     ...
;             float fv[16], den = 0.f; const float f0 = key2f(Lf[0] & ~255u);
; #pragma unroll
;             for (int k = 0; k < 16; ++k) { fv[k] = __expf(key2f(Lf[k] & ~255u) - f0); den += fv[k]; }
	v_min_u32_e32 v3, v3, v4
	v_max_u32_e32 v4, v17, v23
	v_min_u32_e32 v17, v17, v23
	v_max_u32_e32 v23, v22, v27
	v_min_u32_e32 v22, v22, v27
	v_max_u32_e32 v27, v12, v15
	v_min_u32_e32 v12, v12, v15
	v_max_u32_e32 v15, v20, v14
	v_min_u32_e32 v14, v20, v14
	v_max_u32_e32 v20, v18, v6
	v_min_u32_e32 v6, v18, v6
	v_max_u32_e32 v18, v16, v8
	v_min_u32_e32 v8, v16, v8
	v_max_u32_e32 v16, v10, v2
	v_min_u32_e32 v2, v10, v2
	v_max_u32_e32 v10, v0, v3
	v_min_u32_e32 v0, v0, v3
	v_max_u32_e32 v41, v2, v0
	v_min_u32_e32 v0, v2, v0
	v_add_f32_e32 v2, v25, v1
	v_not_b32_e32 v25, v2
	v_or_b32_e32 v42, 0x80000000, v2
	v_cmp_gt_i32_e32 vcc, 0, v2
	v_add_f32_e32 v1, v26, v1
	v_max_u32_e32 v3, v4, v23
	v_cndmask_b32_e32 v2, v42, v25, vcc
	v_and_or_b32 v2, v2, s34, 31
	v_not_b32_e32 v25, v1
	v_or_b32_e32 v26, 0x80000000, v1
	v_cmp_gt_i32_e32 vcc, 0, v1
	v_min_u32_e32 v28, v4, v23
	v_max_u32_e32 v29, v17, v22
	v_cndmask_b32_e32 v1, v26, v25, vcc
	v_max_u32_e32 v25, v3, v2
	v_min_u32_e32 v3, v3, v2
	v_min_u32_e32 v3, v28, v3
	v_min_u32_e32 v30, v17, v22
	v_med3_u32 v2, v4, v23, v2
	v_min_u32_e32 v23, v29, v3
	v_max_u32_e32 v31, v27, v15
	v_max_u32_e32 v4, v29, v3
	v_med3_u32 v3, v17, v22, v3
	v_min_u32_e32 v17, v30, v23
	v_min_u32_e32 v32, v27, v15
	v_min_u32_e32 v23, v31, v17
	v_max_u32_e32 v33, v12, v14
	v_max_u32_e32 v22, v31, v17
	v_med3_u32 v15, v27, v15, v17
	v_min_u32_e32 v17, v32, v23
	v_min_u32_e32 v34, v12, v14
	v_min_u32_e32 v26, v33, v17
	v_max_u32_e32 v35, v20, v18
	v_med3_u32 v12, v12, v14, v17
	v_min_u32_e32 v14, v34, v26
	v_min_u32_e32 v36, v20, v18
	v_min_u32_e32 v26, v35, v14
	v_max_u32_e32 v37, v6, v8
	v_max_u32_e32 v23, v33, v17
	v_max_u32_e32 v17, v35, v14
	v_med3_u32 v14, v20, v18, v14
	v_min_u32_e32 v18, v36, v26
	v_min_u32_e32 v38, v6, v8
	v_min_u32_e32 v26, v37, v18
	v_max_u32_e32 v39, v16, v10
	v_med3_u32 v6, v6, v8, v18
	v_min_u32_e32 v8, v38, v26
	v_min_u32_e32 v40, v16, v10
	v_min_u32_e32 v26, v39, v8
	v_and_or_b32 v1, v1, s34, 15
	v_max_u32_e32 v20, v37, v18
	v_max_u32_e32 v18, v39, v8
	v_med3_u32 v8, v16, v10, v8
	v_min_u32_e32 v10, v40, v26
	v_max_u32_e32 v26, v25, v1
	v_min_u32_e32 v1, v25, v1
	v_max_u32_e32 v25, v2, v1
	v_min_u32_e32 v1, v2, v1
	v_max_u32_e32 v2, v4, v1
	v_min_u32_e32 v1, v4, v1
	v_max_u32_e32 v4, v3, v1
	v_min_u32_e32 v1, v3, v1
	v_max_u32_e32 v3, v22, v1
	v_min_u32_e32 v1, v22, v1
	v_max_u32_e32 v22, v15, v1
	v_min_u32_e32 v1, v15, v1
	v_max_u32_e32 v15, v23, v1
	v_min_u32_e32 v1, v23, v1
	v_max_u32_e32 v23, v12, v1
	v_min_u32_e32 v1, v12, v1
	v_max_u32_e32 v12, v17, v1
	v_min_u32_e32 v1, v17, v1
	v_max_u32_e32 v17, v14, v1
	v_min_u32_e32 v1, v14, v1
	v_max_u32_e32 v14, v20, v1
	v_min_u32_e32 v1, v20, v1
	v_max_u32_e32 v20, v6, v1
	v_min_u32_e32 v1, v6, v1
	v_max_u32_e32 v6, v18, v1
	v_min_u32_e32 v1, v18, v1
	v_max_u32_e32 v16, v41, v10
	v_max_u32_e32 v18, v8, v1
	v_min_u32_e32 v1, v8, v1
	v_min_u32_e32 v10, v41, v10
	v_max_u32_e32 v8, v16, v1
	v_min_u32_e32 v1, v16, v1
	v_max3_u32 v10, v0, v10, v1
	v_and_b32_e32 v0, 0x7fffff00, v26
	v_bitop3_b32 v1, v26, s33, v26 bitop3:0xcf
	v_cmp_gt_i32_e32 vcc, 0, v26
	v_and_b32_e32 v16, 0x7fffff00, v25
	v_bitop3_b32 v27, v25, s33, v25 bitop3:0xcf
	v_cndmask_b32_e32 v0, v1, v0, vcc
	v_cmp_gt_i32_e32 vcc, 0, v25
	v_sub_f32_e32 v1, v0, v0
	v_bitop3_b32 v28, v2, s33, v2 bitop3:0xcf
	v_cndmask_b32_e32 v16, v27, v16, vcc
	v_and_b32_e32 v27, 0x7fffff00, v2
	v_cmp_gt_i32_e32 vcc, 0, v2
	v_mul_f32_e32 v1, 0x3fb8aa3b, v1
	v_sub_f32_e32 v16, v16, v0
	v_cndmask_b32_e32 v27, v28, v27, vcc
	v_and_b32_e32 v28, 0x7fffff00, v4
	v_bitop3_b32 v29, v4, s33, v4 bitop3:0xcf
	v_cmp_gt_i32_e32 vcc, 0, v4
	v_exp_f32_e32 v1, v1
	v_mul_f32_e32 v16, 0x3fb8aa3b, v16
	v_sub_f32_e32 v27, v27, v0
	v_cndmask_b32_e32 v28, v29, v28, vcc
	v_and_b32_e32 v30, 0x7fffff00, v3
	v_bitop3_b32 v31, v3, s33, v3 bitop3:0xcf
	v_cmp_gt_i32_e32 vcc, 0, v3
	v_exp_f32_e32 v16, v16
	v_mul_f32_e32 v27, 0x3fb8aa3b, v27
	v_sub_f32_e32 v28, v28, v0
	v_cndmask_b32_e32 v30, v31, v30, vcc
	v_and_b32_e32 v31, 0x7fffff00, v22
	v_bitop3_b32 v32, v22, s33, v22 bitop3:0xcf
	v_cmp_gt_i32_e32 vcc, 0, v22
	v_exp_f32_e32 v27, v27
	v_mul_f32_e32 v28, 0x3fb8aa3b, v28
	v_sub_f32_e32 v30, v30, v0
	v_cndmask_b32_e32 v31, v32, v31, vcc
	v_and_b32_e32 v32, 0x7fffff00, v15
	v_bitop3_b32 v33, v15, s33, v15 bitop3:0xcf
	v_cmp_gt_i32_e32 vcc, 0, v15
	v_exp_f32_e32 v28, v28
	v_mul_f32_e32 v30, 0x3fb8aa3b, v30
	v_sub_f32_e32 v31, v31, v0
	v_cndmask_b32_e32 v32, v33, v32, vcc
	v_and_b32_e32 v33, 0x7fffff00, v23
	v_bitop3_b32 v34, v23, s33, v23 bitop3:0xcf
	v_cmp_gt_i32_e32 vcc, 0, v23
	v_add_f32_e32 v29, 0, v1
	v_exp_f32_e32 v30, v30
	v_mul_f32_e32 v31, 0x3fb8aa3b, v31
	v_sub_f32_e32 v32, v32, v0
	v_cndmask_b32_e32 v33, v34, v33, vcc
	v_and_b32_e32 v34, 0x7fffff00, v12
	v_bitop3_b32 v35, v12, s33, v12 bitop3:0xcf
	v_cmp_gt_i32_e32 vcc, 0, v12
	v_add_f32_e32 v29, v29, v16
	v_exp_f32_e32 v31, v31
	v_mul_f32_e32 v32, 0x3fb8aa3b, v32
	v_sub_f32_e32 v33, v33, v0
	v_cndmask_b32_e32 v34, v35, v34, vcc
	v_and_b32_e32 v35, 0x7fffff00, v17
	v_bitop3_b32 v36, v17, s33, v17 bitop3:0xcf
	v_cmp_gt_i32_e32 vcc, 0, v17
	v_add_f32_e32 v29, v29, v27
	v_exp_f32_e32 v32, v32
	v_mul_f32_e32 v33, 0x3fb8aa3b, v33
	v_sub_f32_e32 v34, v34, v0
	v_cndmask_b32_e32 v35, v36, v35, vcc
	v_and_b32_e32 v36, 0x7fffff00, v14
	v_bitop3_b32 v37, v14, s33, v14 bitop3:0xcf
	v_cmp_gt_i32_e32 vcc, 0, v14
	v_add_f32_e32 v29, v29, v28
	v_exp_f32_e32 v33, v33
	v_mul_f32_e32 v34, 0x3fb8aa3b, v34
	v_sub_f32_e32 v35, v35, v0
	v_cndmask_b32_e32 v36, v37, v36, vcc
	v_and_b32_e32 v37, 0x7fffff00, v20
	v_bitop3_b32 v38, v20, s33, v20 bitop3:0xcf
	v_cmp_gt_i32_e32 vcc, 0, v20
	v_add_f32_e32 v29, v29, v30
; #define LDS_WAIT() asm volatile("s_waitcnt lgkmcnt(0)" ::: "memory")
; __device__ __forceinline__ void peer_tile(const Args& A, LAS unsigned char* lds, int tile) {
;     ...
;             const float rden = 1.f / den;
;             LDS_WAIT();
; #pragma unroll
;             for (int k = 0; k < 16; ++k) { const unsigned code = 255u - (Lf[k] & 255u); const unsigned e = idx[code >> 4] * 128u + idx[16 + (code & 15u)];
;                 u32x2 sv; sv.x = e; sv.y = __float_as_uint(fv[k] * rden); SEL[(tl * 8 + h) * 16 + k] = sv; }
	v_exp_f32_e32 v34, v34
	v_mul_f32_e32 v35, 0x3fb8aa3b, v35
	v_sub_f32_e32 v36, v36, v0
	v_cndmask_b32_e32 v37, v38, v37, vcc
	v_and_b32_e32 v38, 0x7fffff00, v6
	v_bitop3_b32 v39, v6, s33, v6 bitop3:0xcf
	v_cmp_gt_i32_e32 vcc, 0, v6
	v_add_f32_e32 v29, v29, v31
	v_exp_f32_e32 v35, v35
	v_mul_f32_e32 v36, 0x3fb8aa3b, v36
	v_sub_f32_e32 v37, v37, v0
	v_cndmask_b32_e32 v38, v39, v38, vcc
	v_and_b32_e32 v39, 0x7fffff00, v18
	v_bitop3_b32 v40, v18, s33, v18 bitop3:0xcf
	v_cmp_gt_i32_e32 vcc, 0, v18
	v_add_f32_e32 v29, v29, v32
	v_exp_f32_e32 v36, v36
	v_mul_f32_e32 v37, 0x3fb8aa3b, v37
	v_sub_f32_e32 v38, v38, v0
	v_cndmask_b32_e32 v39, v40, v39, vcc
	v_and_b32_e32 v40, 0x7fffff00, v8
	v_bitop3_b32 v41, v8, s33, v8 bitop3:0xcf
	v_cmp_gt_i32_e32 vcc, 0, v8
	v_add_f32_e32 v29, v29, v33
	v_exp_f32_e32 v37, v37
	v_mul_f32_e32 v38, 0x3fb8aa3b, v38
	v_sub_f32_e32 v39, v39, v0
	v_cndmask_b32_e32 v40, v41, v40, vcc
	v_and_b32_e32 v41, 0x7fffff00, v10
	v_bitop3_b32 v42, v10, s33, v10 bitop3:0xcf
	v_cmp_gt_i32_e32 vcc, 0, v10
	v_add_f32_e32 v29, v29, v34
	v_exp_f32_e32 v38, v38
	v_mul_f32_e32 v39, 0x3fb8aa3b, v39
	v_sub_f32_e32 v40, v40, v0
	v_cndmask_b32_e32 v41, v42, v41, vcc
	v_add_f32_e32 v29, v29, v35
	v_exp_f32_e32 v39, v39
	v_mul_f32_e32 v40, 0x3fb8aa3b, v40
	v_sub_f32_e32 v0, v41, v0
	v_add_f32_e32 v29, v29, v36
	v_exp_f32_e32 v40, v40
	v_mul_f32_e32 v0, 0x3fb8aa3b, v0
	v_add_f32_e32 v29, v29, v37
	v_exp_f32_e32 v41, v0
	v_add_f32_e32 v0, v29, v38
	v_add_f32_e32 v0, v0, v39
	v_add_f32_e32 v0, v0, v40
	v_add_f32_e32 v0, v0, v41
	v_div_scale_f32 v29, s[0:1], v0, v0, 1.0
	v_rcp_f32_e32 v42, v29
	v_not_b32_e32 v21, v26
	v_not_b32_e32 v24, v25
	v_fma_f32 v43, -v29, v42, 1.0
	v_fmac_f32_e32 v42, v43, v42
	v_div_scale_f32 v43, vcc, 1.0, v0, 1.0
	v_mul_f32_e32 v44, v43, v42
	v_fma_f32 v45, -v29, v44, v43
	v_fmac_f32_e32 v44, v45, v42
	v_fma_f32 v29, -v29, v44, v43
	v_div_fmas_f32 v29, v29, v42, v44
	v_div_fixup_f32 v29, v29, v0, 1.0
	v_and_b32_e32 v0, 48, v19
	v_lshrrev_b32_e32 v19, 2, v21
	v_and_b32_e32 v19, 60, v19
	v_bitop3_b32 v21, v26, 15, v26 bitop3:0xc
	v_add_u32_e32 v19, v5, v19
	v_lshl_add_u32 v21, v21, 2, v5
	ds_read_b32 v19, v19
	ds_read_b32 v21, v21 offset:64
	v_lshlrev_b32_e32 v0, 3, v0
	v_add3_u32 v11, v13, v11, v0
	v_mul_f32_e32 v1, v1, v29
	v_not_b32_e32 v13, v2
	s_waitcnt lgkmcnt(0)
	v_lshl_add_u32 v0, v19, 7, v21
	ds_write_b64 v11, v[0:1]
	v_lshrrev_b32_e32 v0, 2, v24
	v_and_b32_e32 v0, 60, v0
	v_bitop3_b32 v1, v25, 15, v25 bitop3:0xc
	v_add_u32_e32 v0, v5, v0
	v_lshl_add_u32 v1, v1, 2, v5
	ds_read_b32 v0, v0
	ds_read_b32 v1, v1 offset:64
	v_cmp_eq_u32_e32 vcc, 0, v9
	s_waitcnt lgkmcnt(0)
	v_lshl_add_u32 v0, v0, 7, v1
	v_mul_f32_e32 v1, v16, v29
	ds_write_b64 v11, v[0:1] offset:8
	v_lshrrev_b32_e32 v0, 2, v13
	v_and_b32_e32 v0, 60, v0
	v_bitop3_b32 v1, v2, 15, v2 bitop3:0xc
	v_add_u32_e32 v0, v5, v0
	v_lshl_add_u32 v1, v1, 2, v5
	ds_read_b32 v0, v0
	ds_read_b32 v1, v1 offset:64
	v_not_b32_e32 v2, v4
	s_waitcnt lgkmcnt(0)
	v_lshl_add_u32 v0, v0, 7, v1
	v_mul_f32_e32 v1, v27, v29
	ds_write_b64 v11, v[0:1] offset:16
	v_lshrrev_b32_e32 v0, 2, v2
	v_and_b32_e32 v0, 60, v0
	v_bitop3_b32 v1, v4, 15, v4 bitop3:0xc
	v_add_u32_e32 v0, v5, v0
	v_lshl_add_u32 v1, v1, 2, v5
	ds_read_b32 v0, v0
	ds_read_b32 v1, v1 offset:64
	v_not_b32_e32 v2, v3
	v_mul_lo_u32 v4, v7, s36
	s_waitcnt lgkmcnt(0)
	v_lshl_add_u32 v0, v0, 7, v1
	v_mul_f32_e32 v1, v28, v29
	ds_write_b64 v11, v[0:1] offset:24
	v_lshrrev_b32_e32 v0, 2, v2
	v_and_b32_e32 v0, 60, v0
	v_bitop3_b32 v1, v3, 15, v3 bitop3:0xc
	v_add_u32_e32 v0, v5, v0
	v_lshl_add_u32 v1, v1, 2, v5
	ds_read_b32 v0, v0
	ds_read_b32 v1, v1 offset:64
	v_not_b32_e32 v2, v22
	s_waitcnt lgkmcnt(0)
	v_lshl_add_u32 v0, v0, 7, v1
	v_mul_f32_e32 v1, v30, v29
	ds_write_b64 v11, v[0:1] offset:32
	v_lshrrev_b32_e32 v0, 2, v2
	v_and_b32_e32 v0, 60, v0
	v_bitop3_b32 v1, v22, 15, v22 bitop3:0xc
	v_add_u32_e32 v0, v5, v0
	v_lshl_add_u32 v1, v1, 2, v5
	ds_read_b32 v0, v0
	ds_read_b32 v1, v1 offset:64
	v_not_b32_e32 v2, v15
	s_waitcnt lgkmcnt(0)
	v_lshl_add_u32 v0, v0, 7, v1
	v_mul_f32_e32 v1, v31, v29
	ds_write_b64 v11, v[0:1] offset:40
	v_lshrrev_b32_e32 v0, 2, v2
	v_and_b32_e32 v0, 60, v0
	v_bitop3_b32 v1, v15, 15, v15 bitop3:0xc
	v_add_u32_e32 v0, v5, v0
	v_lshl_add_u32 v1, v1, 2, v5
	ds_read_b32 v0, v0
	ds_read_b32 v1, v1 offset:64
	v_not_b32_e32 v2, v23
	s_waitcnt lgkmcnt(0)
	v_lshl_add_u32 v0, v0, 7, v1
	v_mul_f32_e32 v1, v32, v29
	ds_write_b64 v11, v[0:1] offset:48
	v_lshrrev_b32_e32 v0, 2, v2
	v_and_b32_e32 v0, 60, v0
	v_bitop3_b32 v1, v23, 15, v23 bitop3:0xc
	v_add_u32_e32 v0, v5, v0
	v_lshl_add_u32 v1, v1, 2, v5
	ds_read_b32 v0, v0
	ds_read_b32 v1, v1 offset:64
	v_not_b32_e32 v2, v12
	s_waitcnt lgkmcnt(0)
	v_lshl_add_u32 v0, v0, 7, v1
	v_mul_f32_e32 v1, v33, v29
	ds_write_b64 v11, v[0:1] offset:56
	v_lshrrev_b32_e32 v0, 2, v2
	v_and_b32_e32 v0, 60, v0
	v_bitop3_b32 v1, v12, 15, v12 bitop3:0xc
	v_add_u32_e32 v0, v5, v0
	v_lshl_add_u32 v1, v1, 2, v5
	ds_read_b32 v0, v0
	ds_read_b32 v1, v1 offset:64
	v_not_b32_e32 v2, v17
	s_waitcnt lgkmcnt(0)
	v_lshl_add_u32 v0, v0, 7, v1
	v_mul_f32_e32 v1, v34, v29
	ds_write_b64 v11, v[0:1] offset:64
	v_lshrrev_b32_e32 v0, 2, v2
	v_and_b32_e32 v0, 60, v0
	v_bitop3_b32 v1, v17, 15, v17 bitop3:0xc
	v_add_u32_e32 v0, v5, v0
	v_lshl_add_u32 v1, v1, 2, v5
	ds_read_b32 v0, v0
	ds_read_b32 v1, v1 offset:64
	v_not_b32_e32 v2, v14
	s_waitcnt lgkmcnt(0)
	v_lshl_add_u32 v0, v0, 7, v1
	v_mul_f32_e32 v1, v35, v29
	ds_write_b64 v11, v[0:1] offset:72
	v_lshrrev_b32_e32 v0, 2, v2
	v_and_b32_e32 v0, 60, v0
	v_bitop3_b32 v1, v14, 15, v14 bitop3:0xc
	v_add_u32_e32 v0, v5, v0
	v_lshl_add_u32 v1, v1, 2, v5
	ds_read_b32 v0, v0
	ds_read_b32 v1, v1 offset:64
	v_not_b32_e32 v2, v20
	s_waitcnt lgkmcnt(0)
; __device__ __forceinline__ unsigned pk2(float lo, float hi) { const f32x2 v = {lo, hi}; const bf16x2_t b = __builtin_convertvector(v, bf16x2_t); return __builtin_bit_cast(unsigned, b); }
; __device__ __forceinline__ float bflo(unsigned u) { return __uint_as_float(u << 16); }
; __device__ __forceinline__ float bfhi(unsigned u) { return __uint_as_float(u & 0xffff0000u); }
; __device__ __forceinline__ void peer_tile(const Args& A, LAS unsigned char* lds, int tile) {
;     ...
;             for (int k = 0; k < 16; ++k) { const unsigned code = 255u - (Lf[k] & 255u); const unsigned e = idx[code >> 4] * 128u + idx[16 + (code & 15u)];
;                 u32x2 sv; sv.x = e; sv.y = __float_as_uint(fv[k] * rden); SEL[(tl * 8 + h) * 16 + k] = sv; }
;     ...
;     const unsigned char* T8v = T8 + (size_t)16384 * 1024;
;     const bf16_t* A3 = (const bf16_t*)(A.ws + WS_A3); const float* RSq = (const float*)(A.ws + WS_RS);
;     for (int pass = 0; pass < 2; ++pass) {
;         const int tb = 8 * w + 4 * pass;
;         u32x4 xpa[4], xpb[4]; f32x2 oacc[4][8];
; #pragma unroll
;         for (int tk = 0; tk < 4; ++tk) { const size_t m = (size_t)tile * 64 + tb + tk;
;             { const u32x4 ra = *(const u32x4*)(A3 + m * 1024 + 16 * lane), rb = *(const u32x4*)(A3 + m * 1024 + 16 * lane + 8);
;               float xr_; { const f32x4 p0 = *(const f32x4*)(RSq + m * 16), p1 = *(const f32x4*)(RSq + m * 16 + 4), p2 = *(const f32x4*)(RSq + m * 16 + 8), p3 = *(const f32x4*)(RSq + m * 16 + 12);
;                 const f32x4 ps = (p0 + p1) + (p2 + p3); xr_ = rsqrtf(((ps[0] + ps[1]) + (ps[2] + ps[3])) * (1.f / 1024.f) + 1e-6f); }
;               const unsigned rr[8] = {ra.x, ra.y, ra.z, ra.w, rb.x, rb.y, rb.z, rb.w}; unsigned hh[8];
;               const float* sp = MOD + (int)(m >> 11) * 6144 + 3072 + 16 * lane;
; #pragma unroll
;               for (int q = 0; q < 8; ++q) { const f32x2 sh = *(const f32x2*)(sp + 2 * q); hh[q] = pk2(bflo(rr[q]) * xr_ + sh[0], bfhi(rr[q]) * xr_ + sh[1]); }
;               xpa[tk] = (u32x4){hh[0], hh[1], hh[2], hh[3]}; xpb[tk] = (u32x4){hh[4], hh[5], hh[6], hh[7]}; }
	v_lshl_add_u32 v0, v0, 7, v1
	v_mul_f32_e32 v1, v36, v29
	ds_write_b64 v11, v[0:1] offset:80
	v_lshrrev_b32_e32 v0, 2, v2
	v_and_b32_e32 v0, 60, v0
	v_bitop3_b32 v1, v20, 15, v20 bitop3:0xc
	v_add_u32_e32 v0, v5, v0
	v_lshl_add_u32 v1, v1, 2, v5
	ds_read_b32 v0, v0
	ds_read_b32 v1, v1 offset:64
	v_not_b32_e32 v2, v6
	s_waitcnt lgkmcnt(0)
	v_lshl_add_u32 v0, v0, 7, v1
	v_mul_f32_e32 v1, v37, v29
	ds_write_b64 v11, v[0:1] offset:88
	v_lshrrev_b32_e32 v0, 2, v2
	v_and_b32_e32 v0, 60, v0
	v_bitop3_b32 v1, v6, 15, v6 bitop3:0xc
	v_add_u32_e32 v0, v5, v0
	v_lshl_add_u32 v1, v1, 2, v5
	ds_read_b32 v0, v0
	ds_read_b32 v1, v1 offset:64
	v_not_b32_e32 v2, v18
	s_waitcnt lgkmcnt(0)
	v_lshl_add_u32 v0, v0, 7, v1
	v_mul_f32_e32 v1, v38, v29
	ds_write_b64 v11, v[0:1] offset:96
	v_lshrrev_b32_e32 v0, 2, v2
	v_and_b32_e32 v0, 60, v0
	v_bitop3_b32 v1, v18, 15, v18 bitop3:0xc
	v_add_u32_e32 v0, v5, v0
	v_lshl_add_u32 v1, v1, 2, v5
	ds_read_b32 v0, v0
	ds_read_b32 v1, v1 offset:64
	v_not_b32_e32 v2, v8
	s_waitcnt lgkmcnt(0)
	v_lshl_add_u32 v0, v0, 7, v1
	v_mul_f32_e32 v1, v39, v29
	ds_write_b64 v11, v[0:1] offset:104
	v_lshrrev_b32_e32 v0, 2, v2
	v_and_b32_e32 v0, 60, v0
	v_bitop3_b32 v1, v8, 15, v8 bitop3:0xc
	v_add_u32_e32 v0, v5, v0
	v_lshl_add_u32 v1, v1, 2, v5
	ds_read_b32 v0, v0
	ds_read_b32 v1, v1 offset:64
	v_not_b32_e32 v2, v10
	s_waitcnt lgkmcnt(0)
	v_lshl_add_u32 v0, v0, 7, v1
	v_mul_f32_e32 v1, v40, v29
	ds_write_b64 v11, v[0:1] offset:112
	v_lshrrev_b32_e32 v0, 2, v2
	v_and_b32_e32 v0, 60, v0
	v_bitop3_b32 v1, v10, 15, v10 bitop3:0xc
	v_add_u32_e32 v0, v5, v0
	v_lshl_add_u32 v1, v1, 2, v5
	ds_read_b32 v0, v0
	ds_read_b32 v1, v1 offset:64
	v_lshlrev_b32_e32 v5, 13, v7
	v_lshl_or_b32 v6, v9, 3, v5
	s_waitcnt lgkmcnt(0)
	v_lshl_add_u32 v0, v0, 7, v1
	v_mul_f32_e32 v1, v41, v29
	ds_write_b64 v11, v[0:1] offset:120
	s_waitcnt lgkmcnt(0)
	s_barrier
	s_mov_b64 exec, -1
	v_and_b32_e32 v240, 63, v214
	v_lshrrev_b32_e32 v242, 6, v214
	v_lshlrev_b32_e32 v240, 4, v240
	v_readfirstlane_b32 s16, v242
	v_lshlrev_b32_e32 v245, 1, v240
	v_lshlrev_b32_e32 v246, 2, v240
	v_lshrrev_b32_e32 v247, 4, v240
	v_and_b32_e32 v247, 48, v247
	v_mov_b32_e32 v244, 0
	v_mov_b32_e32 v243, 0x358637bd
	v_mov_b32_e32 v242, 0xbf3a00e3
	s_add_u32 s4, s50, 0x1000000
	s_addc_u32 s5, s51, 0
	s_add_u32 s6, s50, 0x2000000
	s_addc_u32 s7, s51, 0
	s_add_u32 s8, s50, 0x3000000
	s_addc_u32 s9, s51, 0
	s_add_u32 s52, s50, 0x3010000
	s_addc_u32 s53, s51, 0
	s_add_u32 s12, s50, 0xb000000
	s_addc_u32 s13, s51, 0
	s_add_u32 s14, s50, 0xd000000
	s_addc_u32 s15, s51, 0
	s_lshr_b32 s0, s2, 5
	s_mul_i32 s0, s0, 0x6000
	s_add_u32 s10, s50, s0
	s_addc_u32 s11, s51, 0
	s_add_u32 s80, s10, 0x4000
	s_addc_u32 s81, s11, 0
	s_add_u32 s82, s10, 0x6000
	s_addc_u32 s83, s11, 0
	s_mul_i32 s22, s16, 9920
	s_cmp_eq_u32 s16, 7
	s_cselect_b32 s22, 0x21000, s22
	s_mov_b32 s85, 0xffffffff
	s_mov_b32 s72, 0x3e6d3388
	s_mov_b32 s56, s4
	s_and_b32 s57, s5, 0xffff
	s_or_b32 s57, s57, 0x04000000
	s_mov_b32 s58, 16384
	s_mov_b32 s59, 0x00027000
	s_mov_b32 s60, s6
	s_and_b32 s61, s7, 0xffff
	s_or_b32 s61, s61, 0x04000000
	s_mov_b32 s62, 16384
	s_mov_b32 s63, 0x00027000
	s_lshl_b32 s76, s16, 3
	s_lshl_b32 s0, s2, 6
	s_add_i32 s77, s0, s76
	global_load_dwordx4 v[192:195], v246, s[80:81] offset:0
	global_load_dwordx4 v[196:199], v246, s[80:81] offset:16
	global_load_dwordx4 v[200:203], v246, s[80:81] offset:32
	global_load_dwordx4 v[204:207], v246, s[80:81] offset:48
	s_add_i32 s0, s77, 0
	s_lshl_b32 s1, s0, 11
	s_add_u32 s78, s12, s1
	s_addc_u32 s79, s13, 0
	global_load_dwordx4 v[128:131], v245, s[78:79]
	global_load_dwordx4 v[132:135], v245, s[78:79] offset:16
	global_load_dwordx4 v[136:139], v245, s[78:79] offset:2048
	global_load_dwordx4 v[140:143], v245, s[78:79] offset:2064
	s_lshl_b32 s1, s0, 6
	s_add_u32 s78, s14, s1
	s_addc_u32 s79, s15, 0
	global_load_dwordx4 v[144:147], v244, s[78:79] offset:0
	global_load_dwordx4 v[148:151], v244, s[78:79] offset:16
	global_load_dwordx4 v[152:155], v244, s[78:79] offset:32
	global_load_dwordx4 v[156:159], v244, s[78:79] offset:48
	global_load_dwordx4 v[160:163], v244, s[78:79] offset:64
	global_load_dwordx4 v[164:167], v244, s[78:79] offset:80
	global_load_dwordx4 v[168:171], v244, s[78:79] offset:96
	global_load_dwordx4 v[172:175], v244, s[78:79] offset:112
	s_add_i32 s0, s77, 2
	s_lshl_b32 s1, s0, 11
	s_add_u32 s78, s12, s1
	s_addc_u32 s79, s13, 0
	global_load_dwordx4 v[176:179], v245, s[78:79]
	global_load_dwordx4 v[180:183], v245, s[78:79] offset:16
	global_load_dwordx4 v[184:187], v245, s[78:79] offset:2048
	global_load_dwordx4 v[188:191], v245, s[78:79] offset:2064
	s_lshl_b32 s1, s0, 6
	s_add_u32 s78, s14, s1
	s_addc_u32 s79, s15, 0
	global_load_dwordx4 v[216:219], v244, s[78:79] offset:0
	global_load_dwordx4 v[220:223], v244, s[78:79] offset:16
	global_load_dwordx4 v[224:227], v244, s[78:79] offset:32
	global_load_dwordx4 v[228:231], v244, s[78:79] offset:48
	global_load_dwordx4 v[232:235], v244, s[78:79] offset:64
	global_load_dwordx4 v[236:239], v244, s[78:79] offset:80
	global_load_dwordx4 v[248:251], v244, s[78:79] offset:96
	global_load_dwordx4 v[252:255], v244, s[78:79] offset:112
	s_waitcnt vmcnt(12)
; __device__ __forceinline__ unsigned pk2(float lo, float hi) { const f32x2 v = {lo, hi}; const bf16x2_t b = __builtin_convertvector(v, bf16x2_t); return __builtin_bit_cast(unsigned, b); }
; __device__ __forceinline__ float bflo(unsigned u) { return __uint_as_float(u << 16); }
; __device__ __forceinline__ float bfhi(unsigned u) { return __uint_as_float(u & 0xffff0000u); }
; __device__ __forceinline__ void peer_tile(const Args& A, LAS unsigned char* lds, int tile) {
;     ...
;         for (int tk = 0; tk < 4; ++tk) { const size_t m = (size_t)tile * 64 + tb + tk;
;             { const u32x4 ra = *(const u32x4*)(A3 + m * 1024 + 16 * lane), rb = *(const u32x4*)(A3 + m * 1024 + 16 * lane + 8);
;               float xr_; { const f32x4 p0 = *(const f32x4*)(RSq + m * 16), p1 = *(const f32x4*)(RSq + m * 16 + 4), p2 = *(const f32x4*)(RSq + m * 16 + 8), p3 = *(const f32x4*)(RSq + m * 16 + 12);
;                 const f32x4 ps = (p0 + p1) + (p2 + p3); xr_ = rsqrtf(((ps[0] + ps[1]) + (ps[2] + ps[3])) * (1.f / 1024.f) + 1e-6f); }
;               const unsigned rr[8] = {ra.x, ra.y, ra.z, ra.w, rb.x, rb.y, rb.z, rb.w}; unsigned hh[8];
;               const float* sp = MOD + (int)(m >> 11) * 6144 + 3072 + 16 * lane;
; #pragma unroll
;               for (int q = 0; q < 8; ++q) { const f32x2 sh = *(const f32x2*)(sp + 2 * q); hh[q] = pk2(bflo(rr[q]) * xr_ + sh[0], bfhi(rr[q]) * xr_ + sh[1]); }
;               xpa[tk] = (u32x4){hh[0], hh[1], hh[2], hh[3]}; xpb[tk] = (u32x4){hh[4], hh[5], hh[6], hh[7]}; }
	v_pk_add_f32 v[144:145], v[144:145], v[148:149]
	v_pk_add_f32 v[146:147], v[146:147], v[150:151]
	v_pk_add_f32 v[152:153], v[152:153], v[156:157]
	v_pk_add_f32 v[154:155], v[154:155], v[158:159]
	v_pk_add_f32 v[144:145], v[144:145], v[152:153]
	v_pk_add_f32 v[146:147], v[146:147], v[154:155]
	v_add_f32_e32 v144, v144, v145
	v_add_f32_e32 v146, v146, v147
	v_add_f32_e32 v144, v144, v146
	v_fmamk_f32 v144, v144, 0x3a800000, v243
	v_rsq_f32_e32 v144, v144
	v_pk_add_f32 v[160:161], v[160:161], v[164:165]
	v_pk_add_f32 v[162:163], v[162:163], v[166:167]
	v_pk_add_f32 v[168:169], v[168:169], v[172:173]
	v_pk_add_f32 v[170:171], v[170:171], v[174:175]
	v_pk_add_f32 v[160:161], v[160:161], v[168:169]
	v_pk_add_f32 v[162:163], v[162:163], v[170:171]
	v_add_f32_e32 v160, v160, v161
	v_add_f32_e32 v162, v162, v163
	v_add_f32_e32 v160, v160, v162
	v_fmamk_f32 v160, v160, 0x3a800000, v243
	v_rsq_f32_e32 v160, v160
	v_lshlrev_b32_e32 v208, 16, v128
	v_and_b32_e32 v209, 0xffff0000, v128
	v_fma_f32 v208, v208, v144, v192
	v_fma_f32 v209, v209, v144, v193
	v_cvt_pk_bf16_f32 v210, v208, v209
	v_lshlrev_b32_e32 v0, 16, v210
	v_and_b32_e32 v1, 0xffff0000, v210
	v_lshlrev_b32_e32 v208, 16, v129
	v_and_b32_e32 v209, 0xffff0000, v129
	v_fma_f32 v208, v208, v144, v194
	v_fma_f32 v209, v209, v144, v195
	v_cvt_pk_bf16_f32 v210, v208, v209
	v_lshlrev_b32_e32 v2, 16, v210
	v_and_b32_e32 v3, 0xffff0000, v210
	v_lshlrev_b32_e32 v208, 16, v130
	v_and_b32_e32 v209, 0xffff0000, v130
	v_fma_f32 v208, v208, v144, v196
	v_fma_f32 v209, v209, v144, v197
	v_cvt_pk_bf16_f32 v210, v208, v209
	v_lshlrev_b32_e32 v4, 16, v210
	v_and_b32_e32 v5, 0xffff0000, v210
	v_lshlrev_b32_e32 v208, 16, v131
	v_and_b32_e32 v209, 0xffff0000, v131
	v_fma_f32 v208, v208, v144, v198
	v_fma_f32 v209, v209, v144, v199
	v_cvt_pk_bf16_f32 v210, v208, v209
	v_lshlrev_b32_e32 v6, 16, v210
	v_and_b32_e32 v7, 0xffff0000, v210
	v_lshlrev_b32_e32 v208, 16, v132
	v_and_b32_e32 v209, 0xffff0000, v132
	v_fma_f32 v208, v208, v144, v200
	v_fma_f32 v209, v209, v144, v201
	v_cvt_pk_bf16_f32 v210, v208, v209
	v_lshlrev_b32_e32 v8, 16, v210
	v_and_b32_e32 v9, 0xffff0000, v210
	v_lshlrev_b32_e32 v208, 16, v133
	v_and_b32_e32 v209, 0xffff0000, v133
	v_fma_f32 v208, v208, v144, v202
	v_fma_f32 v209, v209, v144, v203
	v_cvt_pk_bf16_f32 v210, v208, v209
	v_lshlrev_b32_e32 v10, 16, v210
	v_and_b32_e32 v11, 0xffff0000, v210
	v_lshlrev_b32_e32 v208, 16, v134
	v_and_b32_e32 v209, 0xffff0000, v134
	v_fma_f32 v208, v208, v144, v204
	v_fma_f32 v209, v209, v144, v205
	v_cvt_pk_bf16_f32 v210, v208, v209
	v_lshlrev_b32_e32 v12, 16, v210
	v_and_b32_e32 v13, 0xffff0000, v210
	v_lshlrev_b32_e32 v208, 16, v135
	v_and_b32_e32 v209, 0xffff0000, v135
	v_fma_f32 v208, v208, v144, v206
	v_fma_f32 v209, v209, v144, v207
	v_cvt_pk_bf16_f32 v210, v208, v209
	v_lshlrev_b32_e32 v14, 16, v210
	v_and_b32_e32 v15, 0xffff0000, v210
	v_lshlrev_b32_e32 v208, 16, v136
	v_and_b32_e32 v209, 0xffff0000, v136
	v_fma_f32 v208, v208, v160, v192
	v_fma_f32 v209, v209, v160, v193
	v_cvt_pk_bf16_f32 v210, v208, v209
	v_lshlrev_b32_e32 v16, 16, v210
	v_and_b32_e32 v17, 0xffff0000, v210
	v_lshlrev_b32_e32 v208, 16, v137
	v_and_b32_e32 v209, 0xffff0000, v137
	v_fma_f32 v208, v208, v160, v194
	v_fma_f32 v209, v209, v160, v195
	v_cvt_pk_bf16_f32 v210, v208, v209
	v_lshlrev_b32_e32 v18, 16, v210
	v_and_b32_e32 v19, 0xffff0000, v210
	v_lshlrev_b32_e32 v208, 16, v138
	v_and_b32_e32 v209, 0xffff0000, v138
	v_fma_f32 v208, v208, v160, v196
	v_fma_f32 v209, v209, v160, v197
	v_cvt_pk_bf16_f32 v210, v208, v209
	v_lshlrev_b32_e32 v20, 16, v210
	v_and_b32_e32 v21, 0xffff0000, v210
	v_lshlrev_b32_e32 v208, 16, v139
	v_and_b32_e32 v209, 0xffff0000, v139
	v_fma_f32 v208, v208, v160, v198
	v_fma_f32 v209, v209, v160, v199
	v_cvt_pk_bf16_f32 v210, v208, v209
	v_lshlrev_b32_e32 v22, 16, v210
	v_and_b32_e32 v23, 0xffff0000, v210
	v_lshlrev_b32_e32 v208, 16, v140
	v_and_b32_e32 v209, 0xffff0000, v140
	v_fma_f32 v208, v208, v160, v200
	v_fma_f32 v209, v209, v160, v201
	v_cvt_pk_bf16_f32 v210, v208, v209
	v_lshlrev_b32_e32 v24, 16, v210
	v_and_b32_e32 v25, 0xffff0000, v210
	v_lshlrev_b32_e32 v208, 16, v141
	v_and_b32_e32 v209, 0xffff0000, v141
	v_fma_f32 v208, v208, v160, v202
	v_fma_f32 v209, v209, v160, v203
	v_cvt_pk_bf16_f32 v210, v208, v209
	v_lshlrev_b32_e32 v26, 16, v210
	v_and_b32_e32 v27, 0xffff0000, v210
	v_lshlrev_b32_e32 v208, 16, v142
	v_and_b32_e32 v209, 0xffff0000, v142
	v_fma_f32 v208, v208, v160, v204
	v_fma_f32 v209, v209, v160, v205
	v_cvt_pk_bf16_f32 v210, v208, v209
	v_lshlrev_b32_e32 v28, 16, v210
	v_and_b32_e32 v29, 0xffff0000, v210
	v_lshlrev_b32_e32 v208, 16, v143
	v_and_b32_e32 v209, 0xffff0000, v143
	v_fma_f32 v208, v208, v160, v206
	v_fma_f32 v209, v209, v160, v207
	v_cvt_pk_bf16_f32 v210, v208, v209
	v_lshlrev_b32_e32 v30, 16, v210
	v_and_b32_e32 v31, 0xffff0000, v210
	s_nop 0
	s_add_i32 s0, s77, 4
	s_lshl_b32 s1, s0, 11
	s_add_u32 s78, s12, s1
	s_addc_u32 s79, s13, 0
	global_load_dwordx4 v[128:131], v245, s[78:79]
	global_load_dwordx4 v[132:135], v245, s[78:79] offset:16
	global_load_dwordx4 v[136:139], v245, s[78:79] offset:2048
	global_load_dwordx4 v[140:143], v245, s[78:79] offset:2064
	s_lshl_b32 s1, s0, 6
	s_add_u32 s78, s14, s1
	s_addc_u32 s79, s15, 0
	global_load_dwordx4 v[144:147], v244, s[78:79] offset:0
	global_load_dwordx4 v[148:151], v244, s[78:79] offset:16
	global_load_dwordx4 v[152:155], v244, s[78:79] offset:32
	global_load_dwordx4 v[156:159], v244, s[78:79] offset:48
	global_load_dwordx4 v[160:163], v244, s[78:79] offset:64
	global_load_dwordx4 v[164:167], v244, s[78:79] offset:80
	global_load_dwordx4 v[168:171], v244, s[78:79] offset:96
	global_load_dwordx4 v[172:175], v244, s[78:79] offset:112
	s_waitcnt vmcnt(12)
; __device__ __forceinline__ unsigned pk2(float lo, float hi) { const f32x2 v = {lo, hi}; const bf16x2_t b = __builtin_convertvector(v, bf16x2_t); return __builtin_bit_cast(unsigned, b); }
; __device__ __forceinline__ float bflo(unsigned u) { return __uint_as_float(u << 16); }
; __device__ __forceinline__ float bfhi(unsigned u) { return __uint_as_float(u & 0xffff0000u); }
; __device__ __forceinline__ void peer_tile(const Args& A, LAS unsigned char* lds, int tile) {
;     ...
;         for (int tk = 0; tk < 4; ++tk) { const size_t m = (size_t)tile * 64 + tb + tk;
;             { const u32x4 ra = *(const u32x4*)(A3 + m * 1024 + 16 * lane), rb = *(const u32x4*)(A3 + m * 1024 + 16 * lane + 8);
;               float xr_; { const f32x4 p0 = *(const f32x4*)(RSq + m * 16), p1 = *(const f32x4*)(RSq + m * 16 + 4), p2 = *(const f32x4*)(RSq + m * 16 + 8), p3 = *(const f32x4*)(RSq + m * 16 + 12);
;                 const f32x4 ps = (p0 + p1) + (p2 + p3); xr_ = rsqrtf(((ps[0] + ps[1]) + (ps[2] + ps[3])) * (1.f / 1024.f) + 1e-6f); }
;               const unsigned rr[8] = {ra.x, ra.y, ra.z, ra.w, rb.x, rb.y, rb.z, rb.w}; unsigned hh[8];
;               const float* sp = MOD + (int)(m >> 11) * 6144 + 3072 + 16 * lane;
; #pragma unroll
;               for (int q = 0; q < 8; ++q) { const f32x2 sh = *(const f32x2*)(sp + 2 * q); hh[q] = pk2(bflo(rr[q]) * xr_ + sh[0], bfhi(rr[q]) * xr_ + sh[1]); }
;               xpa[tk] = (u32x4){hh[0], hh[1], hh[2], hh[3]}; xpb[tk] = (u32x4){hh[4], hh[5], hh[6], hh[7]}; }
	v_pk_add_f32 v[216:217], v[216:217], v[220:221]
	v_pk_add_f32 v[218:219], v[218:219], v[222:223]
	v_pk_add_f32 v[224:225], v[224:225], v[228:229]
	v_pk_add_f32 v[226:227], v[226:227], v[230:231]
	v_pk_add_f32 v[216:217], v[216:217], v[224:225]
	v_pk_add_f32 v[218:219], v[218:219], v[226:227]
	v_add_f32_e32 v216, v216, v217
	v_add_f32_e32 v218, v218, v219
	v_add_f32_e32 v216, v216, v218
	v_fmamk_f32 v216, v216, 0x3a800000, v243
	v_rsq_f32_e32 v216, v216
	v_pk_add_f32 v[232:233], v[232:233], v[236:237]
	v_pk_add_f32 v[234:235], v[234:235], v[238:239]
	v_pk_add_f32 v[248:249], v[248:249], v[252:253]
	v_pk_add_f32 v[250:251], v[250:251], v[254:255]
	v_pk_add_f32 v[232:233], v[232:233], v[248:249]
	v_pk_add_f32 v[234:235], v[234:235], v[250:251]
	v_add_f32_e32 v232, v232, v233
	v_add_f32_e32 v234, v234, v235
	v_add_f32_e32 v232, v232, v234
	v_fmamk_f32 v232, v232, 0x3a800000, v243
	v_rsq_f32_e32 v232, v232
	v_lshlrev_b32_e32 v208, 16, v176
	v_and_b32_e32 v209, 0xffff0000, v176
	v_fma_f32 v208, v208, v216, v192
	v_fma_f32 v209, v209, v216, v193
	v_cvt_pk_bf16_f32 v210, v208, v209
	v_lshlrev_b32_e32 v32, 16, v210
	v_and_b32_e32 v33, 0xffff0000, v210
	v_lshlrev_b32_e32 v208, 16, v177
	v_and_b32_e32 v209, 0xffff0000, v177
	v_fma_f32 v208, v208, v216, v194
	v_fma_f32 v209, v209, v216, v195
	v_cvt_pk_bf16_f32 v210, v208, v209
	v_lshlrev_b32_e32 v34, 16, v210
	v_and_b32_e32 v35, 0xffff0000, v210
	v_lshlrev_b32_e32 v208, 16, v178
	v_and_b32_e32 v209, 0xffff0000, v178
	v_fma_f32 v208, v208, v216, v196
	v_fma_f32 v209, v209, v216, v197
	v_cvt_pk_bf16_f32 v210, v208, v209
	v_lshlrev_b32_e32 v36, 16, v210
	v_and_b32_e32 v37, 0xffff0000, v210
	v_lshlrev_b32_e32 v208, 16, v179
	v_and_b32_e32 v209, 0xffff0000, v179
	v_fma_f32 v208, v208, v216, v198
	v_fma_f32 v209, v209, v216, v199
	v_cvt_pk_bf16_f32 v210, v208, v209
	v_lshlrev_b32_e32 v38, 16, v210
	v_and_b32_e32 v39, 0xffff0000, v210
	v_lshlrev_b32_e32 v208, 16, v180
	v_and_b32_e32 v209, 0xffff0000, v180
	v_fma_f32 v208, v208, v216, v200
	v_fma_f32 v209, v209, v216, v201
	v_cvt_pk_bf16_f32 v210, v208, v209
	v_lshlrev_b32_e32 v40, 16, v210
	v_and_b32_e32 v41, 0xffff0000, v210
	v_lshlrev_b32_e32 v208, 16, v181
	v_and_b32_e32 v209, 0xffff0000, v181
	v_fma_f32 v208, v208, v216, v202
	v_fma_f32 v209, v209, v216, v203
	v_cvt_pk_bf16_f32 v210, v208, v209
	v_lshlrev_b32_e32 v42, 16, v210
	v_and_b32_e32 v43, 0xffff0000, v210
	v_lshlrev_b32_e32 v208, 16, v182
	v_and_b32_e32 v209, 0xffff0000, v182
	v_fma_f32 v208, v208, v216, v204
	v_fma_f32 v209, v209, v216, v205
	v_cvt_pk_bf16_f32 v210, v208, v209
	v_lshlrev_b32_e32 v44, 16, v210
	v_and_b32_e32 v45, 0xffff0000, v210
	v_lshlrev_b32_e32 v208, 16, v183
	v_and_b32_e32 v209, 0xffff0000, v183
	v_fma_f32 v208, v208, v216, v206
	v_fma_f32 v209, v209, v216, v207
	v_cvt_pk_bf16_f32 v210, v208, v209
	v_lshlrev_b32_e32 v46, 16, v210
	v_and_b32_e32 v47, 0xffff0000, v210
	v_lshlrev_b32_e32 v208, 16, v184
	v_and_b32_e32 v209, 0xffff0000, v184
	v_fma_f32 v208, v208, v232, v192
	v_fma_f32 v209, v209, v232, v193
	v_cvt_pk_bf16_f32 v210, v208, v209
	v_lshlrev_b32_e32 v48, 16, v210
	v_and_b32_e32 v49, 0xffff0000, v210
	v_lshlrev_b32_e32 v208, 16, v185
	v_and_b32_e32 v209, 0xffff0000, v185
	v_fma_f32 v208, v208, v232, v194
	v_fma_f32 v209, v209, v232, v195
	v_cvt_pk_bf16_f32 v210, v208, v209
	v_lshlrev_b32_e32 v50, 16, v210
	v_and_b32_e32 v51, 0xffff0000, v210
	v_lshlrev_b32_e32 v208, 16, v186
	v_and_b32_e32 v209, 0xffff0000, v186
	v_fma_f32 v208, v208, v232, v196
	v_fma_f32 v209, v209, v232, v197
	v_cvt_pk_bf16_f32 v210, v208, v209
	v_lshlrev_b32_e32 v52, 16, v210
	v_and_b32_e32 v53, 0xffff0000, v210
	v_lshlrev_b32_e32 v208, 16, v187
	v_and_b32_e32 v209, 0xffff0000, v187
	v_fma_f32 v208, v208, v232, v198
	v_fma_f32 v209, v209, v232, v199
	v_cvt_pk_bf16_f32 v210, v208, v209
	v_lshlrev_b32_e32 v54, 16, v210
	v_and_b32_e32 v55, 0xffff0000, v210
	v_lshlrev_b32_e32 v208, 16, v188
	v_and_b32_e32 v209, 0xffff0000, v188
	v_fma_f32 v208, v208, v232, v200
	v_fma_f32 v209, v209, v232, v201
	v_cvt_pk_bf16_f32 v210, v208, v209
	v_lshlrev_b32_e32 v56, 16, v210
	v_and_b32_e32 v57, 0xffff0000, v210
	v_lshlrev_b32_e32 v208, 16, v189
	v_and_b32_e32 v209, 0xffff0000, v189
	v_fma_f32 v208, v208, v232, v202
	v_fma_f32 v209, v209, v232, v203
	v_cvt_pk_bf16_f32 v210, v208, v209
	v_lshlrev_b32_e32 v58, 16, v210
	v_and_b32_e32 v59, 0xffff0000, v210
	v_lshlrev_b32_e32 v208, 16, v190
	v_and_b32_e32 v209, 0xffff0000, v190
	v_fma_f32 v208, v208, v232, v204
	v_fma_f32 v209, v209, v232, v205
	v_cvt_pk_bf16_f32 v210, v208, v209
	v_lshlrev_b32_e32 v60, 16, v210
	v_and_b32_e32 v61, 0xffff0000, v210
	v_lshlrev_b32_e32 v208, 16, v191
	v_and_b32_e32 v209, 0xffff0000, v191
	v_fma_f32 v208, v208, v232, v206
	v_fma_f32 v209, v209, v232, v207
	v_cvt_pk_bf16_f32 v210, v208, v209
	v_lshlrev_b32_e32 v62, 16, v210
	v_and_b32_e32 v63, 0xffff0000, v210
	s_nop 0
	s_add_i32 s0, s77, 6
	s_lshl_b32 s1, s0, 11
	s_add_u32 s78, s12, s1
	s_addc_u32 s79, s13, 0
	global_load_dwordx4 v[176:179], v245, s[78:79]
	global_load_dwordx4 v[180:183], v245, s[78:79] offset:16
	global_load_dwordx4 v[184:187], v245, s[78:79] offset:2048
	global_load_dwordx4 v[188:191], v245, s[78:79] offset:2064
	s_lshl_b32 s1, s0, 6
	s_add_u32 s78, s14, s1
	s_addc_u32 s79, s15, 0
	global_load_dwordx4 v[216:219], v244, s[78:79] offset:0
	global_load_dwordx4 v[220:223], v244, s[78:79] offset:16
	global_load_dwordx4 v[224:227], v244, s[78:79] offset:32
	global_load_dwordx4 v[228:231], v244, s[78:79] offset:48
	global_load_dwordx4 v[232:235], v244, s[78:79] offset:64
	global_load_dwordx4 v[236:239], v244, s[78:79] offset:80
	global_load_dwordx4 v[248:251], v244, s[78:79] offset:96
	global_load_dwordx4 v[252:255], v244, s[78:79] offset:112
	s_waitcnt vmcnt(12)
; __device__ __forceinline__ unsigned pk2(float lo, float hi) { const f32x2 v = {lo, hi}; const bf16x2_t b = __builtin_convertvector(v, bf16x2_t); return __builtin_bit_cast(unsigned, b); }
; __device__ __forceinline__ float bflo(unsigned u) { return __uint_as_float(u << 16); }
; __device__ __forceinline__ float bfhi(unsigned u) { return __uint_as_float(u & 0xffff0000u); }
; __device__ __forceinline__ void peer_tile(const Args& A, LAS unsigned char* lds, int tile) {
;     ...
;         for (int tk = 0; tk < 4; ++tk) { const size_t m = (size_t)tile * 64 + tb + tk;
;             { const u32x4 ra = *(const u32x4*)(A3 + m * 1024 + 16 * lane), rb = *(const u32x4*)(A3 + m * 1024 + 16 * lane + 8);
;               float xr_; { const f32x4 p0 = *(const f32x4*)(RSq + m * 16), p1 = *(const f32x4*)(RSq + m * 16 + 4), p2 = *(const f32x4*)(RSq + m * 16 + 8), p3 = *(const f32x4*)(RSq + m * 16 + 12);
;                 const f32x4 ps = (p0 + p1) + (p2 + p3); xr_ = rsqrtf(((ps[0] + ps[1]) + (ps[2] + ps[3])) * (1.f / 1024.f) + 1e-6f); }
;               const unsigned rr[8] = {ra.x, ra.y, ra.z, ra.w, rb.x, rb.y, rb.z, rb.w}; unsigned hh[8];
;               const float* sp = MOD + (int)(m >> 11) * 6144 + 3072 + 16 * lane;
; #pragma unroll
;               for (int q = 0; q < 8; ++q) { const f32x2 sh = *(const f32x2*)(sp + 2 * q); hh[q] = pk2(bflo(rr[q]) * xr_ + sh[0], bfhi(rr[q]) * xr_ + sh[1]); }
;               xpa[tk] = (u32x4){hh[0], hh[1], hh[2], hh[3]}; xpb[tk] = (u32x4){hh[4], hh[5], hh[6], hh[7]}; }
	v_pk_add_f32 v[144:145], v[144:145], v[148:149]
	v_pk_add_f32 v[146:147], v[146:147], v[150:151]
	v_pk_add_f32 v[152:153], v[152:153], v[156:157]
	v_pk_add_f32 v[154:155], v[154:155], v[158:159]
	v_pk_add_f32 v[144:145], v[144:145], v[152:153]
	v_pk_add_f32 v[146:147], v[146:147], v[154:155]
	v_add_f32_e32 v144, v144, v145
	v_add_f32_e32 v146, v146, v147
	v_add_f32_e32 v144, v144, v146
	v_fmamk_f32 v144, v144, 0x3a800000, v243
	v_rsq_f32_e32 v144, v144
	v_pk_add_f32 v[160:161], v[160:161], v[164:165]
	v_pk_add_f32 v[162:163], v[162:163], v[166:167]
	v_pk_add_f32 v[168:169], v[168:169], v[172:173]
	v_pk_add_f32 v[170:171], v[170:171], v[174:175]
	v_pk_add_f32 v[160:161], v[160:161], v[168:169]
	v_pk_add_f32 v[162:163], v[162:163], v[170:171]
	v_add_f32_e32 v160, v160, v161
	v_add_f32_e32 v162, v162, v163
	v_add_f32_e32 v160, v160, v162
	v_fmamk_f32 v160, v160, 0x3a800000, v243
	v_rsq_f32_e32 v160, v160
	v_lshlrev_b32_e32 v208, 16, v128
	v_and_b32_e32 v209, 0xffff0000, v128
	v_fma_f32 v208, v208, v144, v192
	v_fma_f32 v209, v209, v144, v193
	v_cvt_pk_bf16_f32 v210, v208, v209
	v_lshlrev_b32_e32 v64, 16, v210
	v_and_b32_e32 v65, 0xffff0000, v210
	v_lshlrev_b32_e32 v208, 16, v129
	v_and_b32_e32 v209, 0xffff0000, v129
	v_fma_f32 v208, v208, v144, v194
	v_fma_f32 v209, v209, v144, v195
	v_cvt_pk_bf16_f32 v210, v208, v209
	v_lshlrev_b32_e32 v66, 16, v210
	v_and_b32_e32 v67, 0xffff0000, v210
	v_lshlrev_b32_e32 v208, 16, v130
	v_and_b32_e32 v209, 0xffff0000, v130
	v_fma_f32 v208, v208, v144, v196
	v_fma_f32 v209, v209, v144, v197
	v_cvt_pk_bf16_f32 v210, v208, v209
	v_lshlrev_b32_e32 v68, 16, v210
	v_and_b32_e32 v69, 0xffff0000, v210
	v_lshlrev_b32_e32 v208, 16, v131
	v_and_b32_e32 v209, 0xffff0000, v131
	v_fma_f32 v208, v208, v144, v198
	v_fma_f32 v209, v209, v144, v199
	v_cvt_pk_bf16_f32 v210, v208, v209
	v_lshlrev_b32_e32 v70, 16, v210
	v_and_b32_e32 v71, 0xffff0000, v210
	v_lshlrev_b32_e32 v208, 16, v132
	v_and_b32_e32 v209, 0xffff0000, v132
	v_fma_f32 v208, v208, v144, v200
	v_fma_f32 v209, v209, v144, v201
	v_cvt_pk_bf16_f32 v210, v208, v209
	v_lshlrev_b32_e32 v72, 16, v210
	v_and_b32_e32 v73, 0xffff0000, v210
	v_lshlrev_b32_e32 v208, 16, v133
	v_and_b32_e32 v209, 0xffff0000, v133
	v_fma_f32 v208, v208, v144, v202
	v_fma_f32 v209, v209, v144, v203
	v_cvt_pk_bf16_f32 v210, v208, v209
	v_lshlrev_b32_e32 v74, 16, v210
	v_and_b32_e32 v75, 0xffff0000, v210
	v_lshlrev_b32_e32 v208, 16, v134
	v_and_b32_e32 v209, 0xffff0000, v134
	v_fma_f32 v208, v208, v144, v204
	v_fma_f32 v209, v209, v144, v205
	v_cvt_pk_bf16_f32 v210, v208, v209
	v_lshlrev_b32_e32 v76, 16, v210
	v_and_b32_e32 v77, 0xffff0000, v210
	v_lshlrev_b32_e32 v208, 16, v135
	v_and_b32_e32 v209, 0xffff0000, v135
	v_fma_f32 v208, v208, v144, v206
	v_fma_f32 v209, v209, v144, v207
	v_cvt_pk_bf16_f32 v210, v208, v209
	v_lshlrev_b32_e32 v78, 16, v210
	v_and_b32_e32 v79, 0xffff0000, v210
	v_lshlrev_b32_e32 v208, 16, v136
	v_and_b32_e32 v209, 0xffff0000, v136
	v_fma_f32 v208, v208, v160, v192
	v_fma_f32 v209, v209, v160, v193
	v_cvt_pk_bf16_f32 v210, v208, v209
	v_lshlrev_b32_e32 v80, 16, v210
	v_and_b32_e32 v81, 0xffff0000, v210
	v_lshlrev_b32_e32 v208, 16, v137
	v_and_b32_e32 v209, 0xffff0000, v137
	v_fma_f32 v208, v208, v160, v194
	v_fma_f32 v209, v209, v160, v195
	v_cvt_pk_bf16_f32 v210, v208, v209
	v_lshlrev_b32_e32 v82, 16, v210
	v_and_b32_e32 v83, 0xffff0000, v210
	v_lshlrev_b32_e32 v208, 16, v138
	v_and_b32_e32 v209, 0xffff0000, v138
	v_fma_f32 v208, v208, v160, v196
	v_fma_f32 v209, v209, v160, v197
	v_cvt_pk_bf16_f32 v210, v208, v209
	v_lshlrev_b32_e32 v84, 16, v210
	v_and_b32_e32 v85, 0xffff0000, v210
	v_lshlrev_b32_e32 v208, 16, v139
	v_and_b32_e32 v209, 0xffff0000, v139
	v_fma_f32 v208, v208, v160, v198
	v_fma_f32 v209, v209, v160, v199
	v_cvt_pk_bf16_f32 v210, v208, v209
	v_lshlrev_b32_e32 v86, 16, v210
	v_and_b32_e32 v87, 0xffff0000, v210
	v_lshlrev_b32_e32 v208, 16, v140
	v_and_b32_e32 v209, 0xffff0000, v140
	v_fma_f32 v208, v208, v160, v200
	v_fma_f32 v209, v209, v160, v201
	v_cvt_pk_bf16_f32 v210, v208, v209
	v_lshlrev_b32_e32 v88, 16, v210
	v_and_b32_e32 v89, 0xffff0000, v210
	v_lshlrev_b32_e32 v208, 16, v141
	v_and_b32_e32 v209, 0xffff0000, v141
	v_fma_f32 v208, v208, v160, v202
	v_fma_f32 v209, v209, v160, v203
	v_cvt_pk_bf16_f32 v210, v208, v209
	v_lshlrev_b32_e32 v90, 16, v210
	v_and_b32_e32 v91, 0xffff0000, v210
	v_lshlrev_b32_e32 v208, 16, v142
	v_and_b32_e32 v209, 0xffff0000, v142
	v_fma_f32 v208, v208, v160, v204
	v_fma_f32 v209, v209, v160, v205
	v_cvt_pk_bf16_f32 v210, v208, v209
	v_lshlrev_b32_e32 v92, 16, v210
	v_and_b32_e32 v93, 0xffff0000, v210
	v_lshlrev_b32_e32 v208, 16, v143
	v_and_b32_e32 v209, 0xffff0000, v143
	v_fma_f32 v208, v208, v160, v206
	v_fma_f32 v209, v209, v160, v207
	v_cvt_pk_bf16_f32 v210, v208, v209
	v_lshlrev_b32_e32 v94, 16, v210
	v_and_b32_e32 v95, 0xffff0000, v210
	s_nop 0
	s_waitcnt vmcnt(0)
; __device__ __forceinline__ unsigned pk2(float lo, float hi) { const f32x2 v = {lo, hi}; const bf16x2_t b = __builtin_convertvector(v, bf16x2_t); return __builtin_bit_cast(unsigned, b); }
; __device__ __forceinline__ float bflo(unsigned u) { return __uint_as_float(u << 16); }
; __device__ __forceinline__ void peer_tile(const Args& A, LAS unsigned char* lds, int tile) {
;     ...
;     for (int ti = 0; ti < 8; ++ti) {
;         const int tl = 8 * w + ti;
;         const u32x2 e0 = SEL[tl * 128 + lane], e1 = SEL[tl * 128 + 64 + lane];
;         const int p0 = (int)(e0.x >> 10), p1 = (int)(e1.x >> 10);
;         int off = 0;
;         for (int p = 0; p < 16; ++p) {
;             const unsigned long long m0 = __ballot(p0 == p), m1 = __ballot(p1 == p);
;             const int c0 = __popcll(m0), c1 = __popcll(m1);
;             const int r0 = __builtin_amdgcn_mbcnt_hi((unsigned)(m0 >> 32), __builtin_amdgcn_mbcnt_lo((unsigned)m0, 0u));
;             const int r1 = __builtin_amdgcn_mbcnt_hi((unsigned)(m1 >> 32), __builtin_amdgcn_mbcnt_lo((unsigned)m1, 0u));
;             if (p0 == p) SORT[tl * 128 + off + r0] = e0;
;             if (p1 == p) SORT[tl * 128 + off + c0 + r1] = e1;
;             if (lane == 0) OFFS[tl * 17 + p] = off;
;             off += c0 + c1;
;         }
;         if (lane == 0) OFFS[tl * 17 + 16] = off;
;     }
;     ...
;         for (int tk = 0; tk < 4; ++tk) { const size_t m = (size_t)tile * 64 + tb + tk;
;             { const u32x4 ra = *(const u32x4*)(A3 + m * 1024 + 16 * lane), rb = *(const u32x4*)(A3 + m * 1024 + 16 * lane + 8);
;               float xr_; { const f32x4 p0 = *(const f32x4*)(RSq + m * 16), p1 = *(const f32x4*)(RSq + m * 16 + 4), p2 = *(const f32x4*)(RSq + m * 16 + 8), p3 = *(const f32x4*)(RSq + m * 16 + 12);
;                 const f32x4 ps = (p0 + p1) + (p2 + p3); xr_ = rsqrtf(((ps[0] + ps[1]) + (ps[2] + ps[3])) * (1.f / 1024.f) + 1e-6f); }
;               const unsigned rr[8] = {ra.x, ra.y, ra.z, ra.w, rb.x, rb.y, rb.z, rb.w}; unsigned hh[8];
;               const float* sp = MOD + (int)(m >> 11) * 6144 + 3072 + 16 * lane;
; #pragma unroll
;               for (int q = 0; q < 8; ++q) { const f32x2 sh = *(const f32x2*)(sp + 2 * q); hh[q] = pk2(bflo(rr[q]) * xr_ + sh[0], bfhi(rr[q]) * xr_ + sh[1]); }
;               xpa[tk] = (u32x4){hh[0], hh[1], hh[2], hh[3]}; xpb[tk] = (u32x4){hh[4], hh[5], hh[6], hh[7]}; }
	v_pk_add_f32 v[216:217], v[216:217], v[220:221]
	v_pk_add_f32 v[218:219], v[218:219], v[222:223]
	v_pk_add_f32 v[224:225], v[224:225], v[228:229]
	v_pk_add_f32 v[226:227], v[226:227], v[230:231]
	v_pk_add_f32 v[216:217], v[216:217], v[224:225]
	v_pk_add_f32 v[218:219], v[218:219], v[226:227]
	v_add_f32_e32 v216, v216, v217
	v_add_f32_e32 v218, v218, v219
	v_add_f32_e32 v216, v216, v218
	v_fmamk_f32 v216, v216, 0x3a800000, v243
	v_rsq_f32_e32 v216, v216
	v_pk_add_f32 v[232:233], v[232:233], v[236:237]
	v_pk_add_f32 v[234:235], v[234:235], v[238:239]
	v_pk_add_f32 v[248:249], v[248:249], v[252:253]
	v_pk_add_f32 v[250:251], v[250:251], v[254:255]
	v_pk_add_f32 v[232:233], v[232:233], v[248:249]
	v_pk_add_f32 v[234:235], v[234:235], v[250:251]
	v_add_f32_e32 v232, v232, v233
	v_add_f32_e32 v234, v234, v235
	v_add_f32_e32 v232, v232, v234
	v_fmamk_f32 v232, v232, 0x3a800000, v243
	v_rsq_f32_e32 v232, v232
	v_lshlrev_b32_e32 v208, 16, v176
	v_and_b32_e32 v209, 0xffff0000, v176
	v_fma_f32 v208, v208, v216, v192
	v_fma_f32 v209, v209, v216, v193
	v_cvt_pk_bf16_f32 v210, v208, v209
	v_lshlrev_b32_e32 v96, 16, v210
	v_and_b32_e32 v97, 0xffff0000, v210
	v_lshlrev_b32_e32 v208, 16, v177
	v_and_b32_e32 v209, 0xffff0000, v177
	v_fma_f32 v208, v208, v216, v194
	v_fma_f32 v209, v209, v216, v195
	v_cvt_pk_bf16_f32 v210, v208, v209
	v_lshlrev_b32_e32 v98, 16, v210
	v_and_b32_e32 v99, 0xffff0000, v210
	v_lshlrev_b32_e32 v208, 16, v178
	v_and_b32_e32 v209, 0xffff0000, v178
	v_fma_f32 v208, v208, v216, v196
	v_fma_f32 v209, v209, v216, v197
	v_cvt_pk_bf16_f32 v210, v208, v209
	v_lshlrev_b32_e32 v100, 16, v210
	v_and_b32_e32 v101, 0xffff0000, v210
	v_lshlrev_b32_e32 v208, 16, v179
	v_and_b32_e32 v209, 0xffff0000, v179
	v_fma_f32 v208, v208, v216, v198
	v_fma_f32 v209, v209, v216, v199
	v_cvt_pk_bf16_f32 v210, v208, v209
	v_lshlrev_b32_e32 v102, 16, v210
	v_and_b32_e32 v103, 0xffff0000, v210
	v_lshlrev_b32_e32 v208, 16, v180
	v_and_b32_e32 v209, 0xffff0000, v180
	v_fma_f32 v208, v208, v216, v200
	v_fma_f32 v209, v209, v216, v201
	v_cvt_pk_bf16_f32 v210, v208, v209
	v_lshlrev_b32_e32 v104, 16, v210
	v_and_b32_e32 v105, 0xffff0000, v210
	v_lshlrev_b32_e32 v208, 16, v181
	v_and_b32_e32 v209, 0xffff0000, v181
	v_fma_f32 v208, v208, v216, v202
	v_fma_f32 v209, v209, v216, v203
	v_cvt_pk_bf16_f32 v210, v208, v209
	v_lshlrev_b32_e32 v106, 16, v210
	v_and_b32_e32 v107, 0xffff0000, v210
	v_lshlrev_b32_e32 v208, 16, v182
	v_and_b32_e32 v209, 0xffff0000, v182
	v_fma_f32 v208, v208, v216, v204
	v_fma_f32 v209, v209, v216, v205
	v_cvt_pk_bf16_f32 v210, v208, v209
	v_lshlrev_b32_e32 v108, 16, v210
	v_and_b32_e32 v109, 0xffff0000, v210
	v_lshlrev_b32_e32 v208, 16, v183
	v_and_b32_e32 v209, 0xffff0000, v183
	v_fma_f32 v208, v208, v216, v206
	v_fma_f32 v209, v209, v216, v207
	v_cvt_pk_bf16_f32 v210, v208, v209
	v_lshlrev_b32_e32 v110, 16, v210
	v_and_b32_e32 v111, 0xffff0000, v210
	v_lshlrev_b32_e32 v208, 16, v184
	v_and_b32_e32 v209, 0xffff0000, v184
	v_fma_f32 v208, v208, v232, v192
	v_fma_f32 v209, v209, v232, v193
	v_cvt_pk_bf16_f32 v210, v208, v209
	v_lshlrev_b32_e32 v112, 16, v210
	v_and_b32_e32 v113, 0xffff0000, v210
	v_lshlrev_b32_e32 v208, 16, v185
	v_and_b32_e32 v209, 0xffff0000, v185
	v_fma_f32 v208, v208, v232, v194
	v_fma_f32 v209, v209, v232, v195
	v_cvt_pk_bf16_f32 v210, v208, v209
	v_lshlrev_b32_e32 v114, 16, v210
	v_and_b32_e32 v115, 0xffff0000, v210
	v_lshlrev_b32_e32 v208, 16, v186
	v_and_b32_e32 v209, 0xffff0000, v186
	v_fma_f32 v208, v208, v232, v196
	v_fma_f32 v209, v209, v232, v197
	v_cvt_pk_bf16_f32 v210, v208, v209
	v_lshlrev_b32_e32 v116, 16, v210
	v_and_b32_e32 v117, 0xffff0000, v210
	v_lshlrev_b32_e32 v208, 16, v187
	v_and_b32_e32 v209, 0xffff0000, v187
	v_fma_f32 v208, v208, v232, v198
	v_fma_f32 v209, v209, v232, v199
	v_cvt_pk_bf16_f32 v210, v208, v209
	v_lshlrev_b32_e32 v118, 16, v210
	v_and_b32_e32 v119, 0xffff0000, v210
	v_lshlrev_b32_e32 v208, 16, v188
	v_and_b32_e32 v209, 0xffff0000, v188
	v_fma_f32 v208, v208, v232, v200
	v_fma_f32 v209, v209, v232, v201
	v_cvt_pk_bf16_f32 v210, v208, v209
	v_lshlrev_b32_e32 v120, 16, v210
	v_and_b32_e32 v121, 0xffff0000, v210
	v_lshlrev_b32_e32 v208, 16, v189
	v_and_b32_e32 v209, 0xffff0000, v189
	v_fma_f32 v208, v208, v232, v202
	v_fma_f32 v209, v209, v232, v203
	v_cvt_pk_bf16_f32 v210, v208, v209
	v_lshlrev_b32_e32 v122, 16, v210
	v_and_b32_e32 v123, 0xffff0000, v210
	v_lshlrev_b32_e32 v208, 16, v190
	v_and_b32_e32 v209, 0xffff0000, v190
	v_fma_f32 v208, v208, v232, v204
	v_fma_f32 v209, v209, v232, v205
	v_cvt_pk_bf16_f32 v210, v208, v209
	v_lshlrev_b32_e32 v124, 16, v210
	v_and_b32_e32 v125, 0xffff0000, v210
	v_lshlrev_b32_e32 v208, 16, v191
	v_and_b32_e32 v209, 0xffff0000, v191
	v_fma_f32 v208, v208, v232, v206
	v_fma_f32 v209, v209, v232, v207
	v_cvt_pk_bf16_f32 v210, v208, v209
	v_lshlrev_b32_e32 v126, 16, v210
	v_and_b32_e32 v127, 0xffff0000, v210
	s_nop 0
	v_mov_b32_e32 v224, 0x7fffffff
	v_mov_b32_e32 v225, 0x7fffffff
	v_mov_b32_e32 v226, 0x7fffffff
	v_mov_b32_e32 v227, 0x7fffffff
	v_mov_b32_e32 v228, 0
	v_mov_b32_e32 v229, 0
	v_mov_b32_e32 v230, 0
	v_mov_b32_e32 v231, 0
	v_add_u32_e32 v232, s22, v240
	ds_write_b128 v232, v[224:227] offset:0
	ds_write_b128 v232, v[228:231] offset:4992
	ds_write_b128 v232, v[224:227] offset:1024
	ds_write_b128 v232, v[228:231] offset:6016
	ds_write_b128 v232, v[224:227] offset:2048
	ds_write_b128 v232, v[228:231] offset:7040
	ds_write_b128 v232, v[224:227] offset:3072
	ds_write_b128 v232, v[228:231] offset:8064
	s_mov_b32 exec_hi, 0x00ffffff
	ds_write_b128 v232, v[224:227] offset:4096
	s_mov_b32 exec_hi, 0x000fffff
	ds_write_b128 v232, v[228:231] offset:9088
	s_mov_b64 exec, -1
	v_lshrrev_b32_e32 v221, 2, v240
	v_add_u32_e32 v221, s22, v221
	ds_write_b32 v221, v228 offset:4224
	v_lshrrev_b32_e32 v233, 1, v240
	s_lshl_b32 s0, s76, 10
	s_add_i32 s0, s0, 0x11000
	v_add_u32_e32 v233, s0, v233
	ds_read_b64 v[128:129], v233 offset:0
	ds_read_b64 v[130:131], v233 offset:512
	ds_read_b64 v[132:133], v233 offset:1024
	ds_read_b64 v[134:135], v233 offset:1536
	ds_read_b64 v[136:137], v233 offset:2048
	ds_read_b64 v[138:139], v233 offset:2560
	ds_read_b64 v[140:141], v233 offset:3072
	ds_read_b64 v[142:143], v233 offset:3584
	ds_read_b64 v[144:145], v233 offset:4096
	ds_read_b64 v[146:147], v233 offset:4608
	ds_read_b64 v[148:149], v233 offset:5120
	ds_read_b64 v[150:151], v233 offset:5632
	ds_read_b64 v[152:153], v233 offset:6144
	ds_read_b64 v[154:155], v233 offset:6656
	ds_read_b64 v[156:157], v233 offset:7168
	ds_read_b64 v[158:159], v233 offset:7680
	v_mov_b32_e32 v220, 1
	v_lshrrev_b32_e32 v200, 4, v240
	v_lshrrev_b32_e32 v201, 3, v200
	v_and_b32_e32 v200, 7, v200
	s_add_i32 s3, s22, 4224
	s_waitcnt lgkmcnt(0)
; __device__ __forceinline__ void peer_tile(const Args& A, LAS unsigned char* lds, int tile) {
;     ...
;     for (int ti = 0; ti < 8; ++ti) {
;         const int tl = 8 * w + ti;
;         const u32x2 e0 = SEL[tl * 128 + lane], e1 = SEL[tl * 128 + 64 + lane];
;         const int p0 = (int)(e0.x >> 10), p1 = (int)(e1.x >> 10);
;         int off = 0;
;         for (int p = 0; p < 16; ++p) {
;             const unsigned long long m0 = __ballot(p0 == p), m1 = __ballot(p1 == p);
;             const int c0 = __popcll(m0), c1 = __popcll(m1);
;             const int r0 = __builtin_amdgcn_mbcnt_hi((unsigned)(m0 >> 32), __builtin_amdgcn_mbcnt_lo((unsigned)m0, 0u));
;             const int r1 = __builtin_amdgcn_mbcnt_hi((unsigned)(m1 >> 32), __builtin_amdgcn_mbcnt_lo((unsigned)m1, 0u));
;             if (p0 == p) SORT[tl * 128 + off + r0] = e0;
;             if (p1 == p) SORT[tl * 128 + off + c0 + r1] = e1;
;             if (lane == 0) OFFS[tl * 17 + p] = off;
;             off += c0 + c1;
;         }
;         if (lane == 0) OFFS[tl * 17 + 16] = off;
;     }
	v_lshrrev_b32_e32 v160, 11, v128
	v_lshl_add_u32 v176, v160, 2, s3
	v_lshrrev_b32_e32 v161, 11, v130
	v_lshl_add_u32 v177, v161, 2, s3
	v_lshrrev_b32_e32 v162, 11, v132
	v_lshl_add_u32 v178, v162, 2, s3
	v_lshrrev_b32_e32 v163, 11, v134
	v_lshl_add_u32 v179, v163, 2, s3
	v_lshrrev_b32_e32 v164, 11, v136
	v_lshl_add_u32 v180, v164, 2, s3
	v_lshrrev_b32_e32 v165, 11, v138
	v_lshl_add_u32 v181, v165, 2, s3
	v_lshrrev_b32_e32 v166, 11, v140
	v_lshl_add_u32 v182, v166, 2, s3
	v_lshrrev_b32_e32 v167, 11, v142
	v_lshl_add_u32 v183, v167, 2, s3
	v_lshrrev_b32_e32 v168, 11, v144
	v_lshl_add_u32 v184, v168, 2, s3
	v_lshrrev_b32_e32 v169, 11, v146
	v_lshl_add_u32 v185, v169, 2, s3
	v_lshrrev_b32_e32 v170, 11, v148
	v_lshl_add_u32 v186, v170, 2, s3
	v_lshrrev_b32_e32 v171, 11, v150
	v_lshl_add_u32 v187, v171, 2, s3
	v_lshrrev_b32_e32 v172, 11, v152
	v_lshl_add_u32 v188, v172, 2, s3
	v_lshrrev_b32_e32 v173, 11, v154
	v_lshl_add_u32 v189, v173, 2, s3
	v_lshrrev_b32_e32 v174, 11, v156
	v_lshl_add_u32 v190, v174, 2, s3
	v_lshrrev_b32_e32 v175, 11, v158
	v_lshl_add_u32 v191, v175, 2, s3
	ds_add_rtn_u32 v176, v176, v220 offset:0
	ds_add_rtn_u32 v177, v177, v220 offset:0
	ds_add_rtn_u32 v178, v178, v220 offset:32
	ds_add_rtn_u32 v179, v179, v220 offset:32
	ds_add_rtn_u32 v180, v180, v220 offset:64
	ds_add_rtn_u32 v181, v181, v220 offset:64
	ds_add_rtn_u32 v182, v182, v220 offset:96
	ds_add_rtn_u32 v183, v183, v220 offset:96
	ds_add_rtn_u32 v184, v184, v220 offset:128
	ds_add_rtn_u32 v185, v185, v220 offset:128
	ds_add_rtn_u32 v186, v186, v220 offset:160
	ds_add_rtn_u32 v187, v187, v220 offset:160
	ds_add_rtn_u32 v188, v188, v220 offset:192
	ds_add_rtn_u32 v189, v189, v220 offset:192
	ds_add_rtn_u32 v190, v190, v220 offset:224
	ds_add_rtn_u32 v191, v191, v220 offset:224
	v_lshl_add_u32 v207, v201, 5, s3
	ds_read_b32 v203, v221 offset:4224
	ds_read_b128 v[192:195], v207
	ds_read_b128 v[196:199], v207 offset:16
	v_mov_b32_e32 v202, 0
	s_waitcnt lgkmcnt(0)
	v_cmp_lt_u32_e64 s[38:39], 0, v200
	v_cmp_lt_u32_e64 s[40:41], 1, v200
	v_cmp_lt_u32_e64 s[42:43], 2, v200
	v_cmp_lt_u32_e64 s[44:45], 3, v200
	v_cmp_lt_u32_e64 s[64:65], 4, v200
	v_cmp_lt_u32_e64 s[66:67], 5, v200
	v_cmp_lt_u32_e64 s[94:95], 6, v200
	v_cndmask_b32_e64 v206, 0, v192, s[38:39]
	v_add_u32_e32 v202, v202, v206
	v_cndmask_b32_e64 v206, 0, v193, s[40:41]
	v_add_u32_e32 v202, v202, v206
	v_cndmask_b32_e64 v206, 0, v194, s[42:43]
	v_add_u32_e32 v202, v202, v206
	v_cndmask_b32_e64 v206, 0, v195, s[44:45]
	v_add_u32_e32 v202, v202, v206
	v_cndmask_b32_e64 v206, 0, v196, s[64:65]
	v_add_u32_e32 v202, v202, v206
	v_cndmask_b32_e64 v206, 0, v197, s[66:67]
	v_add_u32_e32 v202, v202, v206
	v_cndmask_b32_e64 v206, 0, v198, s[94:95]
	v_add_u32_e32 v202, v202, v206
	v_add_u32_e32 v204, 3, v202
	v_add3_u32 v212, v202, v203, 3
	v_lshrrev_b32_e32 v204, 2, v204
	v_lshrrev_b32_e32 v212, 2, v212
	v_sub_u32_e32 v212, v212, v204
	v_lshl_add_u32 v207, v200, 3, v201
	v_lshl_add_u32 v207, v207, 2, s3
	ds_write_b32 v207, v212 offset:256
	v_lshl_add_u32 v208, v200, 5, s3
	ds_read_b128 v[192:195], v208 offset:256
	ds_read_b128 v[196:199], v208 offset:272
	v_mov_b32_e32 v205, 0
	s_waitcnt lgkmcnt(0)
	v_cmp_lt_u32_e64 s[38:39], 0, v201
	v_cmp_lt_u32_e64 s[40:41], 1, v201
	v_cmp_lt_u32_e64 s[42:43], 2, v201
	v_cmp_lt_u32_e64 s[44:45], 3, v201
	v_cmp_lt_u32_e64 s[64:65], 4, v201
	v_cmp_lt_u32_e64 s[66:67], 5, v201
	v_cmp_lt_u32_e64 s[94:95], 6, v201
	v_cndmask_b32_e64 v206, 0, v192, s[38:39]
	v_add_u32_e32 v205, v205, v206
	v_cndmask_b32_e64 v206, 0, v193, s[40:41]
	v_add_u32_e32 v205, v205, v206
	v_cndmask_b32_e64 v206, 0, v194, s[42:43]
	v_add_u32_e32 v205, v205, v206
	v_cndmask_b32_e64 v206, 0, v195, s[44:45]
	v_add_u32_e32 v205, v205, v206
	v_cndmask_b32_e64 v206, 0, v196, s[64:65]
	v_add_u32_e32 v205, v205, v206
	v_cndmask_b32_e64 v206, 0, v197, s[66:67]
	v_add_u32_e32 v205, v205, v206
	v_cndmask_b32_e64 v206, 0, v198, s[94:95]
	v_add_u32_e32 v205, v205, v206
	v_add_u32_e32 v206, v192, v193
	v_add_u32_e32 v206, v206, v194
	v_add_u32_e32 v206, v206, v195
	v_add_u32_e32 v206, v206, v196
	v_add_u32_e32 v206, v206, v197
	v_add_u32_e32 v206, v206, v198
	v_add_u32_e32 v206, v206, v199
	v_lshl_add_u32 v207, v200, 2, s3
	ds_write_b32 v207, v206 offset:512
	v_mov_b32_e32 v207, s3
	ds_read_b128 v[192:195], v207 offset:512
	ds_read_b128 v[196:199], v207 offset:528
	ds_write_b32 v221, v202 offset:4224
	s_waitcnt lgkmcnt(0)
	v_cmp_lt_u32_e64 s[38:39], 0, v200
	v_cmp_lt_u32_e64 s[40:41], 1, v200
	v_cmp_lt_u32_e64 s[42:43], 2, v200
	v_cmp_lt_u32_e64 s[44:45], 3, v200
	v_cmp_lt_u32_e64 s[64:65], 4, v200
	v_cmp_lt_u32_e64 s[66:67], 5, v200
	v_cmp_lt_u32_e64 s[94:95], 6, v200
	v_cndmask_b32_e64 v206, 0, v192, s[38:39]
	v_add_u32_e32 v205, v205, v206
	v_cndmask_b32_e64 v206, 0, v193, s[40:41]
	v_add_u32_e32 v205, v205, v206
	v_cndmask_b32_e64 v206, 0, v194, s[42:43]
	v_add_u32_e32 v205, v205, v206
	v_cndmask_b32_e64 v206, 0, v195, s[44:45]
	v_add_u32_e32 v205, v205, v206
	v_cndmask_b32_e64 v206, 0, v196, s[64:65]
	v_add_u32_e32 v205, v205, v206
	v_cndmask_b32_e64 v206, 0, v197, s[66:67]
	v_add_u32_e32 v205, v205, v206
	v_cndmask_b32_e64 v206, 0, v198, s[94:95]
	v_add_u32_e32 v205, v205, v206
	v_sub_u32_e32 v205, v205, v204
	v_lshrrev_b32_e32 v208, 4, v240
	v_and_b32_e32 v222, 31, v208
	v_lshrrev_b32_e32 v208, 5, v208
	v_add_u32_e32 v207, 0, v208
	v_lshl_add_u32 v206, v207, 5, s3
	ds_read_b128 v[192:195], v206
	ds_read_b128 v[196:199], v206 offset:16
	v_lshlrev_b32_e32 v206, 2, v222
	v_lshlrev_b32_e32 v223, 3, v207
	s_waitcnt lgkmcnt(0)
; __device__ __forceinline__ void peer_tile(const Args& A, LAS unsigned char* lds, int tile) {
;     ...
;     for (int ti = 0; ti < 8; ++ti) {
;         const int tl = 8 * w + ti;
;         const u32x2 e0 = SEL[tl * 128 + lane], e1 = SEL[tl * 128 + 64 + lane];
;         const int p0 = (int)(e0.x >> 10), p1 = (int)(e1.x >> 10);
;         int off = 0;
;         for (int p = 0; p < 16; ++p) {
;             const unsigned long long m0 = __ballot(p0 == p), m1 = __ballot(p1 == p);
;             const int c0 = __popcll(m0), c1 = __popcll(m1);
;             const int r0 = __builtin_amdgcn_mbcnt_hi((unsigned)(m0 >> 32), __builtin_amdgcn_mbcnt_lo((unsigned)m0, 0u));
;             const int r1 = __builtin_amdgcn_mbcnt_hi((unsigned)(m1 >> 32), __builtin_amdgcn_mbcnt_lo((unsigned)m1, 0u));
;             if (p0 == p) SORT[tl * 128 + off + r0] = e0;
;             if (p1 == p) SORT[tl * 128 + off + c0 + r1] = e1;
;             if (lane == 0) OFFS[tl * 17 + p] = off;
;             off += c0 + c1;
;         }
;         if (lane == 0) OFFS[tl * 17 + 16] = off;
;     }
	v_cmp_le_u32_e64 s[38:39], v193, v206
	v_cmp_le_u32_e64 s[40:41], v194, v206
	v_cmp_le_u32_e64 s[42:43], v195, v206
	v_cmp_le_u32_e64 s[44:45], v196, v206
	v_cmp_le_u32_e64 s[64:65], v197, v206
	v_cmp_le_u32_e64 s[66:67], v198, v206
	v_cmp_le_u32_e64 s[94:95], v199, v206
	v_addc_co_u32_e64 v223, s[92:93], 0, v223, s[38:39]
	v_addc_co_u32_e64 v223, s[92:93], 0, v223, s[40:41]
	v_addc_co_u32_e64 v223, s[92:93], 0, v223, s[42:43]
	v_addc_co_u32_e64 v223, s[92:93], 0, v223, s[44:45]
	v_addc_co_u32_e64 v223, s[92:93], 0, v223, s[64:65]
	v_addc_co_u32_e64 v223, s[92:93], 0, v223, s[66:67]
	v_addc_co_u32_e64 v223, s[92:93], 0, v223, s[94:95]
	v_lshlrev_b32_e32 v223, 2, v223
	ds_bpermute_b32 v216, v223, v205
	v_add_u32_e32 v207, 2, v208
	v_lshl_add_u32 v206, v207, 5, s3
	ds_read_b128 v[192:195], v206
	ds_read_b128 v[196:199], v206 offset:16
	v_lshlrev_b32_e32 v206, 2, v222
	v_lshlrev_b32_e32 v223, 3, v207
	s_waitcnt lgkmcnt(0)
	v_cmp_le_u32_e64 s[38:39], v193, v206
	v_cmp_le_u32_e64 s[40:41], v194, v206
	v_cmp_le_u32_e64 s[42:43], v195, v206
	v_cmp_le_u32_e64 s[44:45], v196, v206
	v_cmp_le_u32_e64 s[64:65], v197, v206
	v_cmp_le_u32_e64 s[66:67], v198, v206
	v_cmp_le_u32_e64 s[94:95], v199, v206
	v_addc_co_u32_e64 v223, s[92:93], 0, v223, s[38:39]
	v_addc_co_u32_e64 v223, s[92:93], 0, v223, s[40:41]
	v_addc_co_u32_e64 v223, s[92:93], 0, v223, s[42:43]
	v_addc_co_u32_e64 v223, s[92:93], 0, v223, s[44:45]
	v_addc_co_u32_e64 v223, s[92:93], 0, v223, s[64:65]
	v_addc_co_u32_e64 v223, s[92:93], 0, v223, s[66:67]
	v_addc_co_u32_e64 v223, s[92:93], 0, v223, s[94:95]
	v_lshlrev_b32_e32 v223, 2, v223
	ds_bpermute_b32 v217, v223, v205
	v_add_u32_e32 v207, 4, v208
	v_lshl_add_u32 v206, v207, 5, s3
	ds_read_b128 v[192:195], v206
	ds_read_b128 v[196:199], v206 offset:16
	v_lshlrev_b32_e32 v206, 2, v222
	v_lshlrev_b32_e32 v223, 3, v207
	s_waitcnt lgkmcnt(0)
	v_cmp_le_u32_e64 s[38:39], v193, v206
	v_cmp_le_u32_e64 s[40:41], v194, v206
	v_cmp_le_u32_e64 s[42:43], v195, v206
	v_cmp_le_u32_e64 s[44:45], v196, v206
	v_cmp_le_u32_e64 s[64:65], v197, v206
	v_cmp_le_u32_e64 s[66:67], v198, v206
	v_cmp_le_u32_e64 s[94:95], v199, v206
	v_addc_co_u32_e64 v223, s[92:93], 0, v223, s[38:39]
	v_addc_co_u32_e64 v223, s[92:93], 0, v223, s[40:41]
	v_addc_co_u32_e64 v223, s[92:93], 0, v223, s[42:43]
	v_addc_co_u32_e64 v223, s[92:93], 0, v223, s[44:45]
	v_addc_co_u32_e64 v223, s[92:93], 0, v223, s[64:65]
	v_addc_co_u32_e64 v223, s[92:93], 0, v223, s[66:67]
	v_addc_co_u32_e64 v223, s[92:93], 0, v223, s[94:95]
	v_lshlrev_b32_e32 v223, 2, v223
	ds_bpermute_b32 v218, v223, v205
	v_add_u32_e32 v207, 6, v208
	v_lshl_add_u32 v206, v207, 5, s3
	ds_read_b128 v[192:195], v206
	ds_read_b128 v[196:199], v206 offset:16
	v_lshlrev_b32_e32 v206, 2, v222
	v_lshlrev_b32_e32 v223, 3, v207
	s_waitcnt lgkmcnt(0)
	v_cmp_le_u32_e64 s[38:39], v193, v206
	v_cmp_le_u32_e64 s[40:41], v194, v206
	v_cmp_le_u32_e64 s[42:43], v195, v206
	v_cmp_le_u32_e64 s[44:45], v196, v206
	v_cmp_le_u32_e64 s[64:65], v197, v206
	v_cmp_le_u32_e64 s[66:67], v198, v206
	v_cmp_le_u32_e64 s[94:95], v199, v206
	v_addc_co_u32_e64 v223, s[92:93], 0, v223, s[38:39]
	v_addc_co_u32_e64 v223, s[92:93], 0, v223, s[40:41]
	v_addc_co_u32_e64 v223, s[92:93], 0, v223, s[42:43]
	v_addc_co_u32_e64 v223, s[92:93], 0, v223, s[44:45]
	v_addc_co_u32_e64 v223, s[92:93], 0, v223, s[64:65]
	v_addc_co_u32_e64 v223, s[92:93], 0, v223, s[66:67]
	v_addc_co_u32_e64 v223, s[92:93], 0, v223, s[94:95]
	v_lshlrev_b32_e32 v223, 2, v223
	ds_bpermute_b32 v219, v223, v205
	s_waitcnt lgkmcnt(0)
	v_add_u32_e32 v216, v216, v222
	v_add_u32_e32 v217, v217, v222
	v_add_u32_e32 v218, v218, v222
	v_add_u32_e32 v219, v219, v222
	v_lshlrev_b32_e32 v160, 2, v160
	ds_bpermute_b32 v160, v160, v202
	v_lshlrev_b32_e32 v161, 2, v161
	ds_bpermute_b32 v161, v161, v202
	v_lshlrev_b32_e32 v162, 2, v162
	v_add_u32_e32 v162, 32, v162
	ds_bpermute_b32 v162, v162, v202
	v_lshlrev_b32_e32 v163, 2, v163
	v_add_u32_e32 v163, 32, v163
	ds_bpermute_b32 v163, v163, v202
	v_lshlrev_b32_e32 v164, 2, v164
	v_add_u32_e32 v164, 64, v164
	ds_bpermute_b32 v164, v164, v202
	v_lshlrev_b32_e32 v165, 2, v165
	v_add_u32_e32 v165, 64, v165
	ds_bpermute_b32 v165, v165, v202
	v_lshlrev_b32_e32 v166, 2, v166
	v_add_u32_e32 v166, 96, v166
	ds_bpermute_b32 v166, v166, v202
	v_lshlrev_b32_e32 v167, 2, v167
	v_add_u32_e32 v167, 96, v167
	ds_bpermute_b32 v167, v167, v202
	v_lshlrev_b32_e32 v168, 2, v168
	v_add_u32_e32 v168, 128, v168
	ds_bpermute_b32 v168, v168, v202
	v_lshlrev_b32_e32 v169, 2, v169
	v_add_u32_e32 v169, 128, v169
	ds_bpermute_b32 v169, v169, v202
	v_lshlrev_b32_e32 v170, 2, v170
	v_add_u32_e32 v170, 160, v170
	ds_bpermute_b32 v170, v170, v202
	v_lshlrev_b32_e32 v171, 2, v171
	v_add_u32_e32 v171, 160, v171
	ds_bpermute_b32 v171, v171, v202
	v_lshlrev_b32_e32 v172, 2, v172
	v_add_u32_e32 v172, 192, v172
	ds_bpermute_b32 v172, v172, v202
	v_lshlrev_b32_e32 v173, 2, v173
	v_add_u32_e32 v173, 192, v173
	ds_bpermute_b32 v173, v173, v202
	v_lshlrev_b32_e32 v174, 2, v174
	v_add_u32_e32 v174, 224, v174
	ds_bpermute_b32 v174, v174, v202
	v_lshlrev_b32_e32 v175, 2, v175
	v_add_u32_e32 v175, 224, v175
	ds_bpermute_b32 v175, v175, v202
	s_waitcnt lgkmcnt(0)
; __device__ __forceinline__ void peer_tile(const Args& A, LAS unsigned char* lds, int tile) {
;     ...
;         for (int p = 0; p < 16; ++p) {
;             const unsigned long long m0 = __ballot(p0 == p), m1 = __ballot(p1 == p);
;             const int c0 = __popcll(m0), c1 = __popcll(m1);
;             const int r0 = __builtin_amdgcn_mbcnt_hi((unsigned)(m0 >> 32), __builtin_amdgcn_mbcnt_lo((unsigned)m0, 0u));
;             const int r1 = __builtin_amdgcn_mbcnt_hi((unsigned)(m1 >> 32), __builtin_amdgcn_mbcnt_lo((unsigned)m1, 0u));
;             if (p0 == p) SORT[tl * 128 + off + r0] = e0;
;             if (p1 == p) SORT[tl * 128 + off + c0 + r1] = e1;
;             if (lane == 0) OFFS[tl * 17 + p] = off;
;             off += c0 + c1;
	v_add_u32_e32 v176, v176, v160
	v_lshrrev_b32_e32 v160, 2, v176
	v_and_b32_e32 v176, 3, v176
	v_lshlrev_b32_e32 v160, 2, v160
	ds_bpermute_b32 v160, v160, v216
	v_add_u32_e32 v177, v177, v161
	v_lshrrev_b32_e32 v161, 2, v177
	v_and_b32_e32 v177, 3, v177
	v_lshlrev_b32_e32 v161, 2, v161
	ds_bpermute_b32 v161, v161, v216
	v_add_u32_e32 v178, v178, v162
	v_lshrrev_b32_e32 v162, 2, v178
	v_and_b32_e32 v178, 3, v178
	v_lshlrev_b32_e32 v162, 2, v162
	v_add_u32_e32 v162, 128, v162
	ds_bpermute_b32 v162, v162, v216
	v_add_u32_e32 v179, v179, v163
	v_lshrrev_b32_e32 v163, 2, v179
	v_and_b32_e32 v179, 3, v179
	v_lshlrev_b32_e32 v163, 2, v163
	v_add_u32_e32 v163, 128, v163
	ds_bpermute_b32 v163, v163, v216
	v_add_u32_e32 v180, v180, v164
	v_lshrrev_b32_e32 v164, 2, v180
	v_and_b32_e32 v180, 3, v180
	v_lshlrev_b32_e32 v164, 2, v164
	ds_bpermute_b32 v164, v164, v217
	v_add_u32_e32 v181, v181, v165
	v_lshrrev_b32_e32 v165, 2, v181
	v_and_b32_e32 v181, 3, v181
	v_lshlrev_b32_e32 v165, 2, v165
	ds_bpermute_b32 v165, v165, v217
	v_add_u32_e32 v182, v182, v166
	v_lshrrev_b32_e32 v166, 2, v182
	v_and_b32_e32 v182, 3, v182
	v_lshlrev_b32_e32 v166, 2, v166
	v_add_u32_e32 v166, 128, v166
	ds_bpermute_b32 v166, v166, v217
	v_add_u32_e32 v183, v183, v167
	v_lshrrev_b32_e32 v167, 2, v183
	v_and_b32_e32 v183, 3, v183
	v_lshlrev_b32_e32 v167, 2, v167
	v_add_u32_e32 v167, 128, v167
	ds_bpermute_b32 v167, v167, v217
	v_add_u32_e32 v184, v184, v168
	v_lshrrev_b32_e32 v168, 2, v184
	v_and_b32_e32 v184, 3, v184
	v_lshlrev_b32_e32 v168, 2, v168
	ds_bpermute_b32 v168, v168, v218
	v_add_u32_e32 v185, v185, v169
	v_lshrrev_b32_e32 v169, 2, v185
	v_and_b32_e32 v185, 3, v185
	v_lshlrev_b32_e32 v169, 2, v169
	ds_bpermute_b32 v169, v169, v218
	v_add_u32_e32 v186, v186, v170
	v_lshrrev_b32_e32 v170, 2, v186
	v_and_b32_e32 v186, 3, v186
	v_lshlrev_b32_e32 v170, 2, v170
	v_add_u32_e32 v170, 128, v170
	ds_bpermute_b32 v170, v170, v218
	v_add_u32_e32 v187, v187, v171
	v_lshrrev_b32_e32 v171, 2, v187
	v_and_b32_e32 v187, 3, v187
	v_lshlrev_b32_e32 v171, 2, v171
	v_add_u32_e32 v171, 128, v171
	ds_bpermute_b32 v171, v171, v218
	v_add_u32_e32 v188, v188, v172
	v_lshrrev_b32_e32 v172, 2, v188
	v_and_b32_e32 v188, 3, v188
	v_lshlrev_b32_e32 v172, 2, v172
	ds_bpermute_b32 v172, v172, v219
	v_add_u32_e32 v189, v189, v173
	v_lshrrev_b32_e32 v173, 2, v189
	v_and_b32_e32 v189, 3, v189
	v_lshlrev_b32_e32 v173, 2, v173
	ds_bpermute_b32 v173, v173, v219
	v_add_u32_e32 v190, v190, v174
	v_lshrrev_b32_e32 v174, 2, v190
	v_and_b32_e32 v190, 3, v190
	v_lshlrev_b32_e32 v174, 2, v174
	v_add_u32_e32 v174, 128, v174
	ds_bpermute_b32 v174, v174, v219
	v_add_u32_e32 v191, v191, v175
	v_lshrrev_b32_e32 v175, 2, v191
	v_and_b32_e32 v191, 3, v191
	v_lshlrev_b32_e32 v175, 2, v175
	v_add_u32_e32 v175, 128, v175
	ds_bpermute_b32 v175, v175, v219
	s_waitcnt lgkmcnt(0)
; #define IT_ADVANCE() do { it_j += 4; while (it_j >= it_end) { if (it_done) break; ++it_tk; if (it_tk == 4) { it_tk = 0; ++it_p; if (it_p == 16) { it_done = true; it_p = 15; it_j = 0; it_end = 1; break; } } \
;             it_j = __builtin_amdgcn_readfirstlane(OFFS[(tb + it_tk) * 17 + it_p]); it_end = __builtin_amdgcn_readfirstlane(OFFS[(tb + it_tk) * 17 + it_p + 1]); } } while (0)
; __device__ __forceinline__ void peer_tile(const Args& A, LAS unsigned char* lds, int tile) {
;     ...
;             if (p0 == p) SORT[tl * 128 + off + r0] = e0;
;             if (p1 == p) SORT[tl * 128 + off + c0 + r1] = e1;
;             if (lane == 0) OFFS[tl * 17 + p] = off;
;             off += c0 + c1;
;         }
;         if (lane == 0) OFFS[tl * 17 + 16] = off;
;     ...
;         int it_p = 0, it_tk = -1, it_j = 0, it_end = 0; bool it_done = false;
;     ...
;         u32x4 uA[4], vA[4], uB[4], vB[4]; float cgA = 0.f, suA = 0.f, svA = 0.f, cgB = 0.f, suB = 0.f, svB = 0.f;
; #pragma unroll
;         for (int k = 0; k < 4; ++k) { uA[k] = (u32x4){0u, 0u, 0u, 0u}; vA[k] = uA[k]; uB[k] = uA[k]; vB[k] = uA[k]; }
;         IT_ADVANCE();
;         LOAD_SET(uA, vA, cgA, suA, svA);
	v_lshl_add_u32 v160, v160, 4, s22
	v_lshl_add_u32 v160, v176, 2, v160
	ds_write_b32 v160, v128
	ds_write_b32 v160, v129 offset:4992
	v_lshl_add_u32 v161, v161, 4, s22
	v_lshl_add_u32 v161, v177, 2, v161
	ds_write_b32 v161, v130
	ds_write_b32 v161, v131 offset:4992
	v_lshl_add_u32 v162, v162, 4, s22
	v_lshl_add_u32 v162, v178, 2, v162
	ds_write_b32 v162, v132
	ds_write_b32 v162, v133 offset:4992
	v_lshl_add_u32 v163, v163, 4, s22
	v_lshl_add_u32 v163, v179, 2, v163
	ds_write_b32 v163, v134
	ds_write_b32 v163, v135 offset:4992
	v_lshl_add_u32 v164, v164, 4, s22
	v_lshl_add_u32 v164, v180, 2, v164
	ds_write_b32 v164, v136
	ds_write_b32 v164, v137 offset:4992
	v_lshl_add_u32 v165, v165, 4, s22
	v_lshl_add_u32 v165, v181, 2, v165
	ds_write_b32 v165, v138
	ds_write_b32 v165, v139 offset:4992
	v_lshl_add_u32 v166, v166, 4, s22
	v_lshl_add_u32 v166, v182, 2, v166
	ds_write_b32 v166, v140
	ds_write_b32 v166, v141 offset:4992
	v_lshl_add_u32 v167, v167, 4, s22
	v_lshl_add_u32 v167, v183, 2, v167
	ds_write_b32 v167, v142
	ds_write_b32 v167, v143 offset:4992
	v_lshl_add_u32 v168, v168, 4, s22
	v_lshl_add_u32 v168, v184, 2, v168
	ds_write_b32 v168, v144
	ds_write_b32 v168, v145 offset:4992
	v_lshl_add_u32 v169, v169, 4, s22
	v_lshl_add_u32 v169, v185, 2, v169
	ds_write_b32 v169, v146
	ds_write_b32 v169, v147 offset:4992
	v_lshl_add_u32 v170, v170, 4, s22
	v_lshl_add_u32 v170, v186, 2, v170
	ds_write_b32 v170, v148
	ds_write_b32 v170, v149 offset:4992
	v_lshl_add_u32 v171, v171, 4, s22
	v_lshl_add_u32 v171, v187, 2, v171
	ds_write_b32 v171, v150
	ds_write_b32 v171, v151 offset:4992
	v_lshl_add_u32 v172, v172, 4, s22
	v_lshl_add_u32 v172, v188, 2, v172
	ds_write_b32 v172, v152
	ds_write_b32 v172, v153 offset:4992
	v_lshl_add_u32 v173, v173, 4, s22
	v_lshl_add_u32 v173, v189, 2, v173
	ds_write_b32 v173, v154
	ds_write_b32 v173, v155 offset:4992
	v_lshl_add_u32 v174, v174, 4, s22
	v_lshl_add_u32 v174, v190, 2, v174
	ds_write_b32 v174, v156
	ds_write_b32 v174, v157 offset:4992
	v_lshl_add_u32 v175, v175, 4, s22
	v_lshl_add_u32 v175, v191, 2, v175
	ds_write_b32 v175, v158
	ds_write_b32 v175, v159 offset:4992
	v_mov_b32_e32 v206, 0x7fffffff
	ds_write_b32 v221, v206 offset:4224
	ds_write_b32 v221, v206 offset:4480
	ds_write_b32 v221, v206 offset:4736
	s_mov_b32 s91, 256
	s_add_i32 s20, s91, 3
	s_and_b32 s20, s20, -4
	s_mov_b32 s24, s8
	s_and_b32 s25, s9, 0xffff
	s_mov_b32 s26, 0x10000
	s_mov_b32 s27, 0x00027000
	s_mov_b32 s28, s52
	s_and_b32 s29, s53, 0xffff
	s_mov_b32 s30, 0x10000
	s_mov_b32 s31, 0x00027000
	s_waitcnt vmcnt(0) lgkmcnt(0)
	v_mov_b32_e32 v213, s22
	v_mov_b32_e32 v233, v240
	v_mov_b32_e32 v235, v240
	v_mov_b32_e32 v237, v240
	v_mov_b32_e32 v239, v240
	ds_read_b32 v232, v213 offset:0
	ds_read_b32 v234, v213 offset:4
	ds_read_b32 v236, v213 offset:8
	ds_read_b32 v238, v213 offset:12
	s_waitcnt lgkmcnt(0)
	buffer_load_dwordx4 v[128:131], v[232:233], s[56:59], 0 idxen offen
	buffer_load_dwordx4 v[132:135], v[234:235], s[56:59], 0 idxen offen
	buffer_load_dwordx4 v[136:139], v[236:237], s[56:59], 0 idxen offen
	buffer_load_dwordx4 v[140:143], v[238:239], s[56:59], 0 idxen offen
	ds_read_b32 v232, v213 offset:16
	ds_read_b32 v234, v213 offset:20
	ds_read_b32 v236, v213 offset:24
	ds_read_b32 v238, v213 offset:28
	s_waitcnt lgkmcnt(0)
	buffer_load_dwordx4 v[144:147], v[232:233], s[56:59], 0 idxen offen
	buffer_load_dwordx4 v[148:151], v[234:235], s[56:59], 0 idxen offen
	buffer_load_dwordx4 v[152:155], v[236:237], s[56:59], 0 idxen offen
	buffer_load_dwordx4 v[156:159], v[238:239], s[56:59], 0 idxen offen
	ds_read_b32 v232, v213 offset:32
	ds_read_b32 v234, v213 offset:36
	ds_read_b32 v236, v213 offset:40
	ds_read_b32 v238, v213 offset:44
	s_waitcnt lgkmcnt(0)
	buffer_load_dwordx4 v[160:163], v[232:233], s[56:59], 0 idxen offen
	buffer_load_dwordx4 v[164:167], v[234:235], s[56:59], 0 idxen offen
	buffer_load_dwordx4 v[168:171], v[236:237], s[56:59], 0 idxen offen
	buffer_load_dwordx4 v[172:175], v[238:239], s[56:59], 0 idxen offen
	ds_read_b32 v232, v213 offset:48
	ds_read_b32 v234, v213 offset:52
	ds_read_b32 v236, v213 offset:56
	ds_read_b32 v238, v213 offset:60
	s_mov_b32 s21, 0
	s_mov_b32 s89, -1
	s_mov_b32 s86, 0
	v_lshrrev_b32_e32 v208, 6, v240
	v_and_b32_e32 v208, 3, v208
	v_lshrrev_b32_e32 v209, 1, v208
	v_lshlrev_b32_e32 v208, 1, v208
	v_and_b32_e32 v208, 2, v208
	v_or_b32_e32 v208, v208, v209
	v_lshlrev_b32_e32 v208, 2, v208
	v_add3_u32 v211, v208, v247, s22
	ds_read_b32 v248, v211
	ds_read_b32 v249, v211 offset:4992
	s_branch .LU_sw0

; __device__ __forceinline__ void peer_tile(const Args& A, LAS unsigned char* lds, int tile) {
;     ...
;         for (int p = 0; p < 16; ++p) {
; #pragma unroll
;             for (int tk = 0; tk < 4; ++tk) {
;                 const int tl = tb + tk;
;                 const int beg = __builtin_amdgcn_readfirstlane(OFFS[tl * 17 + p]), end = __builtin_amdgcn_readfirstlane(OFFS[tl * 17 + p + 1]);
.LU_sw0:
	s_add_i32 s89, s89, 1
	s_cmp_ge_u32 s89, 64
	s_cbranch_scc1 .LU_sw0_end
	s_and_b32 s0, s89, 7
	s_lshr_b32 s1, s89, 3
	s_lshl_b32 s0, s0, 3
	s_or_b32 s0, s0, s1
	s_nop 0
	v_readlane_b32 s90, v212, s0
	s_and_b32 s23, s89, 7
	s_cmp_eq_u32 s90, 0
	s_cbranch_scc1 .LU_sw0
	s_cmp_ge_u32 s23, 4
	s_cbranch_scc1 .LU_sw0_h
	s_cmp_ge_u32 s23, 2
	s_cbranch_scc1 .LU_sw0_23
	s_cmp_eq_u32 s23, 0
	s_cbranch_scc1 .LU_t0_s0
	s_branch .LU_t1_s0
